# hoist: loop-invariant LDS read address adds moved in front of the GEMM main loops (16 VALU ops out of the loops); rest = v95
# speedup vs baseline: 1.0046x; 1.0046x over previous
; template <class Sched, class Epi>
; __device__ __forceinline__ void gemm_phase(LAS unsigned char* lds, const Sched& S, const Epi& E, const int K, const int lda, const int ldb) {
;     ...
;         const bool has_next = S.next(ui + 1, nxt);
;         const char* nA = has_next ? nxt.A : cA; const char* nB = has_next ? nxt.B : cB;
;         const bool chalf = cur.half != 0;
;         for (int t = 0; t < nt; t += 2) {
;             const bool last = (t == nt - 2);
;             const char* a1 = cA + (size_t)(t + 1) * kstep;
;             const char* a2 = last ? nA : cA + (size_t)(t + 2) * kstep; const char* b2 = last ? nB : cB + (size_t)(t + 2) * kstep;
;     ...
; #pragma unroll
;         for (int a = 0; a < 2; ++a)
; #pragma unroll
;             for (int b = 0; b < 2; ++b)
; #pragma unroll
;                 for (int m = 0; m < 4; ++m)
; #pragma unroll
;                     for (int n = 0; n < 2; ++n) acc[a][b][m][n] = (f32x4){0.f, 0.f, 0.f, 0.f};
.LBB0_391:
	s_cmp_eq_u32 s40, 0
	s_cselect_b64 s[36:37], -1, 0
	s_add_u32 s19, s38, 0x100
	s_addc_u32 s21, s39, 0
	v_mov_b32_e32 v4, v203
	v_mov_b32_e32 v5, v203
	s_add_u32 s38, s4, 0x80080
	v_mov_b32_e32 v2, v203
	v_mov_b32_e32 v3, v203
	v_mov_b32_e32 v66, 0
	v_mov_b64_e32 v[8:9], v[4:5]
	v_mov_b64_e32 v[20:21], v[4:5]
	v_mov_b64_e32 v[24:25], v[4:5]
	v_mov_b64_e32 v[36:37], v[4:5]
	v_mov_b64_e32 v[40:41], v[4:5]
	v_mov_b64_e32 v[52:53], v[4:5]
	v_mov_b64_e32 v[56:57], v[4:5]
	v_mov_b64_e32 v[12:13], v[4:5]
	v_mov_b64_e32 v[16:17], v[4:5]
	v_mov_b64_e32 v[28:29], v[4:5]
	v_mov_b64_e32 v[32:33], v[4:5]
	v_mov_b64_e32 v[44:45], v[4:5]
	v_mov_b64_e32 v[48:49], v[4:5]
	v_mov_b64_e32 v[60:61], v[4:5]
	v_mov_b64_e32 v[64:65], v[4:5]
	s_addc_u32 s39, s5, 0
	s_mov_b32 s27, -2
	v_cndmask_b32_e64 v232, 0, 1, s[36:37]
	v_mov_b64_e32 v[6:7], v[2:3]
	v_mov_b64_e32 v[18:19], v[2:3]
	v_mov_b64_e32 v[22:23], v[2:3]
	v_mov_b64_e32 v[34:35], v[2:3]
	v_mov_b64_e32 v[38:39], v[2:3]
	v_mov_b64_e32 v[50:51], v[2:3]
	v_mov_b64_e32 v[54:55], v[2:3]
	v_mov_b64_e32 v[10:11], v[2:3]
	v_mov_b64_e32 v[14:15], v[2:3]
	v_mov_b64_e32 v[26:27], v[2:3]
	v_mov_b64_e32 v[30:31], v[2:3]
	v_mov_b64_e32 v[42:43], v[2:3]
	v_mov_b64_e32 v[46:47], v[2:3]
	v_mov_b64_e32 v[58:59], v[2:3]
	v_mov_b64_e32 v[62:63], v[2:3]
	v_mov_b32_e32 v67, v66
	v_mov_b32_e32 v68, v66
	v_mov_b32_e32 v69, v66
	v_mov_b32_e32 v70, v66
	v_mov_b32_e32 v71, v66
	v_mov_b32_e32 v72, v66
	v_mov_b32_e32 v73, v66
	v_mov_b32_e32 v78, v66
	v_mov_b32_e32 v79, v66
	v_mov_b32_e32 v80, v66
	v_mov_b32_e32 v81, v66
	v_mov_b32_e32 v86, v66
	v_mov_b32_e32 v87, v66
	v_mov_b32_e32 v88, v66
	v_mov_b32_e32 v89, v66
	v_mov_b32_e32 v94, v66
	v_mov_b32_e32 v95, v66
	v_mov_b32_e32 v96, v66
	v_mov_b32_e32 v97, v66
	v_mov_b32_e32 v102, v66
	v_mov_b32_e32 v103, v66
	v_mov_b32_e32 v104, v66
	v_mov_b32_e32 v105, v66
	v_mov_b32_e32 v110, v66
	v_mov_b32_e32 v111, v66
	v_mov_b32_e32 v112, v66
	v_mov_b32_e32 v113, v66
	v_mov_b32_e32 v118, v66
	v_mov_b32_e32 v119, v66
	v_mov_b32_e32 v120, v66
	v_mov_b32_e32 v121, v66
	v_mov_b32_e32 v74, v66
	v_mov_b32_e32 v75, v66
	v_mov_b32_e32 v76, v66
	v_mov_b32_e32 v77, v66
	v_mov_b32_e32 v82, v66
	v_mov_b32_e32 v83, v66
	v_mov_b32_e32 v84, v66
	v_mov_b32_e32 v85, v66
	v_mov_b32_e32 v90, v66
	v_mov_b32_e32 v91, v66
	v_mov_b32_e32 v92, v66
	v_mov_b32_e32 v93, v66
	v_mov_b32_e32 v98, v66
	v_mov_b32_e32 v99, v66
	v_mov_b32_e32 v100, v66
	v_mov_b32_e32 v101, v66
	v_mov_b32_e32 v106, v66
	v_mov_b32_e32 v107, v66
	v_mov_b32_e32 v108, v66
	v_mov_b32_e32 v109, v66
	v_mov_b32_e32 v114, v66
	v_mov_b32_e32 v115, v66
	v_mov_b32_e32 v116, v66
	v_mov_b32_e32 v117, v66
	v_mov_b32_e32 v122, v66
	v_mov_b32_e32 v123, v66
	v_mov_b32_e32 v124, v66
	v_mov_b32_e32 v125, v66
	v_mov_b32_e32 v126, v66
	v_mov_b32_e32 v127, v66
	v_mov_b32_e32 v128, v66
	v_mov_b32_e32 v129, v66
	v_add_u32_e32 v240, 0x18010, v220
	v_add_u32_e32 v241, 0x1c000, v230
	s_branch .LBB0_393
	.p2align 12

; #define PG8_STAGE(bufoff, gbase, voff) do { _Pragma("unroll") for (int _i = 0; _i < 2; ++_i) \
;         __builtin_amdgcn_global_load_lds((const unsigned*)((const char*)(gbase) + (voff)[_i]), (LAS unsigned*)(lds + (bufoff) + ldsw + _i * 8192), 16, 0, 0); } while (0)
; #define PG8_LDA(dst, b, h) do { _Pragma("unroll") for (int m = 0; m < 4; ++m) _Pragma("unroll") for (int k = 0; k < 2; ++k) dst[m][k] = *(const LAS bf16x8*)(lds + PG8_SA(b, h) + aoff + m * 2048 + k * 1024); } while (0)
; #define PG8_LDB(dst, b, h) do { _Pragma("unroll") for (int n = 0; n < 2; ++n) _Pragma("unroll") for (int k = 0; k < 2; ++k) dst[n][k] = *(const LAS bf16x8*)(lds + PG8_SB(b, h) + boff + n * 2048 + k * 1024); } while (0)
; #define PG8_MMA(ai, bj, At, Bt) do { __builtin_amdgcn_s_setprio(1); _Pragma("unroll") for (int m = 0; m < 4; ++m) _Pragma("unroll") for (int n = 0; n < 2; ++n) _Pragma("unroll") for (int k = 0; k < 2; ++k) \
;         acc[ai][bj][m][n] = __builtin_amdgcn_mfma_f32_16x16x32_bf16(Bt[n][k], At[m][k], acc[ai][bj][m][n], 0, 0, 0); __builtin_amdgcn_s_setprio(0); } while (0)
; #define PG8_WAIT_L(n) asm volatile("s_waitcnt lgkmcnt(" #n ")" ::: "memory")
; #define PG8_BAR __builtin_amdgcn_s_barrier()
; #define PG8_SCHED __builtin_amdgcn_sched_barrier(0)
; template <class Sched, class Epi>
; __device__ __forceinline__ void gemm_phase(LAS unsigned char* lds, const Sched& S, const Epi& E, const int K, const int lda, const int ldb) {
;     ...
;             PG8_LDB(B0, 1, 0); PG8_SCHED; PG8_LDA(At, 1, 0); PG8_STAGE(PG8_SA(0, 1), a2 + hstepA, voffA);
;             PG8_WAIT_L(8); PG8_BAR; PG8_WAIT_L(0); PG8_MMA(0, 0, At, B0); PG8_BAR; PG8_SCHED;
;             PG8_LDB(B1, 1, 1); PG8_STAGE(PG8_SB(1, 0), b3, voffB);
;             PG8_BAR; PG8_WAIT_L(0); PG8_MMA(0, 1, At, B1); PG8_BAR;
;             PG8_LDA(At, 1, 1); PG8_STAGE(PG8_SA(1, 0), a3, voffA);
;             PG8_BAR; PG8_WAIT_L(0); if (!chalf) PG8_MMA(1, 0, At, B0); PG8_BAR; PG8_SCHED;
.LBB0_397:
	s_add_i32 s57, 16, 0x18000
	s_barrier
	ds_read_b128 v[146:149], v240
	ds_read_b128 v[150:153], v240 offset:1024
	ds_read_b128 v[154:157], v240 offset:2048
	ds_read_b128 v[158:161], v240 offset:3072
	s_add_u32 s42, s42, 0x80000
	s_addc_u32 s43, s43, 0
	s_mov_b32 m0, s31
	s_waitcnt lgkmcnt(0)
	ds_read_b128 v[162:165], v229 offset:32768
	ds_read_b128 v[166:169], v229 offset:33792
	ds_read_b128 v[170:173], v229 offset:34816
	ds_read_b128 v[174:177], v229 offset:35840
	ds_read_b128 v[178:181], v229 offset:36864
	ds_read_b128 v[182:185], v229 offset:37888
	ds_read_b128 v[186:189], v229 offset:38912
	ds_read_b128 v[190:193], v229 offset:39936
	global_load_lds_dwordx4 v194, s[42:43]
	s_mov_b32 m0, s33
	s_nop 0
	global_load_lds_dwordx4 v198, s[42:43]
	s_waitcnt lgkmcnt(8)
	s_barrier
	s_waitcnt lgkmcnt(0)
	s_setprio 1
	s_waitcnt lgkmcnt(0)
	v_mfma_f32_16x16x32_bf16 v[126:129], v[146:149], v[162:165], v[126:129]
	v_mfma_f32_16x16x32_bf16 v[122:125], v[154:157], v[162:165], v[122:125]
	v_mfma_f32_16x16x32_bf16 v[114:117], v[146:149], v[170:173], v[114:117]
	v_mfma_f32_16x16x32_bf16 v[106:109], v[154:157], v[170:173], v[106:109]
	v_mfma_f32_16x16x32_bf16 v[98:101], v[146:149], v[178:181], v[98:101]
	v_mfma_f32_16x16x32_bf16 v[90:93], v[154:157], v[178:181], v[90:93]
	v_mfma_f32_16x16x32_bf16 v[82:85], v[146:149], v[186:189], v[82:85]
	v_mfma_f32_16x16x32_bf16 v[74:77], v[154:157], v[186:189], v[74:77]
	v_mfma_f32_16x16x32_bf16 v[126:129], v[150:153], v[166:169], v[126:129]
	v_mfma_f32_16x16x32_bf16 v[122:125], v[158:161], v[166:169], v[122:125]
	v_mfma_f32_16x16x32_bf16 v[114:117], v[150:153], v[174:177], v[114:117]
	v_mfma_f32_16x16x32_bf16 v[106:109], v[158:161], v[174:177], v[106:109]
	v_mfma_f32_16x16x32_bf16 v[98:101], v[150:153], v[182:185], v[98:101]
	v_mfma_f32_16x16x32_bf16 v[90:93], v[158:161], v[182:185], v[90:93]
	v_mfma_f32_16x16x32_bf16 v[82:85], v[150:153], v[190:193], v[82:85]
	v_mfma_f32_16x16x32_bf16 v[74:77], v[158:161], v[190:193], v[74:77]
	s_setprio 0
	s_barrier
	s_add_i32 s42, s57, s9
	s_mov_b32 m0, s42
	ds_read_b128 v[130:133], v241
	ds_read_b128 v[134:137], v241 offset:1024
	ds_read_b128 v[138:141], v241 offset:2048
	ds_read_b128 v[142:145], v241 offset:3072
	global_load_lds_dwordx4 v196, s[60:61]
	s_add_i32 m0, s42, 0x2000
	s_nop 0
	global_load_lds_dwordx4 v200, s[62:63]
	s_barrier
	s_waitcnt lgkmcnt(0)
	s_setprio 1
	s_waitcnt lgkmcnt(0)
	v_mfma_f32_16x16x32_bf16 v[118:121], v[130:133], v[162:165], v[118:121]
	v_mfma_f32_16x16x32_bf16 v[110:113], v[138:141], v[162:165], v[110:113]
	v_mfma_f32_16x16x32_bf16 v[102:105], v[130:133], v[170:173], v[102:105]
	v_mfma_f32_16x16x32_bf16 v[94:97], v[138:141], v[170:173], v[94:97]
	v_mfma_f32_16x16x32_bf16 v[86:89], v[130:133], v[178:181], v[86:89]
	v_mfma_f32_16x16x32_bf16 v[78:81], v[138:141], v[178:181], v[78:81]
	v_mfma_f32_16x16x32_bf16 v[70:73], v[130:133], v[186:189], v[70:73]
	v_mfma_f32_16x16x32_bf16 v[66:69], v[138:141], v[186:189], v[66:69]
	v_mfma_f32_16x16x32_bf16 v[118:121], v[134:137], v[166:169], v[118:121]
	v_mfma_f32_16x16x32_bf16 v[110:113], v[142:145], v[166:169], v[110:113]
	v_mfma_f32_16x16x32_bf16 v[102:105], v[134:137], v[174:177], v[102:105]
	v_mfma_f32_16x16x32_bf16 v[94:97], v[142:145], v[174:177], v[94:97]
	v_mfma_f32_16x16x32_bf16 v[86:89], v[134:137], v[182:185], v[86:89]
	v_mfma_f32_16x16x32_bf16 v[78:81], v[142:145], v[182:185], v[78:81]
	v_mfma_f32_16x16x32_bf16 v[70:73], v[134:137], v[190:193], v[70:73]
	v_mfma_f32_16x16x32_bf16 v[66:69], v[142:145], v[190:193], v[66:69]
	s_setprio 0
	s_mov_b32 m0, s46
	s_barrier
	ds_read_b128 v[186:189], v229 offset:49152
	ds_read_b128 v[190:193], v229 offset:50176
	ds_read_b128 v[178:181], v229 offset:51200
	ds_read_b128 v[182:185], v229 offset:52224
	ds_read_b128 v[170:173], v229 offset:53248
	ds_read_b128 v[174:177], v229 offset:54272
	ds_read_b128 v[162:165], v229 offset:55296
	ds_read_b128 v[166:169], v229 offset:56320
	global_load_lds_dwordx4 v194, s[64:65]
	s_mov_b32 m0, s47
	s_and_b64 vcc, exec, s[4:5]
	global_load_lds_dwordx4 v198, s[66:67]
	s_barrier
	s_waitcnt lgkmcnt(0)
	s_cbranch_vccnz .LBB0_399
	s_setprio 1
	s_waitcnt lgkmcnt(0)
	v_mfma_f32_16x16x32_bf16 v[62:65], v[146:149], v[186:189], v[62:65]
	v_mfma_f32_16x16x32_bf16 v[58:61], v[154:157], v[186:189], v[58:61]
	v_mfma_f32_16x16x32_bf16 v[46:49], v[146:149], v[178:181], v[46:49]
	v_mfma_f32_16x16x32_bf16 v[42:45], v[154:157], v[178:181], v[42:45]
	v_mfma_f32_16x16x32_bf16 v[30:33], v[146:149], v[170:173], v[30:33]
	v_mfma_f32_16x16x32_bf16 v[26:29], v[154:157], v[170:173], v[26:29]
	v_mfma_f32_16x16x32_bf16 v[14:17], v[146:149], v[162:165], v[14:17]
	v_mfma_f32_16x16x32_bf16 v[10:13], v[154:157], v[162:165], v[10:13]
	v_mfma_f32_16x16x32_bf16 v[62:65], v[150:153], v[190:193], v[62:65]
	v_mfma_f32_16x16x32_bf16 v[58:61], v[158:161], v[190:193], v[58:61]
	v_mfma_f32_16x16x32_bf16 v[46:49], v[150:153], v[182:185], v[46:49]
	v_mfma_f32_16x16x32_bf16 v[42:45], v[158:161], v[182:185], v[42:45]
	v_mfma_f32_16x16x32_bf16 v[30:33], v[150:153], v[174:177], v[30:33]
	v_mfma_f32_16x16x32_bf16 v[26:29], v[158:161], v[174:177], v[26:29]
	v_mfma_f32_16x16x32_bf16 v[14:17], v[150:153], v[166:169], v[14:17]
	v_mfma_f32_16x16x32_bf16 v[10:13], v[158:161], v[166:169], v[10:13]
	s_setprio 0

; #define PG8_STAGE(bufoff, gbase, voff) do { _Pragma("unroll") for (int _i = 0; _i < 2; ++_i) \
;         __builtin_amdgcn_global_load_lds((const unsigned*)((const char*)(gbase) + (voff)[_i]), (LAS unsigned*)(lds + (bufoff) + ldsw + _i * 8192), 16, 0, 0); } while (0)
; #define PG8_LDA(dst, b, h) do { _Pragma("unroll") for (int m = 0; m < 4; ++m) _Pragma("unroll") for (int k = 0; k < 2; ++k) dst[m][k] = *(const LAS bf16x8*)(lds + PG8_SA(b, h) + aoff + m * 2048 + k * 1024); } while (0)
; #define PG8_LDB(dst, b, h) do { _Pragma("unroll") for (int n = 0; n < 2; ++n) _Pragma("unroll") for (int k = 0; k < 2; ++k) dst[n][k] = *(const LAS bf16x8*)(lds + PG8_SB(b, h) + boff + n * 2048 + k * 1024); } while (0)
; #define PG8_MMA(ai, bj, At, Bt) do { __builtin_amdgcn_s_setprio(1); _Pragma("unroll") for (int m = 0; m < 4; ++m) _Pragma("unroll") for (int n = 0; n < 2; ++n) _Pragma("unroll") for (int k = 0; k < 2; ++k) \
;         acc[ai][bj][m][n] = __builtin_amdgcn_mfma_f32_16x16x32_bf16(Bt[n][k], At[m][k], acc[ai][bj][m][n], 0, 0, 0); __builtin_amdgcn_s_setprio(0); } while (0)
; #define PG8_WAIT_L(n) asm volatile("s_waitcnt lgkmcnt(" #n ")" ::: "memory")
; #define PG8_BAR __builtin_amdgcn_s_barrier()
; #define PG8_SCHED __builtin_amdgcn_sched_barrier(0)
; template <class Sched, class Epi>
; __device__ __forceinline__ void gemm_phase(LAS unsigned char* lds, const Sched& S, const Epi& E, const int K, const int lda, const int ldb) {
;     ...
;         for (int t = 0; t < nt; t += 2) {
;             const bool last = (t == nt - 2);
;             const char* a1 = cA + (size_t)(t + 1) * kstep;
;             const char* a2 = last ? nA : cA + (size_t)(t + 2) * kstep; const char* b2 = last ? nB : cB + (size_t)(t + 2) * kstep;
;             const char* a3 = a2 + kstep; const char* b3 = b2 + kstep;
;             PG8_LDB(B0, 0, 0); PG8_SCHED; PG8_LDA(At, 0, 0); PG8_STAGE(PG8_SA(1, 1), a1 + hstepA, voffA);
;             PG8_WAIT_L(8); PG8_BAR; PG8_WAIT_L(0); PG8_MMA(0, 0, At, B0); PG8_BAR; PG8_SCHED;
;             PG8_LDB(B1, 0, 1); PG8_STAGE(PG8_SB(0, 0), b2, voffB);
;     ...
; #pragma unroll
;         for (int a = 0; a < 2; ++a)
; #pragma unroll
;             for (int b = 0; b < 2; ++b)
; #pragma unroll
;                 for (int m = 0; m < 4; ++m)
; #pragma unroll
;                     for (int n = 0; n < 2; ++n) acc[a][b][m][n] = (f32x4){0.f, 0.f, 0.f, 0.f};
.LBB0_760:
	s_add_u32 s15, s34, 0x100
	s_addc_u32 s17, s35, 0
	s_add_u32 s28, s28, 0x40080
	v_mov_b32_e32 v2, 0
	s_addc_u32 s29, s29, 0
	s_mov_b32 s49, -2
	v_mov_b32_e32 v3, v2
	v_mov_b32_e32 v4, v2
	v_mov_b32_e32 v5, v2
	v_mov_b32_e32 v6, v2
	v_mov_b32_e32 v7, v2
	v_mov_b32_e32 v8, v2
	v_mov_b32_e32 v9, v2
	v_mov_b32_e32 v18, v2
	v_mov_b32_e32 v19, v2
	v_mov_b32_e32 v20, v2
	v_mov_b32_e32 v21, v2
	v_mov_b32_e32 v22, v2
	v_mov_b32_e32 v23, v2
	v_mov_b32_e32 v24, v2
	v_mov_b32_e32 v25, v2
	v_mov_b32_e32 v34, v2
	v_mov_b32_e32 v35, v2
	v_mov_b32_e32 v36, v2
	v_mov_b32_e32 v37, v2
	v_mov_b32_e32 v38, v2
	v_mov_b32_e32 v39, v2
	v_mov_b32_e32 v40, v2
	v_mov_b32_e32 v41, v2
	v_mov_b32_e32 v50, v2
	v_mov_b32_e32 v51, v2
	v_mov_b32_e32 v52, v2
	v_mov_b32_e32 v53, v2
	v_mov_b32_e32 v54, v2
	v_mov_b32_e32 v55, v2
	v_mov_b32_e32 v56, v2
	v_mov_b32_e32 v57, v2
	v_mov_b32_e32 v10, v2
	v_mov_b32_e32 v11, v2
	v_mov_b32_e32 v12, v2
	v_mov_b32_e32 v13, v2
	v_mov_b32_e32 v14, v2
	v_mov_b32_e32 v15, v2
	v_mov_b32_e32 v16, v2
	v_mov_b32_e32 v17, v2
	v_mov_b32_e32 v26, v2
	v_mov_b32_e32 v27, v2
	v_mov_b32_e32 v28, v2
	v_mov_b32_e32 v29, v2
	v_mov_b32_e32 v30, v2
	v_mov_b32_e32 v31, v2
	v_mov_b32_e32 v32, v2
	v_mov_b32_e32 v33, v2
	v_mov_b32_e32 v42, v2
	v_mov_b32_e32 v43, v2
	v_mov_b32_e32 v44, v2
	v_mov_b32_e32 v45, v2
	v_mov_b32_e32 v46, v2
	v_mov_b32_e32 v47, v2
	v_mov_b32_e32 v48, v2
	v_mov_b32_e32 v49, v2
	v_mov_b32_e32 v58, v2
	v_mov_b32_e32 v59, v2
	v_mov_b32_e32 v60, v2
	v_mov_b32_e32 v61, v2
	v_mov_b32_e32 v62, v2
	v_mov_b32_e32 v63, v2
	v_mov_b32_e32 v64, v2
	v_mov_b32_e32 v65, v2
	v_mov_b32_e32 v66, v2
	v_mov_b32_e32 v67, v2
	v_mov_b32_e32 v68, v2
	v_mov_b32_e32 v69, v2
	v_mov_b32_e32 v70, v2
	v_mov_b32_e32 v71, v2
	v_mov_b32_e32 v72, v2
	v_mov_b32_e32 v73, v2
	v_mov_b32_e32 v82, v2
	v_mov_b32_e32 v83, v2
	v_mov_b32_e32 v84, v2
	v_mov_b32_e32 v85, v2
	v_mov_b32_e32 v86, v2
	v_mov_b32_e32 v87, v2
	v_mov_b32_e32 v88, v2
	v_mov_b32_e32 v89, v2
	v_mov_b32_e32 v98, v2
	v_mov_b32_e32 v99, v2
	v_mov_b32_e32 v100, v2
	v_mov_b32_e32 v101, v2
	v_mov_b32_e32 v102, v2
	v_mov_b32_e32 v103, v2
	v_mov_b32_e32 v104, v2
	v_mov_b32_e32 v105, v2
	v_mov_b32_e32 v122, v2
	v_mov_b32_e32 v123, v2
	v_mov_b32_e32 v124, v2
	v_mov_b32_e32 v125, v2
	v_mov_b32_e32 v126, v2
	v_mov_b32_e32 v127, v2
	v_mov_b32_e32 v128, v2
	v_mov_b32_e32 v129, v2
	v_mov_b32_e32 v74, v2
	v_mov_b32_e32 v75, v2
	v_mov_b32_e32 v76, v2
	v_mov_b32_e32 v77, v2
	v_mov_b32_e32 v78, v2
	v_mov_b32_e32 v79, v2
	v_mov_b32_e32 v80, v2
	v_mov_b32_e32 v81, v2
	v_mov_b32_e32 v90, v2
	v_mov_b32_e32 v91, v2
	v_mov_b32_e32 v92, v2
	v_mov_b32_e32 v93, v2
	v_mov_b32_e32 v94, v2
	v_mov_b32_e32 v95, v2
	v_mov_b32_e32 v96, v2
	v_mov_b32_e32 v97, v2
	v_mov_b32_e32 v106, v2
	v_mov_b32_e32 v107, v2
	v_mov_b32_e32 v108, v2
	v_mov_b32_e32 v109, v2
	v_mov_b32_e32 v110, v2
	v_mov_b32_e32 v111, v2
	v_mov_b32_e32 v112, v2
	v_mov_b32_e32 v113, v2
	v_mov_b32_e32 v114, v2
	v_mov_b32_e32 v115, v2
	v_mov_b32_e32 v116, v2
	v_mov_b32_e32 v117, v2
	v_mov_b32_e32 v118, v2
	v_mov_b32_e32 v119, v2
	v_mov_b32_e32 v120, v2
	v_mov_b32_e32 v121, v2
	v_add_u32_e32 v226, 0x18010, v150
	v_add_u32_e32 v227, 0x1c010, v150
	s_branch .Lal_761
	.p2align 11
.Lal_761:
.LBB0_761:
	ds_read_b128 v[144:147], v155
	ds_read_b128 v[158:161], v155 offset:1024
	ds_read_b128 v[162:165], v155 offset:2048
	ds_read_b128 v[166:169], v155 offset:3072
	s_add_u32 s34, s28, 0xfffc0080
	s_addc_u32 s35, s29, -1
	s_cmp_eq_u32 s49, 12
	s_cselect_b32 s37, s25, s35
	s_cselect_b32 s36, s24, s34
	s_cselect_b32 s35, s27, s17
	s_cselect_b32 s34, s26, s15
	s_add_i32 m0, s23, 0xc000
	ds_read_b128 v[170:173], v156
	ds_read_b128 v[174:177], v156 offset:1024
	ds_read_b128 v[178:181], v156 offset:2048
	ds_read_b128 v[182:185], v156 offset:3072
	ds_read_b128 v[186:189], v156 offset:4096
	ds_read_b128 v[190:193], v156 offset:5120
	ds_read_b128 v[194:197], v156 offset:6144
	ds_read_b128 v[198:201], v156 offset:7168
	global_load_lds_dwordx4 v140, s[28:29]
	s_add_i32 m0, s23, 0xe000
	s_nop 0
	global_load_lds_dwordx4 v138, s[28:29]
	s_waitcnt lgkmcnt(8)
	s_barrier
	s_waitcnt lgkmcnt(0)
	s_setprio 1
	s_waitcnt lgkmcnt(0)
	v_mfma_f32_16x16x32_bf16 v[118:121], v[144:147], v[170:173], v[118:121]
	v_mfma_f32_16x16x32_bf16 v[114:117], v[162:165], v[170:173], v[114:117]
	v_mfma_f32_16x16x32_bf16 v[110:113], v[144:147], v[178:181], v[110:113]
	v_mfma_f32_16x16x32_bf16 v[106:109], v[162:165], v[178:181], v[106:109]
	v_mfma_f32_16x16x32_bf16 v[94:97], v[144:147], v[186:189], v[94:97]
	v_mfma_f32_16x16x32_bf16 v[90:93], v[162:165], v[186:189], v[90:93]
	v_mfma_f32_16x16x32_bf16 v[78:81], v[144:147], v[194:197], v[78:81]
	v_mfma_f32_16x16x32_bf16 v[74:77], v[162:165], v[194:197], v[74:77]
	v_mfma_f32_16x16x32_bf16 v[118:121], v[158:161], v[174:177], v[118:121]
	v_mfma_f32_16x16x32_bf16 v[114:117], v[166:169], v[174:177], v[114:117]
	v_mfma_f32_16x16x32_bf16 v[110:113], v[158:161], v[182:185], v[110:113]
	v_mfma_f32_16x16x32_bf16 v[106:109], v[166:169], v[182:185], v[106:109]
	v_mfma_f32_16x16x32_bf16 v[94:97], v[158:161], v[190:193], v[94:97]
	v_mfma_f32_16x16x32_bf16 v[90:93], v[166:169], v[190:193], v[90:93]
	v_mfma_f32_16x16x32_bf16 v[78:81], v[158:161], v[198:201], v[78:81]
	v_mfma_f32_16x16x32_bf16 v[74:77], v[166:169], v[198:201], v[74:77]
	s_setprio 0
	s_barrier
	s_add_i32 s50, s46, s38
	s_add_u32 s62, s34, s8
	s_addc_u32 s63, s35, s9
	s_mov_b32 m0, s50
	ds_read_b128 v[202:205], v157
	ds_read_b128 v[206:209], v157 offset:1024
	ds_read_b128 v[210:213], v157 offset:2048
	ds_read_b128 v[214:217], v157 offset:3072
	global_load_lds_dwordx4 v132, s[34:35]
	s_add_u32 s64, s34, s8
	s_addc_u32 s65, s35, s9
	s_add_i32 m0, s50, 0x2000
	s_nop 0
	global_load_lds_dwordx4 v136, s[34:35]
	s_barrier
; #define PG8_STAGE(bufoff, gbase, voff) do { _Pragma("unroll") for (int _i = 0; _i < 2; ++_i) \
;         __builtin_amdgcn_global_load_lds((const unsigned*)((const char*)(gbase) + (voff)[_i]), (LAS unsigned*)(lds + (bufoff) + ldsw + _i * 8192), 16, 0, 0); } while (0)
; #define PG8_LDA(dst, b, h) do { _Pragma("unroll") for (int m = 0; m < 4; ++m) _Pragma("unroll") for (int k = 0; k < 2; ++k) dst[m][k] = *(const LAS bf16x8*)(lds + PG8_SA(b, h) + aoff + m * 2048 + k * 1024); } while (0)
; #define PG8_LDB(dst, b, h) do { _Pragma("unroll") for (int n = 0; n < 2; ++n) _Pragma("unroll") for (int k = 0; k < 2; ++k) dst[n][k] = *(const LAS bf16x8*)(lds + PG8_SB(b, h) + boff + n * 2048 + k * 1024); } while (0)
; #define PG8_MMA(ai, bj, At, Bt) do { __builtin_amdgcn_s_setprio(1); _Pragma("unroll") for (int m = 0; m < 4; ++m) _Pragma("unroll") for (int n = 0; n < 2; ++n) _Pragma("unroll") for (int k = 0; k < 2; ++k) \
;         acc[ai][bj][m][n] = __builtin_amdgcn_mfma_f32_16x16x32_bf16(Bt[n][k], At[m][k], acc[ai][bj][m][n], 0, 0, 0); __builtin_amdgcn_s_setprio(0); } while (0)
; #define PG8_WAIT_V(n) asm volatile("s_waitcnt vmcnt(" #n ")" ::: "memory")
; #define PG8_WAIT_L(n) asm volatile("s_waitcnt lgkmcnt(" #n ")" ::: "memory")
; #define PG8_BAR __builtin_amdgcn_s_barrier()
; #define PG8_SCHED __builtin_amdgcn_sched_barrier(0)
; template <class Sched, class Epi>
; __device__ __forceinline__ void gemm_phase(LAS unsigned char* lds, const Sched& S, const Epi& E, const int K, const int lda, const int ldb) {
;     ...
;             PG8_LDB(B1, 0, 1); PG8_STAGE(PG8_SB(0, 0), b2, voffB);
;             PG8_BAR; PG8_WAIT_L(0); PG8_MMA(0, 1, At, B1); PG8_BAR;
;             PG8_LDA(At, 0, 1); PG8_STAGE(PG8_SA(0, 0), a2, voffA);
;             PG8_BAR; PG8_WAIT_L(0); if (!chalf) PG8_MMA(1, 0, At, B0); PG8_BAR; PG8_SCHED;
;             PG8_STAGE(PG8_SB(0, 1), b2 + hstepB, voffB);
;             PG8_WAIT_V(6); PG8_BAR; if (!chalf) PG8_MMA(1, 1, At, B1); PG8_BAR;
;             PG8_LDB(B0, 1, 0); PG8_SCHED; PG8_LDA(At, 1, 0); PG8_STAGE(PG8_SA(0, 1), a2 + hstepA, voffA);
;             PG8_WAIT_L(8); PG8_BAR; PG8_WAIT_L(0); PG8_MMA(0, 0, At, B0); PG8_BAR; PG8_SCHED;
	s_waitcnt lgkmcnt(0)
	s_setprio 1
	s_waitcnt lgkmcnt(0)
	v_mfma_f32_16x16x32_bf16 v[126:129], v[202:205], v[170:173], v[126:129]
	v_mfma_f32_16x16x32_bf16 v[122:125], v[210:213], v[170:173], v[122:125]
	v_mfma_f32_16x16x32_bf16 v[102:105], v[202:205], v[178:181], v[102:105]
	v_mfma_f32_16x16x32_bf16 v[98:101], v[210:213], v[178:181], v[98:101]
	v_mfma_f32_16x16x32_bf16 v[86:89], v[202:205], v[186:189], v[86:89]
	v_mfma_f32_16x16x32_bf16 v[82:85], v[210:213], v[186:189], v[82:85]
	v_mfma_f32_16x16x32_bf16 v[70:73], v[202:205], v[194:197], v[70:73]
	v_mfma_f32_16x16x32_bf16 v[66:69], v[210:213], v[194:197], v[66:69]
	v_mfma_f32_16x16x32_bf16 v[126:129], v[206:209], v[174:177], v[126:129]
	v_mfma_f32_16x16x32_bf16 v[122:125], v[214:217], v[174:177], v[122:125]
	v_mfma_f32_16x16x32_bf16 v[102:105], v[206:209], v[182:185], v[102:105]
	v_mfma_f32_16x16x32_bf16 v[98:101], v[214:217], v[182:185], v[98:101]
	v_mfma_f32_16x16x32_bf16 v[86:89], v[206:209], v[190:193], v[86:89]
	v_mfma_f32_16x16x32_bf16 v[82:85], v[214:217], v[190:193], v[82:85]
	v_mfma_f32_16x16x32_bf16 v[70:73], v[206:209], v[198:201], v[70:73]
	v_mfma_f32_16x16x32_bf16 v[66:69], v[214:217], v[198:201], v[66:69]
	s_setprio 0
	s_mov_b32 m0, s23
	s_add_u32 s66, s36, s8
	s_addc_u32 s67, s37, s9
	s_barrier
	ds_read_b128 v[170:173], v156 offset:16384
	ds_read_b128 v[174:177], v156 offset:17408
	ds_read_b128 v[178:181], v156 offset:18432
	ds_read_b128 v[182:185], v156 offset:19456
	ds_read_b128 v[186:189], v156 offset:20480
	ds_read_b128 v[190:193], v156 offset:21504
	ds_read_b128 v[194:197], v156 offset:22528
	ds_read_b128 v[198:201], v156 offset:23552
	global_load_lds_dwordx4 v130, s[36:37]
	s_add_u32 s68, s36, s8
	s_addc_u32 s69, s37, s9
	s_mov_b32 m0, s39
	s_nop 0
	global_load_lds_dwordx4 v134, s[36:37]
	s_barrier
	s_waitcnt lgkmcnt(0)
	s_setprio 1
	s_waitcnt lgkmcnt(0)
	v_mfma_f32_16x16x32_bf16 v[62:65], v[144:147], v[170:173], v[62:65]
	v_mfma_f32_16x16x32_bf16 v[58:61], v[162:165], v[170:173], v[58:61]
	v_mfma_f32_16x16x32_bf16 v[46:49], v[144:147], v[178:181], v[46:49]
	v_mfma_f32_16x16x32_bf16 v[42:45], v[162:165], v[178:181], v[42:45]
	v_mfma_f32_16x16x32_bf16 v[30:33], v[144:147], v[186:189], v[30:33]
	v_mfma_f32_16x16x32_bf16 v[26:29], v[162:165], v[186:189], v[26:29]
	v_mfma_f32_16x16x32_bf16 v[14:17], v[144:147], v[194:197], v[14:17]
	v_mfma_f32_16x16x32_bf16 v[10:13], v[162:165], v[194:197], v[10:13]
	v_mfma_f32_16x16x32_bf16 v[62:65], v[158:161], v[174:177], v[62:65]
	v_mfma_f32_16x16x32_bf16 v[58:61], v[166:169], v[174:177], v[58:61]
	v_mfma_f32_16x16x32_bf16 v[46:49], v[158:161], v[182:185], v[46:49]
	v_mfma_f32_16x16x32_bf16 v[42:45], v[166:169], v[182:185], v[42:45]
	v_mfma_f32_16x16x32_bf16 v[30:33], v[158:161], v[190:193], v[30:33]
	v_mfma_f32_16x16x32_bf16 v[26:29], v[166:169], v[190:193], v[26:29]
	v_mfma_f32_16x16x32_bf16 v[14:17], v[158:161], v[198:201], v[14:17]
	v_mfma_f32_16x16x32_bf16 v[10:13], v[166:169], v[198:201], v[10:13]
	s_setprio 0
	s_barrier
	s_add_u32 s50, s34, 0x40000
	s_addc_u32 s51, s35, 0
	s_add_i32 s52, s47, s38
	s_mov_b32 m0, s52
	s_nop 0
	global_load_lds_dwordx4 v132, s[50:51]
	s_add_i32 m0, s52, 0x2000
	s_nop 0
	global_load_lds_dwordx4 v136, s[50:51]
	s_waitcnt vmcnt(6)
	s_barrier
	s_setprio 1
	v_mfma_f32_16x16x32_bf16 v[54:57], v[202:205], v[170:173], v[54:57]
	v_mfma_f32_16x16x32_bf16 v[50:53], v[210:213], v[170:173], v[50:53]
	v_mfma_f32_16x16x32_bf16 v[38:41], v[202:205], v[178:181], v[38:41]
	v_mfma_f32_16x16x32_bf16 v[34:37], v[210:213], v[178:181], v[34:37]
	v_mfma_f32_16x16x32_bf16 v[22:25], v[202:205], v[186:189], v[22:25]
	v_mfma_f32_16x16x32_bf16 v[18:21], v[210:213], v[186:189], v[18:21]
	v_mfma_f32_16x16x32_bf16 v[6:9], v[202:205], v[194:197], v[6:9]
	v_mfma_f32_16x16x32_bf16 v[2:5], v[210:213], v[194:197], v[2:5]
	v_mfma_f32_16x16x32_bf16 v[54:57], v[206:209], v[174:177], v[54:57]
	v_mfma_f32_16x16x32_bf16 v[50:53], v[214:217], v[174:177], v[50:53]
	v_mfma_f32_16x16x32_bf16 v[38:41], v[206:209], v[182:185], v[38:41]
	v_mfma_f32_16x16x32_bf16 v[34:37], v[214:217], v[182:185], v[34:37]
	v_mfma_f32_16x16x32_bf16 v[22:25], v[206:209], v[190:193], v[22:25]
	v_mfma_f32_16x16x32_bf16 v[18:21], v[214:217], v[190:193], v[18:21]
	v_mfma_f32_16x16x32_bf16 v[6:9], v[206:209], v[198:201], v[6:9]
	v_mfma_f32_16x16x32_bf16 v[2:5], v[214:217], v[198:201], v[2:5]
	s_setprio 0
	s_add_i32 s50, 16, 0x18000
	s_barrier
	ds_read_b128 v[144:147], v226
	ds_read_b128 v[158:161], v226 offset:1024
	ds_read_b128 v[162:165], v226 offset:2048
	ds_read_b128 v[166:169], v226 offset:3072
	s_add_u32 s36, s36, 0x40000
	s_addc_u32 s37, s37, 0
	s_mov_b32 m0, s40
	ds_read_b128 v[170:173], v156 offset:32768
	ds_read_b128 v[174:177], v156 offset:33792
	ds_read_b128 v[178:181], v156 offset:34816
	ds_read_b128 v[182:185], v156 offset:35840
	ds_read_b128 v[186:189], v156 offset:36864
	ds_read_b128 v[190:193], v156 offset:37888
	ds_read_b128 v[194:197], v156 offset:38912
	ds_read_b128 v[198:201], v156 offset:39936
	global_load_lds_dwordx4 v130, s[36:37]
	s_mov_b32 m0, s41
	s_nop 0
	global_load_lds_dwordx4 v134, s[36:37]
	s_waitcnt lgkmcnt(8)
	s_barrier
; #define PG8_STAGE(bufoff, gbase, voff) do { _Pragma("unroll") for (int _i = 0; _i < 2; ++_i) \
;         __builtin_amdgcn_global_load_lds((const unsigned*)((const char*)(gbase) + (voff)[_i]), (LAS unsigned*)(lds + (bufoff) + ldsw + _i * 8192), 16, 0, 0); } while (0)
; #define PG8_LDA(dst, b, h) do { _Pragma("unroll") for (int m = 0; m < 4; ++m) _Pragma("unroll") for (int k = 0; k < 2; ++k) dst[m][k] = *(const LAS bf16x8*)(lds + PG8_SA(b, h) + aoff + m * 2048 + k * 1024); } while (0)
; #define PG8_LDB(dst, b, h) do { _Pragma("unroll") for (int n = 0; n < 2; ++n) _Pragma("unroll") for (int k = 0; k < 2; ++k) dst[n][k] = *(const LAS bf16x8*)(lds + PG8_SB(b, h) + boff + n * 2048 + k * 1024); } while (0)
; #define PG8_MMA(ai, bj, At, Bt) do { __builtin_amdgcn_s_setprio(1); _Pragma("unroll") for (int m = 0; m < 4; ++m) _Pragma("unroll") for (int n = 0; n < 2; ++n) _Pragma("unroll") for (int k = 0; k < 2; ++k) \
;         acc[ai][bj][m][n] = __builtin_amdgcn_mfma_f32_16x16x32_bf16(Bt[n][k], At[m][k], acc[ai][bj][m][n], 0, 0, 0); __builtin_amdgcn_s_setprio(0); } while (0)
; #define PG8_WAIT_V(n) asm volatile("s_waitcnt vmcnt(" #n ")" ::: "memory")
; #define PG8_WAIT_L(n) asm volatile("s_waitcnt lgkmcnt(" #n ")" ::: "memory")
; #define PG8_BAR __builtin_amdgcn_s_barrier()
; #define PG8_SCHED __builtin_amdgcn_sched_barrier(0)
; template <class Sched, class Epi>
; __device__ __forceinline__ void gemm_phase(LAS unsigned char* lds, const Sched& S, const Epi& E, const int K, const int lda, const int ldb) {
;     ...
;             PG8_WAIT_L(8); PG8_BAR; PG8_WAIT_L(0); PG8_MMA(0, 0, At, B0); PG8_BAR; PG8_SCHED;
;             PG8_LDB(B1, 1, 1); PG8_STAGE(PG8_SB(1, 0), b3, voffB);
;             PG8_BAR; PG8_WAIT_L(0); PG8_MMA(0, 1, At, B1); PG8_BAR;
;             PG8_LDA(At, 1, 1); PG8_STAGE(PG8_SA(1, 0), a3, voffA);
;             PG8_BAR; PG8_WAIT_L(0); if (!chalf) PG8_MMA(1, 0, At, B0); PG8_BAR; PG8_SCHED;
;             PG8_STAGE(PG8_SB(1, 1), b3 + hstepB, voffB);
;             PG8_WAIT_V(6); PG8_BAR; if (!chalf) PG8_MMA(1, 1, At, B1); PG8_BAR;
;         }
	s_waitcnt lgkmcnt(0)
	s_setprio 1
	s_waitcnt lgkmcnt(0)
	v_mfma_f32_16x16x32_bf16 v[118:121], v[144:147], v[170:173], v[118:121]
	v_mfma_f32_16x16x32_bf16 v[114:117], v[162:165], v[170:173], v[114:117]
	v_mfma_f32_16x16x32_bf16 v[110:113], v[144:147], v[178:181], v[110:113]
	v_mfma_f32_16x16x32_bf16 v[106:109], v[162:165], v[178:181], v[106:109]
	v_mfma_f32_16x16x32_bf16 v[94:97], v[144:147], v[186:189], v[94:97]
	v_mfma_f32_16x16x32_bf16 v[90:93], v[162:165], v[186:189], v[90:93]
	v_mfma_f32_16x16x32_bf16 v[78:81], v[144:147], v[194:197], v[78:81]
	v_mfma_f32_16x16x32_bf16 v[74:77], v[162:165], v[194:197], v[74:77]
	v_mfma_f32_16x16x32_bf16 v[118:121], v[158:161], v[174:177], v[118:121]
	v_mfma_f32_16x16x32_bf16 v[114:117], v[166:169], v[174:177], v[114:117]
	v_mfma_f32_16x16x32_bf16 v[110:113], v[158:161], v[182:185], v[110:113]
	v_mfma_f32_16x16x32_bf16 v[106:109], v[166:169], v[182:185], v[106:109]
	v_mfma_f32_16x16x32_bf16 v[94:97], v[158:161], v[190:193], v[94:97]
	v_mfma_f32_16x16x32_bf16 v[90:93], v[166:169], v[190:193], v[90:93]
	v_mfma_f32_16x16x32_bf16 v[78:81], v[158:161], v[198:201], v[78:81]
	v_mfma_f32_16x16x32_bf16 v[74:77], v[166:169], v[198:201], v[74:77]
	s_setprio 0
	s_barrier
	s_add_i32 s36, 16, 0x1c000
	s_add_i32 s37, s50, s38
	s_mov_b32 m0, s37
	ds_read_b128 v[202:205], v227
	ds_read_b128 v[206:209], v227 offset:1024
	ds_read_b128 v[210:213], v227 offset:2048
	ds_read_b128 v[214:217], v227 offset:3072
	global_load_lds_dwordx4 v132, s[62:63]
	s_add_i32 m0, s37, 0x2000
	s_nop 0
	global_load_lds_dwordx4 v136, s[64:65]
	s_barrier
	s_waitcnt lgkmcnt(0)
	s_setprio 1
	s_waitcnt lgkmcnt(0)
	v_mfma_f32_16x16x32_bf16 v[126:129], v[202:205], v[170:173], v[126:129]
	v_mfma_f32_16x16x32_bf16 v[122:125], v[210:213], v[170:173], v[122:125]
	v_mfma_f32_16x16x32_bf16 v[102:105], v[202:205], v[178:181], v[102:105]
	v_mfma_f32_16x16x32_bf16 v[98:101], v[210:213], v[178:181], v[98:101]
	v_mfma_f32_16x16x32_bf16 v[86:89], v[202:205], v[186:189], v[86:89]
	v_mfma_f32_16x16x32_bf16 v[82:85], v[210:213], v[186:189], v[82:85]
	v_mfma_f32_16x16x32_bf16 v[70:73], v[202:205], v[194:197], v[70:73]
	v_mfma_f32_16x16x32_bf16 v[66:69], v[210:213], v[194:197], v[66:69]
	v_mfma_f32_16x16x32_bf16 v[126:129], v[206:209], v[174:177], v[126:129]
	v_mfma_f32_16x16x32_bf16 v[122:125], v[214:217], v[174:177], v[122:125]
	v_mfma_f32_16x16x32_bf16 v[102:105], v[206:209], v[182:185], v[102:105]
	v_mfma_f32_16x16x32_bf16 v[98:101], v[214:217], v[182:185], v[98:101]
	v_mfma_f32_16x16x32_bf16 v[86:89], v[206:209], v[190:193], v[86:89]
	v_mfma_f32_16x16x32_bf16 v[82:85], v[214:217], v[190:193], v[82:85]
	v_mfma_f32_16x16x32_bf16 v[70:73], v[206:209], v[198:201], v[70:73]
	v_mfma_f32_16x16x32_bf16 v[66:69], v[214:217], v[198:201], v[66:69]
	s_setprio 0
	s_mov_b32 m0, s42
	s_barrier
	ds_read_b128 v[170:173], v156 offset:49152
	ds_read_b128 v[174:177], v156 offset:50176
	ds_read_b128 v[178:181], v156 offset:51200
	ds_read_b128 v[182:185], v156 offset:52224
	ds_read_b128 v[186:189], v156 offset:53248
	ds_read_b128 v[190:193], v156 offset:54272
	ds_read_b128 v[194:197], v156 offset:55296
	ds_read_b128 v[198:201], v156 offset:56320
	global_load_lds_dwordx4 v130, s[66:67]
	s_mov_b32 m0, s43
	s_nop 0
	global_load_lds_dwordx4 v134, s[68:69]
	s_barrier
	s_waitcnt lgkmcnt(0)
	s_setprio 1
	s_waitcnt lgkmcnt(0)
	v_mfma_f32_16x16x32_bf16 v[62:65], v[144:147], v[170:173], v[62:65]
	v_mfma_f32_16x16x32_bf16 v[58:61], v[162:165], v[170:173], v[58:61]
	v_mfma_f32_16x16x32_bf16 v[46:49], v[144:147], v[178:181], v[46:49]
	v_mfma_f32_16x16x32_bf16 v[42:45], v[162:165], v[178:181], v[42:45]
	v_mfma_f32_16x16x32_bf16 v[30:33], v[144:147], v[186:189], v[30:33]
	v_mfma_f32_16x16x32_bf16 v[26:29], v[162:165], v[186:189], v[26:29]
	v_mfma_f32_16x16x32_bf16 v[14:17], v[144:147], v[194:197], v[14:17]
	v_mfma_f32_16x16x32_bf16 v[10:13], v[162:165], v[194:197], v[10:13]
	v_mfma_f32_16x16x32_bf16 v[62:65], v[158:161], v[174:177], v[62:65]
	v_mfma_f32_16x16x32_bf16 v[58:61], v[166:169], v[174:177], v[58:61]
	v_mfma_f32_16x16x32_bf16 v[46:49], v[158:161], v[182:185], v[46:49]
	v_mfma_f32_16x16x32_bf16 v[42:45], v[166:169], v[182:185], v[42:45]
	v_mfma_f32_16x16x32_bf16 v[30:33], v[158:161], v[190:193], v[30:33]
	v_mfma_f32_16x16x32_bf16 v[26:29], v[166:169], v[190:193], v[26:29]
	v_mfma_f32_16x16x32_bf16 v[14:17], v[158:161], v[198:201], v[14:17]
	v_mfma_f32_16x16x32_bf16 v[10:13], v[166:169], v[198:201], v[10:13]
	s_setprio 0
	s_barrier
	s_add_u32 s34, s34, 0x40080
	s_addc_u32 s35, s35, 0
	s_add_i32 s36, s36, s38
	s_mov_b32 m0, s36
	s_nop 0
	global_load_lds_dwordx4 v132, s[34:35]
	s_add_i32 m0, s36, 0x2000
	s_nop 0
	global_load_lds_dwordx4 v136, s[34:35]
	s_waitcnt vmcnt(6)
	s_barrier
	s_setprio 1
	v_mfma_f32_16x16x32_bf16 v[54:57], v[202:205], v[170:173], v[54:57]
	v_mfma_f32_16x16x32_bf16 v[50:53], v[210:213], v[170:173], v[50:53]
	v_mfma_f32_16x16x32_bf16 v[38:41], v[202:205], v[178:181], v[38:41]
	v_mfma_f32_16x16x32_bf16 v[34:37], v[210:213], v[178:181], v[34:37]
	v_mfma_f32_16x16x32_bf16 v[22:25], v[202:205], v[186:189], v[22:25]
	v_mfma_f32_16x16x32_bf16 v[18:21], v[210:213], v[186:189], v[18:21]
	v_mfma_f32_16x16x32_bf16 v[6:9], v[202:205], v[194:197], v[6:9]
	v_mfma_f32_16x16x32_bf16 v[2:5], v[210:213], v[194:197], v[2:5]
	v_mfma_f32_16x16x32_bf16 v[54:57], v[206:209], v[174:177], v[54:57]
	v_mfma_f32_16x16x32_bf16 v[50:53], v[214:217], v[174:177], v[50:53]
	v_mfma_f32_16x16x32_bf16 v[38:41], v[206:209], v[182:185], v[38:41]
	v_mfma_f32_16x16x32_bf16 v[34:37], v[214:217], v[182:185], v[34:37]
	v_mfma_f32_16x16x32_bf16 v[22:25], v[206:209], v[190:193], v[22:25]
	v_mfma_f32_16x16x32_bf16 v[18:21], v[214:217], v[190:193], v[18:21]
	v_mfma_f32_16x16x32_bf16 v[6:9], v[206:209], v[198:201], v[6:9]
	v_mfma_f32_16x16x32_bf16 v[2:5], v[214:217], v[198:201], v[2:5]
	s_setprio 0
	s_add_i32 s49, s49, 2
	s_add_u32 s15, s15, 0x100
	s_addc_u32 s17, s17, 0
	s_add_u32 s28, s28, 0x100
	s_addc_u32 s29, s29, 0
	s_cmp_gt_u32 s49, 13
	s_barrier
; __device__ __forceinline__ u32x4 pack8(const float (&f)[8]) { u32x4 r; r[0] = cvt_pk_bf16(f[0], f[1]); r[1] = cvt_pk_bf16(f[2], f[3]); r[2] = cvt_pk_bf16(f[4], f[5]); r[3] = cvt_pk_bf16(f[6], f[7]); return r; }
;     __device__ __forceinline__ void operator()(EPI_ARGS) const {
;         const int col = u.pn * 128 + wc * 32 + 8 * fq;
; #pragma unroll
;         for (int ai = 0; ai < 2; ++ai) if (ai == 0 || !u.half) { u32x4 zz[4];
; #pragma unroll
;             for (int m = 0; m < 4; ++m) zz[m] = *(const u32x4*)(parts + E_PZB + (size_t)EPI_ROW * 1024 + col);
; #pragma unroll
;             for (int m = 0; m < 4; ++m) { float z[8]; unpack8(zz[m], z);
;                 const f32x4 a0 = acc[ai][0][m][0], a1 = acc[ai][0][m][1], b0 = acc[ai][1][m][0], b1 = acc[ai][1][m][1]; float o[8];
; #pragma unroll
;                 for (int j = 0; j < 4; ++j) { o[j] = a0[j] * z[j] * __builtin_amdgcn_rcpf((1.0f + __expf(-b0[j])) * (1.0f + __expf(-z[j]))); o[4 + j] = a1[j] * z[4 + j] * __builtin_amdgcn_rcpf((1.0f + __expf(-b1[j])) * (1.0f + __expf(-z[4 + j]))); }
;                 *(u32x4*)(O + (size_t)EPI_ROW * 1024 + col) = pack8(o); } }
	s_cbranch_scc0 .LBB0_761
	v_lshl_or_b32 v144, s48, 7, v154
	v_ashrrev_i32_e32 v145, 31, v144
	v_add_u32_e32 v148, s22, v1
	v_lshlrev_b64 v[144:145], 1, v[144:145]
	v_ashrrev_i32_e32 v149, 31, v148
	v_lshl_add_u64 v[146:147], s[6:7], 0, v[144:145]
	v_lshlrev_b64 v[166:167], 11, v[148:149]
	v_lshl_add_u64 v[158:159], v[146:147], 0, v[166:167]
	global_load_dwordx4 v[158:161], v[158:159], off
	v_mul_f32_e32 v149, 0xbfb8aa3b, v122
	v_mul_f32_e32 v123, 0xbfb8aa3b, v123
	v_add_u32_e32 v122, 16, v148
	v_exp_f32_e32 v174, v123
	v_ashrrev_i32_e32 v123, 31, v122
	v_lshlrev_b64 v[122:123], 11, v[122:123]
	v_mul_f32_e32 v126, 0xbfb8aa3b, v126
	v_mul_f32_e32 v127, 0xbfb8aa3b, v127
	v_mul_f32_e32 v128, 0xbfb8aa3b, v128
	v_mul_f32_e32 v129, 0xbfb8aa3b, v129
	v_lshl_add_u64 v[122:123], v[146:147], 0, v[122:123]
	v_exp_f32_e32 v168, v126
	v_exp_f32_e32 v172, v127
	v_exp_f32_e32 v176, v128
	v_exp_f32_e32 v180, v129
	global_load_dwordx4 v[126:129], v[122:123], off
	v_mul_f32_e32 v163, 0xbfb8aa3b, v124
	v_mul_f32_e32 v125, 0xbfb8aa3b, v125
	v_add_u32_e32 v124, 32, v148
	v_add_u32_e32 v162, 48, v148
	v_exp_f32_e32 v178, v163
	v_exp_f32_e32 v182, v125
	v_ashrrev_i32_e32 v125, 31, v124
	v_ashrrev_i32_e32 v163, 31, v162
	v_lshlrev_b64 v[122:123], 11, v[124:125]
	v_lshlrev_b64 v[124:125], 11, v[162:163]
	v_lshl_add_u64 v[122:123], v[146:147], 0, v[122:123]
	v_lshl_add_u64 v[124:125], v[146:147], 0, v[124:125]
	global_load_dwordx4 v[162:165], v[122:123], off
	s_nop 0
	global_load_dwordx4 v[122:125], v[124:125], off
	v_exp_f32_e32 v170, v149
	v_mul_f32_e32 v102, 0xbfb8aa3b, v102
	v_mul_f32_e32 v98, 0xbfb8aa3b, v98
	v_mul_f32_e32 v100, 0xbfb8aa3b, v100
	v_mul_f32_e32 v86, 0xbfb8aa3b, v86
	v_mul_f32_e32 v82, 0xbfb8aa3b, v82
	v_mul_f32_e32 v84, 0xbfb8aa3b, v84
	v_mul_f32_e32 v70, 0xbfb8aa3b, v70
	v_mul_f32_e32 v66, 0xbfb8aa3b, v66
	v_mul_f32_e32 v68, 0xbfb8aa3b, v68
	v_mul_f32_e32 v54, 0xbfb8aa3b, v54
	v_mul_f32_e32 v50, 0xbfb8aa3b, v50
	v_mul_f32_e32 v52, 0xbfb8aa3b, v52
	v_mul_f32_e32 v38, 0xbfb8aa3b, v38
	v_mul_f32_e32 v34, 0xbfb8aa3b, v34
	v_mul_f32_e32 v36, 0xbfb8aa3b, v36
	v_mul_f32_e32 v22, 0xbfb8aa3b, v22
	v_mul_f32_e32 v18, 0xbfb8aa3b, v18
	v_mul_f32_e32 v20, 0xbfb8aa3b, v20
	v_mul_f32_e32 v6, 0xbfb8aa3b, v6
	v_mul_f32_e32 v2, 0xbfb8aa3b, v2
	v_mul_f32_e32 v4, 0xbfb8aa3b, v4
	s_and_b64 vcc, exec, s[12:13]
	s_mov_b32 s48, s14
	s_mov_b64 s[34:35], s[20:21]
	s_mov_b64 s[28:29], s[18:19]
	s_waitcnt vmcnt(0)
	v_lshlrev_b32_e32 v149, 16, v158
	v_and_b32_e32 v158, 0xffff0000, v158
	v_lshlrev_b32_e32 v169, 16, v159
	v_and_b32_e32 v184, 0xffff0000, v159
	v_lshlrev_b32_e32 v159, 16, v160
	v_and_b32_e32 v160, 0xffff0000, v160
	v_lshlrev_b32_e32 v171, 16, v161
	v_mul_f32_e32 v186, v118, v149
	v_mul_f32_e32 v118, 0xbfb8aa3b, v149
	v_mul_f32_e32 v149, v114, v159
	v_mul_f32_e32 v114, 0xbfb8aa3b, v159
	v_mul_f32_e32 v187, v119, v158
	v_mul_f32_e32 v119, 0xbfb8aa3b, v158
	v_mul_f32_e32 v188, v115, v160
	v_mul_f32_e32 v115, 0xbfb8aa3b, v160
	v_mul_f32_e32 v158, 0xbfb8aa3b, v169
	v_mul_f32_e32 v159, 0xbfb8aa3b, v171
	v_mul_f32_e32 v120, v120, v169
	v_mul_f32_e32 v116, v116, v171
	v_exp_f32_e32 v169, v118
	v_exp_f32_e32 v171, v114
	v_exp_f32_e32 v173, v119
	v_exp_f32_e32 v175, v115
	v_exp_f32_e32 v177, v158
	v_exp_f32_e32 v179, v159
	v_and_b32_e32 v185, 0xffff0000, v161
	v_mul_f32_e32 v160, 0xbfb8aa3b, v184
	v_mul_f32_e32 v161, 0xbfb8aa3b, v185
	v_exp_f32_e32 v181, v160
	v_exp_f32_e32 v183, v161
	v_pk_add_f32 v[114:115], v[168:169], 1.0 op_sel_hi:[1,0]
	v_pk_add_f32 v[118:119], v[170:171], 1.0 op_sel_hi:[1,0]
	v_pk_add_f32 v[158:159], v[172:173], 1.0 op_sel_hi:[1,0]
	v_pk_add_f32 v[160:161], v[174:175], 1.0 op_sel_hi:[1,0]
	v_pk_add_f32 v[168:169], v[176:177], 1.0 op_sel_hi:[1,0]
	v_pk_add_f32 v[170:171], v[178:179], 1.0 op_sel_hi:[1,0]
	v_mul_f32_e32 v114, v114, v115
	v_mul_f32_e32 v115, v118, v119
	v_mul_f32_e32 v118, v158, v159
	v_mul_f32_e32 v119, v160, v161
	v_mul_f32_e32 v158, v168, v169
	v_mul_f32_e32 v159, v170, v171
	v_rcp_f32_e32 v115, v115
	v_rcp_f32_e32 v118, v118
	v_rcp_f32_e32 v119, v119
	v_rcp_f32_e32 v158, v158
	v_rcp_f32_e32 v159, v159
	v_pk_add_f32 v[172:173], v[180:181], 1.0 op_sel_hi:[1,0]
	v_pk_add_f32 v[174:175], v[182:183], 1.0 op_sel_hi:[1,0]
	v_mul_f32_e32 v160, v172, v173
	v_rcp_f32_e32 v114, v114
	v_mul_f32_e32 v149, v149, v115
	v_mul_f32_e32 v115, v187, v118
	v_mul_f32_e32 v118, v188, v119
	v_mul_f32_e32 v119, v120, v158
	v_mul_f32_e32 v120, v116, v159
	v_mul_f32_e32 v116, v174, v175
	v_rcp_f32_e32 v160, v160
	v_rcp_f32_e32 v116, v116
	v_mul_f32_e32 v114, v186, v114
	v_mul_f32_e32 v121, v121, v184
	v_mul_f32_e32 v117, v117, v185
	v_mul_f32_e32 v121, v121, v160
	v_mul_f32_e32 v117, v117, v116
	v_cvt_pk_bf16_f32 v114, v114, v115
	v_cvt_pk_bf16_f32 v115, v119, v121
	v_cvt_pk_bf16_f32 v116, v149, v118
	v_lshl_add_u64 v[118:119], s[4:5], 0, v[166:167]
	v_lshl_add_u64 v[118:119], v[118:119], 0, v[144:145]
	v_cvt_pk_bf16_f32 v117, v120, v117
	global_store_dwordx4 v[118:119], v[114:117], off
	v_lshlrev_b32_e32 v118, 16, v126
	v_and_b32_e32 v119, 0xffff0000, v126
	v_lshlrev_b32_e32 v126, 16, v128
	v_exp_f32_e32 v114, v102
	v_mul_f32_e32 v102, 0xbfb8aa3b, v118
	v_exp_f32_e32 v115, v102
	v_exp_f32_e32 v116, v98
	v_mul_f32_e32 v98, 0xbfb8aa3b, v126
	v_exp_f32_e32 v117, v98
	v_pk_add_f32 v[114:115], v[114:115], 1.0 op_sel_hi:[1,0]
	v_mul_f32_e32 v110, v110, v118
	v_mul_f32_e32 v98, v114, v115
	v_pk_add_f32 v[114:115], v[116:117], 1.0 op_sel_hi:[1,0]
	v_rcp_f32_e32 v98, v98
	v_mul_f32_e32 v102, v114, v115
	v_rcp_f32_e32 v102, v102
	v_lshlrev_b32_e32 v120, 16, v127
	v_mul_f32_e32 v110, v110, v98
	v_mul_f32_e32 v98, v106, v126
	v_mul_f32_e32 v106, v98, v102
; __device__ __forceinline__ u32x4 pack8(const float (&f)[8]) { u32x4 r; r[0] = cvt_pk_bf16(f[0], f[1]); r[1] = cvt_pk_bf16(f[2], f[3]); r[2] = cvt_pk_bf16(f[4], f[5]); r[3] = cvt_pk_bf16(f[6], f[7]); return r; }
;     __device__ __forceinline__ void operator()(EPI_ARGS) const {
;     ...
;         for (int ai = 0; ai < 2; ++ai) if (ai == 0 || !u.half) { u32x4 zz[4];
; #pragma unroll
;             for (int m = 0; m < 4; ++m) zz[m] = *(const u32x4*)(parts + E_PZB + (size_t)EPI_ROW * 1024 + col);
; #pragma unroll
;             for (int m = 0; m < 4; ++m) { float z[8]; unpack8(zz[m], z);
;                 const f32x4 a0 = acc[ai][0][m][0], a1 = acc[ai][0][m][1], b0 = acc[ai][1][m][0], b1 = acc[ai][1][m][1]; float o[8];
; #pragma unroll
;                 for (int j = 0; j < 4; ++j) { o[j] = a0[j] * z[j] * __builtin_amdgcn_rcpf((1.0f + __expf(-b0[j])) * (1.0f + __expf(-z[j]))); o[4 + j] = a1[j] * z[4 + j] * __builtin_amdgcn_rcpf((1.0f + __expf(-b1[j])) * (1.0f + __expf(-z[4 + j]))); }
;                 *(u32x4*)(O + (size_t)EPI_ROW * 1024 + col) = pack8(o); } }
	v_mul_f32_e32 v98, 0xbfb8aa3b, v103
	v_and_b32_e32 v121, 0xffff0000, v127
	v_and_b32_e32 v127, 0xffff0000, v128
	v_exp_f32_e32 v102, v98
	v_mul_f32_e32 v98, 0xbfb8aa3b, v119
	v_exp_f32_e32 v103, v98
	v_mul_f32_e32 v98, 0xbfb8aa3b, v99
	v_mul_f32_e32 v99, 0xbfb8aa3b, v127
	v_exp_f32_e32 v98, v98
	v_exp_f32_e32 v99, v99
	v_pk_add_f32 v[102:103], v[102:103], 1.0 op_sel_hi:[1,0]
	v_lshlrev_b32_e32 v128, 16, v129
	v_mul_f32_e32 v102, v102, v103
	v_pk_add_f32 v[98:99], v[98:99], 1.0 op_sel_hi:[1,0]
	v_rcp_f32_e32 v102, v102
	v_mul_f32_e32 v98, v98, v99
	v_rcp_f32_e32 v98, v98
	v_mul_f32_e32 v99, v111, v119
	v_mul_f32_e32 v111, v99, v102
	v_mul_f32_e32 v99, v107, v127
	v_mul_f32_e32 v107, v99, v98
	v_mul_f32_e32 v98, 0xbfb8aa3b, v104
	v_mul_f32_e32 v99, 0xbfb8aa3b, v120
	v_exp_f32_e32 v98, v98
	v_exp_f32_e32 v99, v99
	v_exp_f32_e32 v102, v100
	v_mul_f32_e32 v100, 0xbfb8aa3b, v128
	v_exp_f32_e32 v103, v100
	v_pk_add_f32 v[98:99], v[98:99], 1.0 op_sel_hi:[1,0]
	v_and_b32_e32 v129, 0xffff0000, v129
	v_mul_f32_e32 v98, v98, v99
	v_rcp_f32_e32 v100, v98
	v_pk_add_f32 v[98:99], v[102:103], 1.0 op_sel_hi:[1,0]
	s_nop 0
	v_mul_f32_e32 v98, v98, v99
	v_rcp_f32_e32 v98, v98
	v_mul_f32_e32 v99, v112, v120
	v_mul_f32_e32 v102, v99, v100
	v_mul_f32_e32 v99, v108, v128
	v_mul_f32_e32 v103, v99, v98
	v_mul_f32_e32 v98, 0xbfb8aa3b, v105
	v_mul_f32_e32 v99, 0xbfb8aa3b, v121
	v_exp_f32_e32 v98, v98
	v_exp_f32_e32 v99, v99
	v_mul_f32_e32 v100, 0xbfb8aa3b, v101
	v_mul_f32_e32 v101, 0xbfb8aa3b, v129
	v_exp_f32_e32 v100, v100
	v_exp_f32_e32 v101, v101
	v_pk_add_f32 v[98:99], v[98:99], 1.0 op_sel_hi:[1,0]
	v_lshlrev_b32_e32 v108, 16, v165
	v_mul_f32_e32 v98, v98, v99
	v_rcp_f32_e32 v104, v98
	v_pk_add_f32 v[98:99], v[100:101], 1.0 op_sel_hi:[1,0]
	v_mul_f32_e32 v100, v109, v129
	v_mul_f32_e32 v98, v98, v99
	v_rcp_f32_e32 v98, v98
	v_mul_f32_e32 v99, v113, v121
	v_mul_f32_e32 v99, v99, v104
	v_lshlrev_b32_e32 v104, 16, v163
	v_mul_f32_e32 v101, v100, v98
	v_cvt_pk_bf16_f32 v98, v110, v111
	v_cvt_pk_bf16_f32 v99, v102, v99
	v_add_u32_e32 v102, s22, v151
	v_cvt_pk_bf16_f32 v100, v106, v107
	v_cvt_pk_bf16_f32 v101, v103, v101
	v_ashrrev_i32_e32 v103, 31, v102
	v_lshlrev_b64 v[102:103], 11, v[102:103]
	v_lshl_add_u64 v[102:103], s[4:5], 0, v[102:103]
	v_lshl_add_u64 v[102:103], v[102:103], 0, v[144:145]
	global_store_dwordx4 v[102:103], v[98:101], off
	v_lshlrev_b32_e32 v102, 16, v162
	v_lshlrev_b32_e32 v106, 16, v164
	v_exp_f32_e32 v98, v86
	v_mul_f32_e32 v86, 0xbfb8aa3b, v102
	v_exp_f32_e32 v99, v86
	v_exp_f32_e32 v100, v82
	v_mul_f32_e32 v82, 0xbfb8aa3b, v106
	v_exp_f32_e32 v101, v82
	v_pk_add_f32 v[98:99], v[98:99], 1.0 op_sel_hi:[1,0]
	v_mul_f32_e32 v94, v94, v102
	v_mul_f32_e32 v82, v98, v99
	v_pk_add_f32 v[98:99], v[100:101], 1.0 op_sel_hi:[1,0]
	v_rcp_f32_e32 v82, v82
	v_mul_f32_e32 v86, v98, v99
	v_rcp_f32_e32 v86, v86
	v_and_b32_e32 v103, 0xffff0000, v162
	v_mul_f32_e32 v94, v94, v82
	v_mul_f32_e32 v82, v90, v106
	v_mul_f32_e32 v90, v82, v86
	v_mul_f32_e32 v82, 0xbfb8aa3b, v87
	v_and_b32_e32 v107, 0xffff0000, v164
	v_exp_f32_e32 v86, v82
	v_mul_f32_e32 v82, 0xbfb8aa3b, v103
	v_exp_f32_e32 v87, v82
	v_mul_f32_e32 v82, 0xbfb8aa3b, v83
	v_mul_f32_e32 v83, 0xbfb8aa3b, v107
	v_exp_f32_e32 v82, v82
	v_exp_f32_e32 v83, v83
	v_pk_add_f32 v[86:87], v[86:87], 1.0 op_sel_hi:[1,0]
	v_and_b32_e32 v105, 0xffff0000, v163
	v_mul_f32_e32 v86, v86, v87
	v_pk_add_f32 v[82:83], v[82:83], 1.0 op_sel_hi:[1,0]
	v_rcp_f32_e32 v86, v86
	v_mul_f32_e32 v82, v82, v83
	v_rcp_f32_e32 v82, v82
	v_mul_f32_e32 v83, v95, v103
	v_mul_f32_e32 v95, v83, v86
	v_mul_f32_e32 v83, v91, v107
	v_mul_f32_e32 v91, v83, v82
	v_mul_f32_e32 v82, 0xbfb8aa3b, v88
	v_mul_f32_e32 v83, 0xbfb8aa3b, v104
	v_exp_f32_e32 v82, v82
	v_exp_f32_e32 v83, v83
	v_exp_f32_e32 v86, v84
	v_mul_f32_e32 v84, 0xbfb8aa3b, v108
	v_exp_f32_e32 v87, v84
	v_pk_add_f32 v[82:83], v[82:83], 1.0 op_sel_hi:[1,0]
	v_and_b32_e32 v109, 0xffff0000, v165
	v_mul_f32_e32 v82, v82, v83
	v_rcp_f32_e32 v84, v82
	v_pk_add_f32 v[82:83], v[86:87], 1.0 op_sel_hi:[1,0]
	s_nop 0
	v_mul_f32_e32 v82, v82, v83
	v_rcp_f32_e32 v82, v82
	v_mul_f32_e32 v83, v96, v104
	v_mul_f32_e32 v86, v83, v84
	v_mul_f32_e32 v83, v92, v108
	v_mul_f32_e32 v87, v83, v82
	v_mul_f32_e32 v82, 0xbfb8aa3b, v89
	v_mul_f32_e32 v83, 0xbfb8aa3b, v105
	v_exp_f32_e32 v82, v82
	v_exp_f32_e32 v83, v83
	v_mul_f32_e32 v84, 0xbfb8aa3b, v85
	v_mul_f32_e32 v85, 0xbfb8aa3b, v109
	v_exp_f32_e32 v84, v84
	v_exp_f32_e32 v85, v85
	v_pk_add_f32 v[82:83], v[82:83], 1.0 op_sel_hi:[1,0]
	v_lshlrev_b32_e32 v92, 16, v125
	v_mul_f32_e32 v82, v82, v83
	v_rcp_f32_e32 v88, v82
	v_pk_add_f32 v[82:83], v[84:85], 1.0 op_sel_hi:[1,0]
	v_mul_f32_e32 v84, v93, v109
	v_mul_f32_e32 v82, v82, v83
	v_rcp_f32_e32 v82, v82
	v_mul_f32_e32 v83, v97, v105
	v_mul_f32_e32 v83, v83, v88
	v_lshlrev_b32_e32 v88, 16, v123
	v_mul_f32_e32 v85, v84, v82
	v_cvt_pk_bf16_f32 v82, v94, v95
	v_cvt_pk_bf16_f32 v83, v86, v83
	v_add_u32_e32 v86, s22, v152
	v_cvt_pk_bf16_f32 v84, v90, v91
	v_cvt_pk_bf16_f32 v85, v87, v85
	v_ashrrev_i32_e32 v87, 31, v86
	v_lshlrev_b64 v[86:87], 11, v[86:87]
	v_lshl_add_u64 v[86:87], s[4:5], 0, v[86:87]
	v_lshl_add_u64 v[86:87], v[86:87], 0, v[144:145]
	global_store_dwordx4 v[86:87], v[82:85], off
	v_lshlrev_b32_e32 v86, 16, v122
	v_lshlrev_b32_e32 v90, 16, v124
	v_exp_f32_e32 v82, v70
	v_mul_f32_e32 v70, 0xbfb8aa3b, v86
	v_exp_f32_e32 v83, v70
	v_exp_f32_e32 v84, v66
	v_mul_f32_e32 v66, 0xbfb8aa3b, v90
	v_exp_f32_e32 v85, v66
	v_pk_add_f32 v[82:83], v[82:83], 1.0 op_sel_hi:[1,0]
	v_mul_f32_e32 v78, v78, v86
	v_mul_f32_e32 v66, v82, v83
	v_pk_add_f32 v[82:83], v[84:85], 1.0 op_sel_hi:[1,0]
	v_rcp_f32_e32 v66, v66
; __device__ __forceinline__ u32x4 pack8(const float (&f)[8]) { u32x4 r; r[0] = cvt_pk_bf16(f[0], f[1]); r[1] = cvt_pk_bf16(f[2], f[3]); r[2] = cvt_pk_bf16(f[4], f[5]); r[3] = cvt_pk_bf16(f[6], f[7]); return r; }
;     __device__ __forceinline__ void operator()(EPI_ARGS) const {
;     ...
;         for (int ai = 0; ai < 2; ++ai) if (ai == 0 || !u.half) { u32x4 zz[4];
; #pragma unroll
;             for (int m = 0; m < 4; ++m) zz[m] = *(const u32x4*)(parts + E_PZB + (size_t)EPI_ROW * 1024 + col);
; #pragma unroll
;             for (int m = 0; m < 4; ++m) { float z[8]; unpack8(zz[m], z);
;                 const f32x4 a0 = acc[ai][0][m][0], a1 = acc[ai][0][m][1], b0 = acc[ai][1][m][0], b1 = acc[ai][1][m][1]; float o[8];
; #pragma unroll
;                 for (int j = 0; j < 4; ++j) { o[j] = a0[j] * z[j] * __builtin_amdgcn_rcpf((1.0f + __expf(-b0[j])) * (1.0f + __expf(-z[j]))); o[4 + j] = a1[j] * z[4 + j] * __builtin_amdgcn_rcpf((1.0f + __expf(-b1[j])) * (1.0f + __expf(-z[4 + j]))); }
;                 *(u32x4*)(O + (size_t)EPI_ROW * 1024 + col) = pack8(o); } }
	v_mul_f32_e32 v70, v82, v83
	v_rcp_f32_e32 v70, v70
	v_and_b32_e32 v87, 0xffff0000, v122
	v_mul_f32_e32 v78, v78, v66
	v_mul_f32_e32 v66, v74, v90
	v_mul_f32_e32 v74, v66, v70
	v_mul_f32_e32 v66, 0xbfb8aa3b, v71
	v_and_b32_e32 v91, 0xffff0000, v124
	v_exp_f32_e32 v70, v66
	v_mul_f32_e32 v66, 0xbfb8aa3b, v87
	v_exp_f32_e32 v71, v66
	v_mul_f32_e32 v66, 0xbfb8aa3b, v67
	v_mul_f32_e32 v67, 0xbfb8aa3b, v91
	v_exp_f32_e32 v66, v66
	v_exp_f32_e32 v67, v67
	v_pk_add_f32 v[70:71], v[70:71], 1.0 op_sel_hi:[1,0]
	v_and_b32_e32 v89, 0xffff0000, v123
	v_mul_f32_e32 v70, v70, v71
	v_pk_add_f32 v[66:67], v[66:67], 1.0 op_sel_hi:[1,0]
	v_rcp_f32_e32 v70, v70
	v_mul_f32_e32 v66, v66, v67
	v_rcp_f32_e32 v66, v66
	v_mul_f32_e32 v67, v79, v87
	v_mul_f32_e32 v79, v67, v70
	v_mul_f32_e32 v67, v75, v91
	v_mul_f32_e32 v75, v67, v66
	v_mul_f32_e32 v66, 0xbfb8aa3b, v72
	v_mul_f32_e32 v67, 0xbfb8aa3b, v88
	v_exp_f32_e32 v66, v66
	v_exp_f32_e32 v67, v67
	v_exp_f32_e32 v70, v68
	v_mul_f32_e32 v68, 0xbfb8aa3b, v92
	v_exp_f32_e32 v71, v68
	v_pk_add_f32 v[66:67], v[66:67], 1.0 op_sel_hi:[1,0]
	v_and_b32_e32 v93, 0xffff0000, v125
	v_mul_f32_e32 v66, v66, v67
	v_rcp_f32_e32 v68, v66
	v_pk_add_f32 v[66:67], v[70:71], 1.0 op_sel_hi:[1,0]
	s_nop 0
	v_mul_f32_e32 v66, v66, v67
	v_rcp_f32_e32 v66, v66
	v_mul_f32_e32 v67, v80, v88
	v_mul_f32_e32 v70, v67, v68
	v_mul_f32_e32 v67, v76, v92
	v_mul_f32_e32 v71, v67, v66
	v_mul_f32_e32 v66, 0xbfb8aa3b, v73
	v_mul_f32_e32 v67, 0xbfb8aa3b, v89
	v_exp_f32_e32 v66, v66
	v_exp_f32_e32 v67, v67
	v_mul_f32_e32 v68, 0xbfb8aa3b, v69
	v_mul_f32_e32 v69, 0xbfb8aa3b, v93
	v_exp_f32_e32 v68, v68
	v_exp_f32_e32 v69, v69
	v_pk_add_f32 v[66:67], v[66:67], 1.0 op_sel_hi:[1,0]
	s_nop 0
	v_mul_f32_e32 v66, v66, v67
	v_rcp_f32_e32 v72, v66
	v_pk_add_f32 v[66:67], v[68:69], 1.0 op_sel_hi:[1,0]
	v_mul_f32_e32 v68, v77, v93
	v_mul_f32_e32 v66, v66, v67
	v_rcp_f32_e32 v66, v66
	v_mul_f32_e32 v67, v81, v89
	v_mul_f32_e32 v67, v67, v72
	v_mul_f32_e32 v69, v68, v66
	v_cvt_pk_bf16_f32 v66, v78, v79
	v_cvt_pk_bf16_f32 v67, v70, v67
	v_add_u32_e32 v70, s22, v153
	v_cvt_pk_bf16_f32 v68, v74, v75
	v_cvt_pk_bf16_f32 v69, v71, v69
	v_ashrrev_i32_e32 v71, 31, v70
	v_lshlrev_b64 v[70:71], 11, v[70:71]
	v_lshl_add_u64 v[70:71], s[4:5], 0, v[70:71]
	v_lshl_add_u64 v[70:71], v[70:71], 0, v[144:145]
	global_store_dwordx4 v[70:71], v[66:69], off
	s_mov_b32 s22, s16
	s_nop 0
	v_add_u32_e32 v66, 0x80, v148
	v_ashrrev_i32_e32 v67, 31, v66
	v_lshlrev_b64 v[88:89], 11, v[66:67]
	v_lshl_add_u64 v[66:67], v[146:147], 0, v[88:89]
	global_load_dwordx4 v[80:83], v[66:67], off
	v_add_u32_e32 v66, 0x90, v148
	v_ashrrev_i32_e32 v67, 31, v66
	v_lshlrev_b64 v[78:79], 11, v[66:67]
	v_lshl_add_u64 v[66:67], v[146:147], 0, v[78:79]
	global_load_dwordx4 v[84:87], v[66:67], off
	v_add_u32_e32 v66, 0xa0, v148
	v_ashrrev_i32_e32 v67, 31, v66
	v_lshlrev_b64 v[76:77], 11, v[66:67]
	v_add_u32_e32 v66, 0xb0, v148
	v_ashrrev_i32_e32 v67, 31, v66
	v_lshl_add_u64 v[90:91], v[146:147], 0, v[76:77]
	v_lshlrev_b64 v[74:75], 11, v[66:67]
	v_lshl_add_u64 v[92:93], v[146:147], 0, v[74:75]
	global_load_dwordx4 v[70:73], v[90:91], off
	global_load_dwordx4 v[66:69], v[92:93], off
	s_waitcnt vmcnt(0)
	v_lshlrev_b32_e32 v90, 16, v80
	v_and_b32_e32 v91, 0xffff0000, v80
	v_lshlrev_b32_e32 v94, 16, v82
	v_exp_f32_e32 v80, v54
	v_mul_f32_e32 v54, 0xbfb8aa3b, v90
	v_lshlrev_b32_e32 v92, 16, v81
	v_and_b32_e32 v93, 0xffff0000, v81
	v_and_b32_e32 v95, 0xffff0000, v82
	v_exp_f32_e32 v81, v54
	v_exp_f32_e32 v82, v50
	v_mul_f32_e32 v50, 0xbfb8aa3b, v94
	v_lshlrev_b32_e32 v96, 16, v83
	v_and_b32_e32 v97, 0xffff0000, v83
	v_exp_f32_e32 v83, v50
	v_pk_add_f32 v[80:81], v[80:81], 1.0 op_sel_hi:[1,0]
	v_mul_f32_e32 v62, v62, v90
	v_mul_f32_e32 v50, v80, v81
	v_pk_add_f32 v[80:81], v[82:83], 1.0 op_sel_hi:[1,0]
	v_rcp_f32_e32 v50, v50
	v_mul_f32_e32 v54, v80, v81
	v_rcp_f32_e32 v54, v54
	v_mul_f32_e32 v62, v62, v50
	v_mul_f32_e32 v50, v58, v94
	v_mul_f32_e32 v58, v50, v54
	v_mul_f32_e32 v50, 0xbfb8aa3b, v55
	v_exp_f32_e32 v54, v50
	v_mul_f32_e32 v50, 0xbfb8aa3b, v91
	v_exp_f32_e32 v55, v50
	v_mul_f32_e32 v50, 0xbfb8aa3b, v51
	v_mul_f32_e32 v51, 0xbfb8aa3b, v95
	v_exp_f32_e32 v50, v50
	v_exp_f32_e32 v51, v51
	v_pk_add_f32 v[54:55], v[54:55], 1.0 op_sel_hi:[1,0]
	v_pk_add_f32 v[50:51], v[50:51], 1.0 op_sel_hi:[1,0]
	v_mul_f32_e32 v54, v54, v55
	v_rcp_f32_e32 v54, v54
	v_mul_f32_e32 v50, v50, v51
	v_rcp_f32_e32 v50, v50
	v_mul_f32_e32 v51, v63, v91
	v_mul_f32_e32 v63, v51, v54
	v_mul_f32_e32 v51, v59, v95
	v_mul_f32_e32 v59, v51, v50
	v_mul_f32_e32 v50, 0xbfb8aa3b, v56
	v_mul_f32_e32 v51, 0xbfb8aa3b, v92
	v_exp_f32_e32 v50, v50
	v_exp_f32_e32 v51, v51
	v_exp_f32_e32 v54, v52
	v_mul_f32_e32 v52, 0xbfb8aa3b, v96
	v_exp_f32_e32 v55, v52
	v_pk_add_f32 v[50:51], v[50:51], 1.0 op_sel_hi:[1,0]
	s_nop 0
	v_mul_f32_e32 v50, v50, v51
	v_rcp_f32_e32 v52, v50
	v_pk_add_f32 v[50:51], v[54:55], 1.0 op_sel_hi:[1,0]
	s_nop 0
	v_mul_f32_e32 v50, v50, v51
	v_rcp_f32_e32 v50, v50
	v_mul_f32_e32 v51, v64, v92
	v_mul_f32_e32 v54, v51, v52
	v_mul_f32_e32 v51, v60, v96
	v_mul_f32_e32 v55, v51, v50
	v_mul_f32_e32 v50, 0xbfb8aa3b, v57
	v_mul_f32_e32 v51, 0xbfb8aa3b, v93
	v_exp_f32_e32 v50, v50
	v_exp_f32_e32 v51, v51
	v_mul_f32_e32 v52, 0xbfb8aa3b, v53
	v_mul_f32_e32 v53, 0xbfb8aa3b, v97
	v_exp_f32_e32 v52, v52
	v_exp_f32_e32 v53, v53
	v_pk_add_f32 v[50:51], v[50:51], 1.0 op_sel_hi:[1,0]
	v_lshlrev_b32_e32 v60, 16, v87
	v_mul_f32_e32 v50, v50, v51
	v_rcp_f32_e32 v56, v50
	v_pk_add_f32 v[50:51], v[52:53], 1.0 op_sel_hi:[1,0]
	v_mul_f32_e32 v52, v61, v97
	v_mul_f32_e32 v50, v50, v51
	v_rcp_f32_e32 v50, v50
	v_mul_f32_e32 v51, v65, v93
	v_mul_f32_e32 v51, v51, v56
; __device__ __forceinline__ u32x4 pack8(const float (&f)[8]) { u32x4 r; r[0] = cvt_pk_bf16(f[0], f[1]); r[1] = cvt_pk_bf16(f[2], f[3]); r[2] = cvt_pk_bf16(f[4], f[5]); r[3] = cvt_pk_bf16(f[6], f[7]); return r; }
;     __device__ __forceinline__ void operator()(EPI_ARGS) const {
;     ...
;         for (int ai = 0; ai < 2; ++ai) if (ai == 0 || !u.half) { u32x4 zz[4];
; #pragma unroll
;             for (int m = 0; m < 4; ++m) zz[m] = *(const u32x4*)(parts + E_PZB + (size_t)EPI_ROW * 1024 + col);
; #pragma unroll
;             for (int m = 0; m < 4; ++m) { float z[8]; unpack8(zz[m], z);
;                 const f32x4 a0 = acc[ai][0][m][0], a1 = acc[ai][0][m][1], b0 = acc[ai][1][m][0], b1 = acc[ai][1][m][1]; float o[8];
; #pragma unroll
;                 for (int j = 0; j < 4; ++j) { o[j] = a0[j] * z[j] * __builtin_amdgcn_rcpf((1.0f + __expf(-b0[j])) * (1.0f + __expf(-z[j]))); o[4 + j] = a1[j] * z[4 + j] * __builtin_amdgcn_rcpf((1.0f + __expf(-b1[j])) * (1.0f + __expf(-z[4 + j]))); }
;                 *(u32x4*)(O + (size_t)EPI_ROW * 1024 + col) = pack8(o); } }
	v_lshlrev_b32_e32 v56, 16, v85
	v_mul_f32_e32 v53, v52, v50
	v_cvt_pk_bf16_f32 v50, v62, v63
	v_cvt_pk_bf16_f32 v51, v54, v51
	v_cvt_pk_bf16_f32 v52, v58, v59
	v_cvt_pk_bf16_f32 v53, v55, v53
	v_lshl_add_u64 v[54:55], s[4:5], 0, v[88:89]
	v_lshl_add_u64 v[54:55], v[54:55], 0, v[144:145]
	global_store_dwordx4 v[54:55], v[50:53], off
	v_lshlrev_b32_e32 v54, 16, v84
	v_lshlrev_b32_e32 v58, 16, v86
	v_exp_f32_e32 v50, v38
	v_mul_f32_e32 v38, 0xbfb8aa3b, v54
	v_exp_f32_e32 v51, v38
	v_exp_f32_e32 v52, v34
	v_mul_f32_e32 v34, 0xbfb8aa3b, v58
	v_exp_f32_e32 v53, v34
	v_pk_add_f32 v[50:51], v[50:51], 1.0 op_sel_hi:[1,0]
	v_mul_f32_e32 v46, v46, v54
	v_mul_f32_e32 v34, v50, v51
	v_pk_add_f32 v[50:51], v[52:53], 1.0 op_sel_hi:[1,0]
	v_rcp_f32_e32 v34, v34
	v_mul_f32_e32 v38, v50, v51
	v_rcp_f32_e32 v38, v38
	v_and_b32_e32 v55, 0xffff0000, v84
	v_mul_f32_e32 v46, v46, v34
	v_mul_f32_e32 v34, v42, v58
	v_mul_f32_e32 v42, v34, v38
	v_mul_f32_e32 v34, 0xbfb8aa3b, v39
	v_and_b32_e32 v59, 0xffff0000, v86
	v_exp_f32_e32 v38, v34
	v_mul_f32_e32 v34, 0xbfb8aa3b, v55
	v_exp_f32_e32 v39, v34
	v_mul_f32_e32 v34, 0xbfb8aa3b, v35
	v_mul_f32_e32 v35, 0xbfb8aa3b, v59
	v_exp_f32_e32 v34, v34
	v_exp_f32_e32 v35, v35
	v_pk_add_f32 v[38:39], v[38:39], 1.0 op_sel_hi:[1,0]
	v_and_b32_e32 v57, 0xffff0000, v85
	v_mul_f32_e32 v38, v38, v39
	v_pk_add_f32 v[34:35], v[34:35], 1.0 op_sel_hi:[1,0]
	v_rcp_f32_e32 v38, v38
	v_mul_f32_e32 v34, v34, v35
	v_rcp_f32_e32 v34, v34
	v_mul_f32_e32 v35, v47, v55
	v_mul_f32_e32 v47, v35, v38
	v_mul_f32_e32 v35, v43, v59
	v_mul_f32_e32 v43, v35, v34
	v_mul_f32_e32 v34, 0xbfb8aa3b, v40
	v_mul_f32_e32 v35, 0xbfb8aa3b, v56
	v_exp_f32_e32 v34, v34
	v_exp_f32_e32 v35, v35
	v_exp_f32_e32 v38, v36
	v_mul_f32_e32 v36, 0xbfb8aa3b, v60
	v_exp_f32_e32 v39, v36
	v_pk_add_f32 v[34:35], v[34:35], 1.0 op_sel_hi:[1,0]
	v_and_b32_e32 v61, 0xffff0000, v87
	v_mul_f32_e32 v34, v34, v35
	v_rcp_f32_e32 v36, v34
	v_pk_add_f32 v[34:35], v[38:39], 1.0 op_sel_hi:[1,0]
	s_nop 0
	v_mul_f32_e32 v34, v34, v35
	v_rcp_f32_e32 v34, v34
	v_mul_f32_e32 v35, v48, v56
	v_mul_f32_e32 v38, v35, v36
	v_mul_f32_e32 v35, v44, v60
	v_mul_f32_e32 v39, v35, v34
	v_mul_f32_e32 v34, 0xbfb8aa3b, v41
	v_mul_f32_e32 v35, 0xbfb8aa3b, v57
	v_exp_f32_e32 v34, v34
	v_exp_f32_e32 v35, v35
	v_mul_f32_e32 v36, 0xbfb8aa3b, v37
	v_mul_f32_e32 v37, 0xbfb8aa3b, v61
	v_exp_f32_e32 v36, v36
	v_exp_f32_e32 v37, v37
	v_pk_add_f32 v[34:35], v[34:35], 1.0 op_sel_hi:[1,0]
	v_lshlrev_b32_e32 v44, 16, v73
	v_mul_f32_e32 v34, v34, v35
	v_rcp_f32_e32 v40, v34
	v_pk_add_f32 v[34:35], v[36:37], 1.0 op_sel_hi:[1,0]
	v_mul_f32_e32 v36, v45, v61
	v_mul_f32_e32 v34, v34, v35
	v_rcp_f32_e32 v34, v34
	v_mul_f32_e32 v35, v49, v57
	v_mul_f32_e32 v35, v35, v40
	v_lshlrev_b32_e32 v40, 16, v71
	v_mul_f32_e32 v37, v36, v34
	v_cvt_pk_bf16_f32 v34, v46, v47
	v_cvt_pk_bf16_f32 v35, v38, v35
	v_cvt_pk_bf16_f32 v36, v42, v43
	v_cvt_pk_bf16_f32 v37, v39, v37
	v_lshl_add_u64 v[38:39], s[4:5], 0, v[78:79]
	v_lshl_add_u64 v[38:39], v[38:39], 0, v[144:145]
	global_store_dwordx4 v[38:39], v[34:37], off
	v_lshlrev_b32_e32 v38, 16, v70
	v_lshlrev_b32_e32 v42, 16, v72
	v_exp_f32_e32 v34, v22
	v_mul_f32_e32 v22, 0xbfb8aa3b, v38
	v_exp_f32_e32 v35, v22
	v_exp_f32_e32 v36, v18
	v_mul_f32_e32 v18, 0xbfb8aa3b, v42
	v_exp_f32_e32 v37, v18
	v_pk_add_f32 v[34:35], v[34:35], 1.0 op_sel_hi:[1,0]
	v_mul_f32_e32 v30, v30, v38
	v_mul_f32_e32 v18, v34, v35
	v_pk_add_f32 v[34:35], v[36:37], 1.0 op_sel_hi:[1,0]
	v_rcp_f32_e32 v18, v18
	v_mul_f32_e32 v22, v34, v35
	v_rcp_f32_e32 v22, v22
	v_and_b32_e32 v39, 0xffff0000, v70
	v_mul_f32_e32 v30, v30, v18
	v_mul_f32_e32 v18, v26, v42
	v_mul_f32_e32 v26, v18, v22
	v_mul_f32_e32 v18, 0xbfb8aa3b, v23
	v_and_b32_e32 v43, 0xffff0000, v72
	v_exp_f32_e32 v22, v18
	v_mul_f32_e32 v18, 0xbfb8aa3b, v39
	v_exp_f32_e32 v23, v18
	v_mul_f32_e32 v18, 0xbfb8aa3b, v19
	v_mul_f32_e32 v19, 0xbfb8aa3b, v43
	v_exp_f32_e32 v18, v18
	v_exp_f32_e32 v19, v19
	v_pk_add_f32 v[22:23], v[22:23], 1.0 op_sel_hi:[1,0]
	v_and_b32_e32 v41, 0xffff0000, v71
	v_mul_f32_e32 v22, v22, v23
	v_pk_add_f32 v[18:19], v[18:19], 1.0 op_sel_hi:[1,0]
	v_rcp_f32_e32 v22, v22
	v_mul_f32_e32 v18, v18, v19
	v_rcp_f32_e32 v18, v18
	v_mul_f32_e32 v19, v31, v39
; __device__ __forceinline__ u32x4 pack8(const float (&f)[8]) { u32x4 r; r[0] = cvt_pk_bf16(f[0], f[1]); r[1] = cvt_pk_bf16(f[2], f[3]); r[2] = cvt_pk_bf16(f[4], f[5]); r[3] = cvt_pk_bf16(f[6], f[7]); return r; }
; #define PG8_WAIT_V(n) asm volatile("s_waitcnt vmcnt(" #n ")" ::: "memory")
; #define PG8_BAR __builtin_amdgcn_s_barrier()
; template <class Sched, class Epi>
; __device__ __forceinline__ void gemm_phase(LAS unsigned char* lds, const Sched& S, const Epi& E, const int K, const int lda, const int ldb) {
;     ...
;         if (!has_next) break;
; #pragma unroll
;         for (int a = 0; a < 2; ++a)
; #pragma unroll
;             for (int b = 0; b < 2; ++b)
; #pragma unroll
;                 for (int m = 0; m < 4; ++m)
; #pragma unroll
;                     for (int n = 0; n < 2; ++n) acc[a][b][m][n] = (f32x4){0.f, 0.f, 0.f, 0.f};
;         cur = nxt; cA = nA; cB = nB; ++ui;
;     }
;     PG8_WAIT_V(0);
;     if (wr == 0) PG8_BAR;
;     PG8_BAR;
;     __device__ __forceinline__ void operator()(EPI_ARGS) const {
;     ...
;             for (int m = 0; m < 4; ++m) { float z[8]; unpack8(zz[m], z);
;                 const f32x4 a0 = acc[ai][0][m][0], a1 = acc[ai][0][m][1], b0 = acc[ai][1][m][0], b1 = acc[ai][1][m][1]; float o[8];
; #pragma unroll
;                 for (int j = 0; j < 4; ++j) { o[j] = a0[j] * z[j] * __builtin_amdgcn_rcpf((1.0f + __expf(-b0[j])) * (1.0f + __expf(-z[j]))); o[4 + j] = a1[j] * z[4 + j] * __builtin_amdgcn_rcpf((1.0f + __expf(-b1[j])) * (1.0f + __expf(-z[4 + j]))); }
;                 *(u32x4*)(O + (size_t)EPI_ROW * 1024 + col) = pack8(o); } }
	v_mul_f32_e32 v31, v19, v22
	v_mul_f32_e32 v19, v27, v43
	v_mul_f32_e32 v27, v19, v18
	v_mul_f32_e32 v18, 0xbfb8aa3b, v24
	v_mul_f32_e32 v19, 0xbfb8aa3b, v40
	v_exp_f32_e32 v18, v18
	v_exp_f32_e32 v19, v19
	v_exp_f32_e32 v22, v20
	v_mul_f32_e32 v20, 0xbfb8aa3b, v44
	v_exp_f32_e32 v23, v20
	v_pk_add_f32 v[18:19], v[18:19], 1.0 op_sel_hi:[1,0]
	v_and_b32_e32 v45, 0xffff0000, v73
	v_mul_f32_e32 v18, v18, v19
	v_rcp_f32_e32 v20, v18
	v_pk_add_f32 v[18:19], v[22:23], 1.0 op_sel_hi:[1,0]
	s_nop 0
	v_mul_f32_e32 v18, v18, v19
	v_rcp_f32_e32 v18, v18
	v_mul_f32_e32 v19, v32, v40
	v_mul_f32_e32 v22, v19, v20
	v_mul_f32_e32 v19, v28, v44
	v_mul_f32_e32 v23, v19, v18
	v_mul_f32_e32 v18, 0xbfb8aa3b, v25
	v_mul_f32_e32 v19, 0xbfb8aa3b, v41
	v_exp_f32_e32 v18, v18
	v_exp_f32_e32 v19, v19
	v_mul_f32_e32 v20, 0xbfb8aa3b, v21
	v_mul_f32_e32 v21, 0xbfb8aa3b, v45
	v_exp_f32_e32 v20, v20
	v_exp_f32_e32 v21, v21
	v_pk_add_f32 v[18:19], v[18:19], 1.0 op_sel_hi:[1,0]
	v_lshlrev_b32_e32 v28, 16, v69
	v_mul_f32_e32 v18, v18, v19
	v_rcp_f32_e32 v24, v18
	v_pk_add_f32 v[18:19], v[20:21], 1.0 op_sel_hi:[1,0]
	v_mul_f32_e32 v20, v29, v45
	v_mul_f32_e32 v18, v18, v19
	v_rcp_f32_e32 v18, v18
	v_mul_f32_e32 v19, v33, v41
	v_mul_f32_e32 v19, v19, v24
	v_lshlrev_b32_e32 v24, 16, v67
	v_mul_f32_e32 v21, v20, v18
	v_cvt_pk_bf16_f32 v18, v30, v31
	v_cvt_pk_bf16_f32 v19, v22, v19
	v_cvt_pk_bf16_f32 v20, v26, v27
	v_cvt_pk_bf16_f32 v21, v23, v21
	v_lshl_add_u64 v[22:23], s[4:5], 0, v[76:77]
	v_lshl_add_u64 v[22:23], v[22:23], 0, v[144:145]
	global_store_dwordx4 v[22:23], v[18:21], off
	v_lshlrev_b32_e32 v22, 16, v66
	v_lshlrev_b32_e32 v26, 16, v68
	v_exp_f32_e32 v18, v6
	v_mul_f32_e32 v6, 0xbfb8aa3b, v22
	v_exp_f32_e32 v19, v6
	v_exp_f32_e32 v20, v2
	v_mul_f32_e32 v2, 0xbfb8aa3b, v26
	v_exp_f32_e32 v21, v2
	v_pk_add_f32 v[18:19], v[18:19], 1.0 op_sel_hi:[1,0]
	v_mul_f32_e32 v14, v14, v22
	v_mul_f32_e32 v2, v18, v19
	v_pk_add_f32 v[18:19], v[20:21], 1.0 op_sel_hi:[1,0]
	v_rcp_f32_e32 v2, v2
	v_mul_f32_e32 v6, v18, v19
	v_rcp_f32_e32 v6, v6
	v_and_b32_e32 v23, 0xffff0000, v66
	v_mul_f32_e32 v14, v14, v2
	v_mul_f32_e32 v2, v10, v26
	v_mul_f32_e32 v10, v2, v6
	v_mul_f32_e32 v2, 0xbfb8aa3b, v7
	v_and_b32_e32 v27, 0xffff0000, v68
	v_exp_f32_e32 v6, v2
	v_mul_f32_e32 v2, 0xbfb8aa3b, v23
	v_exp_f32_e32 v7, v2
	v_mul_f32_e32 v2, 0xbfb8aa3b, v3
	v_mul_f32_e32 v3, 0xbfb8aa3b, v27
	v_exp_f32_e32 v2, v2
	v_exp_f32_e32 v3, v3
	v_pk_add_f32 v[6:7], v[6:7], 1.0 op_sel_hi:[1,0]
	v_and_b32_e32 v25, 0xffff0000, v67
	v_mul_f32_e32 v6, v6, v7
	v_pk_add_f32 v[2:3], v[2:3], 1.0 op_sel_hi:[1,0]
	v_rcp_f32_e32 v6, v6
	v_mul_f32_e32 v2, v2, v3
	v_rcp_f32_e32 v2, v2
	v_mul_f32_e32 v3, v15, v23
	v_mul_f32_e32 v15, v3, v6
	v_mul_f32_e32 v3, v11, v27
	v_mul_f32_e32 v11, v3, v2
	v_mul_f32_e32 v2, 0xbfb8aa3b, v8
	v_mul_f32_e32 v3, 0xbfb8aa3b, v24
	v_exp_f32_e32 v2, v2
	v_exp_f32_e32 v3, v3
	v_exp_f32_e32 v6, v4
	v_mul_f32_e32 v4, 0xbfb8aa3b, v28
	v_exp_f32_e32 v7, v4
	v_pk_add_f32 v[2:3], v[2:3], 1.0 op_sel_hi:[1,0]
	v_and_b32_e32 v29, 0xffff0000, v69
	v_mul_f32_e32 v2, v2, v3
	v_rcp_f32_e32 v4, v2
	v_pk_add_f32 v[2:3], v[6:7], 1.0 op_sel_hi:[1,0]
	s_nop 0
	v_mul_f32_e32 v2, v2, v3
	v_rcp_f32_e32 v2, v2
	v_mul_f32_e32 v3, v16, v24
	v_mul_f32_e32 v6, v3, v4
	v_mul_f32_e32 v3, v12, v28
	v_mul_f32_e32 v7, v3, v2
	v_mul_f32_e32 v2, 0xbfb8aa3b, v9
	v_mul_f32_e32 v3, 0xbfb8aa3b, v25
	v_exp_f32_e32 v2, v2
	v_exp_f32_e32 v3, v3
	v_mul_f32_e32 v4, 0xbfb8aa3b, v5
	v_mul_f32_e32 v5, 0xbfb8aa3b, v29
	v_exp_f32_e32 v4, v4
	v_exp_f32_e32 v5, v5
	v_pk_add_f32 v[2:3], v[2:3], 1.0 op_sel_hi:[1,0]
	s_nop 0
	v_mul_f32_e32 v2, v2, v3
	v_rcp_f32_e32 v8, v2
	v_pk_add_f32 v[2:3], v[4:5], 1.0 op_sel_hi:[1,0]
	v_mul_f32_e32 v4, v13, v29
	v_mul_f32_e32 v2, v2, v3
	v_rcp_f32_e32 v2, v2
	v_mul_f32_e32 v3, v17, v25
	v_mul_f32_e32 v3, v3, v8
	v_mul_f32_e32 v5, v4, v2
	v_cvt_pk_bf16_f32 v2, v14, v15
	v_cvt_pk_bf16_f32 v3, v6, v3
	v_cvt_pk_bf16_f32 v4, v10, v11
	v_cvt_pk_bf16_f32 v5, v7, v5
	v_lshl_add_u64 v[6:7], s[4:5], 0, v[74:75]
	v_lshl_add_u64 v[6:7], v[6:7], 0, v[144:145]
	global_store_dwordx4 v[6:7], v[2:5], off
	s_cbranch_vccz .LBB0_754
	s_waitcnt vmcnt(0)
	s_cmpk_gt_u32 s2, 0xff
	s_cbranch_scc1 .LBB0_765
	s_barrier

; #define PG8_STAGE(bufoff, gbase, voff) do { _Pragma("unroll") for (int _i = 0; _i < 2; ++_i) \
;         __builtin_amdgcn_global_load_lds((const unsigned*)((const char*)(gbase) + (voff)[_i]), (LAS unsigned*)(lds + (bufoff) + ldsw + _i * 8192), 16, 0, 0); } while (0)
; #define PG8_LDA(dst, b, h) do { _Pragma("unroll") for (int m = 0; m < 4; ++m) _Pragma("unroll") for (int k = 0; k < 2; ++k) dst[m][k] = *(const LAS bf16x8*)(lds + PG8_SA(b, h) + aoff + m * 2048 + k * 1024); } while (0)
; #define PG8_LDB(dst, b, h) do { _Pragma("unroll") for (int n = 0; n < 2; ++n) _Pragma("unroll") for (int k = 0; k < 2; ++k) dst[n][k] = *(const LAS bf16x8*)(lds + PG8_SB(b, h) + boff + n * 2048 + k * 1024); } while (0)
; #define PG8_WAIT_L(n) asm volatile("s_waitcnt lgkmcnt(" #n ")" ::: "memory")
; #define PG8_BAR __builtin_amdgcn_s_barrier()
; #define PG8_SCHED __builtin_amdgcn_sched_barrier(0)
; template <class Sched, class Epi>
; __device__ __forceinline__ void gemm_phase(LAS unsigned char* lds, const Sched& S, const Epi& E, const int K, const int lda, const int ldb) {
;     ...
;         for (int t = 0; t < nt; t += 2) {
;             const bool last = (t == nt - 2);
;             const char* a1 = cA + (size_t)(t + 1) * kstep;
;             const char* a2 = last ? nA : cA + (size_t)(t + 2) * kstep; const char* b2 = last ? nB : cB + (size_t)(t + 2) * kstep;
;             const char* a3 = a2 + kstep; const char* b3 = b2 + kstep;
;             PG8_LDB(B0, 0, 0); PG8_SCHED; PG8_LDA(At, 0, 0); PG8_STAGE(PG8_SA(1, 1), a1 + hstepA, voffA);
;             PG8_WAIT_L(8); PG8_BAR; PG8_WAIT_L(0); PG8_MMA(0, 0, At, B0); PG8_BAR; PG8_SCHED;
;             PG8_LDB(B1, 0, 1); PG8_STAGE(PG8_SB(0, 0), b2, voffB);
;             PG8_BAR; PG8_WAIT_L(0); PG8_MMA(0, 1, At, B1); PG8_BAR;
;             PG8_LDA(At, 0, 1); PG8_STAGE(PG8_SA(0, 0), a2, voffA);
;             PG8_BAR; PG8_WAIT_L(0); if (!chalf) PG8_MMA(1, 0, At, B0); PG8_BAR; PG8_SCHED;
;     ...
; #pragma unroll
;         for (int a = 0; a < 2; ++a)
; #pragma unroll
;             for (int b = 0; b < 2; ++b)
; #pragma unroll
;                 for (int m = 0; m < 4; ++m)
; #pragma unroll
;                     for (int n = 0; n < 2; ++n) acc[a][b][m][n] = (f32x4){0.f, 0.f, 0.f, 0.f};
;         cur = nxt; cA = nA; cB = nB; ++ui;
.LBB0_841:
	s_add_u32 s17, s34, 0x100
	s_addc_u32 s19, s35, 0
	s_add_u32 s6, s28, 0x40080
	v_mov_b32_e32 v2, 0
	s_addc_u32 s7, s29, 0
	s_mov_b32 s21, -2
	v_mov_b32_e32 v3, v2
	v_mov_b32_e32 v4, v2
	v_mov_b32_e32 v5, v2
	v_mov_b32_e32 v6, v2
	v_mov_b32_e32 v7, v2
	v_mov_b32_e32 v8, v2
	v_mov_b32_e32 v9, v2
	v_mov_b32_e32 v10, v2
	v_mov_b32_e32 v11, v2
	v_mov_b32_e32 v12, v2
	v_mov_b32_e32 v13, v2
	v_mov_b32_e32 v14, v2
	v_mov_b32_e32 v15, v2
	v_mov_b32_e32 v16, v2
	v_mov_b32_e32 v17, v2
	v_mov_b32_e32 v18, v2
	v_mov_b32_e32 v19, v2
	v_mov_b32_e32 v20, v2
	v_mov_b32_e32 v21, v2
	v_mov_b32_e32 v22, v2
	v_mov_b32_e32 v23, v2
	v_mov_b32_e32 v24, v2
	v_mov_b32_e32 v25, v2
	v_mov_b32_e32 v26, v2
	v_mov_b32_e32 v27, v2
	v_mov_b32_e32 v28, v2
	v_mov_b32_e32 v29, v2
	v_mov_b32_e32 v30, v2
	v_mov_b32_e32 v31, v2
	v_mov_b32_e32 v32, v2
	v_mov_b32_e32 v33, v2
	v_mov_b32_e32 v34, v2
	v_mov_b32_e32 v35, v2
	v_mov_b32_e32 v36, v2
	v_mov_b32_e32 v37, v2
	v_mov_b32_e32 v38, v2
	v_mov_b32_e32 v39, v2
	v_mov_b32_e32 v40, v2
	v_mov_b32_e32 v41, v2
	v_mov_b32_e32 v42, v2
	v_mov_b32_e32 v43, v2
	v_mov_b32_e32 v44, v2
	v_mov_b32_e32 v45, v2
	v_mov_b32_e32 v46, v2
	v_mov_b32_e32 v47, v2
	v_mov_b32_e32 v48, v2
	v_mov_b32_e32 v49, v2
	v_mov_b32_e32 v50, v2
	v_mov_b32_e32 v51, v2
	v_mov_b32_e32 v52, v2
	v_mov_b32_e32 v53, v2
	v_mov_b32_e32 v54, v2
	v_mov_b32_e32 v55, v2
	v_mov_b32_e32 v56, v2
	v_mov_b32_e32 v57, v2
	v_mov_b32_e32 v58, v2
	v_mov_b32_e32 v59, v2
	v_mov_b32_e32 v60, v2
	v_mov_b32_e32 v61, v2
	v_mov_b32_e32 v62, v2
	v_mov_b32_e32 v63, v2
	v_mov_b32_e32 v64, v2
	v_mov_b32_e32 v65, v2
	v_mov_b32_e32 v66, v2
	v_mov_b32_e32 v67, v2
	v_mov_b32_e32 v68, v2
	v_mov_b32_e32 v69, v2
	v_mov_b32_e32 v70, v2
	v_mov_b32_e32 v71, v2
	v_mov_b32_e32 v72, v2
	v_mov_b32_e32 v73, v2
	v_mov_b32_e32 v74, v2
	v_mov_b32_e32 v75, v2
	v_mov_b32_e32 v76, v2
	v_mov_b32_e32 v77, v2
	v_mov_b32_e32 v78, v2
	v_mov_b32_e32 v79, v2
	v_mov_b32_e32 v80, v2
	v_mov_b32_e32 v81, v2
	v_mov_b32_e32 v82, v2
	v_mov_b32_e32 v83, v2
	v_mov_b32_e32 v84, v2
	v_mov_b32_e32 v85, v2
	v_mov_b32_e32 v86, v2
	v_mov_b32_e32 v87, v2
	v_mov_b32_e32 v88, v2
	v_mov_b32_e32 v89, v2
	v_mov_b32_e32 v90, v2
	v_mov_b32_e32 v91, v2
	v_mov_b32_e32 v92, v2
	v_mov_b32_e32 v93, v2
	v_mov_b32_e32 v94, v2
	v_mov_b32_e32 v95, v2
	v_mov_b32_e32 v96, v2
	v_mov_b32_e32 v97, v2
	v_mov_b32_e32 v98, v2
	v_mov_b32_e32 v99, v2
	v_mov_b32_e32 v100, v2
	v_mov_b32_e32 v101, v2
	v_mov_b32_e32 v102, v2
	v_mov_b32_e32 v103, v2
	v_mov_b32_e32 v104, v2
	v_mov_b32_e32 v105, v2
	v_mov_b32_e32 v106, v2
	v_mov_b32_e32 v107, v2
	v_mov_b32_e32 v108, v2
	v_mov_b32_e32 v109, v2
	v_mov_b32_e32 v110, v2
	v_mov_b32_e32 v111, v2
	v_mov_b32_e32 v112, v2
	v_mov_b32_e32 v113, v2
	v_mov_b32_e32 v114, v2
	v_mov_b32_e32 v115, v2
	v_mov_b32_e32 v116, v2
	v_mov_b32_e32 v117, v2
	v_mov_b32_e32 v118, v2
	v_mov_b32_e32 v119, v2
	v_mov_b32_e32 v120, v2
	v_mov_b32_e32 v121, v2
	v_mov_b32_e32 v122, v2
	v_mov_b32_e32 v123, v2
	v_mov_b32_e32 v124, v2
	v_mov_b32_e32 v125, v2
	v_mov_b32_e32 v126, v2
	v_mov_b32_e32 v127, v2
	v_mov_b32_e32 v128, v2
	v_mov_b32_e32 v129, v2
	v_add_u32_e32 v250, 0x18010, v224
	v_add_u32_e32 v251, 0x1c010, v224
	s_branch .Lal_842
	.p2align 11
.Lal_842:
.LBB0_842:
	ds_read_b128 v[130:133], v233
	ds_read_b128 v[134:137], v233 offset:1024
	ds_read_b128 v[138:141], v233 offset:2048
	ds_read_b128 v[142:145], v233 offset:3072
	s_add_u32 s28, s6, 0xfffc0080
	s_addc_u32 s29, s7, -1
	s_cmp_eq_u32 s21, 12
	s_cselect_b32 s35, s23, s29
	s_cselect_b32 s34, s22, s28
	s_cselect_b32 s29, s25, s19
	s_cselect_b32 s28, s24, s17
	s_add_i32 m0, s31, 0xc000
	ds_read_b128 v[146:149], v234
	ds_read_b128 v[150:153], v234 offset:1024
	ds_read_b128 v[154:157], v234 offset:2048
	ds_read_b128 v[158:161], v234 offset:3072
	ds_read_b128 v[162:165], v234 offset:4096
	ds_read_b128 v[166:169], v234 offset:5120
	ds_read_b128 v[170:173], v234 offset:6144
	ds_read_b128 v[174:177], v234 offset:7168
	global_load_lds_dwordx4 v208, s[6:7]
	s_add_i32 m0, s31, 0xe000
	s_nop 0
	global_load_lds_dwordx4 v206, s[6:7]
	s_waitcnt lgkmcnt(8)
	s_barrier
	s_waitcnt lgkmcnt(0)
	s_setprio 1
	s_waitcnt lgkmcnt(0)
	v_mfma_f32_16x16x32_bf16 v[126:129], v[130:133], v[146:149], v[126:129]
	v_mfma_f32_16x16x32_bf16 v[122:125], v[138:141], v[146:149], v[122:125]
	v_mfma_f32_16x16x32_bf16 v[118:121], v[130:133], v[154:157], v[118:121]
	v_mfma_f32_16x16x32_bf16 v[114:117], v[138:141], v[154:157], v[114:117]
	v_mfma_f32_16x16x32_bf16 v[110:113], v[130:133], v[162:165], v[110:113]
	v_mfma_f32_16x16x32_bf16 v[106:109], v[138:141], v[162:165], v[106:109]
	v_mfma_f32_16x16x32_bf16 v[102:105], v[130:133], v[170:173], v[102:105]
	v_mfma_f32_16x16x32_bf16 v[98:101], v[138:141], v[170:173], v[98:101]
	v_mfma_f32_16x16x32_bf16 v[126:129], v[134:137], v[150:153], v[126:129]
	v_mfma_f32_16x16x32_bf16 v[122:125], v[142:145], v[150:153], v[122:125]
	v_mfma_f32_16x16x32_bf16 v[118:121], v[134:137], v[158:161], v[118:121]
	v_mfma_f32_16x16x32_bf16 v[114:117], v[142:145], v[158:161], v[114:117]
	v_mfma_f32_16x16x32_bf16 v[110:113], v[134:137], v[166:169], v[110:113]
	v_mfma_f32_16x16x32_bf16 v[106:109], v[142:145], v[166:169], v[106:109]
	v_mfma_f32_16x16x32_bf16 v[102:105], v[134:137], v[174:177], v[102:105]
	v_mfma_f32_16x16x32_bf16 v[98:101], v[142:145], v[174:177], v[98:101]
	s_setprio 0
	s_barrier
	s_add_i32 s49, s43, s27
	s_add_u32 s52, s28, s14
	s_addc_u32 s53, s29, s15
	s_mov_b32 m0, s49
	ds_read_b128 v[178:181], v235
	ds_read_b128 v[182:185], v235 offset:1024
	ds_read_b128 v[186:189], v235 offset:2048
	ds_read_b128 v[190:193], v235 offset:3072
	global_load_lds_dwordx4 v200, s[28:29]
	s_add_u32 s54, s28, s14
	s_addc_u32 s55, s29, s15
	s_add_i32 m0, s49, 0x2000
	s_nop 0
	global_load_lds_dwordx4 v204, s[28:29]
	s_barrier
; #define PG8_STAGE(bufoff, gbase, voff) do { _Pragma("unroll") for (int _i = 0; _i < 2; ++_i) \
;         __builtin_amdgcn_global_load_lds((const unsigned*)((const char*)(gbase) + (voff)[_i]), (LAS unsigned*)(lds + (bufoff) + ldsw + _i * 8192), 16, 0, 0); } while (0)
; #define PG8_LDA(dst, b, h) do { _Pragma("unroll") for (int m = 0; m < 4; ++m) _Pragma("unroll") for (int k = 0; k < 2; ++k) dst[m][k] = *(const LAS bf16x8*)(lds + PG8_SA(b, h) + aoff + m * 2048 + k * 1024); } while (0)
; #define PG8_LDB(dst, b, h) do { _Pragma("unroll") for (int n = 0; n < 2; ++n) _Pragma("unroll") for (int k = 0; k < 2; ++k) dst[n][k] = *(const LAS bf16x8*)(lds + PG8_SB(b, h) + boff + n * 2048 + k * 1024); } while (0)
; #define PG8_MMA(ai, bj, At, Bt) do { __builtin_amdgcn_s_setprio(1); _Pragma("unroll") for (int m = 0; m < 4; ++m) _Pragma("unroll") for (int n = 0; n < 2; ++n) _Pragma("unroll") for (int k = 0; k < 2; ++k) \
;         acc[ai][bj][m][n] = __builtin_amdgcn_mfma_f32_16x16x32_bf16(Bt[n][k], At[m][k], acc[ai][bj][m][n], 0, 0, 0); __builtin_amdgcn_s_setprio(0); } while (0)
; #define PG8_WAIT_V(n) asm volatile("s_waitcnt vmcnt(" #n ")" ::: "memory")
; #define PG8_WAIT_L(n) asm volatile("s_waitcnt lgkmcnt(" #n ")" ::: "memory")
; #define PG8_BAR __builtin_amdgcn_s_barrier()
; #define PG8_SCHED __builtin_amdgcn_sched_barrier(0)
; template <class Sched, class Epi>
; __device__ __forceinline__ void gemm_phase(LAS unsigned char* lds, const Sched& S, const Epi& E, const int K, const int lda, const int ldb) {
;     ...
;             PG8_LDB(B1, 0, 1); PG8_STAGE(PG8_SB(0, 0), b2, voffB);
;             PG8_BAR; PG8_WAIT_L(0); PG8_MMA(0, 1, At, B1); PG8_BAR;
;             PG8_LDA(At, 0, 1); PG8_STAGE(PG8_SA(0, 0), a2, voffA);
;             PG8_BAR; PG8_WAIT_L(0); if (!chalf) PG8_MMA(1, 0, At, B0); PG8_BAR; PG8_SCHED;
;             PG8_STAGE(PG8_SB(0, 1), b2 + hstepB, voffB);
;             PG8_WAIT_V(6); PG8_BAR; if (!chalf) PG8_MMA(1, 1, At, B1); PG8_BAR;
;             PG8_LDB(B0, 1, 0); PG8_SCHED; PG8_LDA(At, 1, 0); PG8_STAGE(PG8_SA(0, 1), a2 + hstepA, voffA);
;             PG8_WAIT_L(8); PG8_BAR; PG8_WAIT_L(0); PG8_MMA(0, 0, At, B0); PG8_BAR; PG8_SCHED;
;             PG8_LDB(B1, 1, 1); PG8_STAGE(PG8_SB(1, 0), b3, voffB);
	s_waitcnt lgkmcnt(0)
	s_setprio 1
	s_waitcnt lgkmcnt(0)
	v_mfma_f32_16x16x32_bf16 v[94:97], v[178:181], v[146:149], v[94:97]
	v_mfma_f32_16x16x32_bf16 v[90:93], v[186:189], v[146:149], v[90:93]
	v_mfma_f32_16x16x32_bf16 v[86:89], v[178:181], v[154:157], v[86:89]
	v_mfma_f32_16x16x32_bf16 v[82:85], v[186:189], v[154:157], v[82:85]
	v_mfma_f32_16x16x32_bf16 v[78:81], v[178:181], v[162:165], v[78:81]
	v_mfma_f32_16x16x32_bf16 v[74:77], v[186:189], v[162:165], v[74:77]
	v_mfma_f32_16x16x32_bf16 v[70:73], v[178:181], v[170:173], v[70:73]
	v_mfma_f32_16x16x32_bf16 v[66:69], v[186:189], v[170:173], v[66:69]
	v_mfma_f32_16x16x32_bf16 v[94:97], v[182:185], v[150:153], v[94:97]
	v_mfma_f32_16x16x32_bf16 v[90:93], v[190:193], v[150:153], v[90:93]
	v_mfma_f32_16x16x32_bf16 v[86:89], v[182:185], v[158:161], v[86:89]
	v_mfma_f32_16x16x32_bf16 v[82:85], v[190:193], v[158:161], v[82:85]
	v_mfma_f32_16x16x32_bf16 v[78:81], v[182:185], v[166:169], v[78:81]
	v_mfma_f32_16x16x32_bf16 v[74:77], v[190:193], v[166:169], v[74:77]
	v_mfma_f32_16x16x32_bf16 v[70:73], v[182:185], v[174:177], v[70:73]
	v_mfma_f32_16x16x32_bf16 v[66:69], v[190:193], v[174:177], v[66:69]
	s_setprio 0
	s_mov_b32 m0, s31
	s_add_u32 s56, s34, s14
	s_addc_u32 s57, s35, s15
	s_barrier
	ds_read_b128 v[146:149], v234 offset:16384
	ds_read_b128 v[150:153], v234 offset:17408
	ds_read_b128 v[154:157], v234 offset:18432
	ds_read_b128 v[158:161], v234 offset:19456
	ds_read_b128 v[162:165], v234 offset:20480
	ds_read_b128 v[166:169], v234 offset:21504
	ds_read_b128 v[170:173], v234 offset:22528
	ds_read_b128 v[174:177], v234 offset:23552
	global_load_lds_dwordx4 v198, s[34:35]
	s_add_u32 s58, s34, s14
	s_addc_u32 s59, s35, s15
	s_mov_b32 m0, s33
	s_nop 0
	global_load_lds_dwordx4 v202, s[34:35]
	s_barrier
	s_waitcnt lgkmcnt(0)
	s_setprio 1
	s_waitcnt lgkmcnt(0)
	v_mfma_f32_16x16x32_bf16 v[62:65], v[130:133], v[146:149], v[62:65]
	v_mfma_f32_16x16x32_bf16 v[58:61], v[138:141], v[146:149], v[58:61]
	v_mfma_f32_16x16x32_bf16 v[54:57], v[130:133], v[154:157], v[54:57]
	v_mfma_f32_16x16x32_bf16 v[50:53], v[138:141], v[154:157], v[50:53]
	v_mfma_f32_16x16x32_bf16 v[46:49], v[130:133], v[162:165], v[46:49]
	v_mfma_f32_16x16x32_bf16 v[42:45], v[138:141], v[162:165], v[42:45]
	v_mfma_f32_16x16x32_bf16 v[38:41], v[130:133], v[170:173], v[38:41]
	v_mfma_f32_16x16x32_bf16 v[34:37], v[138:141], v[170:173], v[34:37]
	v_mfma_f32_16x16x32_bf16 v[62:65], v[134:137], v[150:153], v[62:65]
	v_mfma_f32_16x16x32_bf16 v[58:61], v[142:145], v[150:153], v[58:61]
	v_mfma_f32_16x16x32_bf16 v[54:57], v[134:137], v[158:161], v[54:57]
	v_mfma_f32_16x16x32_bf16 v[50:53], v[142:145], v[158:161], v[50:53]
	v_mfma_f32_16x16x32_bf16 v[46:49], v[134:137], v[166:169], v[46:49]
	v_mfma_f32_16x16x32_bf16 v[42:45], v[142:145], v[166:169], v[42:45]
	v_mfma_f32_16x16x32_bf16 v[38:41], v[134:137], v[174:177], v[38:41]
	v_mfma_f32_16x16x32_bf16 v[34:37], v[142:145], v[174:177], v[34:37]
	s_setprio 0
	s_barrier
	s_add_u32 s50, s28, 0x40000
	s_addc_u32 s51, s29, 0
	s_add_i32 s49, s44, s27
	s_mov_b32 m0, s49
	s_nop 0
	global_load_lds_dwordx4 v200, s[50:51]
	s_add_i32 m0, s49, 0x2000
	s_nop 0
	global_load_lds_dwordx4 v204, s[50:51]
	s_waitcnt vmcnt(6)
	s_barrier
	s_setprio 1
	v_mfma_f32_16x16x32_bf16 v[30:33], v[178:181], v[146:149], v[30:33]
	v_mfma_f32_16x16x32_bf16 v[26:29], v[186:189], v[146:149], v[26:29]
	v_mfma_f32_16x16x32_bf16 v[22:25], v[178:181], v[154:157], v[22:25]
	v_mfma_f32_16x16x32_bf16 v[18:21], v[186:189], v[154:157], v[18:21]
	v_mfma_f32_16x16x32_bf16 v[14:17], v[178:181], v[162:165], v[14:17]
	v_mfma_f32_16x16x32_bf16 v[10:13], v[186:189], v[162:165], v[10:13]
	v_mfma_f32_16x16x32_bf16 v[6:9], v[178:181], v[170:173], v[6:9]
	v_mfma_f32_16x16x32_bf16 v[2:5], v[186:189], v[170:173], v[2:5]
	v_mfma_f32_16x16x32_bf16 v[30:33], v[182:185], v[150:153], v[30:33]
	v_mfma_f32_16x16x32_bf16 v[26:29], v[190:193], v[150:153], v[26:29]
	v_mfma_f32_16x16x32_bf16 v[22:25], v[182:185], v[158:161], v[22:25]
	v_mfma_f32_16x16x32_bf16 v[18:21], v[190:193], v[158:161], v[18:21]
	v_mfma_f32_16x16x32_bf16 v[14:17], v[182:185], v[166:169], v[14:17]
	v_mfma_f32_16x16x32_bf16 v[10:13], v[190:193], v[166:169], v[10:13]
	v_mfma_f32_16x16x32_bf16 v[6:9], v[182:185], v[174:177], v[6:9]
	v_mfma_f32_16x16x32_bf16 v[2:5], v[190:193], v[174:177], v[2:5]
	s_setprio 0
	s_add_i32 s49, 16, 0x18000
	s_barrier
	ds_read_b128 v[130:133], v250
	ds_read_b128 v[134:137], v250 offset:1024
	ds_read_b128 v[138:141], v250 offset:2048
	ds_read_b128 v[142:145], v250 offset:3072
	s_add_u32 s34, s34, 0x40000
	s_addc_u32 s35, s35, 0
	s_mov_b32 m0, s36
	ds_read_b128 v[146:149], v234 offset:32768
	ds_read_b128 v[150:153], v234 offset:33792
	ds_read_b128 v[154:157], v234 offset:34816
	ds_read_b128 v[158:161], v234 offset:35840
	ds_read_b128 v[162:165], v234 offset:36864
	ds_read_b128 v[166:169], v234 offset:37888
	ds_read_b128 v[170:173], v234 offset:38912
	ds_read_b128 v[174:177], v234 offset:39936
	global_load_lds_dwordx4 v198, s[34:35]
	s_mov_b32 m0, s37
	s_nop 0
	global_load_lds_dwordx4 v202, s[34:35]
	s_waitcnt lgkmcnt(8)
	s_barrier
; #define PG8_STAGE(bufoff, gbase, voff) do { _Pragma("unroll") for (int _i = 0; _i < 2; ++_i) \
;         __builtin_amdgcn_global_load_lds((const unsigned*)((const char*)(gbase) + (voff)[_i]), (LAS unsigned*)(lds + (bufoff) + ldsw + _i * 8192), 16, 0, 0); } while (0)
; #define PG8_LDA(dst, b, h) do { _Pragma("unroll") for (int m = 0; m < 4; ++m) _Pragma("unroll") for (int k = 0; k < 2; ++k) dst[m][k] = *(const LAS bf16x8*)(lds + PG8_SA(b, h) + aoff + m * 2048 + k * 1024); } while (0)
; #define PG8_LDB(dst, b, h) do { _Pragma("unroll") for (int n = 0; n < 2; ++n) _Pragma("unroll") for (int k = 0; k < 2; ++k) dst[n][k] = *(const LAS bf16x8*)(lds + PG8_SB(b, h) + boff + n * 2048 + k * 1024); } while (0)
; #define PG8_MMA(ai, bj, At, Bt) do { __builtin_amdgcn_s_setprio(1); _Pragma("unroll") for (int m = 0; m < 4; ++m) _Pragma("unroll") for (int n = 0; n < 2; ++n) _Pragma("unroll") for (int k = 0; k < 2; ++k) \
;         acc[ai][bj][m][n] = __builtin_amdgcn_mfma_f32_16x16x32_bf16(Bt[n][k], At[m][k], acc[ai][bj][m][n], 0, 0, 0); __builtin_amdgcn_s_setprio(0); } while (0)
; #define PG8_WAIT_V(n) asm volatile("s_waitcnt vmcnt(" #n ")" ::: "memory")
; #define PG8_WAIT_L(n) asm volatile("s_waitcnt lgkmcnt(" #n ")" ::: "memory")
; #define PG8_BAR __builtin_amdgcn_s_barrier()
; #define PG8_SCHED __builtin_amdgcn_sched_barrier(0)
; template <class Sched, class Epi>
; __device__ __forceinline__ void gemm_phase(LAS unsigned char* lds, const Sched& S, const Epi& E, const int K, const int lda, const int ldb) {
;     ...
;             PG8_LDB(B1, 1, 1); PG8_STAGE(PG8_SB(1, 0), b3, voffB);
;             PG8_BAR; PG8_WAIT_L(0); PG8_MMA(0, 1, At, B1); PG8_BAR;
;             PG8_LDA(At, 1, 1); PG8_STAGE(PG8_SA(1, 0), a3, voffA);
;             PG8_BAR; PG8_WAIT_L(0); if (!chalf) PG8_MMA(1, 0, At, B0); PG8_BAR; PG8_SCHED;
;             PG8_STAGE(PG8_SB(1, 1), b3 + hstepB, voffB);
;             PG8_WAIT_V(6); PG8_BAR; if (!chalf) PG8_MMA(1, 1, At, B1); PG8_BAR;
;         }
;     __device__ __forceinline__ void operator()(EPI_ARGS) const {
;         const int br = u.z; const int nb = u.half ? 2 : 4;
;         u32x4 gg[2][4], pp[2][4];
	s_waitcnt lgkmcnt(0)
	s_setprio 1
	s_waitcnt lgkmcnt(0)
	v_mfma_f32_16x16x32_bf16 v[126:129], v[130:133], v[146:149], v[126:129]
	v_mfma_f32_16x16x32_bf16 v[122:125], v[138:141], v[146:149], v[122:125]
	v_mfma_f32_16x16x32_bf16 v[118:121], v[130:133], v[154:157], v[118:121]
	v_mfma_f32_16x16x32_bf16 v[114:117], v[138:141], v[154:157], v[114:117]
	v_mfma_f32_16x16x32_bf16 v[110:113], v[130:133], v[162:165], v[110:113]
	v_mfma_f32_16x16x32_bf16 v[106:109], v[138:141], v[162:165], v[106:109]
	v_mfma_f32_16x16x32_bf16 v[102:105], v[130:133], v[170:173], v[102:105]
	v_mfma_f32_16x16x32_bf16 v[98:101], v[138:141], v[170:173], v[98:101]
	v_mfma_f32_16x16x32_bf16 v[126:129], v[134:137], v[150:153], v[126:129]
	v_mfma_f32_16x16x32_bf16 v[122:125], v[142:145], v[150:153], v[122:125]
	v_mfma_f32_16x16x32_bf16 v[118:121], v[134:137], v[158:161], v[118:121]
	v_mfma_f32_16x16x32_bf16 v[114:117], v[142:145], v[158:161], v[114:117]
	v_mfma_f32_16x16x32_bf16 v[110:113], v[134:137], v[166:169], v[110:113]
	v_mfma_f32_16x16x32_bf16 v[106:109], v[142:145], v[166:169], v[106:109]
	v_mfma_f32_16x16x32_bf16 v[102:105], v[134:137], v[174:177], v[102:105]
	v_mfma_f32_16x16x32_bf16 v[98:101], v[142:145], v[174:177], v[98:101]
	s_setprio 0
	s_barrier
	s_add_i32 s34, 16, 0x1c000
	s_add_i32 s35, s49, s27
	s_mov_b32 m0, s35
	ds_read_b128 v[178:181], v251
	ds_read_b128 v[182:185], v251 offset:1024
	ds_read_b128 v[186:189], v251 offset:2048
	ds_read_b128 v[190:193], v251 offset:3072
	global_load_lds_dwordx4 v200, s[52:53]
	s_add_i32 m0, s35, 0x2000
	s_nop 0
	global_load_lds_dwordx4 v204, s[54:55]
	s_barrier
	s_waitcnt lgkmcnt(0)
	s_setprio 1
	s_waitcnt lgkmcnt(0)
	v_mfma_f32_16x16x32_bf16 v[94:97], v[178:181], v[146:149], v[94:97]
	v_mfma_f32_16x16x32_bf16 v[90:93], v[186:189], v[146:149], v[90:93]
	v_mfma_f32_16x16x32_bf16 v[86:89], v[178:181], v[154:157], v[86:89]
	v_mfma_f32_16x16x32_bf16 v[82:85], v[186:189], v[154:157], v[82:85]
	v_mfma_f32_16x16x32_bf16 v[78:81], v[178:181], v[162:165], v[78:81]
	v_mfma_f32_16x16x32_bf16 v[74:77], v[186:189], v[162:165], v[74:77]
	v_mfma_f32_16x16x32_bf16 v[70:73], v[178:181], v[170:173], v[70:73]
	v_mfma_f32_16x16x32_bf16 v[66:69], v[186:189], v[170:173], v[66:69]
	v_mfma_f32_16x16x32_bf16 v[94:97], v[182:185], v[150:153], v[94:97]
	v_mfma_f32_16x16x32_bf16 v[90:93], v[190:193], v[150:153], v[90:93]
	v_mfma_f32_16x16x32_bf16 v[86:89], v[182:185], v[158:161], v[86:89]
	v_mfma_f32_16x16x32_bf16 v[82:85], v[190:193], v[158:161], v[82:85]
	v_mfma_f32_16x16x32_bf16 v[78:81], v[182:185], v[166:169], v[78:81]
	v_mfma_f32_16x16x32_bf16 v[74:77], v[190:193], v[166:169], v[74:77]
	v_mfma_f32_16x16x32_bf16 v[70:73], v[182:185], v[174:177], v[70:73]
	v_mfma_f32_16x16x32_bf16 v[66:69], v[190:193], v[174:177], v[66:69]
	s_setprio 0
	s_mov_b32 m0, s39
	s_barrier
	ds_read_b128 v[146:149], v234 offset:49152
	ds_read_b128 v[150:153], v234 offset:50176
	ds_read_b128 v[154:157], v234 offset:51200
	ds_read_b128 v[158:161], v234 offset:52224
	ds_read_b128 v[162:165], v234 offset:53248
	ds_read_b128 v[166:169], v234 offset:54272
	ds_read_b128 v[170:173], v234 offset:55296
	ds_read_b128 v[174:177], v234 offset:56320
	global_load_lds_dwordx4 v198, s[56:57]
	s_mov_b32 m0, s40
	s_nop 0
	global_load_lds_dwordx4 v202, s[58:59]
	s_barrier
	s_waitcnt lgkmcnt(0)
	s_setprio 1
	s_waitcnt lgkmcnt(0)
	v_mfma_f32_16x16x32_bf16 v[62:65], v[130:133], v[146:149], v[62:65]
	v_mfma_f32_16x16x32_bf16 v[58:61], v[138:141], v[146:149], v[58:61]
	v_mfma_f32_16x16x32_bf16 v[54:57], v[130:133], v[154:157], v[54:57]
	v_mfma_f32_16x16x32_bf16 v[50:53], v[138:141], v[154:157], v[50:53]
	v_mfma_f32_16x16x32_bf16 v[46:49], v[130:133], v[162:165], v[46:49]
	v_mfma_f32_16x16x32_bf16 v[42:45], v[138:141], v[162:165], v[42:45]
	v_mfma_f32_16x16x32_bf16 v[38:41], v[130:133], v[170:173], v[38:41]
	v_mfma_f32_16x16x32_bf16 v[34:37], v[138:141], v[170:173], v[34:37]
	v_mfma_f32_16x16x32_bf16 v[62:65], v[134:137], v[150:153], v[62:65]
	v_mfma_f32_16x16x32_bf16 v[58:61], v[142:145], v[150:153], v[58:61]
	v_mfma_f32_16x16x32_bf16 v[54:57], v[134:137], v[158:161], v[54:57]
	v_mfma_f32_16x16x32_bf16 v[50:53], v[142:145], v[158:161], v[50:53]
	v_mfma_f32_16x16x32_bf16 v[46:49], v[134:137], v[166:169], v[46:49]
	v_mfma_f32_16x16x32_bf16 v[42:45], v[142:145], v[166:169], v[42:45]
	v_mfma_f32_16x16x32_bf16 v[38:41], v[134:137], v[174:177], v[38:41]
	v_mfma_f32_16x16x32_bf16 v[34:37], v[142:145], v[174:177], v[34:37]
	s_setprio 0
	s_barrier
	s_add_u32 s28, s28, 0x40080
	s_addc_u32 s29, s29, 0
	s_add_i32 s34, s34, s27
	s_mov_b32 m0, s34
	s_nop 0
	global_load_lds_dwordx4 v200, s[28:29]
	s_add_i32 m0, s34, 0x2000
	s_nop 0
	global_load_lds_dwordx4 v204, s[28:29]
	s_waitcnt vmcnt(6)
	s_barrier
	s_setprio 1
	v_mfma_f32_16x16x32_bf16 v[30:33], v[178:181], v[146:149], v[30:33]
	v_mfma_f32_16x16x32_bf16 v[26:29], v[186:189], v[146:149], v[26:29]
	v_mfma_f32_16x16x32_bf16 v[22:25], v[178:181], v[154:157], v[22:25]
	v_mfma_f32_16x16x32_bf16 v[18:21], v[186:189], v[154:157], v[18:21]
	v_mfma_f32_16x16x32_bf16 v[14:17], v[178:181], v[162:165], v[14:17]
	v_mfma_f32_16x16x32_bf16 v[10:13], v[186:189], v[162:165], v[10:13]
	v_mfma_f32_16x16x32_bf16 v[6:9], v[178:181], v[170:173], v[6:9]
	v_mfma_f32_16x16x32_bf16 v[2:5], v[186:189], v[170:173], v[2:5]
	v_mfma_f32_16x16x32_bf16 v[30:33], v[182:185], v[150:153], v[30:33]
	v_mfma_f32_16x16x32_bf16 v[26:29], v[190:193], v[150:153], v[26:29]
	v_mfma_f32_16x16x32_bf16 v[22:25], v[182:185], v[158:161], v[22:25]
	v_mfma_f32_16x16x32_bf16 v[18:21], v[190:193], v[158:161], v[18:21]
	v_mfma_f32_16x16x32_bf16 v[14:17], v[182:185], v[166:169], v[14:17]
	v_mfma_f32_16x16x32_bf16 v[10:13], v[190:193], v[166:169], v[10:13]
	v_mfma_f32_16x16x32_bf16 v[6:9], v[182:185], v[174:177], v[6:9]
	v_mfma_f32_16x16x32_bf16 v[2:5], v[190:193], v[174:177], v[2:5]
	s_setprio 0
	s_add_i32 s21, s21, 2
	s_add_u32 s17, s17, 0x100
	s_addc_u32 s19, s19, 0
	s_add_u32 s6, s6, 0x100
	s_addc_u32 s7, s7, 0
	s_cmp_gt_u32 s21, 13
	s_barrier
	s_cbranch_scc0 .LBB0_842
	s_lshl_b32 s6, s48, 11
	s_ashr_i32 s7, s6, 31
	s_lshl_b64 s[28:29], s[6:7], 1
	v_lshl_or_b32 v134, s47, 8, v232
	s_add_u32 s6, s41, s28
	v_ashrrev_i32_e32 v135, 31, v134
	s_addc_u32 s7, s42, s29
	v_lshlrev_b64 v[212:213], 1, v[134:135]
	v_add_u32_e32 v130, s26, v1
	v_lshl_add_u64 v[216:217], s[6:7], 0, v[212:213]
	v_mad_i64_i32 v[132:133], s[6:7], v130, s45, v[216:217]
	global_load_dwordx4 v[194:197], v[132:133], off
	v_ashrrev_i32_e32 v131, 31, v130
	s_cmp_gt_i32 s48, 0
	v_lshl_add_u64 v[218:219], s[12:13], 0, v[212:213]
	v_lshlrev_b64 v[132:133], 12, v[130:131]
	s_cselect_b64 s[34:35], -1, 0
	s_cmp_lt_i32 s48, 1
	v_lshl_add_u64 v[136:137], v[218:219], 0, v[132:133]
	s_cbranch_scc1 .LBB0_845
	global_load_dwordx4 v[190:193], v[136:137], off
	s_branch .LBB0_846

; #define PG8_STAGE(bufoff, gbase, voff) do { _Pragma("unroll") for (int _i = 0; _i < 2; ++_i) \
;         __builtin_amdgcn_global_load_lds((const unsigned*)((const char*)(gbase) + (voff)[_i]), (LAS unsigned*)(lds + (bufoff) + ldsw + _i * 8192), 16, 0, 0); } while (0)
; #define PG8_LDA(dst, b, h) do { _Pragma("unroll") for (int m = 0; m < 4; ++m) _Pragma("unroll") for (int k = 0; k < 2; ++k) dst[m][k] = *(const LAS bf16x8*)(lds + PG8_SA(b, h) + aoff + m * 2048 + k * 1024); } while (0)
; #define PG8_LDB(dst, b, h) do { _Pragma("unroll") for (int n = 0; n < 2; ++n) _Pragma("unroll") for (int k = 0; k < 2; ++k) dst[n][k] = *(const LAS bf16x8*)(lds + PG8_SB(b, h) + boff + n * 2048 + k * 1024); } while (0)
; #define PG8_WAIT_L(n) asm volatile("s_waitcnt lgkmcnt(" #n ")" ::: "memory")
; #define PG8_BAR __builtin_amdgcn_s_barrier()
; #define PG8_SCHED __builtin_amdgcn_sched_barrier(0)
; template <class Sched, class Epi>
; __device__ __forceinline__ void gemm_phase(LAS unsigned char* lds, const Sched& S, const Epi& E, const int K, const int lda, const int ldb) {
;     ...
;         for (int t = 0; t < nt; t += 2) {
;             const bool last = (t == nt - 2);
;             const char* a1 = cA + (size_t)(t + 1) * kstep;
;             const char* a2 = last ? nA : cA + (size_t)(t + 2) * kstep; const char* b2 = last ? nB : cB + (size_t)(t + 2) * kstep;
;             const char* a3 = a2 + kstep; const char* b3 = b2 + kstep;
;             PG8_LDB(B0, 0, 0); PG8_SCHED; PG8_LDA(At, 0, 0); PG8_STAGE(PG8_SA(1, 1), a1 + hstepA, voffA);
;             PG8_WAIT_L(8); PG8_BAR; PG8_WAIT_L(0); PG8_MMA(0, 0, At, B0); PG8_BAR; PG8_SCHED;
;             PG8_LDB(B1, 0, 1); PG8_STAGE(PG8_SB(0, 0), b2, voffB);
;             PG8_BAR; PG8_WAIT_L(0); PG8_MMA(0, 1, At, B1); PG8_BAR;
;             PG8_LDA(At, 0, 1); PG8_STAGE(PG8_SA(0, 0), a2, voffA);
;             PG8_BAR; PG8_WAIT_L(0); if (!chalf) PG8_MMA(1, 0, At, B0); PG8_BAR; PG8_SCHED;
;     ...
; #pragma unroll
;         for (int a = 0; a < 2; ++a)
; #pragma unroll
;             for (int b = 0; b < 2; ++b)
; #pragma unroll
;                 for (int m = 0; m < 4; ++m)
; #pragma unroll
;                     for (int n = 0; n < 2; ++n) acc[a][b][m][n] = (f32x4){0.f, 0.f, 0.f, 0.f};
;         cur = nxt; cA = nA; cB = nB; ++ui;
.LBB0_956:
	s_add_u32 s15, s28, 0x100
	s_addc_u32 s17, s29, 0
	s_add_u32 s26, s26, 0x80080
	v_mov_b32_e32 v2, 0
	s_addc_u32 s27, s27, 0
	s_mov_b32 s46, -2
	v_mov_b32_e32 v3, v2
	v_mov_b32_e32 v4, v2
	v_mov_b32_e32 v5, v2
	v_mov_b32_e32 v6, v2
	v_mov_b32_e32 v7, v2
	v_mov_b32_e32 v8, v2
	v_mov_b32_e32 v9, v2
	v_mov_b32_e32 v10, v2
	v_mov_b32_e32 v11, v2
	v_mov_b32_e32 v12, v2
	v_mov_b32_e32 v13, v2
	v_mov_b32_e32 v18, v2
	v_mov_b32_e32 v19, v2
	v_mov_b32_e32 v20, v2
	v_mov_b32_e32 v21, v2
	v_mov_b32_e32 v26, v2
	v_mov_b32_e32 v27, v2
	v_mov_b32_e32 v28, v2
	v_mov_b32_e32 v29, v2
	v_mov_b32_e32 v34, v2
	v_mov_b32_e32 v35, v2
	v_mov_b32_e32 v36, v2
	v_mov_b32_e32 v37, v2
	v_mov_b32_e32 v42, v2
	v_mov_b32_e32 v43, v2
	v_mov_b32_e32 v44, v2
	v_mov_b32_e32 v45, v2
	v_mov_b32_e32 v50, v2
	v_mov_b32_e32 v51, v2
	v_mov_b32_e32 v52, v2
	v_mov_b32_e32 v53, v2
	v_mov_b32_e32 v14, v2
	v_mov_b32_e32 v15, v2
	v_mov_b32_e32 v16, v2
	v_mov_b32_e32 v17, v2
	v_mov_b32_e32 v22, v2
	v_mov_b32_e32 v23, v2
	v_mov_b32_e32 v24, v2
	v_mov_b32_e32 v25, v2
	v_mov_b32_e32 v30, v2
	v_mov_b32_e32 v31, v2
	v_mov_b32_e32 v32, v2
	v_mov_b32_e32 v33, v2
	v_mov_b32_e32 v38, v2
	v_mov_b32_e32 v39, v2
	v_mov_b32_e32 v40, v2
	v_mov_b32_e32 v41, v2
	v_mov_b32_e32 v46, v2
	v_mov_b32_e32 v47, v2
	v_mov_b32_e32 v48, v2
	v_mov_b32_e32 v49, v2
	v_mov_b32_e32 v54, v2
	v_mov_b32_e32 v55, v2
	v_mov_b32_e32 v56, v2
	v_mov_b32_e32 v57, v2
	v_mov_b32_e32 v58, v2
	v_mov_b32_e32 v59, v2
	v_mov_b32_e32 v60, v2
	v_mov_b32_e32 v61, v2
	v_mov_b32_e32 v62, v2
	v_mov_b32_e32 v63, v2
	v_mov_b32_e32 v64, v2
	v_mov_b32_e32 v65, v2
	v_mov_b32_e32 v66, v2
	v_mov_b32_e32 v67, v2
	v_mov_b32_e32 v68, v2
	v_mov_b32_e32 v69, v2
	v_mov_b32_e32 v70, v2
	v_mov_b32_e32 v71, v2
	v_mov_b32_e32 v72, v2
	v_mov_b32_e32 v73, v2
	v_mov_b32_e32 v78, v2
	v_mov_b32_e32 v79, v2
	v_mov_b32_e32 v80, v2
	v_mov_b32_e32 v81, v2
	v_mov_b32_e32 v86, v2
	v_mov_b32_e32 v87, v2
	v_mov_b32_e32 v88, v2
	v_mov_b32_e32 v89, v2
	v_mov_b32_e32 v94, v2
	v_mov_b32_e32 v95, v2
	v_mov_b32_e32 v96, v2
	v_mov_b32_e32 v97, v2
	v_mov_b32_e32 v102, v2
	v_mov_b32_e32 v103, v2
	v_mov_b32_e32 v104, v2
	v_mov_b32_e32 v105, v2
	v_mov_b32_e32 v110, v2
	v_mov_b32_e32 v111, v2
	v_mov_b32_e32 v112, v2
	v_mov_b32_e32 v113, v2
	v_mov_b32_e32 v118, v2
	v_mov_b32_e32 v119, v2
	v_mov_b32_e32 v120, v2
	v_mov_b32_e32 v121, v2
	v_mov_b32_e32 v74, v2
	v_mov_b32_e32 v75, v2
	v_mov_b32_e32 v76, v2
	v_mov_b32_e32 v77, v2
	v_mov_b32_e32 v82, v2
	v_mov_b32_e32 v83, v2
	v_mov_b32_e32 v84, v2
	v_mov_b32_e32 v85, v2
	v_mov_b32_e32 v90, v2
	v_mov_b32_e32 v91, v2
	v_mov_b32_e32 v92, v2
	v_mov_b32_e32 v93, v2
	v_mov_b32_e32 v98, v2
	v_mov_b32_e32 v99, v2
	v_mov_b32_e32 v100, v2
	v_mov_b32_e32 v101, v2
	v_mov_b32_e32 v106, v2
	v_mov_b32_e32 v107, v2
	v_mov_b32_e32 v108, v2
	v_mov_b32_e32 v109, v2
	v_mov_b32_e32 v114, v2
	v_mov_b32_e32 v115, v2
	v_mov_b32_e32 v116, v2
	v_mov_b32_e32 v117, v2
	v_mov_b32_e32 v122, v2
	v_mov_b32_e32 v123, v2
	v_mov_b32_e32 v124, v2
	v_mov_b32_e32 v125, v2
	v_mov_b32_e32 v126, v2
	v_mov_b32_e32 v127, v2
	v_mov_b32_e32 v128, v2
	v_mov_b32_e32 v129, v2
	v_add_u32_e32 v238, 0x18010, v144
	v_add_u32_e32 v239, 0x1c010, v144
	s_branch .Lal_957
	.p2align 11
.Lal_957:
.LBB0_957:
	ds_read_b128 v[156:159], v153
	ds_read_b128 v[160:163], v153 offset:1024
	ds_read_b128 v[164:167], v153 offset:2048
	ds_read_b128 v[168:171], v153 offset:3072
	s_add_u32 s28, s26, 0xfff80080
	s_addc_u32 s29, s27, -1
	s_cmp_eq_u32 s46, 28
	s_cselect_b32 s35, s23, s29
	s_cselect_b32 s34, s22, s28
	s_cselect_b32 s29, s25, s17
	s_cselect_b32 s28, s24, s15
	s_add_i32 m0, s5, 0xc000
	ds_read_b128 v[172:175], v154
	ds_read_b128 v[176:179], v154 offset:1024
	ds_read_b128 v[180:183], v154 offset:2048
	ds_read_b128 v[184:187], v154 offset:3072
	ds_read_b128 v[188:191], v154 offset:4096
	ds_read_b128 v[192:195], v154 offset:5120
	ds_read_b128 v[196:199], v154 offset:6144
	ds_read_b128 v[200:203], v154 offset:7168
	global_load_lds_dwordx4 v140, s[26:27]
	s_add_i32 m0, s5, 0xe000
	s_nop 0
	global_load_lds_dwordx4 v138, s[26:27]
	s_waitcnt lgkmcnt(8)
	s_barrier
	s_waitcnt lgkmcnt(0)
	s_setprio 1
	s_waitcnt lgkmcnt(0)
	v_mfma_f32_16x16x32_bf16 v[126:129], v[156:159], v[172:175], v[126:129]
	v_mfma_f32_16x16x32_bf16 v[122:125], v[164:167], v[172:175], v[122:125]
	v_mfma_f32_16x16x32_bf16 v[114:117], v[156:159], v[180:183], v[114:117]
	v_mfma_f32_16x16x32_bf16 v[106:109], v[164:167], v[180:183], v[106:109]
	v_mfma_f32_16x16x32_bf16 v[98:101], v[156:159], v[188:191], v[98:101]
	v_mfma_f32_16x16x32_bf16 v[90:93], v[164:167], v[188:191], v[90:93]
	v_mfma_f32_16x16x32_bf16 v[82:85], v[156:159], v[196:199], v[82:85]
	v_mfma_f32_16x16x32_bf16 v[74:77], v[164:167], v[196:199], v[74:77]
	v_mfma_f32_16x16x32_bf16 v[126:129], v[160:163], v[176:179], v[126:129]
	v_mfma_f32_16x16x32_bf16 v[122:125], v[168:171], v[176:179], v[122:125]
	v_mfma_f32_16x16x32_bf16 v[114:117], v[160:163], v[184:187], v[114:117]
	v_mfma_f32_16x16x32_bf16 v[106:109], v[168:171], v[184:187], v[106:109]
	v_mfma_f32_16x16x32_bf16 v[98:101], v[160:163], v[192:195], v[98:101]
	v_mfma_f32_16x16x32_bf16 v[90:93], v[168:171], v[192:195], v[90:93]
	v_mfma_f32_16x16x32_bf16 v[82:85], v[160:163], v[200:203], v[82:85]
	v_mfma_f32_16x16x32_bf16 v[74:77], v[168:171], v[200:203], v[74:77]
	s_setprio 0
	s_barrier
	s_add_i32 s47, s43, s33
	s_add_u32 s52, s28, s8
	s_addc_u32 s53, s29, s9
	s_mov_b32 m0, s47
	ds_read_b128 v[204:207], v155
	ds_read_b128 v[208:211], v155 offset:1024
	ds_read_b128 v[212:215], v155 offset:2048
	ds_read_b128 v[216:219], v155 offset:3072
	global_load_lds_dwordx4 v132, s[28:29]
	s_add_u32 s54, s28, s8
	s_addc_u32 s55, s29, s9
	s_add_i32 m0, s47, 0x2000
	s_nop 0
	global_load_lds_dwordx4 v136, s[28:29]
	s_barrier
; #define PG8_STAGE(bufoff, gbase, voff) do { _Pragma("unroll") for (int _i = 0; _i < 2; ++_i) \
;         __builtin_amdgcn_global_load_lds((const unsigned*)((const char*)(gbase) + (voff)[_i]), (LAS unsigned*)(lds + (bufoff) + ldsw + _i * 8192), 16, 0, 0); } while (0)
; #define PG8_LDA(dst, b, h) do { _Pragma("unroll") for (int m = 0; m < 4; ++m) _Pragma("unroll") for (int k = 0; k < 2; ++k) dst[m][k] = *(const LAS bf16x8*)(lds + PG8_SA(b, h) + aoff + m * 2048 + k * 1024); } while (0)
; #define PG8_LDB(dst, b, h) do { _Pragma("unroll") for (int n = 0; n < 2; ++n) _Pragma("unroll") for (int k = 0; k < 2; ++k) dst[n][k] = *(const LAS bf16x8*)(lds + PG8_SB(b, h) + boff + n * 2048 + k * 1024); } while (0)
; #define PG8_MMA(ai, bj, At, Bt) do { __builtin_amdgcn_s_setprio(1); _Pragma("unroll") for (int m = 0; m < 4; ++m) _Pragma("unroll") for (int n = 0; n < 2; ++n) _Pragma("unroll") for (int k = 0; k < 2; ++k) \
;         acc[ai][bj][m][n] = __builtin_amdgcn_mfma_f32_16x16x32_bf16(Bt[n][k], At[m][k], acc[ai][bj][m][n], 0, 0, 0); __builtin_amdgcn_s_setprio(0); } while (0)
; #define PG8_WAIT_V(n) asm volatile("s_waitcnt vmcnt(" #n ")" ::: "memory")
; #define PG8_WAIT_L(n) asm volatile("s_waitcnt lgkmcnt(" #n ")" ::: "memory")
; #define PG8_BAR __builtin_amdgcn_s_barrier()
; #define PG8_SCHED __builtin_amdgcn_sched_barrier(0)
; template <class Sched, class Epi>
; __device__ __forceinline__ void gemm_phase(LAS unsigned char* lds, const Sched& S, const Epi& E, const int K, const int lda, const int ldb) {
;     ...
;             PG8_LDB(B1, 0, 1); PG8_STAGE(PG8_SB(0, 0), b2, voffB);
;             PG8_BAR; PG8_WAIT_L(0); PG8_MMA(0, 1, At, B1); PG8_BAR;
;             PG8_LDA(At, 0, 1); PG8_STAGE(PG8_SA(0, 0), a2, voffA);
;             PG8_BAR; PG8_WAIT_L(0); if (!chalf) PG8_MMA(1, 0, At, B0); PG8_BAR; PG8_SCHED;
;             PG8_STAGE(PG8_SB(0, 1), b2 + hstepB, voffB);
;             PG8_WAIT_V(6); PG8_BAR; if (!chalf) PG8_MMA(1, 1, At, B1); PG8_BAR;
;             PG8_LDB(B0, 1, 0); PG8_SCHED; PG8_LDA(At, 1, 0); PG8_STAGE(PG8_SA(0, 1), a2 + hstepA, voffA);
;             PG8_WAIT_L(8); PG8_BAR; PG8_WAIT_L(0); PG8_MMA(0, 0, At, B0); PG8_BAR; PG8_SCHED;
;             PG8_LDB(B1, 1, 1); PG8_STAGE(PG8_SB(1, 0), b3, voffB);
	s_waitcnt lgkmcnt(0)
	s_setprio 1
	s_waitcnt lgkmcnt(0)
	v_mfma_f32_16x16x32_bf16 v[118:121], v[204:207], v[172:175], v[118:121]
	v_mfma_f32_16x16x32_bf16 v[110:113], v[212:215], v[172:175], v[110:113]
	v_mfma_f32_16x16x32_bf16 v[102:105], v[204:207], v[180:183], v[102:105]
	v_mfma_f32_16x16x32_bf16 v[94:97], v[212:215], v[180:183], v[94:97]
	v_mfma_f32_16x16x32_bf16 v[86:89], v[204:207], v[188:191], v[86:89]
	v_mfma_f32_16x16x32_bf16 v[78:81], v[212:215], v[188:191], v[78:81]
	v_mfma_f32_16x16x32_bf16 v[70:73], v[204:207], v[196:199], v[70:73]
	v_mfma_f32_16x16x32_bf16 v[66:69], v[212:215], v[196:199], v[66:69]
	v_mfma_f32_16x16x32_bf16 v[118:121], v[208:211], v[176:179], v[118:121]
	v_mfma_f32_16x16x32_bf16 v[110:113], v[216:219], v[176:179], v[110:113]
	v_mfma_f32_16x16x32_bf16 v[102:105], v[208:211], v[184:187], v[102:105]
	v_mfma_f32_16x16x32_bf16 v[94:97], v[216:219], v[184:187], v[94:97]
	v_mfma_f32_16x16x32_bf16 v[86:89], v[208:211], v[192:195], v[86:89]
	v_mfma_f32_16x16x32_bf16 v[78:81], v[216:219], v[192:195], v[78:81]
	v_mfma_f32_16x16x32_bf16 v[70:73], v[208:211], v[200:203], v[70:73]
	v_mfma_f32_16x16x32_bf16 v[66:69], v[216:219], v[200:203], v[66:69]
	s_setprio 0
	s_mov_b32 m0, s5
	s_add_u32 s56, s34, s8
	s_addc_u32 s57, s35, s9
	s_barrier
	ds_read_b128 v[172:175], v154 offset:16384
	ds_read_b128 v[176:179], v154 offset:17408
	ds_read_b128 v[180:183], v154 offset:18432
	ds_read_b128 v[184:187], v154 offset:19456
	ds_read_b128 v[188:191], v154 offset:20480
	ds_read_b128 v[192:195], v154 offset:21504
	ds_read_b128 v[196:199], v154 offset:22528
	ds_read_b128 v[200:203], v154 offset:23552
	global_load_lds_dwordx4 v130, s[34:35]
	s_add_u32 s58, s34, s8
	s_addc_u32 s59, s35, s9
	s_mov_b32 m0, s36
	s_nop 0
	global_load_lds_dwordx4 v134, s[34:35]
	s_barrier
	s_waitcnt lgkmcnt(0)
	s_setprio 1
	s_waitcnt lgkmcnt(0)
	v_mfma_f32_16x16x32_bf16 v[62:65], v[156:159], v[172:175], v[62:65]
	v_mfma_f32_16x16x32_bf16 v[58:61], v[164:167], v[172:175], v[58:61]
	v_mfma_f32_16x16x32_bf16 v[54:57], v[156:159], v[180:183], v[54:57]
	v_mfma_f32_16x16x32_bf16 v[46:49], v[164:167], v[180:183], v[46:49]
	v_mfma_f32_16x16x32_bf16 v[38:41], v[156:159], v[188:191], v[38:41]
	v_mfma_f32_16x16x32_bf16 v[30:33], v[164:167], v[188:191], v[30:33]
	v_mfma_f32_16x16x32_bf16 v[22:25], v[156:159], v[196:199], v[22:25]
	v_mfma_f32_16x16x32_bf16 v[14:17], v[164:167], v[196:199], v[14:17]
	v_mfma_f32_16x16x32_bf16 v[62:65], v[160:163], v[176:179], v[62:65]
	v_mfma_f32_16x16x32_bf16 v[58:61], v[168:171], v[176:179], v[58:61]
	v_mfma_f32_16x16x32_bf16 v[54:57], v[160:163], v[184:187], v[54:57]
	v_mfma_f32_16x16x32_bf16 v[46:49], v[168:171], v[184:187], v[46:49]
	v_mfma_f32_16x16x32_bf16 v[38:41], v[160:163], v[192:195], v[38:41]
	v_mfma_f32_16x16x32_bf16 v[30:33], v[168:171], v[192:195], v[30:33]
	v_mfma_f32_16x16x32_bf16 v[22:25], v[160:163], v[200:203], v[22:25]
	v_mfma_f32_16x16x32_bf16 v[14:17], v[168:171], v[200:203], v[14:17]
	s_setprio 0
	s_barrier
	s_add_u32 s48, s28, 0x80000
	s_addc_u32 s49, s29, 0
	s_add_i32 s47, s44, s33
	s_mov_b32 m0, s47
	s_nop 0
	global_load_lds_dwordx4 v132, s[48:49]
	s_add_i32 m0, s47, 0x2000
	s_nop 0
	global_load_lds_dwordx4 v136, s[48:49]
	s_waitcnt vmcnt(6)
	s_barrier
	s_setprio 1
	v_mfma_f32_16x16x32_bf16 v[50:53], v[204:207], v[172:175], v[50:53]
	v_mfma_f32_16x16x32_bf16 v[42:45], v[212:215], v[172:175], v[42:45]
	v_mfma_f32_16x16x32_bf16 v[34:37], v[204:207], v[180:183], v[34:37]
	v_mfma_f32_16x16x32_bf16 v[26:29], v[212:215], v[180:183], v[26:29]
	v_mfma_f32_16x16x32_bf16 v[18:21], v[204:207], v[188:191], v[18:21]
	v_mfma_f32_16x16x32_bf16 v[10:13], v[212:215], v[188:191], v[10:13]
	v_mfma_f32_16x16x32_bf16 v[6:9], v[204:207], v[196:199], v[6:9]
	v_mfma_f32_16x16x32_bf16 v[2:5], v[212:215], v[196:199], v[2:5]
	v_mfma_f32_16x16x32_bf16 v[50:53], v[208:211], v[176:179], v[50:53]
	v_mfma_f32_16x16x32_bf16 v[42:45], v[216:219], v[176:179], v[42:45]
	v_mfma_f32_16x16x32_bf16 v[34:37], v[208:211], v[184:187], v[34:37]
	v_mfma_f32_16x16x32_bf16 v[26:29], v[216:219], v[184:187], v[26:29]
	v_mfma_f32_16x16x32_bf16 v[18:21], v[208:211], v[192:195], v[18:21]
	v_mfma_f32_16x16x32_bf16 v[10:13], v[216:219], v[192:195], v[10:13]
	v_mfma_f32_16x16x32_bf16 v[6:9], v[208:211], v[200:203], v[6:9]
	v_mfma_f32_16x16x32_bf16 v[2:5], v[216:219], v[200:203], v[2:5]
	s_setprio 0
	s_add_i32 s47, 16, 0x18000
	s_barrier
	ds_read_b128 v[156:159], v238
	ds_read_b128 v[160:163], v238 offset:1024
	ds_read_b128 v[164:167], v238 offset:2048
	ds_read_b128 v[168:171], v238 offset:3072
	s_add_u32 s34, s34, 0x80000
	s_addc_u32 s35, s35, 0
	s_mov_b32 m0, s37
	ds_read_b128 v[172:175], v154 offset:32768
	ds_read_b128 v[176:179], v154 offset:33792
	ds_read_b128 v[180:183], v154 offset:34816
	ds_read_b128 v[184:187], v154 offset:35840
	ds_read_b128 v[188:191], v154 offset:36864
	ds_read_b128 v[192:195], v154 offset:37888
	ds_read_b128 v[196:199], v154 offset:38912
	ds_read_b128 v[200:203], v154 offset:39936
	global_load_lds_dwordx4 v130, s[34:35]
	s_mov_b32 m0, s38
	s_nop 0
	global_load_lds_dwordx4 v134, s[34:35]
	s_waitcnt lgkmcnt(8)
	s_barrier
; #define PG8_STAGE(bufoff, gbase, voff) do { _Pragma("unroll") for (int _i = 0; _i < 2; ++_i) \
;         __builtin_amdgcn_global_load_lds((const unsigned*)((const char*)(gbase) + (voff)[_i]), (LAS unsigned*)(lds + (bufoff) + ldsw + _i * 8192), 16, 0, 0); } while (0)
; #define PG8_LDA(dst, b, h) do { _Pragma("unroll") for (int m = 0; m < 4; ++m) _Pragma("unroll") for (int k = 0; k < 2; ++k) dst[m][k] = *(const LAS bf16x8*)(lds + PG8_SA(b, h) + aoff + m * 2048 + k * 1024); } while (0)
; #define PG8_LDB(dst, b, h) do { _Pragma("unroll") for (int n = 0; n < 2; ++n) _Pragma("unroll") for (int k = 0; k < 2; ++k) dst[n][k] = *(const LAS bf16x8*)(lds + PG8_SB(b, h) + boff + n * 2048 + k * 1024); } while (0)
; #define PG8_MMA(ai, bj, At, Bt) do { __builtin_amdgcn_s_setprio(1); _Pragma("unroll") for (int m = 0; m < 4; ++m) _Pragma("unroll") for (int n = 0; n < 2; ++n) _Pragma("unroll") for (int k = 0; k < 2; ++k) \
;         acc[ai][bj][m][n] = __builtin_amdgcn_mfma_f32_16x16x32_bf16(Bt[n][k], At[m][k], acc[ai][bj][m][n], 0, 0, 0); __builtin_amdgcn_s_setprio(0); } while (0)
; #define PG8_WAIT_V(n) asm volatile("s_waitcnt vmcnt(" #n ")" ::: "memory")
; #define PG8_WAIT_L(n) asm volatile("s_waitcnt lgkmcnt(" #n ")" ::: "memory")
; #define PG8_BAR __builtin_amdgcn_s_barrier()
; #define PG8_SCHED __builtin_amdgcn_sched_barrier(0)
; template <class Sched, class Epi>
; __device__ __forceinline__ void gemm_phase(LAS unsigned char* lds, const Sched& S, const Epi& E, const int K, const int lda, const int ldb) {
;     ...
;             PG8_LDB(B1, 1, 1); PG8_STAGE(PG8_SB(1, 0), b3, voffB);
;             PG8_BAR; PG8_WAIT_L(0); PG8_MMA(0, 1, At, B1); PG8_BAR;
;             PG8_LDA(At, 1, 1); PG8_STAGE(PG8_SA(1, 0), a3, voffA);
;             PG8_BAR; PG8_WAIT_L(0); if (!chalf) PG8_MMA(1, 0, At, B0); PG8_BAR; PG8_SCHED;
;             PG8_STAGE(PG8_SB(1, 1), b3 + hstepB, voffB);
;             PG8_WAIT_V(6); PG8_BAR; if (!chalf) PG8_MMA(1, 1, At, B1); PG8_BAR;
;         }
	s_waitcnt lgkmcnt(0)
	s_setprio 1
	s_waitcnt lgkmcnt(0)
	v_mfma_f32_16x16x32_bf16 v[126:129], v[156:159], v[172:175], v[126:129]
	v_mfma_f32_16x16x32_bf16 v[122:125], v[164:167], v[172:175], v[122:125]
	v_mfma_f32_16x16x32_bf16 v[114:117], v[156:159], v[180:183], v[114:117]
	v_mfma_f32_16x16x32_bf16 v[106:109], v[164:167], v[180:183], v[106:109]
	v_mfma_f32_16x16x32_bf16 v[98:101], v[156:159], v[188:191], v[98:101]
	v_mfma_f32_16x16x32_bf16 v[90:93], v[164:167], v[188:191], v[90:93]
	v_mfma_f32_16x16x32_bf16 v[82:85], v[156:159], v[196:199], v[82:85]
	v_mfma_f32_16x16x32_bf16 v[74:77], v[164:167], v[196:199], v[74:77]
	v_mfma_f32_16x16x32_bf16 v[126:129], v[160:163], v[176:179], v[126:129]
	v_mfma_f32_16x16x32_bf16 v[122:125], v[168:171], v[176:179], v[122:125]
	v_mfma_f32_16x16x32_bf16 v[114:117], v[160:163], v[184:187], v[114:117]
	v_mfma_f32_16x16x32_bf16 v[106:109], v[168:171], v[184:187], v[106:109]
	v_mfma_f32_16x16x32_bf16 v[98:101], v[160:163], v[192:195], v[98:101]
	v_mfma_f32_16x16x32_bf16 v[90:93], v[168:171], v[192:195], v[90:93]
	v_mfma_f32_16x16x32_bf16 v[82:85], v[160:163], v[200:203], v[82:85]
	v_mfma_f32_16x16x32_bf16 v[74:77], v[168:171], v[200:203], v[74:77]
	s_setprio 0
	s_barrier
	s_add_i32 s34, 16, 0x1c000
	s_add_i32 s35, s47, s33
	s_mov_b32 m0, s35
	ds_read_b128 v[204:207], v239
	ds_read_b128 v[208:211], v239 offset:1024
	ds_read_b128 v[212:215], v239 offset:2048
	ds_read_b128 v[216:219], v239 offset:3072
	global_load_lds_dwordx4 v132, s[52:53]
	s_add_i32 m0, s35, 0x2000
	s_nop 0
	global_load_lds_dwordx4 v136, s[54:55]
	s_barrier
	s_waitcnt lgkmcnt(0)
	s_setprio 1
	s_waitcnt lgkmcnt(0)
	v_mfma_f32_16x16x32_bf16 v[118:121], v[204:207], v[172:175], v[118:121]
	v_mfma_f32_16x16x32_bf16 v[110:113], v[212:215], v[172:175], v[110:113]
	v_mfma_f32_16x16x32_bf16 v[102:105], v[204:207], v[180:183], v[102:105]
	v_mfma_f32_16x16x32_bf16 v[94:97], v[212:215], v[180:183], v[94:97]
	v_mfma_f32_16x16x32_bf16 v[86:89], v[204:207], v[188:191], v[86:89]
	v_mfma_f32_16x16x32_bf16 v[78:81], v[212:215], v[188:191], v[78:81]
	v_mfma_f32_16x16x32_bf16 v[70:73], v[204:207], v[196:199], v[70:73]
	v_mfma_f32_16x16x32_bf16 v[66:69], v[212:215], v[196:199], v[66:69]
	v_mfma_f32_16x16x32_bf16 v[118:121], v[208:211], v[176:179], v[118:121]
	v_mfma_f32_16x16x32_bf16 v[110:113], v[216:219], v[176:179], v[110:113]
	v_mfma_f32_16x16x32_bf16 v[102:105], v[208:211], v[184:187], v[102:105]
	v_mfma_f32_16x16x32_bf16 v[94:97], v[216:219], v[184:187], v[94:97]
	v_mfma_f32_16x16x32_bf16 v[86:89], v[208:211], v[192:195], v[86:89]
	v_mfma_f32_16x16x32_bf16 v[78:81], v[216:219], v[192:195], v[78:81]
	v_mfma_f32_16x16x32_bf16 v[70:73], v[208:211], v[200:203], v[70:73]
	v_mfma_f32_16x16x32_bf16 v[66:69], v[216:219], v[200:203], v[66:69]
	s_setprio 0
	s_mov_b32 m0, s39
	s_barrier
	ds_read_b128 v[172:175], v154 offset:49152
	ds_read_b128 v[176:179], v154 offset:50176
	ds_read_b128 v[180:183], v154 offset:51200
	ds_read_b128 v[184:187], v154 offset:52224
	ds_read_b128 v[188:191], v154 offset:53248
	ds_read_b128 v[192:195], v154 offset:54272
	ds_read_b128 v[196:199], v154 offset:55296
	ds_read_b128 v[200:203], v154 offset:56320
	global_load_lds_dwordx4 v130, s[56:57]
	s_mov_b32 m0, s40
	s_nop 0
	global_load_lds_dwordx4 v134, s[58:59]
	s_barrier
	s_waitcnt lgkmcnt(0)
	s_setprio 1
	s_waitcnt lgkmcnt(0)
	v_mfma_f32_16x16x32_bf16 v[62:65], v[156:159], v[172:175], v[62:65]
	v_mfma_f32_16x16x32_bf16 v[58:61], v[164:167], v[172:175], v[58:61]
	v_mfma_f32_16x16x32_bf16 v[54:57], v[156:159], v[180:183], v[54:57]
	v_mfma_f32_16x16x32_bf16 v[46:49], v[164:167], v[180:183], v[46:49]
	v_mfma_f32_16x16x32_bf16 v[38:41], v[156:159], v[188:191], v[38:41]
	v_mfma_f32_16x16x32_bf16 v[30:33], v[164:167], v[188:191], v[30:33]
	v_mfma_f32_16x16x32_bf16 v[22:25], v[156:159], v[196:199], v[22:25]
	v_mfma_f32_16x16x32_bf16 v[14:17], v[164:167], v[196:199], v[14:17]
	v_mfma_f32_16x16x32_bf16 v[62:65], v[160:163], v[176:179], v[62:65]
	v_mfma_f32_16x16x32_bf16 v[58:61], v[168:171], v[176:179], v[58:61]
	v_mfma_f32_16x16x32_bf16 v[54:57], v[160:163], v[184:187], v[54:57]
	v_mfma_f32_16x16x32_bf16 v[46:49], v[168:171], v[184:187], v[46:49]
	v_mfma_f32_16x16x32_bf16 v[38:41], v[160:163], v[192:195], v[38:41]
	v_mfma_f32_16x16x32_bf16 v[30:33], v[168:171], v[192:195], v[30:33]
	v_mfma_f32_16x16x32_bf16 v[22:25], v[160:163], v[200:203], v[22:25]
	v_mfma_f32_16x16x32_bf16 v[14:17], v[168:171], v[200:203], v[14:17]
	s_setprio 0
	s_barrier
	s_add_u32 s28, s28, 0x80080
	s_addc_u32 s29, s29, 0
	s_add_i32 s34, s34, s33
	s_mov_b32 m0, s34
	s_nop 0
	global_load_lds_dwordx4 v132, s[28:29]
	s_add_i32 m0, s34, 0x2000
	s_nop 0
	global_load_lds_dwordx4 v136, s[28:29]
	s_waitcnt vmcnt(6)
	s_barrier
	s_setprio 1
	v_mfma_f32_16x16x32_bf16 v[50:53], v[204:207], v[172:175], v[50:53]
	v_mfma_f32_16x16x32_bf16 v[42:45], v[212:215], v[172:175], v[42:45]
	v_mfma_f32_16x16x32_bf16 v[34:37], v[204:207], v[180:183], v[34:37]
	v_mfma_f32_16x16x32_bf16 v[26:29], v[212:215], v[180:183], v[26:29]
	v_mfma_f32_16x16x32_bf16 v[18:21], v[204:207], v[188:191], v[18:21]
	v_mfma_f32_16x16x32_bf16 v[10:13], v[212:215], v[188:191], v[10:13]
	v_mfma_f32_16x16x32_bf16 v[6:9], v[204:207], v[196:199], v[6:9]
	v_mfma_f32_16x16x32_bf16 v[2:5], v[212:215], v[196:199], v[2:5]
	v_mfma_f32_16x16x32_bf16 v[50:53], v[208:211], v[176:179], v[50:53]
	v_mfma_f32_16x16x32_bf16 v[42:45], v[216:219], v[176:179], v[42:45]
	v_mfma_f32_16x16x32_bf16 v[34:37], v[208:211], v[184:187], v[34:37]
	v_mfma_f32_16x16x32_bf16 v[26:29], v[216:219], v[184:187], v[26:29]
	v_mfma_f32_16x16x32_bf16 v[18:21], v[208:211], v[192:195], v[18:21]
	v_mfma_f32_16x16x32_bf16 v[10:13], v[216:219], v[192:195], v[10:13]
	v_mfma_f32_16x16x32_bf16 v[6:9], v[208:211], v[200:203], v[6:9]
	v_mfma_f32_16x16x32_bf16 v[2:5], v[216:219], v[200:203], v[2:5]
	s_setprio 0
	s_add_i32 s46, s46, 2
	s_add_u32 s15, s15, 0x100
	s_addc_u32 s17, s17, 0
	s_add_u32 s26, s26, 0x100
	s_addc_u32 s27, s27, 0
	s_cmp_gt_u32 s46, 29
	s_barrier
; __device__ __forceinline__ unsigned cvt_pk_bf16(float lo, float hi) { unsigned r; asm volatile("v_cvt_pk_bf16_f32 %0, %1, %2" : "=v"(r) : "v"(lo), "v"(hi)); return r; }
; #define EPI_FOR_ROWS _Pragma("unroll") for (int ai = 0; ai < 2; ++ai) if (ai == 0 || !u.half) _Pragma("unroll") for (int m = 0; m < 4; ++m)
;     __device__ __forceinline__ void operator()(EPI_ARGS) const {
;         EPI_FOR_ROWS { bf16_t* rp = O + (size_t)EPI_ROW * ldc;
; #pragma unroll
;             for (int bj = 0; bj < 2; ++bj) { const f32x4 v0 = acc[ai][bj][m][0], v1 = acc[ai][bj][m][1]; u32x4 o;
;                 o[0] = cvt_pk_bf16(v0[0], v0[1]); o[1] = cvt_pk_bf16(v0[2], v0[3]); o[2] = cvt_pk_bf16(v1[0], v1[1]); o[3] = cvt_pk_bf16(v1[2], v1[3]);
;                 *(u32x4*)(rp + EPI_COL(bj)) = o; } }
;     }
	s_cbranch_scc0 .LBB0_957
	v_add_u32_e32 v156, s4, v1
	v_ashrrev_i32_e32 v157, 31, v156
	v_cvt_pk_bf16_f32 v126, v126, v127
	v_cvt_pk_bf16_f32 v127, v128, v129
	v_cvt_pk_bf16_f32 v128, v122, v123
	v_lshl_or_b32 v122, s45, 8, v152
	v_lshlrev_b64 v[156:157], 12, v[156:157]
	v_ashrrev_i32_e32 v123, 31, v122
	v_lshl_add_u64 v[156:157], s[6:7], 0, v[156:157]
	v_lshlrev_b64 v[122:123], 1, v[122:123]
	v_cvt_pk_bf16_f32 v129, v124, v125
	v_lshl_add_u64 v[124:125], v[156:157], 0, v[122:123]
	global_store_dwordx4 v[124:125], v[126:129], off
	v_cvt_pk_bf16_f32 v118, v118, v119
	v_cvt_pk_bf16_f32 v119, v120, v121
	v_cvt_pk_bf16_f32 v120, v110, v111
	v_add_u32_e32 v110, s4, v145
	v_ashrrev_i32_e32 v111, 31, v110
	v_lshlrev_b64 v[110:111], 12, v[110:111]
	v_cvt_pk_bf16_f32 v121, v112, v113
	global_store_dwordx4 v[124:125], v[118:121], off offset:256
	s_and_b64 vcc, exec, s[12:13]
	s_mov_b32 s45, s14
	v_lshl_add_u64 v[118:119], s[6:7], 0, v[110:111]
	v_cvt_pk_bf16_f32 v110, v114, v115
	v_cvt_pk_bf16_f32 v111, v116, v117
	v_cvt_pk_bf16_f32 v112, v106, v107
	v_lshl_add_u64 v[106:107], v[118:119], 0, v[122:123]
	v_cvt_pk_bf16_f32 v113, v108, v109
	global_store_dwordx4 v[106:107], v[110:113], off
	v_cvt_pk_bf16_f32 v102, v102, v103
	v_cvt_pk_bf16_f32 v103, v104, v105
	v_cvt_pk_bf16_f32 v104, v94, v95
	v_add_u32_e32 v94, s4, v146
	v_ashrrev_i32_e32 v95, 31, v94
	v_lshlrev_b64 v[94:95], 12, v[94:95]
	v_cvt_pk_bf16_f32 v105, v96, v97
	global_store_dwordx4 v[106:107], v[102:105], off offset:256
	s_mov_b64 s[28:29], s[20:21]
	s_mov_b64 s[26:27], s[18:19]
	v_lshl_add_u64 v[102:103], s[6:7], 0, v[94:95]
	v_cvt_pk_bf16_f32 v94, v98, v99
	v_cvt_pk_bf16_f32 v95, v100, v101
	v_cvt_pk_bf16_f32 v96, v90, v91
	v_lshl_add_u64 v[90:91], v[102:103], 0, v[122:123]
	v_cvt_pk_bf16_f32 v97, v92, v93
	global_store_dwordx4 v[90:91], v[94:97], off
	v_cvt_pk_bf16_f32 v86, v86, v87
	v_cvt_pk_bf16_f32 v87, v88, v89
	v_cvt_pk_bf16_f32 v88, v78, v79
	v_add_u32_e32 v78, s4, v147
	v_ashrrev_i32_e32 v79, 31, v78
	v_lshlrev_b64 v[78:79], 12, v[78:79]
	v_cvt_pk_bf16_f32 v89, v80, v81
	global_store_dwordx4 v[90:91], v[86:89], off offset:256
	s_nop 1
	v_lshl_add_u64 v[86:87], s[6:7], 0, v[78:79]
	v_cvt_pk_bf16_f32 v78, v82, v83
	v_cvt_pk_bf16_f32 v79, v84, v85
	v_cvt_pk_bf16_f32 v80, v74, v75
	v_lshl_add_u64 v[74:75], v[86:87], 0, v[122:123]
	v_cvt_pk_bf16_f32 v81, v76, v77
	global_store_dwordx4 v[74:75], v[78:81], off
	v_cvt_pk_bf16_f32 v70, v70, v71
	v_cvt_pk_bf16_f32 v71, v72, v73
	v_cvt_pk_bf16_f32 v72, v66, v67
	v_add_u32_e32 v66, s4, v148
	v_ashrrev_i32_e32 v67, 31, v66
	v_lshlrev_b64 v[66:67], 12, v[66:67]
	v_lshl_add_u64 v[66:67], s[6:7], 0, v[66:67]
	v_cvt_pk_bf16_f32 v73, v68, v69
	global_store_dwordx4 v[74:75], v[70:73], off offset:256
	v_cvt_pk_bf16_f32 v62, v62, v63
	v_cvt_pk_bf16_f32 v63, v64, v65
	v_cvt_pk_bf16_f32 v64, v58, v59
	v_lshl_add_u64 v[58:59], v[66:67], 0, v[122:123]
	v_cvt_pk_bf16_f32 v65, v60, v61
	global_store_dwordx4 v[58:59], v[62:65], off
	v_cvt_pk_bf16_f32 v50, v50, v51
	v_cvt_pk_bf16_f32 v51, v52, v53
	v_cvt_pk_bf16_f32 v52, v42, v43
	v_add_u32_e32 v42, s4, v149
	v_ashrrev_i32_e32 v43, 31, v42
	v_lshlrev_b64 v[42:43], 12, v[42:43]
	v_cvt_pk_bf16_f32 v53, v44, v45
	global_store_dwordx4 v[58:59], v[50:53], off offset:256
	s_nop 1
	v_lshl_add_u64 v[50:51], s[6:7], 0, v[42:43]
	v_cvt_pk_bf16_f32 v42, v54, v55
	v_cvt_pk_bf16_f32 v43, v56, v57
	v_cvt_pk_bf16_f32 v44, v46, v47
	v_lshl_add_u64 v[46:47], v[50:51], 0, v[122:123]
	v_cvt_pk_bf16_f32 v45, v48, v49
	global_store_dwordx4 v[46:47], v[42:45], off
	v_cvt_pk_bf16_f32 v34, v34, v35
	v_cvt_pk_bf16_f32 v35, v36, v37
	v_cvt_pk_bf16_f32 v36, v26, v27
	v_add_u32_e32 v26, s4, v150
	v_ashrrev_i32_e32 v27, 31, v26
	v_lshlrev_b64 v[26:27], 12, v[26:27]
	v_cvt_pk_bf16_f32 v37, v28, v29
	global_store_dwordx4 v[46:47], v[34:37], off offset:256
	s_nop 1
	v_lshl_add_u64 v[34:35], s[6:7], 0, v[26:27]
	v_cvt_pk_bf16_f32 v26, v38, v39
	v_cvt_pk_bf16_f32 v27, v40, v41
	v_cvt_pk_bf16_f32 v28, v30, v31
	v_lshl_add_u64 v[30:31], v[34:35], 0, v[122:123]
	v_cvt_pk_bf16_f32 v29, v32, v33
	global_store_dwordx4 v[30:31], v[26:29], off
	v_cvt_pk_bf16_f32 v18, v18, v19
	v_cvt_pk_bf16_f32 v19, v20, v21
	v_cvt_pk_bf16_f32 v20, v10, v11
	v_add_u32_e32 v10, s4, v151
	v_ashrrev_i32_e32 v11, 31, v10
	v_lshlrev_b64 v[10:11], 12, v[10:11]
	v_cvt_pk_bf16_f32 v21, v12, v13
	global_store_dwordx4 v[30:31], v[18:21], off offset:256
	s_mov_b32 s4, s16
	s_nop 0
	v_lshl_add_u64 v[18:19], s[6:7], 0, v[10:11]
	v_cvt_pk_bf16_f32 v10, v22, v23
	v_cvt_pk_bf16_f32 v11, v24, v25
	v_cvt_pk_bf16_f32 v12, v14, v15
	v_lshl_add_u64 v[14:15], v[18:19], 0, v[122:123]
	v_cvt_pk_bf16_f32 v13, v16, v17
	global_store_dwordx4 v[14:15], v[10:13], off
	v_cvt_pk_bf16_f32 v6, v6, v7
	v_cvt_pk_bf16_f32 v7, v8, v9
	v_cvt_pk_bf16_f32 v8, v2, v3
	v_cvt_pk_bf16_f32 v9, v4, v5
	global_store_dwordx4 v[14:15], v[6:9], off offset:256
	s_cbranch_vccz .LBB0_950
	s_waitcnt vmcnt(0)
	s_cmpk_gt_u32 s2, 0xff
	s_cbranch_scc1 .LBB0_961
	s_barrier

; template <class Sched, class Epi>
; __device__ __forceinline__ void gemm_phase(LAS unsigned char* lds, const Sched& S, const Epi& E, const int K, const int lda, const int ldb) {
;     ...
; #pragma unroll
;         for (int a = 0; a < 2; ++a)
; #pragma unroll
;             for (int b = 0; b < 2; ++b)
; #pragma unroll
;                 for (int m = 0; m < 4; ++m)
; #pragma unroll
;                     for (int n = 0; n < 2; ++n) acc[a][b][m][n] = (f32x4){0.f, 0.f, 0.f, 0.f};
;         cur = nxt; cA = nA; cB = nB; ++ui;
.LBB0_1091:
	s_add_u32 s13, s26, 0x100
	s_addc_u32 s15, s27, 0
	s_add_u32 s24, s24, 0x80080
	v_mov_b32_e32 v2, 0
	s_addc_u32 s25, s25, 0
	s_mov_b32 s48, -2
	v_mov_b32_e32 v3, v2
	v_mov_b32_e32 v4, v2
	v_mov_b32_e32 v5, v2
	v_mov_b32_e32 v6, v2
	v_mov_b32_e32 v7, v2
	v_mov_b32_e32 v8, v2
	v_mov_b32_e32 v9, v2
	v_mov_b32_e32 v14, v2
	v_mov_b32_e32 v15, v2
	v_mov_b32_e32 v16, v2
	v_mov_b32_e32 v17, v2
	v_mov_b32_e32 v22, v2
	v_mov_b32_e32 v23, v2
	v_mov_b32_e32 v24, v2
	v_mov_b32_e32 v25, v2
	v_mov_b32_e32 v30, v2
	v_mov_b32_e32 v31, v2
	v_mov_b32_e32 v32, v2
	v_mov_b32_e32 v33, v2
	v_mov_b32_e32 v38, v2
	v_mov_b32_e32 v39, v2
	v_mov_b32_e32 v40, v2
	v_mov_b32_e32 v41, v2
	v_mov_b32_e32 v46, v2
	v_mov_b32_e32 v47, v2
	v_mov_b32_e32 v48, v2
	v_mov_b32_e32 v49, v2
	v_mov_b32_e32 v54, v2
	v_mov_b32_e32 v55, v2
	v_mov_b32_e32 v56, v2
	v_mov_b32_e32 v57, v2
	v_mov_b32_e32 v10, v2
	v_mov_b32_e32 v11, v2
	v_mov_b32_e32 v12, v2
	v_mov_b32_e32 v13, v2
	v_mov_b32_e32 v18, v2
	v_mov_b32_e32 v19, v2
	v_mov_b32_e32 v20, v2
	v_mov_b32_e32 v21, v2
	v_mov_b32_e32 v26, v2
	v_mov_b32_e32 v27, v2
	v_mov_b32_e32 v28, v2
	v_mov_b32_e32 v29, v2
	v_mov_b32_e32 v34, v2
	v_mov_b32_e32 v35, v2
	v_mov_b32_e32 v36, v2
	v_mov_b32_e32 v37, v2
	v_mov_b32_e32 v42, v2
	v_mov_b32_e32 v43, v2
	v_mov_b32_e32 v44, v2
	v_mov_b32_e32 v45, v2
	v_mov_b32_e32 v50, v2
	v_mov_b32_e32 v51, v2
	v_mov_b32_e32 v52, v2
	v_mov_b32_e32 v53, v2
	v_mov_b32_e32 v58, v2
	v_mov_b32_e32 v59, v2
	v_mov_b32_e32 v60, v2
	v_mov_b32_e32 v61, v2
	v_mov_b32_e32 v62, v2
	v_mov_b32_e32 v63, v2
	v_mov_b32_e32 v64, v2
	v_mov_b32_e32 v65, v2
	v_mov_b32_e32 v66, v2
	v_mov_b32_e32 v67, v2
	v_mov_b32_e32 v68, v2
	v_mov_b32_e32 v69, v2
	v_mov_b32_e32 v70, v2
	v_mov_b32_e32 v71, v2
	v_mov_b32_e32 v72, v2
	v_mov_b32_e32 v73, v2
	v_mov_b32_e32 v78, v2
	v_mov_b32_e32 v79, v2
	v_mov_b32_e32 v80, v2
	v_mov_b32_e32 v81, v2
	v_mov_b32_e32 v86, v2
	v_mov_b32_e32 v87, v2
	v_mov_b32_e32 v88, v2
	v_mov_b32_e32 v89, v2
	v_mov_b32_e32 v94, v2
	v_mov_b32_e32 v95, v2
	v_mov_b32_e32 v96, v2
	v_mov_b32_e32 v97, v2
	v_mov_b32_e32 v102, v2
	v_mov_b32_e32 v103, v2
	v_mov_b32_e32 v104, v2
	v_mov_b32_e32 v105, v2
	v_mov_b32_e32 v110, v2
	v_mov_b32_e32 v111, v2
	v_mov_b32_e32 v112, v2
	v_mov_b32_e32 v113, v2
	v_mov_b32_e32 v118, v2
	v_mov_b32_e32 v119, v2
	v_mov_b32_e32 v120, v2
	v_mov_b32_e32 v121, v2
	v_mov_b32_e32 v74, v2
	v_mov_b32_e32 v75, v2
	v_mov_b32_e32 v76, v2
	v_mov_b32_e32 v77, v2
	v_mov_b32_e32 v82, v2
	v_mov_b32_e32 v83, v2
	v_mov_b32_e32 v84, v2
	v_mov_b32_e32 v85, v2
	v_mov_b32_e32 v90, v2
	v_mov_b32_e32 v91, v2
	v_mov_b32_e32 v92, v2
	v_mov_b32_e32 v93, v2
	v_mov_b32_e32 v98, v2
	v_mov_b32_e32 v99, v2
	v_mov_b32_e32 v100, v2
	v_mov_b32_e32 v101, v2
	v_mov_b32_e32 v106, v2
	v_mov_b32_e32 v107, v2
	v_mov_b32_e32 v108, v2
	v_mov_b32_e32 v109, v2
	v_mov_b32_e32 v114, v2
	v_mov_b32_e32 v115, v2
	v_mov_b32_e32 v116, v2
	v_mov_b32_e32 v117, v2
	v_mov_b32_e32 v122, v2
	v_mov_b32_e32 v123, v2
	v_mov_b32_e32 v124, v2
	v_mov_b32_e32 v125, v2
	v_mov_b32_e32 v126, v2
	v_mov_b32_e32 v127, v2
	v_mov_b32_e32 v128, v2
	v_mov_b32_e32 v129, v2
	v_add_u32_e32 v224, 0x18010, v148
	v_add_u32_e32 v225, 0x1c010, v148
	s_branch .Lal_1092

; #define PG8_STAGE(bufoff, gbase, voff) do { _Pragma("unroll") for (int _i = 0; _i < 2; ++_i) \
;         __builtin_amdgcn_global_load_lds((const unsigned*)((const char*)(gbase) + (voff)[_i]), (LAS unsigned*)(lds + (bufoff) + ldsw + _i * 8192), 16, 0, 0); } while (0)
; #define PG8_LDA(dst, b, h) do { _Pragma("unroll") for (int m = 0; m < 4; ++m) _Pragma("unroll") for (int k = 0; k < 2; ++k) dst[m][k] = *(const LAS bf16x8*)(lds + PG8_SA(b, h) + aoff + m * 2048 + k * 1024); } while (0)
; #define PG8_LDB(dst, b, h) do { _Pragma("unroll") for (int n = 0; n < 2; ++n) _Pragma("unroll") for (int k = 0; k < 2; ++k) dst[n][k] = *(const LAS bf16x8*)(lds + PG8_SB(b, h) + boff + n * 2048 + k * 1024); } while (0)
; #define PG8_MMA(ai, bj, At, Bt) do { __builtin_amdgcn_s_setprio(1); _Pragma("unroll") for (int m = 0; m < 4; ++m) _Pragma("unroll") for (int n = 0; n < 2; ++n) _Pragma("unroll") for (int k = 0; k < 2; ++k) \
;         acc[ai][bj][m][n] = __builtin_amdgcn_mfma_f32_16x16x32_bf16(Bt[n][k], At[m][k], acc[ai][bj][m][n], 0, 0, 0); __builtin_amdgcn_s_setprio(0); } while (0)
; #define PG8_WAIT_L(n) asm volatile("s_waitcnt lgkmcnt(" #n ")" ::: "memory")
; #define PG8_BAR __builtin_amdgcn_s_barrier()
; #define PG8_SCHED __builtin_amdgcn_sched_barrier(0)
; template <class Sched, class Epi>
; __device__ __forceinline__ void gemm_phase(LAS unsigned char* lds, const Sched& S, const Epi& E, const int K, const int lda, const int ldb) {
;     ...
;         for (int t = 0; t < nt; t += 2) {
;             const bool last = (t == nt - 2);
;             const char* a1 = cA + (size_t)(t + 1) * kstep;
;             const char* a2 = last ? nA : cA + (size_t)(t + 2) * kstep; const char* b2 = last ? nB : cB + (size_t)(t + 2) * kstep;
;             const char* a3 = a2 + kstep; const char* b3 = b2 + kstep;
;             PG8_LDB(B0, 0, 0); PG8_SCHED; PG8_LDA(At, 0, 0); PG8_STAGE(PG8_SA(1, 1), a1 + hstepA, voffA);
;             PG8_WAIT_L(8); PG8_BAR; PG8_WAIT_L(0); PG8_MMA(0, 0, At, B0); PG8_BAR; PG8_SCHED;
;             PG8_LDB(B1, 0, 1); PG8_STAGE(PG8_SB(0, 0), b2, voffB);
;             PG8_BAR; PG8_WAIT_L(0); PG8_MMA(0, 1, At, B1); PG8_BAR;
;             PG8_LDA(At, 0, 1); PG8_STAGE(PG8_SA(0, 0), a2, voffA);
;             PG8_BAR; PG8_WAIT_L(0); if (!chalf) PG8_MMA(1, 0, At, B0); PG8_BAR; PG8_SCHED;
.Lal_1092:
.LBB0_1092:
	ds_read_b128 v[160:163], v156
	ds_read_b128 v[164:167], v156 offset:1024
	ds_read_b128 v[168:171], v156 offset:2048
	ds_read_b128 v[172:175], v156 offset:3072
	s_add_u32 s26, s24, 0xfff80080
	s_addc_u32 s27, s25, -1
	s_cmp_eq_u32 s48, 28
	s_cselect_b32 s29, s21, s27
	s_cselect_b32 s28, s20, s26
	s_cselect_b32 s27, s23, s15
	s_cselect_b32 s26, s22, s13
	s_add_i32 m0, s5, 0xc000
	ds_read_b128 v[176:179], v157
	ds_read_b128 v[180:183], v157 offset:1024
	ds_read_b128 v[184:187], v157 offset:2048
	ds_read_b128 v[188:191], v157 offset:3072
	ds_read_b128 v[192:195], v157 offset:4096
	ds_read_b128 v[196:199], v157 offset:5120
	ds_read_b128 v[200:203], v157 offset:6144
	ds_read_b128 v[204:207], v157 offset:7168
	global_load_lds_dwordx4 v142, s[24:25]
	s_add_i32 m0, s5, 0xe000
	s_nop 0
	global_load_lds_dwordx4 v140, s[24:25]
	s_waitcnt lgkmcnt(8)
	s_barrier
	s_waitcnt lgkmcnt(0)
	s_setprio 1
	s_waitcnt lgkmcnt(0)
	v_mfma_f32_16x16x32_bf16 v[126:129], v[160:163], v[176:179], v[126:129]
	v_mfma_f32_16x16x32_bf16 v[122:125], v[168:171], v[176:179], v[122:125]
	v_mfma_f32_16x16x32_bf16 v[114:117], v[160:163], v[184:187], v[114:117]
	v_mfma_f32_16x16x32_bf16 v[106:109], v[168:171], v[184:187], v[106:109]
	v_mfma_f32_16x16x32_bf16 v[98:101], v[160:163], v[192:195], v[98:101]
	v_mfma_f32_16x16x32_bf16 v[90:93], v[168:171], v[192:195], v[90:93]
	v_mfma_f32_16x16x32_bf16 v[82:85], v[160:163], v[200:203], v[82:85]
	v_mfma_f32_16x16x32_bf16 v[74:77], v[168:171], v[200:203], v[74:77]
	v_mfma_f32_16x16x32_bf16 v[126:129], v[164:167], v[180:183], v[126:129]
	v_mfma_f32_16x16x32_bf16 v[122:125], v[172:175], v[180:183], v[122:125]
	v_mfma_f32_16x16x32_bf16 v[114:117], v[164:167], v[188:191], v[114:117]
	v_mfma_f32_16x16x32_bf16 v[106:109], v[172:175], v[188:191], v[106:109]
	v_mfma_f32_16x16x32_bf16 v[98:101], v[164:167], v[196:199], v[98:101]
	v_mfma_f32_16x16x32_bf16 v[90:93], v[172:175], v[196:199], v[90:93]
	v_mfma_f32_16x16x32_bf16 v[82:85], v[164:167], v[204:207], v[82:85]
	v_mfma_f32_16x16x32_bf16 v[74:77], v[172:175], v[204:207], v[74:77]
	s_setprio 0
	s_barrier
	s_add_i32 s49, s44, s11
	s_add_u32 s52, s26, s6
	s_addc_u32 s53, s27, s7
	s_mov_b32 m0, s49
	ds_read_b128 v[208:211], v158
	ds_read_b128 v[212:215], v158 offset:1024
	ds_read_b128 v[216:219], v158 offset:2048
	ds_read_b128 v[220:223], v158 offset:3072
	global_load_lds_dwordx4 v134, s[26:27]
	s_add_u32 s54, s26, s6
	s_addc_u32 s55, s27, s7
	s_add_i32 m0, s49, 0x2000
	s_nop 0
	global_load_lds_dwordx4 v130, s[26:27]
	s_barrier
	s_waitcnt lgkmcnt(0)
	s_setprio 1
	s_waitcnt lgkmcnt(0)
	v_mfma_f32_16x16x32_bf16 v[118:121], v[208:211], v[176:179], v[118:121]
	v_mfma_f32_16x16x32_bf16 v[110:113], v[216:219], v[176:179], v[110:113]
	v_mfma_f32_16x16x32_bf16 v[102:105], v[208:211], v[184:187], v[102:105]
	v_mfma_f32_16x16x32_bf16 v[94:97], v[216:219], v[184:187], v[94:97]
	v_mfma_f32_16x16x32_bf16 v[86:89], v[208:211], v[192:195], v[86:89]
	v_mfma_f32_16x16x32_bf16 v[78:81], v[216:219], v[192:195], v[78:81]
	v_mfma_f32_16x16x32_bf16 v[70:73], v[208:211], v[200:203], v[70:73]
	v_mfma_f32_16x16x32_bf16 v[66:69], v[216:219], v[200:203], v[66:69]
	v_mfma_f32_16x16x32_bf16 v[118:121], v[212:215], v[180:183], v[118:121]
	v_mfma_f32_16x16x32_bf16 v[110:113], v[220:223], v[180:183], v[110:113]
	v_mfma_f32_16x16x32_bf16 v[102:105], v[212:215], v[188:191], v[102:105]
	v_mfma_f32_16x16x32_bf16 v[94:97], v[220:223], v[188:191], v[94:97]
	v_mfma_f32_16x16x32_bf16 v[86:89], v[212:215], v[196:199], v[86:89]
	v_mfma_f32_16x16x32_bf16 v[78:81], v[220:223], v[196:199], v[78:81]
	v_mfma_f32_16x16x32_bf16 v[70:73], v[212:215], v[204:207], v[70:73]
	v_mfma_f32_16x16x32_bf16 v[66:69], v[220:223], v[204:207], v[66:69]
	s_setprio 0
	s_mov_b32 m0, s5
	s_add_u32 s56, s28, s6
	s_addc_u32 s57, s29, s7
	s_barrier
	ds_read_b128 v[176:179], v157 offset:16384
	ds_read_b128 v[180:183], v157 offset:17408
	ds_read_b128 v[184:187], v157 offset:18432
	ds_read_b128 v[188:191], v157 offset:19456
	ds_read_b128 v[192:195], v157 offset:20480
	ds_read_b128 v[196:199], v157 offset:21504
	ds_read_b128 v[200:203], v157 offset:22528
	ds_read_b128 v[204:207], v157 offset:23552
	global_load_lds_dwordx4 v136, s[28:29]
	s_add_u32 s58, s28, s6
	s_addc_u32 s59, s29, s7
	s_mov_b32 m0, s35
	s_nop 0
	global_load_lds_dwordx4 v132, s[28:29]
	s_barrier
	s_waitcnt lgkmcnt(0)
	s_setprio 1
	s_waitcnt lgkmcnt(0)
	v_mfma_f32_16x16x32_bf16 v[62:65], v[160:163], v[176:179], v[62:65]
	v_mfma_f32_16x16x32_bf16 v[58:61], v[168:171], v[176:179], v[58:61]
	v_mfma_f32_16x16x32_bf16 v[50:53], v[160:163], v[184:187], v[50:53]
	v_mfma_f32_16x16x32_bf16 v[42:45], v[168:171], v[184:187], v[42:45]
	v_mfma_f32_16x16x32_bf16 v[34:37], v[160:163], v[192:195], v[34:37]
	v_mfma_f32_16x16x32_bf16 v[26:29], v[168:171], v[192:195], v[26:29]
	v_mfma_f32_16x16x32_bf16 v[18:21], v[160:163], v[200:203], v[18:21]
	v_mfma_f32_16x16x32_bf16 v[10:13], v[168:171], v[200:203], v[10:13]
	v_mfma_f32_16x16x32_bf16 v[62:65], v[164:167], v[180:183], v[62:65]
	v_mfma_f32_16x16x32_bf16 v[58:61], v[172:175], v[180:183], v[58:61]
	v_mfma_f32_16x16x32_bf16 v[50:53], v[164:167], v[188:191], v[50:53]
	v_mfma_f32_16x16x32_bf16 v[42:45], v[172:175], v[188:191], v[42:45]
	v_mfma_f32_16x16x32_bf16 v[34:37], v[164:167], v[196:199], v[34:37]
	v_mfma_f32_16x16x32_bf16 v[26:29], v[172:175], v[196:199], v[26:29]
	v_mfma_f32_16x16x32_bf16 v[18:21], v[164:167], v[204:207], v[18:21]
	v_mfma_f32_16x16x32_bf16 v[10:13], v[172:175], v[204:207], v[10:13]
	s_setprio 0
	s_barrier
; #define PG8_STAGE(bufoff, gbase, voff) do { _Pragma("unroll") for (int _i = 0; _i < 2; ++_i) \
;         __builtin_amdgcn_global_load_lds((const unsigned*)((const char*)(gbase) + (voff)[_i]), (LAS unsigned*)(lds + (bufoff) + ldsw + _i * 8192), 16, 0, 0); } while (0)
; #define PG8_LDA(dst, b, h) do { _Pragma("unroll") for (int m = 0; m < 4; ++m) _Pragma("unroll") for (int k = 0; k < 2; ++k) dst[m][k] = *(const LAS bf16x8*)(lds + PG8_SA(b, h) + aoff + m * 2048 + k * 1024); } while (0)
; #define PG8_LDB(dst, b, h) do { _Pragma("unroll") for (int n = 0; n < 2; ++n) _Pragma("unroll") for (int k = 0; k < 2; ++k) dst[n][k] = *(const LAS bf16x8*)(lds + PG8_SB(b, h) + boff + n * 2048 + k * 1024); } while (0)
; #define PG8_MMA(ai, bj, At, Bt) do { __builtin_amdgcn_s_setprio(1); _Pragma("unroll") for (int m = 0; m < 4; ++m) _Pragma("unroll") for (int n = 0; n < 2; ++n) _Pragma("unroll") for (int k = 0; k < 2; ++k) \
;         acc[ai][bj][m][n] = __builtin_amdgcn_mfma_f32_16x16x32_bf16(Bt[n][k], At[m][k], acc[ai][bj][m][n], 0, 0, 0); __builtin_amdgcn_s_setprio(0); } while (0)
; #define PG8_WAIT_V(n) asm volatile("s_waitcnt vmcnt(" #n ")" ::: "memory")
; #define PG8_WAIT_L(n) asm volatile("s_waitcnt lgkmcnt(" #n ")" ::: "memory")
; #define PG8_BAR __builtin_amdgcn_s_barrier()
; #define PG8_SCHED __builtin_amdgcn_sched_barrier(0)
; template <class Sched, class Epi>
; __device__ __forceinline__ void gemm_phase(LAS unsigned char* lds, const Sched& S, const Epi& E, const int K, const int lda, const int ldb) {
;     ...
;             PG8_STAGE(PG8_SB(0, 1), b2 + hstepB, voffB);
;             PG8_WAIT_V(6); PG8_BAR; if (!chalf) PG8_MMA(1, 1, At, B1); PG8_BAR;
;             PG8_LDB(B0, 1, 0); PG8_SCHED; PG8_LDA(At, 1, 0); PG8_STAGE(PG8_SA(0, 1), a2 + hstepA, voffA);
;             PG8_WAIT_L(8); PG8_BAR; PG8_WAIT_L(0); PG8_MMA(0, 0, At, B0); PG8_BAR; PG8_SCHED;
;             PG8_LDB(B1, 1, 1); PG8_STAGE(PG8_SB(1, 0), b3, voffB);
;             PG8_BAR; PG8_WAIT_L(0); PG8_MMA(0, 1, At, B1); PG8_BAR;
;             PG8_LDA(At, 1, 1); PG8_STAGE(PG8_SA(1, 0), a3, voffA);
	s_add_u32 s50, s26, 0x80000
	s_addc_u32 s51, s27, 0
	s_add_i32 s49, s45, s11
	s_mov_b32 m0, s49
	s_nop 0
	global_load_lds_dwordx4 v134, s[50:51]
	s_add_i32 m0, s49, 0x2000
	s_nop 0
	global_load_lds_dwordx4 v130, s[50:51]
	s_waitcnt vmcnt(6)
	s_barrier
	s_setprio 1
	v_mfma_f32_16x16x32_bf16 v[54:57], v[208:211], v[176:179], v[54:57]
	v_mfma_f32_16x16x32_bf16 v[46:49], v[216:219], v[176:179], v[46:49]
	v_mfma_f32_16x16x32_bf16 v[38:41], v[208:211], v[184:187], v[38:41]
	v_mfma_f32_16x16x32_bf16 v[30:33], v[216:219], v[184:187], v[30:33]
	v_mfma_f32_16x16x32_bf16 v[22:25], v[208:211], v[192:195], v[22:25]
	v_mfma_f32_16x16x32_bf16 v[14:17], v[216:219], v[192:195], v[14:17]
	v_mfma_f32_16x16x32_bf16 v[6:9], v[208:211], v[200:203], v[6:9]
	v_mfma_f32_16x16x32_bf16 v[2:5], v[216:219], v[200:203], v[2:5]
	v_mfma_f32_16x16x32_bf16 v[54:57], v[212:215], v[180:183], v[54:57]
	v_mfma_f32_16x16x32_bf16 v[46:49], v[220:223], v[180:183], v[46:49]
	v_mfma_f32_16x16x32_bf16 v[38:41], v[212:215], v[188:191], v[38:41]
	v_mfma_f32_16x16x32_bf16 v[30:33], v[220:223], v[188:191], v[30:33]
	v_mfma_f32_16x16x32_bf16 v[22:25], v[212:215], v[196:199], v[22:25]
	v_mfma_f32_16x16x32_bf16 v[14:17], v[220:223], v[196:199], v[14:17]
	v_mfma_f32_16x16x32_bf16 v[6:9], v[212:215], v[204:207], v[6:9]
	v_mfma_f32_16x16x32_bf16 v[2:5], v[220:223], v[204:207], v[2:5]
	s_setprio 0
	s_add_i32 s49, 16, 0x18000
	s_barrier
	ds_read_b128 v[160:163], v224
	ds_read_b128 v[164:167], v224 offset:1024
	ds_read_b128 v[168:171], v224 offset:2048
	ds_read_b128 v[172:175], v224 offset:3072
	s_add_u32 s28, s28, 0x80000
	s_addc_u32 s29, s29, 0
	s_mov_b32 m0, s36
	ds_read_b128 v[176:179], v157 offset:32768
	ds_read_b128 v[180:183], v157 offset:33792
	ds_read_b128 v[184:187], v157 offset:34816
	ds_read_b128 v[188:191], v157 offset:35840
	ds_read_b128 v[192:195], v157 offset:36864
	ds_read_b128 v[196:199], v157 offset:37888
	ds_read_b128 v[200:203], v157 offset:38912
	ds_read_b128 v[204:207], v157 offset:39936
	global_load_lds_dwordx4 v136, s[28:29]
	s_mov_b32 m0, s37
	s_nop 0
	global_load_lds_dwordx4 v132, s[28:29]
	s_waitcnt lgkmcnt(8)
	s_barrier
	s_waitcnt lgkmcnt(0)
	s_setprio 1
	s_waitcnt lgkmcnt(0)
	v_mfma_f32_16x16x32_bf16 v[126:129], v[160:163], v[176:179], v[126:129]
	v_mfma_f32_16x16x32_bf16 v[122:125], v[168:171], v[176:179], v[122:125]
	v_mfma_f32_16x16x32_bf16 v[114:117], v[160:163], v[184:187], v[114:117]
	v_mfma_f32_16x16x32_bf16 v[106:109], v[168:171], v[184:187], v[106:109]
	v_mfma_f32_16x16x32_bf16 v[98:101], v[160:163], v[192:195], v[98:101]
	v_mfma_f32_16x16x32_bf16 v[90:93], v[168:171], v[192:195], v[90:93]
	v_mfma_f32_16x16x32_bf16 v[82:85], v[160:163], v[200:203], v[82:85]
	v_mfma_f32_16x16x32_bf16 v[74:77], v[168:171], v[200:203], v[74:77]
	v_mfma_f32_16x16x32_bf16 v[126:129], v[164:167], v[180:183], v[126:129]
	v_mfma_f32_16x16x32_bf16 v[122:125], v[172:175], v[180:183], v[122:125]
	v_mfma_f32_16x16x32_bf16 v[114:117], v[164:167], v[188:191], v[114:117]
	v_mfma_f32_16x16x32_bf16 v[106:109], v[172:175], v[188:191], v[106:109]
	v_mfma_f32_16x16x32_bf16 v[98:101], v[164:167], v[196:199], v[98:101]
	v_mfma_f32_16x16x32_bf16 v[90:93], v[172:175], v[196:199], v[90:93]
	v_mfma_f32_16x16x32_bf16 v[82:85], v[164:167], v[204:207], v[82:85]
	v_mfma_f32_16x16x32_bf16 v[74:77], v[172:175], v[204:207], v[74:77]
	s_setprio 0
	s_barrier
	s_add_i32 s28, 16, 0x1c000
	s_add_i32 s29, s49, s11
	s_mov_b32 m0, s29
	ds_read_b128 v[208:211], v225
	ds_read_b128 v[212:215], v225 offset:1024
	ds_read_b128 v[216:219], v225 offset:2048
	ds_read_b128 v[220:223], v225 offset:3072
	global_load_lds_dwordx4 v134, s[52:53]
	s_add_i32 m0, s29, 0x2000
	s_nop 0
	global_load_lds_dwordx4 v130, s[54:55]
	s_barrier
; #define PG8_STAGE(bufoff, gbase, voff) do { _Pragma("unroll") for (int _i = 0; _i < 2; ++_i) \
;         __builtin_amdgcn_global_load_lds((const unsigned*)((const char*)(gbase) + (voff)[_i]), (LAS unsigned*)(lds + (bufoff) + ldsw + _i * 8192), 16, 0, 0); } while (0)
; #define PG8_LDA(dst, b, h) do { _Pragma("unroll") for (int m = 0; m < 4; ++m) _Pragma("unroll") for (int k = 0; k < 2; ++k) dst[m][k] = *(const LAS bf16x8*)(lds + PG8_SA(b, h) + aoff + m * 2048 + k * 1024); } while (0)
; #define PG8_MMA(ai, bj, At, Bt) do { __builtin_amdgcn_s_setprio(1); _Pragma("unroll") for (int m = 0; m < 4; ++m) _Pragma("unroll") for (int n = 0; n < 2; ++n) _Pragma("unroll") for (int k = 0; k < 2; ++k) \
;         acc[ai][bj][m][n] = __builtin_amdgcn_mfma_f32_16x16x32_bf16(Bt[n][k], At[m][k], acc[ai][bj][m][n], 0, 0, 0); __builtin_amdgcn_s_setprio(0); } while (0)
; #define PG8_WAIT_V(n) asm volatile("s_waitcnt vmcnt(" #n ")" ::: "memory")
; #define PG8_WAIT_L(n) asm volatile("s_waitcnt lgkmcnt(" #n ")" ::: "memory")
; #define PG8_BAR __builtin_amdgcn_s_barrier()
; #define PG8_SCHED __builtin_amdgcn_sched_barrier(0)
; template <class Sched, class Epi>
; __device__ __forceinline__ void gemm_phase(LAS unsigned char* lds, const Sched& S, const Epi& E, const int K, const int lda, const int ldb) {
;     ...
;             PG8_LDA(At, 1, 1); PG8_STAGE(PG8_SA(1, 0), a3, voffA);
;             PG8_BAR; PG8_WAIT_L(0); if (!chalf) PG8_MMA(1, 0, At, B0); PG8_BAR; PG8_SCHED;
;             PG8_STAGE(PG8_SB(1, 1), b3 + hstepB, voffB);
;             PG8_WAIT_V(6); PG8_BAR; if (!chalf) PG8_MMA(1, 1, At, B1); PG8_BAR;
;         }
;     __device__ __forceinline__ void operator()(EPI_ARGS) const {
;         const int c0 = u.pn * 256; size_t eb; int pitch, cl;
;         if (c0 < C_U) { eb = E_PC; pitch = 4096; cl = c0; } else if (c0 < C_ZB) { eb = E_PU; pitch = 1024; cl = c0 - C_U; } else if (c0 < C_F) { eb = E_PZB; pitch = 1024; cl = c0 - C_ZB; }
;         else if (c0 < C_ZC) { eb = E_PF; pitch = 1024; cl = c0 - C_F; } else if (c0 < C_GL) { eb = E_PZC; pitch = 1024; cl = c0 - C_ZC; } else { eb = E_PGL; pitch = 6144; cl = c0 - C_GL; }
	s_waitcnt lgkmcnt(0)
	s_setprio 1
	s_waitcnt lgkmcnt(0)
	v_mfma_f32_16x16x32_bf16 v[118:121], v[208:211], v[176:179], v[118:121]
	v_mfma_f32_16x16x32_bf16 v[110:113], v[216:219], v[176:179], v[110:113]
	v_mfma_f32_16x16x32_bf16 v[102:105], v[208:211], v[184:187], v[102:105]
	v_mfma_f32_16x16x32_bf16 v[94:97], v[216:219], v[184:187], v[94:97]
	v_mfma_f32_16x16x32_bf16 v[86:89], v[208:211], v[192:195], v[86:89]
	v_mfma_f32_16x16x32_bf16 v[78:81], v[216:219], v[192:195], v[78:81]
	v_mfma_f32_16x16x32_bf16 v[70:73], v[208:211], v[200:203], v[70:73]
	v_mfma_f32_16x16x32_bf16 v[66:69], v[216:219], v[200:203], v[66:69]
	v_mfma_f32_16x16x32_bf16 v[118:121], v[212:215], v[180:183], v[118:121]
	v_mfma_f32_16x16x32_bf16 v[110:113], v[220:223], v[180:183], v[110:113]
	v_mfma_f32_16x16x32_bf16 v[102:105], v[212:215], v[188:191], v[102:105]
	v_mfma_f32_16x16x32_bf16 v[94:97], v[220:223], v[188:191], v[94:97]
	v_mfma_f32_16x16x32_bf16 v[86:89], v[212:215], v[196:199], v[86:89]
	v_mfma_f32_16x16x32_bf16 v[78:81], v[220:223], v[196:199], v[78:81]
	v_mfma_f32_16x16x32_bf16 v[70:73], v[212:215], v[204:207], v[70:73]
	v_mfma_f32_16x16x32_bf16 v[66:69], v[220:223], v[204:207], v[66:69]
	s_setprio 0
	s_mov_b32 m0, s41
	s_barrier
	ds_read_b128 v[176:179], v157 offset:49152
	ds_read_b128 v[180:183], v157 offset:50176
	ds_read_b128 v[184:187], v157 offset:51200
	ds_read_b128 v[188:191], v157 offset:52224
	ds_read_b128 v[192:195], v157 offset:53248
	ds_read_b128 v[196:199], v157 offset:54272
	ds_read_b128 v[200:203], v157 offset:55296
	ds_read_b128 v[204:207], v157 offset:56320
	global_load_lds_dwordx4 v136, s[56:57]
	s_mov_b32 m0, s42
	s_nop 0
	global_load_lds_dwordx4 v132, s[58:59]
	s_barrier
	s_waitcnt lgkmcnt(0)
	s_setprio 1
	s_waitcnt lgkmcnt(0)
	v_mfma_f32_16x16x32_bf16 v[62:65], v[160:163], v[176:179], v[62:65]
	v_mfma_f32_16x16x32_bf16 v[58:61], v[168:171], v[176:179], v[58:61]
	v_mfma_f32_16x16x32_bf16 v[50:53], v[160:163], v[184:187], v[50:53]
	v_mfma_f32_16x16x32_bf16 v[42:45], v[168:171], v[184:187], v[42:45]
	v_mfma_f32_16x16x32_bf16 v[34:37], v[160:163], v[192:195], v[34:37]
	v_mfma_f32_16x16x32_bf16 v[26:29], v[168:171], v[192:195], v[26:29]
	v_mfma_f32_16x16x32_bf16 v[18:21], v[160:163], v[200:203], v[18:21]
	v_mfma_f32_16x16x32_bf16 v[10:13], v[168:171], v[200:203], v[10:13]
	v_mfma_f32_16x16x32_bf16 v[62:65], v[164:167], v[180:183], v[62:65]
	v_mfma_f32_16x16x32_bf16 v[58:61], v[172:175], v[180:183], v[58:61]
	v_mfma_f32_16x16x32_bf16 v[50:53], v[164:167], v[188:191], v[50:53]
	v_mfma_f32_16x16x32_bf16 v[42:45], v[172:175], v[188:191], v[42:45]
	v_mfma_f32_16x16x32_bf16 v[34:37], v[164:167], v[196:199], v[34:37]
	v_mfma_f32_16x16x32_bf16 v[26:29], v[172:175], v[196:199], v[26:29]
	v_mfma_f32_16x16x32_bf16 v[18:21], v[164:167], v[204:207], v[18:21]
	v_mfma_f32_16x16x32_bf16 v[10:13], v[172:175], v[204:207], v[10:13]
	s_setprio 0
	s_barrier
	s_add_u32 s26, s26, 0x80080
	s_addc_u32 s27, s27, 0
	s_add_i32 s28, s28, s11
	s_mov_b32 m0, s28
	s_nop 0
	global_load_lds_dwordx4 v134, s[26:27]
	s_add_i32 m0, s28, 0x2000
	s_nop 0
	global_load_lds_dwordx4 v130, s[26:27]
	s_waitcnt vmcnt(6)
	s_barrier
	s_setprio 1
	v_mfma_f32_16x16x32_bf16 v[54:57], v[208:211], v[176:179], v[54:57]
	v_mfma_f32_16x16x32_bf16 v[46:49], v[216:219], v[176:179], v[46:49]
	v_mfma_f32_16x16x32_bf16 v[38:41], v[208:211], v[184:187], v[38:41]
	v_mfma_f32_16x16x32_bf16 v[30:33], v[216:219], v[184:187], v[30:33]
	v_mfma_f32_16x16x32_bf16 v[22:25], v[208:211], v[192:195], v[22:25]
	v_mfma_f32_16x16x32_bf16 v[14:17], v[216:219], v[192:195], v[14:17]
	v_mfma_f32_16x16x32_bf16 v[6:9], v[208:211], v[200:203], v[6:9]
	v_mfma_f32_16x16x32_bf16 v[2:5], v[216:219], v[200:203], v[2:5]
	v_mfma_f32_16x16x32_bf16 v[54:57], v[212:215], v[180:183], v[54:57]
	v_mfma_f32_16x16x32_bf16 v[46:49], v[220:223], v[180:183], v[46:49]
	v_mfma_f32_16x16x32_bf16 v[38:41], v[212:215], v[188:191], v[38:41]
	v_mfma_f32_16x16x32_bf16 v[30:33], v[220:223], v[188:191], v[30:33]
	v_mfma_f32_16x16x32_bf16 v[22:25], v[212:215], v[196:199], v[22:25]
	v_mfma_f32_16x16x32_bf16 v[14:17], v[220:223], v[196:199], v[14:17]
	v_mfma_f32_16x16x32_bf16 v[6:9], v[212:215], v[204:207], v[6:9]
	v_mfma_f32_16x16x32_bf16 v[2:5], v[220:223], v[204:207], v[2:5]
	s_setprio 0
	s_add_i32 s48, s48, 2
	s_add_u32 s13, s13, 0x100
	s_addc_u32 s15, s15, 0
	s_add_u32 s24, s24, 0x100
	s_addc_u32 s25, s25, 0
	s_cmp_gt_u32 s48, 29
	s_barrier
	s_cbranch_scc0 .LBB0_1092
	s_lshl_b32 s22, s47, 8
	s_cmp_lt_i32 s47, 16
	s_cbranch_scc1 .LBB0_1109
	s_cmp_gt_u32 s47, 19
	s_mov_b64 s[26:27], -1
	s_cbranch_scc0 .LBB0_1107
	s_cmp_gt_u32 s47, 23
	s_cbranch_scc0 .LBB0_1104
	s_cmp_gt_u32 s47, 27
	s_cbranch_scc0 .LBB0_1101
	s_cmp_gt_u32 s47, 31
	s_mov_b64 s[20:21], -1
	s_cbranch_scc0 .LBB0_1099
	s_add_i32 s13, s22, 0xffffe000
	s_mov_b64 s[20:21], 0

; #define PG8_STAGE(bufoff, gbase, voff) do { _Pragma("unroll") for (int _i = 0; _i < 2; ++_i) \
;         __builtin_amdgcn_global_load_lds((const unsigned*)((const char*)(gbase) + (voff)[_i]), (LAS unsigned*)(lds + (bufoff) + ldsw + _i * 8192), 16, 0, 0); } while (0)
; #define PG8_LDA(dst, b, h) do { _Pragma("unroll") for (int m = 0; m < 4; ++m) _Pragma("unroll") for (int k = 0; k < 2; ++k) dst[m][k] = *(const LAS bf16x8*)(lds + PG8_SA(b, h) + aoff + m * 2048 + k * 1024); } while (0)
; #define PG8_LDB(dst, b, h) do { _Pragma("unroll") for (int n = 0; n < 2; ++n) _Pragma("unroll") for (int k = 0; k < 2; ++k) dst[n][k] = *(const LAS bf16x8*)(lds + PG8_SB(b, h) + boff + n * 2048 + k * 1024); } while (0)
; #define PG8_WAIT_L(n) asm volatile("s_waitcnt lgkmcnt(" #n ")" ::: "memory")
; #define PG8_BAR __builtin_amdgcn_s_barrier()
; #define PG8_SCHED __builtin_amdgcn_sched_barrier(0)
; template <class Sched, class Epi>
; __device__ __forceinline__ void gemm_phase(LAS unsigned char* lds, const Sched& S, const Epi& E, const int K, const int lda, const int ldb) {
;     ...
;         for (int t = 0; t < nt; t += 2) {
;             const bool last = (t == nt - 2);
;             const char* a1 = cA + (size_t)(t + 1) * kstep;
;             const char* a2 = last ? nA : cA + (size_t)(t + 2) * kstep; const char* b2 = last ? nB : cB + (size_t)(t + 2) * kstep;
;             const char* a3 = a2 + kstep; const char* b3 = b2 + kstep;
;             PG8_LDB(B0, 0, 0); PG8_SCHED; PG8_LDA(At, 0, 0); PG8_STAGE(PG8_SA(1, 1), a1 + hstepA, voffA);
;             PG8_WAIT_L(8); PG8_BAR; PG8_WAIT_L(0); PG8_MMA(0, 0, At, B0); PG8_BAR; PG8_SCHED;
;             PG8_LDB(B1, 0, 1); PG8_STAGE(PG8_SB(0, 0), b2, voffB);
;             PG8_BAR; PG8_WAIT_L(0); PG8_MMA(0, 1, At, B1); PG8_BAR;
;             PG8_LDA(At, 0, 1); PG8_STAGE(PG8_SA(0, 0), a2, voffA);
;             PG8_BAR; PG8_WAIT_L(0); if (!chalf) PG8_MMA(1, 0, At, B0); PG8_BAR; PG8_SCHED;
;     ...
; #pragma unroll
;         for (int a = 0; a < 2; ++a)
; #pragma unroll
;             for (int b = 0; b < 2; ++b)
; #pragma unroll
;                 for (int m = 0; m < 4; ++m)
; #pragma unroll
;                     for (int n = 0; n < 2; ++n) acc[a][b][m][n] = (f32x4){0.f, 0.f, 0.f, 0.f};
;         cur = nxt; cA = nA; cB = nB; ++ui;
.LBB0_1414:
	s_add_u32 s15, s34, 0x100
	s_addc_u32 s17, s35, 0
	s_add_u32 s28, s28, 0x40080
	v_mov_b32_e32 v2, 0
	s_addc_u32 s29, s29, 0
	s_mov_b32 s49, -2
	v_mov_b32_e32 v3, v2
	v_mov_b32_e32 v4, v2
	v_mov_b32_e32 v5, v2
	v_mov_b32_e32 v6, v2
	v_mov_b32_e32 v7, v2
	v_mov_b32_e32 v8, v2
	v_mov_b32_e32 v9, v2
	v_mov_b32_e32 v18, v2
	v_mov_b32_e32 v19, v2
	v_mov_b32_e32 v20, v2
	v_mov_b32_e32 v21, v2
	v_mov_b32_e32 v22, v2
	v_mov_b32_e32 v23, v2
	v_mov_b32_e32 v24, v2
	v_mov_b32_e32 v25, v2
	v_mov_b32_e32 v34, v2
	v_mov_b32_e32 v35, v2
	v_mov_b32_e32 v36, v2
	v_mov_b32_e32 v37, v2
	v_mov_b32_e32 v38, v2
	v_mov_b32_e32 v39, v2
	v_mov_b32_e32 v40, v2
	v_mov_b32_e32 v41, v2
	v_mov_b32_e32 v50, v2
	v_mov_b32_e32 v51, v2
	v_mov_b32_e32 v52, v2
	v_mov_b32_e32 v53, v2
	v_mov_b32_e32 v54, v2
	v_mov_b32_e32 v55, v2
	v_mov_b32_e32 v56, v2
	v_mov_b32_e32 v57, v2
	v_mov_b32_e32 v10, v2
	v_mov_b32_e32 v11, v2
	v_mov_b32_e32 v12, v2
	v_mov_b32_e32 v13, v2
	v_mov_b32_e32 v14, v2
	v_mov_b32_e32 v15, v2
	v_mov_b32_e32 v16, v2
	v_mov_b32_e32 v17, v2
	v_mov_b32_e32 v26, v2
	v_mov_b32_e32 v27, v2
	v_mov_b32_e32 v28, v2
	v_mov_b32_e32 v29, v2
	v_mov_b32_e32 v30, v2
	v_mov_b32_e32 v31, v2
	v_mov_b32_e32 v32, v2
	v_mov_b32_e32 v33, v2
	v_mov_b32_e32 v42, v2
	v_mov_b32_e32 v43, v2
	v_mov_b32_e32 v44, v2
	v_mov_b32_e32 v45, v2
	v_mov_b32_e32 v46, v2
	v_mov_b32_e32 v47, v2
	v_mov_b32_e32 v48, v2
	v_mov_b32_e32 v49, v2
	v_mov_b32_e32 v58, v2
	v_mov_b32_e32 v59, v2
	v_mov_b32_e32 v60, v2
	v_mov_b32_e32 v61, v2
	v_mov_b32_e32 v62, v2
	v_mov_b32_e32 v63, v2
	v_mov_b32_e32 v64, v2
	v_mov_b32_e32 v65, v2
	v_mov_b32_e32 v66, v2
	v_mov_b32_e32 v67, v2
	v_mov_b32_e32 v68, v2
	v_mov_b32_e32 v69, v2
	v_mov_b32_e32 v70, v2
	v_mov_b32_e32 v71, v2
	v_mov_b32_e32 v72, v2
	v_mov_b32_e32 v73, v2
	v_mov_b32_e32 v82, v2
	v_mov_b32_e32 v83, v2
	v_mov_b32_e32 v84, v2
	v_mov_b32_e32 v85, v2
	v_mov_b32_e32 v86, v2
	v_mov_b32_e32 v87, v2
	v_mov_b32_e32 v88, v2
	v_mov_b32_e32 v89, v2
	v_mov_b32_e32 v98, v2
	v_mov_b32_e32 v99, v2
	v_mov_b32_e32 v100, v2
	v_mov_b32_e32 v101, v2
	v_mov_b32_e32 v102, v2
	v_mov_b32_e32 v103, v2
	v_mov_b32_e32 v104, v2
	v_mov_b32_e32 v105, v2
	v_mov_b32_e32 v122, v2
	v_mov_b32_e32 v123, v2
	v_mov_b32_e32 v124, v2
	v_mov_b32_e32 v125, v2
	v_mov_b32_e32 v126, v2
	v_mov_b32_e32 v127, v2
	v_mov_b32_e32 v128, v2
	v_mov_b32_e32 v129, v2
	v_mov_b32_e32 v74, v2
	v_mov_b32_e32 v75, v2
	v_mov_b32_e32 v76, v2
	v_mov_b32_e32 v77, v2
	v_mov_b32_e32 v78, v2
	v_mov_b32_e32 v79, v2
	v_mov_b32_e32 v80, v2
	v_mov_b32_e32 v81, v2
	v_mov_b32_e32 v90, v2
	v_mov_b32_e32 v91, v2
	v_mov_b32_e32 v92, v2
	v_mov_b32_e32 v93, v2
	v_mov_b32_e32 v94, v2
	v_mov_b32_e32 v95, v2
	v_mov_b32_e32 v96, v2
	v_mov_b32_e32 v97, v2
	v_mov_b32_e32 v106, v2
	v_mov_b32_e32 v107, v2
	v_mov_b32_e32 v108, v2
	v_mov_b32_e32 v109, v2
	v_mov_b32_e32 v110, v2
	v_mov_b32_e32 v111, v2
	v_mov_b32_e32 v112, v2
	v_mov_b32_e32 v113, v2
	v_mov_b32_e32 v114, v2
	v_mov_b32_e32 v115, v2
	v_mov_b32_e32 v116, v2
	v_mov_b32_e32 v117, v2
	v_mov_b32_e32 v118, v2
	v_mov_b32_e32 v119, v2
	v_mov_b32_e32 v120, v2
	v_mov_b32_e32 v121, v2
	v_add_u32_e32 v218, 0x18010, v150
	v_add_u32_e32 v219, 0x1c010, v150
	s_branch .Lal_1415
	.p2align 11
.Lal_1415:
.LBB0_1415:
	ds_read_b128 v[144:147], v155
	ds_read_b128 v[158:161], v155 offset:1024
	ds_read_b128 v[162:165], v155 offset:2048
	ds_read_b128 v[166:169], v155 offset:3072
	s_add_u32 s34, s28, 0xfffc0080
	s_addc_u32 s35, s29, -1
	s_cmp_eq_u32 s49, 12
	s_cselect_b32 s37, s25, s35
	s_cselect_b32 s36, s24, s34
	s_cselect_b32 s35, s27, s17
	s_cselect_b32 s34, s26, s15
	s_add_i32 m0, s23, 0xc000
	ds_read_b128 v[170:173], v156
	ds_read_b128 v[174:177], v156 offset:1024
	ds_read_b128 v[178:181], v156 offset:2048
	ds_read_b128 v[182:185], v156 offset:3072
	ds_read_b128 v[186:189], v156 offset:4096
	ds_read_b128 v[190:193], v156 offset:5120
	ds_read_b128 v[194:197], v156 offset:6144
	ds_read_b128 v[198:201], v156 offset:7168
	global_load_lds_dwordx4 v140, s[28:29]
	s_add_i32 m0, s23, 0xe000
	s_nop 0
	global_load_lds_dwordx4 v138, s[28:29]
	s_waitcnt lgkmcnt(8)
	s_barrier
	s_waitcnt lgkmcnt(0)
	s_setprio 1
	s_waitcnt lgkmcnt(0)
	v_mfma_f32_16x16x32_bf16 v[118:121], v[144:147], v[170:173], v[118:121]
	v_mfma_f32_16x16x32_bf16 v[114:117], v[162:165], v[170:173], v[114:117]
	v_mfma_f32_16x16x32_bf16 v[110:113], v[144:147], v[178:181], v[110:113]
	v_mfma_f32_16x16x32_bf16 v[106:109], v[162:165], v[178:181], v[106:109]
	v_mfma_f32_16x16x32_bf16 v[94:97], v[144:147], v[186:189], v[94:97]
	v_mfma_f32_16x16x32_bf16 v[90:93], v[162:165], v[186:189], v[90:93]
	v_mfma_f32_16x16x32_bf16 v[78:81], v[144:147], v[194:197], v[78:81]
	v_mfma_f32_16x16x32_bf16 v[74:77], v[162:165], v[194:197], v[74:77]
	v_mfma_f32_16x16x32_bf16 v[118:121], v[158:161], v[174:177], v[118:121]
	v_mfma_f32_16x16x32_bf16 v[114:117], v[166:169], v[174:177], v[114:117]
	v_mfma_f32_16x16x32_bf16 v[110:113], v[158:161], v[182:185], v[110:113]
	v_mfma_f32_16x16x32_bf16 v[106:109], v[166:169], v[182:185], v[106:109]
	v_mfma_f32_16x16x32_bf16 v[94:97], v[158:161], v[190:193], v[94:97]
	v_mfma_f32_16x16x32_bf16 v[90:93], v[166:169], v[190:193], v[90:93]
	v_mfma_f32_16x16x32_bf16 v[78:81], v[158:161], v[198:201], v[78:81]
	v_mfma_f32_16x16x32_bf16 v[74:77], v[166:169], v[198:201], v[74:77]
	s_setprio 0
	s_barrier
	s_add_i32 s50, s46, s38
	s_add_u32 s62, s34, s8
	s_addc_u32 s63, s35, s9
	s_mov_b32 m0, s50
	ds_read_b128 v[202:205], v157
	ds_read_b128 v[206:209], v157 offset:1024
	ds_read_b128 v[210:213], v157 offset:2048
	ds_read_b128 v[214:217], v157 offset:3072
	global_load_lds_dwordx4 v132, s[34:35]
	s_add_u32 s64, s34, s8
	s_addc_u32 s65, s35, s9
	s_add_i32 m0, s50, 0x2000
	s_nop 0
	global_load_lds_dwordx4 v136, s[34:35]
	s_barrier
; #define PG8_STAGE(bufoff, gbase, voff) do { _Pragma("unroll") for (int _i = 0; _i < 2; ++_i) \
;         __builtin_amdgcn_global_load_lds((const unsigned*)((const char*)(gbase) + (voff)[_i]), (LAS unsigned*)(lds + (bufoff) + ldsw + _i * 8192), 16, 0, 0); } while (0)
; #define PG8_LDA(dst, b, h) do { _Pragma("unroll") for (int m = 0; m < 4; ++m) _Pragma("unroll") for (int k = 0; k < 2; ++k) dst[m][k] = *(const LAS bf16x8*)(lds + PG8_SA(b, h) + aoff + m * 2048 + k * 1024); } while (0)
; #define PG8_LDB(dst, b, h) do { _Pragma("unroll") for (int n = 0; n < 2; ++n) _Pragma("unroll") for (int k = 0; k < 2; ++k) dst[n][k] = *(const LAS bf16x8*)(lds + PG8_SB(b, h) + boff + n * 2048 + k * 1024); } while (0)
; #define PG8_MMA(ai, bj, At, Bt) do { __builtin_amdgcn_s_setprio(1); _Pragma("unroll") for (int m = 0; m < 4; ++m) _Pragma("unroll") for (int n = 0; n < 2; ++n) _Pragma("unroll") for (int k = 0; k < 2; ++k) \
;         acc[ai][bj][m][n] = __builtin_amdgcn_mfma_f32_16x16x32_bf16(Bt[n][k], At[m][k], acc[ai][bj][m][n], 0, 0, 0); __builtin_amdgcn_s_setprio(0); } while (0)
; #define PG8_WAIT_V(n) asm volatile("s_waitcnt vmcnt(" #n ")" ::: "memory")
; #define PG8_WAIT_L(n) asm volatile("s_waitcnt lgkmcnt(" #n ")" ::: "memory")
; #define PG8_BAR __builtin_amdgcn_s_barrier()
; #define PG8_SCHED __builtin_amdgcn_sched_barrier(0)
; template <class Sched, class Epi>
; __device__ __forceinline__ void gemm_phase(LAS unsigned char* lds, const Sched& S, const Epi& E, const int K, const int lda, const int ldb) {
;     ...
;             PG8_LDB(B1, 0, 1); PG8_STAGE(PG8_SB(0, 0), b2, voffB);
;             PG8_BAR; PG8_WAIT_L(0); PG8_MMA(0, 1, At, B1); PG8_BAR;
;             PG8_LDA(At, 0, 1); PG8_STAGE(PG8_SA(0, 0), a2, voffA);
;             PG8_BAR; PG8_WAIT_L(0); if (!chalf) PG8_MMA(1, 0, At, B0); PG8_BAR; PG8_SCHED;
;             PG8_STAGE(PG8_SB(0, 1), b2 + hstepB, voffB);
;             PG8_WAIT_V(6); PG8_BAR; if (!chalf) PG8_MMA(1, 1, At, B1); PG8_BAR;
;             PG8_LDB(B0, 1, 0); PG8_SCHED; PG8_LDA(At, 1, 0); PG8_STAGE(PG8_SA(0, 1), a2 + hstepA, voffA);
;             PG8_WAIT_L(8); PG8_BAR; PG8_WAIT_L(0); PG8_MMA(0, 0, At, B0); PG8_BAR; PG8_SCHED;
;             PG8_LDB(B1, 1, 1); PG8_STAGE(PG8_SB(1, 0), b3, voffB);
	s_waitcnt lgkmcnt(0)
	s_setprio 1
	s_waitcnt lgkmcnt(0)
	v_mfma_f32_16x16x32_bf16 v[126:129], v[202:205], v[170:173], v[126:129]
	v_mfma_f32_16x16x32_bf16 v[122:125], v[210:213], v[170:173], v[122:125]
	v_mfma_f32_16x16x32_bf16 v[102:105], v[202:205], v[178:181], v[102:105]
	v_mfma_f32_16x16x32_bf16 v[98:101], v[210:213], v[178:181], v[98:101]
	v_mfma_f32_16x16x32_bf16 v[86:89], v[202:205], v[186:189], v[86:89]
	v_mfma_f32_16x16x32_bf16 v[82:85], v[210:213], v[186:189], v[82:85]
	v_mfma_f32_16x16x32_bf16 v[70:73], v[202:205], v[194:197], v[70:73]
	v_mfma_f32_16x16x32_bf16 v[66:69], v[210:213], v[194:197], v[66:69]
	v_mfma_f32_16x16x32_bf16 v[126:129], v[206:209], v[174:177], v[126:129]
	v_mfma_f32_16x16x32_bf16 v[122:125], v[214:217], v[174:177], v[122:125]
	v_mfma_f32_16x16x32_bf16 v[102:105], v[206:209], v[182:185], v[102:105]
	v_mfma_f32_16x16x32_bf16 v[98:101], v[214:217], v[182:185], v[98:101]
	v_mfma_f32_16x16x32_bf16 v[86:89], v[206:209], v[190:193], v[86:89]
	v_mfma_f32_16x16x32_bf16 v[82:85], v[214:217], v[190:193], v[82:85]
	v_mfma_f32_16x16x32_bf16 v[70:73], v[206:209], v[198:201], v[70:73]
	v_mfma_f32_16x16x32_bf16 v[66:69], v[214:217], v[198:201], v[66:69]
	s_setprio 0
	s_mov_b32 m0, s23
	s_add_u32 s66, s36, s8
	s_addc_u32 s67, s37, s9
	s_barrier
	ds_read_b128 v[170:173], v156 offset:16384
	ds_read_b128 v[174:177], v156 offset:17408
	ds_read_b128 v[178:181], v156 offset:18432
	ds_read_b128 v[182:185], v156 offset:19456
	ds_read_b128 v[186:189], v156 offset:20480
	ds_read_b128 v[190:193], v156 offset:21504
	ds_read_b128 v[194:197], v156 offset:22528
	ds_read_b128 v[198:201], v156 offset:23552
	global_load_lds_dwordx4 v130, s[36:37]
	s_add_u32 s68, s36, s8
	s_addc_u32 s69, s37, s9
	s_mov_b32 m0, s39
	s_nop 0
	global_load_lds_dwordx4 v134, s[36:37]
	s_barrier
	s_waitcnt lgkmcnt(0)
	s_setprio 1
	s_waitcnt lgkmcnt(0)
	v_mfma_f32_16x16x32_bf16 v[62:65], v[144:147], v[170:173], v[62:65]
	v_mfma_f32_16x16x32_bf16 v[58:61], v[162:165], v[170:173], v[58:61]
	v_mfma_f32_16x16x32_bf16 v[46:49], v[144:147], v[178:181], v[46:49]
	v_mfma_f32_16x16x32_bf16 v[42:45], v[162:165], v[178:181], v[42:45]
	v_mfma_f32_16x16x32_bf16 v[30:33], v[144:147], v[186:189], v[30:33]
	v_mfma_f32_16x16x32_bf16 v[26:29], v[162:165], v[186:189], v[26:29]
	v_mfma_f32_16x16x32_bf16 v[14:17], v[144:147], v[194:197], v[14:17]
	v_mfma_f32_16x16x32_bf16 v[10:13], v[162:165], v[194:197], v[10:13]
	v_mfma_f32_16x16x32_bf16 v[62:65], v[158:161], v[174:177], v[62:65]
	v_mfma_f32_16x16x32_bf16 v[58:61], v[166:169], v[174:177], v[58:61]
	v_mfma_f32_16x16x32_bf16 v[46:49], v[158:161], v[182:185], v[46:49]
	v_mfma_f32_16x16x32_bf16 v[42:45], v[166:169], v[182:185], v[42:45]
	v_mfma_f32_16x16x32_bf16 v[30:33], v[158:161], v[190:193], v[30:33]
	v_mfma_f32_16x16x32_bf16 v[26:29], v[166:169], v[190:193], v[26:29]
	v_mfma_f32_16x16x32_bf16 v[14:17], v[158:161], v[198:201], v[14:17]
	v_mfma_f32_16x16x32_bf16 v[10:13], v[166:169], v[198:201], v[10:13]
	s_setprio 0
	s_barrier
	s_add_u32 s50, s34, 0x40000
	s_addc_u32 s51, s35, 0
	s_add_i32 s52, s47, s38
	s_mov_b32 m0, s52
	s_nop 0
	global_load_lds_dwordx4 v132, s[50:51]
	s_add_i32 m0, s52, 0x2000
	s_nop 0
	global_load_lds_dwordx4 v136, s[50:51]
	s_waitcnt vmcnt(6)
	s_barrier
	s_setprio 1
	v_mfma_f32_16x16x32_bf16 v[54:57], v[202:205], v[170:173], v[54:57]
	v_mfma_f32_16x16x32_bf16 v[50:53], v[210:213], v[170:173], v[50:53]
	v_mfma_f32_16x16x32_bf16 v[38:41], v[202:205], v[178:181], v[38:41]
	v_mfma_f32_16x16x32_bf16 v[34:37], v[210:213], v[178:181], v[34:37]
	v_mfma_f32_16x16x32_bf16 v[22:25], v[202:205], v[186:189], v[22:25]
	v_mfma_f32_16x16x32_bf16 v[18:21], v[210:213], v[186:189], v[18:21]
	v_mfma_f32_16x16x32_bf16 v[6:9], v[202:205], v[194:197], v[6:9]
	v_mfma_f32_16x16x32_bf16 v[2:5], v[210:213], v[194:197], v[2:5]
	v_mfma_f32_16x16x32_bf16 v[54:57], v[206:209], v[174:177], v[54:57]
	v_mfma_f32_16x16x32_bf16 v[50:53], v[214:217], v[174:177], v[50:53]
	v_mfma_f32_16x16x32_bf16 v[38:41], v[206:209], v[182:185], v[38:41]
	v_mfma_f32_16x16x32_bf16 v[34:37], v[214:217], v[182:185], v[34:37]
	v_mfma_f32_16x16x32_bf16 v[22:25], v[206:209], v[190:193], v[22:25]
	v_mfma_f32_16x16x32_bf16 v[18:21], v[214:217], v[190:193], v[18:21]
	v_mfma_f32_16x16x32_bf16 v[6:9], v[206:209], v[198:201], v[6:9]
	v_mfma_f32_16x16x32_bf16 v[2:5], v[214:217], v[198:201], v[2:5]
	s_setprio 0
	s_add_i32 s50, 16, 0x18000
	s_barrier
	ds_read_b128 v[144:147], v218
	ds_read_b128 v[158:161], v218 offset:1024
	ds_read_b128 v[162:165], v218 offset:2048
	ds_read_b128 v[166:169], v218 offset:3072
	s_add_u32 s36, s36, 0x40000
	s_addc_u32 s37, s37, 0
	s_mov_b32 m0, s40
	ds_read_b128 v[170:173], v156 offset:32768
	ds_read_b128 v[174:177], v156 offset:33792
	ds_read_b128 v[178:181], v156 offset:34816
	ds_read_b128 v[182:185], v156 offset:35840
	ds_read_b128 v[186:189], v156 offset:36864
	ds_read_b128 v[190:193], v156 offset:37888
	ds_read_b128 v[194:197], v156 offset:38912
	ds_read_b128 v[198:201], v156 offset:39936
	global_load_lds_dwordx4 v130, s[36:37]
	s_mov_b32 m0, s41
	s_nop 0
	global_load_lds_dwordx4 v134, s[36:37]
	s_waitcnt lgkmcnt(8)
	s_barrier
; #define PG8_STAGE(bufoff, gbase, voff) do { _Pragma("unroll") for (int _i = 0; _i < 2; ++_i) \
;         __builtin_amdgcn_global_load_lds((const unsigned*)((const char*)(gbase) + (voff)[_i]), (LAS unsigned*)(lds + (bufoff) + ldsw + _i * 8192), 16, 0, 0); } while (0)
; #define PG8_LDA(dst, b, h) do { _Pragma("unroll") for (int m = 0; m < 4; ++m) _Pragma("unroll") for (int k = 0; k < 2; ++k) dst[m][k] = *(const LAS bf16x8*)(lds + PG8_SA(b, h) + aoff + m * 2048 + k * 1024); } while (0)
; #define PG8_LDB(dst, b, h) do { _Pragma("unroll") for (int n = 0; n < 2; ++n) _Pragma("unroll") for (int k = 0; k < 2; ++k) dst[n][k] = *(const LAS bf16x8*)(lds + PG8_SB(b, h) + boff + n * 2048 + k * 1024); } while (0)
; #define PG8_MMA(ai, bj, At, Bt) do { __builtin_amdgcn_s_setprio(1); _Pragma("unroll") for (int m = 0; m < 4; ++m) _Pragma("unroll") for (int n = 0; n < 2; ++n) _Pragma("unroll") for (int k = 0; k < 2; ++k) \
;         acc[ai][bj][m][n] = __builtin_amdgcn_mfma_f32_16x16x32_bf16(Bt[n][k], At[m][k], acc[ai][bj][m][n], 0, 0, 0); __builtin_amdgcn_s_setprio(0); } while (0)
; #define PG8_WAIT_V(n) asm volatile("s_waitcnt vmcnt(" #n ")" ::: "memory")
; #define PG8_WAIT_L(n) asm volatile("s_waitcnt lgkmcnt(" #n ")" ::: "memory")
; #define PG8_BAR __builtin_amdgcn_s_barrier()
; #define PG8_SCHED __builtin_amdgcn_sched_barrier(0)
; template <class Sched, class Epi>
; __device__ __forceinline__ void gemm_phase(LAS unsigned char* lds, const Sched& S, const Epi& E, const int K, const int lda, const int ldb) {
;     ...
;             PG8_LDB(B1, 1, 1); PG8_STAGE(PG8_SB(1, 0), b3, voffB);
;             PG8_BAR; PG8_WAIT_L(0); PG8_MMA(0, 1, At, B1); PG8_BAR;
;             PG8_LDA(At, 1, 1); PG8_STAGE(PG8_SA(1, 0), a3, voffA);
;             PG8_BAR; PG8_WAIT_L(0); if (!chalf) PG8_MMA(1, 0, At, B0); PG8_BAR; PG8_SCHED;
;             PG8_STAGE(PG8_SB(1, 1), b3 + hstepB, voffB);
;             PG8_WAIT_V(6); PG8_BAR; if (!chalf) PG8_MMA(1, 1, At, B1); PG8_BAR;
;         }
	s_waitcnt lgkmcnt(0)
	s_setprio 1
	s_waitcnt lgkmcnt(0)
	v_mfma_f32_16x16x32_bf16 v[118:121], v[144:147], v[170:173], v[118:121]
	v_mfma_f32_16x16x32_bf16 v[114:117], v[162:165], v[170:173], v[114:117]
	v_mfma_f32_16x16x32_bf16 v[110:113], v[144:147], v[178:181], v[110:113]
	v_mfma_f32_16x16x32_bf16 v[106:109], v[162:165], v[178:181], v[106:109]
	v_mfma_f32_16x16x32_bf16 v[94:97], v[144:147], v[186:189], v[94:97]
	v_mfma_f32_16x16x32_bf16 v[90:93], v[162:165], v[186:189], v[90:93]
	v_mfma_f32_16x16x32_bf16 v[78:81], v[144:147], v[194:197], v[78:81]
	v_mfma_f32_16x16x32_bf16 v[74:77], v[162:165], v[194:197], v[74:77]
	v_mfma_f32_16x16x32_bf16 v[118:121], v[158:161], v[174:177], v[118:121]
	v_mfma_f32_16x16x32_bf16 v[114:117], v[166:169], v[174:177], v[114:117]
	v_mfma_f32_16x16x32_bf16 v[110:113], v[158:161], v[182:185], v[110:113]
	v_mfma_f32_16x16x32_bf16 v[106:109], v[166:169], v[182:185], v[106:109]
	v_mfma_f32_16x16x32_bf16 v[94:97], v[158:161], v[190:193], v[94:97]
	v_mfma_f32_16x16x32_bf16 v[90:93], v[166:169], v[190:193], v[90:93]
	v_mfma_f32_16x16x32_bf16 v[78:81], v[158:161], v[198:201], v[78:81]
	v_mfma_f32_16x16x32_bf16 v[74:77], v[166:169], v[198:201], v[74:77]
	s_setprio 0
	s_barrier
	s_add_i32 s36, 16, 0x1c000
	s_add_i32 s37, s50, s38
	s_mov_b32 m0, s37
	ds_read_b128 v[202:205], v219
	ds_read_b128 v[206:209], v219 offset:1024
	ds_read_b128 v[210:213], v219 offset:2048
	ds_read_b128 v[214:217], v219 offset:3072
	global_load_lds_dwordx4 v132, s[62:63]
	s_add_i32 m0, s37, 0x2000
	s_nop 0
	global_load_lds_dwordx4 v136, s[64:65]
	s_barrier
	s_waitcnt lgkmcnt(0)
	s_setprio 1
	s_waitcnt lgkmcnt(0)
	v_mfma_f32_16x16x32_bf16 v[126:129], v[202:205], v[170:173], v[126:129]
	v_mfma_f32_16x16x32_bf16 v[122:125], v[210:213], v[170:173], v[122:125]
	v_mfma_f32_16x16x32_bf16 v[102:105], v[202:205], v[178:181], v[102:105]
	v_mfma_f32_16x16x32_bf16 v[98:101], v[210:213], v[178:181], v[98:101]
	v_mfma_f32_16x16x32_bf16 v[86:89], v[202:205], v[186:189], v[86:89]
	v_mfma_f32_16x16x32_bf16 v[82:85], v[210:213], v[186:189], v[82:85]
	v_mfma_f32_16x16x32_bf16 v[70:73], v[202:205], v[194:197], v[70:73]
	v_mfma_f32_16x16x32_bf16 v[66:69], v[210:213], v[194:197], v[66:69]
	v_mfma_f32_16x16x32_bf16 v[126:129], v[206:209], v[174:177], v[126:129]
	v_mfma_f32_16x16x32_bf16 v[122:125], v[214:217], v[174:177], v[122:125]
	v_mfma_f32_16x16x32_bf16 v[102:105], v[206:209], v[182:185], v[102:105]
	v_mfma_f32_16x16x32_bf16 v[98:101], v[214:217], v[182:185], v[98:101]
	v_mfma_f32_16x16x32_bf16 v[86:89], v[206:209], v[190:193], v[86:89]
	v_mfma_f32_16x16x32_bf16 v[82:85], v[214:217], v[190:193], v[82:85]
	v_mfma_f32_16x16x32_bf16 v[70:73], v[206:209], v[198:201], v[70:73]
	v_mfma_f32_16x16x32_bf16 v[66:69], v[214:217], v[198:201], v[66:69]
	s_setprio 0
	s_mov_b32 m0, s42
	s_barrier
	ds_read_b128 v[170:173], v156 offset:49152
	ds_read_b128 v[174:177], v156 offset:50176
	ds_read_b128 v[178:181], v156 offset:51200
	ds_read_b128 v[182:185], v156 offset:52224
	ds_read_b128 v[186:189], v156 offset:53248
	ds_read_b128 v[190:193], v156 offset:54272
	ds_read_b128 v[194:197], v156 offset:55296
	ds_read_b128 v[198:201], v156 offset:56320
	global_load_lds_dwordx4 v130, s[66:67]
	s_mov_b32 m0, s43
	s_nop 0
	global_load_lds_dwordx4 v134, s[68:69]
	s_barrier
	s_waitcnt lgkmcnt(0)
	s_setprio 1
	s_waitcnt lgkmcnt(0)
	v_mfma_f32_16x16x32_bf16 v[62:65], v[144:147], v[170:173], v[62:65]
	v_mfma_f32_16x16x32_bf16 v[58:61], v[162:165], v[170:173], v[58:61]
	v_mfma_f32_16x16x32_bf16 v[46:49], v[144:147], v[178:181], v[46:49]
	v_mfma_f32_16x16x32_bf16 v[42:45], v[162:165], v[178:181], v[42:45]
	v_mfma_f32_16x16x32_bf16 v[30:33], v[144:147], v[186:189], v[30:33]
	v_mfma_f32_16x16x32_bf16 v[26:29], v[162:165], v[186:189], v[26:29]
	v_mfma_f32_16x16x32_bf16 v[14:17], v[144:147], v[194:197], v[14:17]
	v_mfma_f32_16x16x32_bf16 v[10:13], v[162:165], v[194:197], v[10:13]
	v_mfma_f32_16x16x32_bf16 v[62:65], v[158:161], v[174:177], v[62:65]
	v_mfma_f32_16x16x32_bf16 v[58:61], v[166:169], v[174:177], v[58:61]
	v_mfma_f32_16x16x32_bf16 v[46:49], v[158:161], v[182:185], v[46:49]
	v_mfma_f32_16x16x32_bf16 v[42:45], v[166:169], v[182:185], v[42:45]
	v_mfma_f32_16x16x32_bf16 v[30:33], v[158:161], v[190:193], v[30:33]
	v_mfma_f32_16x16x32_bf16 v[26:29], v[166:169], v[190:193], v[26:29]
	v_mfma_f32_16x16x32_bf16 v[14:17], v[158:161], v[198:201], v[14:17]
	v_mfma_f32_16x16x32_bf16 v[10:13], v[166:169], v[198:201], v[10:13]
	s_setprio 0
	s_barrier
	s_add_u32 s34, s34, 0x40080
	s_addc_u32 s35, s35, 0
	s_add_i32 s36, s36, s38
	s_mov_b32 m0, s36
	s_nop 0
	global_load_lds_dwordx4 v132, s[34:35]
	s_add_i32 m0, s36, 0x2000
	s_nop 0
	global_load_lds_dwordx4 v136, s[34:35]
	s_waitcnt vmcnt(6)
	s_barrier
	s_setprio 1
	v_mfma_f32_16x16x32_bf16 v[54:57], v[202:205], v[170:173], v[54:57]
	v_mfma_f32_16x16x32_bf16 v[50:53], v[210:213], v[170:173], v[50:53]
	v_mfma_f32_16x16x32_bf16 v[38:41], v[202:205], v[178:181], v[38:41]
	v_mfma_f32_16x16x32_bf16 v[34:37], v[210:213], v[178:181], v[34:37]
	v_mfma_f32_16x16x32_bf16 v[22:25], v[202:205], v[186:189], v[22:25]
	v_mfma_f32_16x16x32_bf16 v[18:21], v[210:213], v[186:189], v[18:21]
	v_mfma_f32_16x16x32_bf16 v[6:9], v[202:205], v[194:197], v[6:9]
	v_mfma_f32_16x16x32_bf16 v[2:5], v[210:213], v[194:197], v[2:5]
	v_mfma_f32_16x16x32_bf16 v[54:57], v[206:209], v[174:177], v[54:57]
	v_mfma_f32_16x16x32_bf16 v[50:53], v[214:217], v[174:177], v[50:53]
	v_mfma_f32_16x16x32_bf16 v[38:41], v[206:209], v[182:185], v[38:41]
	v_mfma_f32_16x16x32_bf16 v[34:37], v[214:217], v[182:185], v[34:37]
	v_mfma_f32_16x16x32_bf16 v[22:25], v[206:209], v[190:193], v[22:25]
	v_mfma_f32_16x16x32_bf16 v[18:21], v[214:217], v[190:193], v[18:21]
	v_mfma_f32_16x16x32_bf16 v[6:9], v[206:209], v[198:201], v[6:9]
	v_mfma_f32_16x16x32_bf16 v[2:5], v[214:217], v[198:201], v[2:5]
	s_setprio 0
	s_add_i32 s49, s49, 2
	s_add_u32 s15, s15, 0x100
	s_addc_u32 s17, s17, 0
	s_add_u32 s28, s28, 0x100
	s_addc_u32 s29, s29, 0
	s_cmp_gt_u32 s49, 13
	s_barrier
; __device__ __forceinline__ u32x4 pack8(const float (&f)[8]) { u32x4 r; r[0] = cvt_pk_bf16(f[0], f[1]); r[1] = cvt_pk_bf16(f[2], f[3]); r[2] = cvt_pk_bf16(f[4], f[5]); r[3] = cvt_pk_bf16(f[6], f[7]); return r; }
;     __device__ __forceinline__ void operator()(EPI_ARGS) const {
;         const int col = u.pn * 128 + wc * 32 + 8 * fq;
; #pragma unroll
;         for (int ai = 0; ai < 2; ++ai) if (ai == 0 || !u.half) { u32x4 zz[4];
; #pragma unroll
;             for (int m = 0; m < 4; ++m) zz[m] = *(const u32x4*)(parts + E_PZB + (size_t)EPI_ROW * 1024 + col);
; #pragma unroll
;             for (int m = 0; m < 4; ++m) { float z[8]; unpack8(zz[m], z);
;                 const f32x4 a0 = acc[ai][0][m][0], a1 = acc[ai][0][m][1], b0 = acc[ai][1][m][0], b1 = acc[ai][1][m][1]; float o[8];
; #pragma unroll
;                 for (int j = 0; j < 4; ++j) { o[j] = a0[j] * z[j] * __builtin_amdgcn_rcpf((1.0f + __expf(-b0[j])) * (1.0f + __expf(-z[j]))); o[4 + j] = a1[j] * z[4 + j] * __builtin_amdgcn_rcpf((1.0f + __expf(-b1[j])) * (1.0f + __expf(-z[4 + j]))); }
;                 *(u32x4*)(O + (size_t)EPI_ROW * 1024 + col) = pack8(o); } }
	s_cbranch_scc0 .LBB0_1415
	v_lshl_or_b32 v144, s48, 7, v154
	v_ashrrev_i32_e32 v145, 31, v144
	v_add_u32_e32 v148, s22, v1
	v_lshlrev_b64 v[144:145], 1, v[144:145]
	v_ashrrev_i32_e32 v149, 31, v148
	v_lshl_add_u64 v[146:147], s[4:5], 0, v[144:145]
	v_lshlrev_b64 v[166:167], 11, v[148:149]
	v_lshl_add_u64 v[158:159], v[146:147], 0, v[166:167]
	global_load_dwordx4 v[158:161], v[158:159], off
	v_mul_f32_e32 v149, 0xbfb8aa3b, v122
	v_mul_f32_e32 v123, 0xbfb8aa3b, v123
	v_add_u32_e32 v122, 16, v148
	v_exp_f32_e32 v174, v123
	v_ashrrev_i32_e32 v123, 31, v122
	v_lshlrev_b64 v[122:123], 11, v[122:123]
	v_mul_f32_e32 v126, 0xbfb8aa3b, v126
	v_mul_f32_e32 v127, 0xbfb8aa3b, v127
	v_mul_f32_e32 v128, 0xbfb8aa3b, v128
	v_mul_f32_e32 v129, 0xbfb8aa3b, v129
	v_lshl_add_u64 v[122:123], v[146:147], 0, v[122:123]
	v_exp_f32_e32 v168, v126
	v_exp_f32_e32 v172, v127
	v_exp_f32_e32 v176, v128
	v_exp_f32_e32 v180, v129
	global_load_dwordx4 v[126:129], v[122:123], off
	v_mul_f32_e32 v163, 0xbfb8aa3b, v124
	v_mul_f32_e32 v125, 0xbfb8aa3b, v125
	v_add_u32_e32 v124, 32, v148
	v_add_u32_e32 v162, 48, v148
	v_exp_f32_e32 v178, v163
	v_exp_f32_e32 v182, v125
	v_ashrrev_i32_e32 v125, 31, v124
	v_ashrrev_i32_e32 v163, 31, v162
	v_lshlrev_b64 v[122:123], 11, v[124:125]
	v_lshlrev_b64 v[124:125], 11, v[162:163]
	v_lshl_add_u64 v[122:123], v[146:147], 0, v[122:123]
	v_lshl_add_u64 v[124:125], v[146:147], 0, v[124:125]
	global_load_dwordx4 v[162:165], v[122:123], off
	s_nop 0
	global_load_dwordx4 v[122:125], v[124:125], off
	v_exp_f32_e32 v170, v149
	v_mul_f32_e32 v102, 0xbfb8aa3b, v102
	v_mul_f32_e32 v98, 0xbfb8aa3b, v98
	v_mul_f32_e32 v100, 0xbfb8aa3b, v100
	v_mul_f32_e32 v86, 0xbfb8aa3b, v86
	v_mul_f32_e32 v82, 0xbfb8aa3b, v82
	v_mul_f32_e32 v84, 0xbfb8aa3b, v84
	v_mul_f32_e32 v70, 0xbfb8aa3b, v70
	v_mul_f32_e32 v66, 0xbfb8aa3b, v66
	v_mul_f32_e32 v68, 0xbfb8aa3b, v68
	v_mul_f32_e32 v54, 0xbfb8aa3b, v54
	v_mul_f32_e32 v50, 0xbfb8aa3b, v50
	v_mul_f32_e32 v52, 0xbfb8aa3b, v52
	v_mul_f32_e32 v38, 0xbfb8aa3b, v38
	v_mul_f32_e32 v34, 0xbfb8aa3b, v34
	v_mul_f32_e32 v36, 0xbfb8aa3b, v36
	v_mul_f32_e32 v22, 0xbfb8aa3b, v22
	v_mul_f32_e32 v18, 0xbfb8aa3b, v18
	v_mul_f32_e32 v20, 0xbfb8aa3b, v20
	v_mul_f32_e32 v6, 0xbfb8aa3b, v6
	v_mul_f32_e32 v2, 0xbfb8aa3b, v2
	v_mul_f32_e32 v4, 0xbfb8aa3b, v4
	s_and_b64 vcc, exec, s[12:13]
	s_mov_b32 s48, s14
	s_mov_b64 s[34:35], s[20:21]
	s_mov_b64 s[28:29], s[18:19]
	s_waitcnt vmcnt(0)
	v_lshlrev_b32_e32 v149, 16, v158
	v_and_b32_e32 v158, 0xffff0000, v158
	v_lshlrev_b32_e32 v169, 16, v159
	v_and_b32_e32 v184, 0xffff0000, v159
	v_lshlrev_b32_e32 v159, 16, v160
	v_and_b32_e32 v160, 0xffff0000, v160
	v_lshlrev_b32_e32 v171, 16, v161
	v_mul_f32_e32 v186, v118, v149
	v_mul_f32_e32 v118, 0xbfb8aa3b, v149
	v_mul_f32_e32 v149, v114, v159
	v_mul_f32_e32 v114, 0xbfb8aa3b, v159
	v_mul_f32_e32 v187, v119, v158
	v_mul_f32_e32 v119, 0xbfb8aa3b, v158
	v_mul_f32_e32 v188, v115, v160
	v_mul_f32_e32 v115, 0xbfb8aa3b, v160
	v_mul_f32_e32 v158, 0xbfb8aa3b, v169
	v_mul_f32_e32 v159, 0xbfb8aa3b, v171
	v_mul_f32_e32 v120, v120, v169
	v_mul_f32_e32 v116, v116, v171
	v_exp_f32_e32 v169, v118
	v_exp_f32_e32 v171, v114
	v_exp_f32_e32 v173, v119
	v_exp_f32_e32 v175, v115
	v_exp_f32_e32 v177, v158
	v_exp_f32_e32 v179, v159
	v_and_b32_e32 v185, 0xffff0000, v161
	v_mul_f32_e32 v160, 0xbfb8aa3b, v184
	v_mul_f32_e32 v161, 0xbfb8aa3b, v185
	v_exp_f32_e32 v181, v160
	v_exp_f32_e32 v183, v161
	v_pk_add_f32 v[114:115], v[168:169], 1.0 op_sel_hi:[1,0]
	v_pk_add_f32 v[118:119], v[170:171], 1.0 op_sel_hi:[1,0]
	v_pk_add_f32 v[158:159], v[172:173], 1.0 op_sel_hi:[1,0]
	v_pk_add_f32 v[160:161], v[174:175], 1.0 op_sel_hi:[1,0]
	v_pk_add_f32 v[168:169], v[176:177], 1.0 op_sel_hi:[1,0]
	v_pk_add_f32 v[170:171], v[178:179], 1.0 op_sel_hi:[1,0]
	v_mul_f32_e32 v114, v114, v115
	v_mul_f32_e32 v115, v118, v119
	v_mul_f32_e32 v118, v158, v159
	v_mul_f32_e32 v119, v160, v161
	v_mul_f32_e32 v158, v168, v169
	v_mul_f32_e32 v159, v170, v171
	v_rcp_f32_e32 v115, v115
	v_rcp_f32_e32 v118, v118
	v_rcp_f32_e32 v119, v119
	v_rcp_f32_e32 v158, v158
	v_rcp_f32_e32 v159, v159
	v_pk_add_f32 v[172:173], v[180:181], 1.0 op_sel_hi:[1,0]
	v_pk_add_f32 v[174:175], v[182:183], 1.0 op_sel_hi:[1,0]
	v_mul_f32_e32 v160, v172, v173
	v_rcp_f32_e32 v114, v114
	v_mul_f32_e32 v149, v149, v115
	v_mul_f32_e32 v115, v187, v118
	v_mul_f32_e32 v118, v188, v119
	v_mul_f32_e32 v119, v120, v158
	v_mul_f32_e32 v120, v116, v159
	v_mul_f32_e32 v116, v174, v175
	v_rcp_f32_e32 v160, v160
	v_rcp_f32_e32 v116, v116
	v_mul_f32_e32 v114, v186, v114
	v_mul_f32_e32 v121, v121, v184
	v_mul_f32_e32 v117, v117, v185
	v_mul_f32_e32 v121, v121, v160
	v_mul_f32_e32 v117, v117, v116
	v_cvt_pk_bf16_f32 v114, v114, v115
	v_cvt_pk_bf16_f32 v115, v119, v121
	v_cvt_pk_bf16_f32 v116, v149, v118
	v_lshl_add_u64 v[118:119], s[6:7], 0, v[166:167]
	v_lshl_add_u64 v[118:119], v[118:119], 0, v[144:145]
	v_cvt_pk_bf16_f32 v117, v120, v117
	global_store_dwordx4 v[118:119], v[114:117], off
	v_lshlrev_b32_e32 v118, 16, v126
	v_and_b32_e32 v119, 0xffff0000, v126
	v_lshlrev_b32_e32 v126, 16, v128
	v_exp_f32_e32 v114, v102
	v_mul_f32_e32 v102, 0xbfb8aa3b, v118
	v_exp_f32_e32 v115, v102
	v_exp_f32_e32 v116, v98
	v_mul_f32_e32 v98, 0xbfb8aa3b, v126
	v_exp_f32_e32 v117, v98
	v_pk_add_f32 v[114:115], v[114:115], 1.0 op_sel_hi:[1,0]
	v_mul_f32_e32 v110, v110, v118
	v_mul_f32_e32 v98, v114, v115
	v_pk_add_f32 v[114:115], v[116:117], 1.0 op_sel_hi:[1,0]
	v_rcp_f32_e32 v98, v98
	v_mul_f32_e32 v102, v114, v115
	v_rcp_f32_e32 v102, v102
	v_lshlrev_b32_e32 v120, 16, v127
	v_mul_f32_e32 v110, v110, v98
	v_mul_f32_e32 v98, v106, v126
	v_mul_f32_e32 v106, v98, v102
; __device__ __forceinline__ u32x4 pack8(const float (&f)[8]) { u32x4 r; r[0] = cvt_pk_bf16(f[0], f[1]); r[1] = cvt_pk_bf16(f[2], f[3]); r[2] = cvt_pk_bf16(f[4], f[5]); r[3] = cvt_pk_bf16(f[6], f[7]); return r; }
;     __device__ __forceinline__ void operator()(EPI_ARGS) const {
;     ...
;         for (int ai = 0; ai < 2; ++ai) if (ai == 0 || !u.half) { u32x4 zz[4];
; #pragma unroll
;             for (int m = 0; m < 4; ++m) zz[m] = *(const u32x4*)(parts + E_PZB + (size_t)EPI_ROW * 1024 + col);
; #pragma unroll
;             for (int m = 0; m < 4; ++m) { float z[8]; unpack8(zz[m], z);
;                 const f32x4 a0 = acc[ai][0][m][0], a1 = acc[ai][0][m][1], b0 = acc[ai][1][m][0], b1 = acc[ai][1][m][1]; float o[8];
; #pragma unroll
;                 for (int j = 0; j < 4; ++j) { o[j] = a0[j] * z[j] * __builtin_amdgcn_rcpf((1.0f + __expf(-b0[j])) * (1.0f + __expf(-z[j]))); o[4 + j] = a1[j] * z[4 + j] * __builtin_amdgcn_rcpf((1.0f + __expf(-b1[j])) * (1.0f + __expf(-z[4 + j]))); }
;                 *(u32x4*)(O + (size_t)EPI_ROW * 1024 + col) = pack8(o); } }
	v_mul_f32_e32 v98, 0xbfb8aa3b, v103
	v_and_b32_e32 v121, 0xffff0000, v127
	v_and_b32_e32 v127, 0xffff0000, v128
	v_exp_f32_e32 v102, v98
	v_mul_f32_e32 v98, 0xbfb8aa3b, v119
	v_exp_f32_e32 v103, v98
	v_mul_f32_e32 v98, 0xbfb8aa3b, v99
	v_mul_f32_e32 v99, 0xbfb8aa3b, v127
	v_exp_f32_e32 v98, v98
	v_exp_f32_e32 v99, v99
	v_pk_add_f32 v[102:103], v[102:103], 1.0 op_sel_hi:[1,0]
	v_lshlrev_b32_e32 v128, 16, v129
	v_mul_f32_e32 v102, v102, v103
	v_pk_add_f32 v[98:99], v[98:99], 1.0 op_sel_hi:[1,0]
	v_rcp_f32_e32 v102, v102
	v_mul_f32_e32 v98, v98, v99
	v_rcp_f32_e32 v98, v98
	v_mul_f32_e32 v99, v111, v119
	v_mul_f32_e32 v111, v99, v102
	v_mul_f32_e32 v99, v107, v127
	v_mul_f32_e32 v107, v99, v98
	v_mul_f32_e32 v98, 0xbfb8aa3b, v104
	v_mul_f32_e32 v99, 0xbfb8aa3b, v120
	v_exp_f32_e32 v98, v98
	v_exp_f32_e32 v99, v99
	v_exp_f32_e32 v102, v100
	v_mul_f32_e32 v100, 0xbfb8aa3b, v128
	v_exp_f32_e32 v103, v100
	v_pk_add_f32 v[98:99], v[98:99], 1.0 op_sel_hi:[1,0]
	v_and_b32_e32 v129, 0xffff0000, v129
	v_mul_f32_e32 v98, v98, v99
	v_rcp_f32_e32 v100, v98
	v_pk_add_f32 v[98:99], v[102:103], 1.0 op_sel_hi:[1,0]
	s_nop 0
	v_mul_f32_e32 v98, v98, v99
	v_rcp_f32_e32 v98, v98
	v_mul_f32_e32 v99, v112, v120
	v_mul_f32_e32 v102, v99, v100
	v_mul_f32_e32 v99, v108, v128
	v_mul_f32_e32 v103, v99, v98
	v_mul_f32_e32 v98, 0xbfb8aa3b, v105
	v_mul_f32_e32 v99, 0xbfb8aa3b, v121
	v_exp_f32_e32 v98, v98
	v_exp_f32_e32 v99, v99
	v_mul_f32_e32 v100, 0xbfb8aa3b, v101
	v_mul_f32_e32 v101, 0xbfb8aa3b, v129
	v_exp_f32_e32 v100, v100
	v_exp_f32_e32 v101, v101
	v_pk_add_f32 v[98:99], v[98:99], 1.0 op_sel_hi:[1,0]
	v_lshlrev_b32_e32 v108, 16, v165
	v_mul_f32_e32 v98, v98, v99
	v_rcp_f32_e32 v104, v98
	v_pk_add_f32 v[98:99], v[100:101], 1.0 op_sel_hi:[1,0]
	v_mul_f32_e32 v100, v109, v129
	v_mul_f32_e32 v98, v98, v99
	v_rcp_f32_e32 v98, v98
	v_mul_f32_e32 v99, v113, v121
	v_mul_f32_e32 v99, v99, v104
	v_lshlrev_b32_e32 v104, 16, v163
	v_mul_f32_e32 v101, v100, v98
	v_cvt_pk_bf16_f32 v98, v110, v111
	v_cvt_pk_bf16_f32 v99, v102, v99
	v_add_u32_e32 v102, s22, v151
	v_cvt_pk_bf16_f32 v100, v106, v107
	v_cvt_pk_bf16_f32 v101, v103, v101
	v_ashrrev_i32_e32 v103, 31, v102
	v_lshlrev_b64 v[102:103], 11, v[102:103]
	v_lshl_add_u64 v[102:103], s[6:7], 0, v[102:103]
	v_lshl_add_u64 v[102:103], v[102:103], 0, v[144:145]
	global_store_dwordx4 v[102:103], v[98:101], off
	v_lshlrev_b32_e32 v102, 16, v162
	v_lshlrev_b32_e32 v106, 16, v164
	v_exp_f32_e32 v98, v86
	v_mul_f32_e32 v86, 0xbfb8aa3b, v102
	v_exp_f32_e32 v99, v86
	v_exp_f32_e32 v100, v82
	v_mul_f32_e32 v82, 0xbfb8aa3b, v106
	v_exp_f32_e32 v101, v82
	v_pk_add_f32 v[98:99], v[98:99], 1.0 op_sel_hi:[1,0]
	v_mul_f32_e32 v94, v94, v102
	v_mul_f32_e32 v82, v98, v99
	v_pk_add_f32 v[98:99], v[100:101], 1.0 op_sel_hi:[1,0]
	v_rcp_f32_e32 v82, v82
	v_mul_f32_e32 v86, v98, v99
	v_rcp_f32_e32 v86, v86
	v_and_b32_e32 v103, 0xffff0000, v162
	v_mul_f32_e32 v94, v94, v82
	v_mul_f32_e32 v82, v90, v106
	v_mul_f32_e32 v90, v82, v86
	v_mul_f32_e32 v82, 0xbfb8aa3b, v87
	v_and_b32_e32 v107, 0xffff0000, v164
	v_exp_f32_e32 v86, v82
	v_mul_f32_e32 v82, 0xbfb8aa3b, v103
	v_exp_f32_e32 v87, v82
	v_mul_f32_e32 v82, 0xbfb8aa3b, v83
	v_mul_f32_e32 v83, 0xbfb8aa3b, v107
	v_exp_f32_e32 v82, v82
	v_exp_f32_e32 v83, v83
	v_pk_add_f32 v[86:87], v[86:87], 1.0 op_sel_hi:[1,0]
	v_and_b32_e32 v105, 0xffff0000, v163
	v_mul_f32_e32 v86, v86, v87
	v_pk_add_f32 v[82:83], v[82:83], 1.0 op_sel_hi:[1,0]
	v_rcp_f32_e32 v86, v86
	v_mul_f32_e32 v82, v82, v83
	v_rcp_f32_e32 v82, v82
	v_mul_f32_e32 v83, v95, v103
	v_mul_f32_e32 v95, v83, v86
	v_mul_f32_e32 v83, v91, v107
	v_mul_f32_e32 v91, v83, v82
	v_mul_f32_e32 v82, 0xbfb8aa3b, v88
	v_mul_f32_e32 v83, 0xbfb8aa3b, v104
	v_exp_f32_e32 v82, v82
	v_exp_f32_e32 v83, v83
	v_exp_f32_e32 v86, v84
	v_mul_f32_e32 v84, 0xbfb8aa3b, v108
	v_exp_f32_e32 v87, v84
	v_pk_add_f32 v[82:83], v[82:83], 1.0 op_sel_hi:[1,0]
	v_and_b32_e32 v109, 0xffff0000, v165
	v_mul_f32_e32 v82, v82, v83
	v_rcp_f32_e32 v84, v82
	v_pk_add_f32 v[82:83], v[86:87], 1.0 op_sel_hi:[1,0]
	s_nop 0
	v_mul_f32_e32 v82, v82, v83
	v_rcp_f32_e32 v82, v82
	v_mul_f32_e32 v83, v96, v104
	v_mul_f32_e32 v86, v83, v84
	v_mul_f32_e32 v83, v92, v108
	v_mul_f32_e32 v87, v83, v82
	v_mul_f32_e32 v82, 0xbfb8aa3b, v89
	v_mul_f32_e32 v83, 0xbfb8aa3b, v105
	v_exp_f32_e32 v82, v82
	v_exp_f32_e32 v83, v83
	v_mul_f32_e32 v84, 0xbfb8aa3b, v85
	v_mul_f32_e32 v85, 0xbfb8aa3b, v109
	v_exp_f32_e32 v84, v84
	v_exp_f32_e32 v85, v85
	v_pk_add_f32 v[82:83], v[82:83], 1.0 op_sel_hi:[1,0]
	v_lshlrev_b32_e32 v92, 16, v125
	v_mul_f32_e32 v82, v82, v83
	v_rcp_f32_e32 v88, v82
	v_pk_add_f32 v[82:83], v[84:85], 1.0 op_sel_hi:[1,0]
	v_mul_f32_e32 v84, v93, v109
	v_mul_f32_e32 v82, v82, v83
	v_rcp_f32_e32 v82, v82
	v_mul_f32_e32 v83, v97, v105
	v_mul_f32_e32 v83, v83, v88
	v_lshlrev_b32_e32 v88, 16, v123
	v_mul_f32_e32 v85, v84, v82
	v_cvt_pk_bf16_f32 v82, v94, v95
	v_cvt_pk_bf16_f32 v83, v86, v83
	v_add_u32_e32 v86, s22, v152
	v_cvt_pk_bf16_f32 v84, v90, v91
	v_cvt_pk_bf16_f32 v85, v87, v85
	v_ashrrev_i32_e32 v87, 31, v86
	v_lshlrev_b64 v[86:87], 11, v[86:87]
	v_lshl_add_u64 v[86:87], s[6:7], 0, v[86:87]
	v_lshl_add_u64 v[86:87], v[86:87], 0, v[144:145]
	global_store_dwordx4 v[86:87], v[82:85], off
	v_lshlrev_b32_e32 v86, 16, v122
	v_lshlrev_b32_e32 v90, 16, v124
	v_exp_f32_e32 v82, v70
	v_mul_f32_e32 v70, 0xbfb8aa3b, v86
	v_exp_f32_e32 v83, v70
	v_exp_f32_e32 v84, v66
	v_mul_f32_e32 v66, 0xbfb8aa3b, v90
	v_exp_f32_e32 v85, v66
	v_pk_add_f32 v[82:83], v[82:83], 1.0 op_sel_hi:[1,0]
	v_mul_f32_e32 v78, v78, v86
	v_mul_f32_e32 v66, v82, v83
	v_pk_add_f32 v[82:83], v[84:85], 1.0 op_sel_hi:[1,0]
	v_rcp_f32_e32 v66, v66
; __device__ __forceinline__ u32x4 pack8(const float (&f)[8]) { u32x4 r; r[0] = cvt_pk_bf16(f[0], f[1]); r[1] = cvt_pk_bf16(f[2], f[3]); r[2] = cvt_pk_bf16(f[4], f[5]); r[3] = cvt_pk_bf16(f[6], f[7]); return r; }
;     __device__ __forceinline__ void operator()(EPI_ARGS) const {
;     ...
;         for (int ai = 0; ai < 2; ++ai) if (ai == 0 || !u.half) { u32x4 zz[4];
; #pragma unroll
;             for (int m = 0; m < 4; ++m) zz[m] = *(const u32x4*)(parts + E_PZB + (size_t)EPI_ROW * 1024 + col);
; #pragma unroll
;             for (int m = 0; m < 4; ++m) { float z[8]; unpack8(zz[m], z);
;                 const f32x4 a0 = acc[ai][0][m][0], a1 = acc[ai][0][m][1], b0 = acc[ai][1][m][0], b1 = acc[ai][1][m][1]; float o[8];
; #pragma unroll
;                 for (int j = 0; j < 4; ++j) { o[j] = a0[j] * z[j] * __builtin_amdgcn_rcpf((1.0f + __expf(-b0[j])) * (1.0f + __expf(-z[j]))); o[4 + j] = a1[j] * z[4 + j] * __builtin_amdgcn_rcpf((1.0f + __expf(-b1[j])) * (1.0f + __expf(-z[4 + j]))); }
;                 *(u32x4*)(O + (size_t)EPI_ROW * 1024 + col) = pack8(o); } }
	v_mul_f32_e32 v70, v82, v83
	v_rcp_f32_e32 v70, v70
	v_and_b32_e32 v87, 0xffff0000, v122
	v_mul_f32_e32 v78, v78, v66
	v_mul_f32_e32 v66, v74, v90
	v_mul_f32_e32 v74, v66, v70
	v_mul_f32_e32 v66, 0xbfb8aa3b, v71
	v_and_b32_e32 v91, 0xffff0000, v124
	v_exp_f32_e32 v70, v66
	v_mul_f32_e32 v66, 0xbfb8aa3b, v87
	v_exp_f32_e32 v71, v66
	v_mul_f32_e32 v66, 0xbfb8aa3b, v67
	v_mul_f32_e32 v67, 0xbfb8aa3b, v91
	v_exp_f32_e32 v66, v66
	v_exp_f32_e32 v67, v67
	v_pk_add_f32 v[70:71], v[70:71], 1.0 op_sel_hi:[1,0]
	v_and_b32_e32 v89, 0xffff0000, v123
	v_mul_f32_e32 v70, v70, v71
	v_pk_add_f32 v[66:67], v[66:67], 1.0 op_sel_hi:[1,0]
	v_rcp_f32_e32 v70, v70
	v_mul_f32_e32 v66, v66, v67
	v_rcp_f32_e32 v66, v66
	v_mul_f32_e32 v67, v79, v87
	v_mul_f32_e32 v79, v67, v70
	v_mul_f32_e32 v67, v75, v91
	v_mul_f32_e32 v75, v67, v66
	v_mul_f32_e32 v66, 0xbfb8aa3b, v72
	v_mul_f32_e32 v67, 0xbfb8aa3b, v88
	v_exp_f32_e32 v66, v66
	v_exp_f32_e32 v67, v67
	v_exp_f32_e32 v70, v68
	v_mul_f32_e32 v68, 0xbfb8aa3b, v92
	v_exp_f32_e32 v71, v68
	v_pk_add_f32 v[66:67], v[66:67], 1.0 op_sel_hi:[1,0]
	v_and_b32_e32 v93, 0xffff0000, v125
	v_mul_f32_e32 v66, v66, v67
	v_rcp_f32_e32 v68, v66
	v_pk_add_f32 v[66:67], v[70:71], 1.0 op_sel_hi:[1,0]
	s_nop 0
	v_mul_f32_e32 v66, v66, v67
	v_rcp_f32_e32 v66, v66
	v_mul_f32_e32 v67, v80, v88
	v_mul_f32_e32 v70, v67, v68
	v_mul_f32_e32 v67, v76, v92
	v_mul_f32_e32 v71, v67, v66
	v_mul_f32_e32 v66, 0xbfb8aa3b, v73
	v_mul_f32_e32 v67, 0xbfb8aa3b, v89
	v_exp_f32_e32 v66, v66
	v_exp_f32_e32 v67, v67
	v_mul_f32_e32 v68, 0xbfb8aa3b, v69
	v_mul_f32_e32 v69, 0xbfb8aa3b, v93
	v_exp_f32_e32 v68, v68
	v_exp_f32_e32 v69, v69
	v_pk_add_f32 v[66:67], v[66:67], 1.0 op_sel_hi:[1,0]
	s_nop 0
	v_mul_f32_e32 v66, v66, v67
	v_rcp_f32_e32 v72, v66
	v_pk_add_f32 v[66:67], v[68:69], 1.0 op_sel_hi:[1,0]
	v_mul_f32_e32 v68, v77, v93
	v_mul_f32_e32 v66, v66, v67
	v_rcp_f32_e32 v66, v66
	v_mul_f32_e32 v67, v81, v89
	v_mul_f32_e32 v67, v67, v72
	v_mul_f32_e32 v69, v68, v66
	v_cvt_pk_bf16_f32 v66, v78, v79
	v_cvt_pk_bf16_f32 v67, v70, v67
	v_add_u32_e32 v70, s22, v153
	v_cvt_pk_bf16_f32 v68, v74, v75
	v_cvt_pk_bf16_f32 v69, v71, v69
	v_ashrrev_i32_e32 v71, 31, v70
	v_lshlrev_b64 v[70:71], 11, v[70:71]
	v_lshl_add_u64 v[70:71], s[6:7], 0, v[70:71]
	v_lshl_add_u64 v[70:71], v[70:71], 0, v[144:145]
	global_store_dwordx4 v[70:71], v[66:69], off
	s_mov_b32 s22, s16
	s_nop 0
	v_add_u32_e32 v66, 0x80, v148
	v_ashrrev_i32_e32 v67, 31, v66
	v_lshlrev_b64 v[88:89], 11, v[66:67]
	v_lshl_add_u64 v[66:67], v[146:147], 0, v[88:89]
	global_load_dwordx4 v[80:83], v[66:67], off
	v_add_u32_e32 v66, 0x90, v148
	v_ashrrev_i32_e32 v67, 31, v66
	v_lshlrev_b64 v[78:79], 11, v[66:67]
	v_lshl_add_u64 v[66:67], v[146:147], 0, v[78:79]
	global_load_dwordx4 v[84:87], v[66:67], off
	v_add_u32_e32 v66, 0xa0, v148
	v_ashrrev_i32_e32 v67, 31, v66
	v_lshlrev_b64 v[76:77], 11, v[66:67]
	v_add_u32_e32 v66, 0xb0, v148
	v_ashrrev_i32_e32 v67, 31, v66
	v_lshl_add_u64 v[90:91], v[146:147], 0, v[76:77]
	v_lshlrev_b64 v[74:75], 11, v[66:67]
	v_lshl_add_u64 v[92:93], v[146:147], 0, v[74:75]
	global_load_dwordx4 v[70:73], v[90:91], off
	global_load_dwordx4 v[66:69], v[92:93], off
	s_waitcnt vmcnt(0)
	v_lshlrev_b32_e32 v90, 16, v80
	v_and_b32_e32 v91, 0xffff0000, v80
	v_lshlrev_b32_e32 v94, 16, v82
	v_exp_f32_e32 v80, v54
	v_mul_f32_e32 v54, 0xbfb8aa3b, v90
	v_lshlrev_b32_e32 v92, 16, v81
	v_and_b32_e32 v93, 0xffff0000, v81
	v_and_b32_e32 v95, 0xffff0000, v82
	v_exp_f32_e32 v81, v54
	v_exp_f32_e32 v82, v50
	v_mul_f32_e32 v50, 0xbfb8aa3b, v94
	v_lshlrev_b32_e32 v96, 16, v83
	v_and_b32_e32 v97, 0xffff0000, v83
	v_exp_f32_e32 v83, v50
	v_pk_add_f32 v[80:81], v[80:81], 1.0 op_sel_hi:[1,0]
	v_mul_f32_e32 v62, v62, v90
	v_mul_f32_e32 v50, v80, v81
	v_pk_add_f32 v[80:81], v[82:83], 1.0 op_sel_hi:[1,0]
	v_rcp_f32_e32 v50, v50
	v_mul_f32_e32 v54, v80, v81
	v_rcp_f32_e32 v54, v54
	v_mul_f32_e32 v62, v62, v50
	v_mul_f32_e32 v50, v58, v94
	v_mul_f32_e32 v58, v50, v54
	v_mul_f32_e32 v50, 0xbfb8aa3b, v55
	v_exp_f32_e32 v54, v50
	v_mul_f32_e32 v50, 0xbfb8aa3b, v91
	v_exp_f32_e32 v55, v50
	v_mul_f32_e32 v50, 0xbfb8aa3b, v51
	v_mul_f32_e32 v51, 0xbfb8aa3b, v95
	v_exp_f32_e32 v50, v50
	v_exp_f32_e32 v51, v51
	v_pk_add_f32 v[54:55], v[54:55], 1.0 op_sel_hi:[1,0]
	v_pk_add_f32 v[50:51], v[50:51], 1.0 op_sel_hi:[1,0]
	v_mul_f32_e32 v54, v54, v55
	v_rcp_f32_e32 v54, v54
	v_mul_f32_e32 v50, v50, v51
	v_rcp_f32_e32 v50, v50
	v_mul_f32_e32 v51, v63, v91
	v_mul_f32_e32 v63, v51, v54
	v_mul_f32_e32 v51, v59, v95
	v_mul_f32_e32 v59, v51, v50
	v_mul_f32_e32 v50, 0xbfb8aa3b, v56
	v_mul_f32_e32 v51, 0xbfb8aa3b, v92
	v_exp_f32_e32 v50, v50
	v_exp_f32_e32 v51, v51
	v_exp_f32_e32 v54, v52
	v_mul_f32_e32 v52, 0xbfb8aa3b, v96
	v_exp_f32_e32 v55, v52
	v_pk_add_f32 v[50:51], v[50:51], 1.0 op_sel_hi:[1,0]
	s_nop 0
	v_mul_f32_e32 v50, v50, v51
	v_rcp_f32_e32 v52, v50
	v_pk_add_f32 v[50:51], v[54:55], 1.0 op_sel_hi:[1,0]
	s_nop 0
	v_mul_f32_e32 v50, v50, v51
	v_rcp_f32_e32 v50, v50
	v_mul_f32_e32 v51, v64, v92
	v_mul_f32_e32 v54, v51, v52
	v_mul_f32_e32 v51, v60, v96
	v_mul_f32_e32 v55, v51, v50
	v_mul_f32_e32 v50, 0xbfb8aa3b, v57
	v_mul_f32_e32 v51, 0xbfb8aa3b, v93
	v_exp_f32_e32 v50, v50
	v_exp_f32_e32 v51, v51
	v_mul_f32_e32 v52, 0xbfb8aa3b, v53
	v_mul_f32_e32 v53, 0xbfb8aa3b, v97
	v_exp_f32_e32 v52, v52
	v_exp_f32_e32 v53, v53
	v_pk_add_f32 v[50:51], v[50:51], 1.0 op_sel_hi:[1,0]
	v_lshlrev_b32_e32 v60, 16, v87
	v_mul_f32_e32 v50, v50, v51
	v_rcp_f32_e32 v56, v50
	v_pk_add_f32 v[50:51], v[52:53], 1.0 op_sel_hi:[1,0]
	v_mul_f32_e32 v52, v61, v97
	v_mul_f32_e32 v50, v50, v51
	v_rcp_f32_e32 v50, v50
	v_mul_f32_e32 v51, v65, v93
	v_mul_f32_e32 v51, v51, v56
; __device__ __forceinline__ u32x4 pack8(const float (&f)[8]) { u32x4 r; r[0] = cvt_pk_bf16(f[0], f[1]); r[1] = cvt_pk_bf16(f[2], f[3]); r[2] = cvt_pk_bf16(f[4], f[5]); r[3] = cvt_pk_bf16(f[6], f[7]); return r; }
;     __device__ __forceinline__ void operator()(EPI_ARGS) const {
;     ...
;         for (int ai = 0; ai < 2; ++ai) if (ai == 0 || !u.half) { u32x4 zz[4];
; #pragma unroll
;             for (int m = 0; m < 4; ++m) zz[m] = *(const u32x4*)(parts + E_PZB + (size_t)EPI_ROW * 1024 + col);
; #pragma unroll
;             for (int m = 0; m < 4; ++m) { float z[8]; unpack8(zz[m], z);
;                 const f32x4 a0 = acc[ai][0][m][0], a1 = acc[ai][0][m][1], b0 = acc[ai][1][m][0], b1 = acc[ai][1][m][1]; float o[8];
; #pragma unroll
;                 for (int j = 0; j < 4; ++j) { o[j] = a0[j] * z[j] * __builtin_amdgcn_rcpf((1.0f + __expf(-b0[j])) * (1.0f + __expf(-z[j]))); o[4 + j] = a1[j] * z[4 + j] * __builtin_amdgcn_rcpf((1.0f + __expf(-b1[j])) * (1.0f + __expf(-z[4 + j]))); }
;                 *(u32x4*)(O + (size_t)EPI_ROW * 1024 + col) = pack8(o); } }
	v_lshlrev_b32_e32 v56, 16, v85
	v_mul_f32_e32 v53, v52, v50
	v_cvt_pk_bf16_f32 v50, v62, v63
	v_cvt_pk_bf16_f32 v51, v54, v51
	v_cvt_pk_bf16_f32 v52, v58, v59
	v_cvt_pk_bf16_f32 v53, v55, v53
	v_lshl_add_u64 v[54:55], s[6:7], 0, v[88:89]
	v_lshl_add_u64 v[54:55], v[54:55], 0, v[144:145]
	global_store_dwordx4 v[54:55], v[50:53], off
	v_lshlrev_b32_e32 v54, 16, v84
	v_lshlrev_b32_e32 v58, 16, v86
	v_exp_f32_e32 v50, v38
	v_mul_f32_e32 v38, 0xbfb8aa3b, v54
	v_exp_f32_e32 v51, v38
	v_exp_f32_e32 v52, v34
	v_mul_f32_e32 v34, 0xbfb8aa3b, v58
	v_exp_f32_e32 v53, v34
	v_pk_add_f32 v[50:51], v[50:51], 1.0 op_sel_hi:[1,0]
	v_mul_f32_e32 v46, v46, v54
	v_mul_f32_e32 v34, v50, v51
	v_pk_add_f32 v[50:51], v[52:53], 1.0 op_sel_hi:[1,0]
	v_rcp_f32_e32 v34, v34
	v_mul_f32_e32 v38, v50, v51
	v_rcp_f32_e32 v38, v38
	v_and_b32_e32 v55, 0xffff0000, v84
	v_mul_f32_e32 v46, v46, v34
	v_mul_f32_e32 v34, v42, v58
	v_mul_f32_e32 v42, v34, v38
	v_mul_f32_e32 v34, 0xbfb8aa3b, v39
	v_and_b32_e32 v59, 0xffff0000, v86
	v_exp_f32_e32 v38, v34
	v_mul_f32_e32 v34, 0xbfb8aa3b, v55
	v_exp_f32_e32 v39, v34
	v_mul_f32_e32 v34, 0xbfb8aa3b, v35
	v_mul_f32_e32 v35, 0xbfb8aa3b, v59
	v_exp_f32_e32 v34, v34
	v_exp_f32_e32 v35, v35
	v_pk_add_f32 v[38:39], v[38:39], 1.0 op_sel_hi:[1,0]
	v_and_b32_e32 v57, 0xffff0000, v85
	v_mul_f32_e32 v38, v38, v39
	v_pk_add_f32 v[34:35], v[34:35], 1.0 op_sel_hi:[1,0]
	v_rcp_f32_e32 v38, v38
	v_mul_f32_e32 v34, v34, v35
	v_rcp_f32_e32 v34, v34
	v_mul_f32_e32 v35, v47, v55
	v_mul_f32_e32 v47, v35, v38
	v_mul_f32_e32 v35, v43, v59
	v_mul_f32_e32 v43, v35, v34
	v_mul_f32_e32 v34, 0xbfb8aa3b, v40
	v_mul_f32_e32 v35, 0xbfb8aa3b, v56
	v_exp_f32_e32 v34, v34
	v_exp_f32_e32 v35, v35
	v_exp_f32_e32 v38, v36
	v_mul_f32_e32 v36, 0xbfb8aa3b, v60
	v_exp_f32_e32 v39, v36
	v_pk_add_f32 v[34:35], v[34:35], 1.0 op_sel_hi:[1,0]
	v_and_b32_e32 v61, 0xffff0000, v87
	v_mul_f32_e32 v34, v34, v35
	v_rcp_f32_e32 v36, v34
	v_pk_add_f32 v[34:35], v[38:39], 1.0 op_sel_hi:[1,0]
	s_nop 0
	v_mul_f32_e32 v34, v34, v35
	v_rcp_f32_e32 v34, v34
	v_mul_f32_e32 v35, v48, v56
	v_mul_f32_e32 v38, v35, v36
	v_mul_f32_e32 v35, v44, v60
	v_mul_f32_e32 v39, v35, v34
	v_mul_f32_e32 v34, 0xbfb8aa3b, v41
	v_mul_f32_e32 v35, 0xbfb8aa3b, v57
	v_exp_f32_e32 v34, v34
	v_exp_f32_e32 v35, v35
	v_mul_f32_e32 v36, 0xbfb8aa3b, v37
	v_mul_f32_e32 v37, 0xbfb8aa3b, v61
	v_exp_f32_e32 v36, v36
	v_exp_f32_e32 v37, v37
	v_pk_add_f32 v[34:35], v[34:35], 1.0 op_sel_hi:[1,0]
	v_lshlrev_b32_e32 v44, 16, v73
	v_mul_f32_e32 v34, v34, v35
	v_rcp_f32_e32 v40, v34
	v_pk_add_f32 v[34:35], v[36:37], 1.0 op_sel_hi:[1,0]
	v_mul_f32_e32 v36, v45, v61
	v_mul_f32_e32 v34, v34, v35
	v_rcp_f32_e32 v34, v34
	v_mul_f32_e32 v35, v49, v57
	v_mul_f32_e32 v35, v35, v40
	v_lshlrev_b32_e32 v40, 16, v71
	v_mul_f32_e32 v37, v36, v34
	v_cvt_pk_bf16_f32 v34, v46, v47
	v_cvt_pk_bf16_f32 v35, v38, v35
	v_cvt_pk_bf16_f32 v36, v42, v43
	v_cvt_pk_bf16_f32 v37, v39, v37
	v_lshl_add_u64 v[38:39], s[6:7], 0, v[78:79]
	v_lshl_add_u64 v[38:39], v[38:39], 0, v[144:145]
	global_store_dwordx4 v[38:39], v[34:37], off
	v_lshlrev_b32_e32 v38, 16, v70
	v_lshlrev_b32_e32 v42, 16, v72
	v_exp_f32_e32 v34, v22
	v_mul_f32_e32 v22, 0xbfb8aa3b, v38
	v_exp_f32_e32 v35, v22
	v_exp_f32_e32 v36, v18
	v_mul_f32_e32 v18, 0xbfb8aa3b, v42
	v_exp_f32_e32 v37, v18
	v_pk_add_f32 v[34:35], v[34:35], 1.0 op_sel_hi:[1,0]
	v_mul_f32_e32 v30, v30, v38
	v_mul_f32_e32 v18, v34, v35
	v_pk_add_f32 v[34:35], v[36:37], 1.0 op_sel_hi:[1,0]
	v_rcp_f32_e32 v18, v18
	v_mul_f32_e32 v22, v34, v35
	v_rcp_f32_e32 v22, v22
	v_and_b32_e32 v39, 0xffff0000, v70
	v_mul_f32_e32 v30, v30, v18
	v_mul_f32_e32 v18, v26, v42
	v_mul_f32_e32 v26, v18, v22
	v_mul_f32_e32 v18, 0xbfb8aa3b, v23
	v_and_b32_e32 v43, 0xffff0000, v72
	v_exp_f32_e32 v22, v18
	v_mul_f32_e32 v18, 0xbfb8aa3b, v39
	v_exp_f32_e32 v23, v18
	v_mul_f32_e32 v18, 0xbfb8aa3b, v19
	v_mul_f32_e32 v19, 0xbfb8aa3b, v43
	v_exp_f32_e32 v18, v18
	v_exp_f32_e32 v19, v19
	v_pk_add_f32 v[22:23], v[22:23], 1.0 op_sel_hi:[1,0]
	v_and_b32_e32 v41, 0xffff0000, v71
	v_mul_f32_e32 v22, v22, v23
	v_pk_add_f32 v[18:19], v[18:19], 1.0 op_sel_hi:[1,0]
	v_rcp_f32_e32 v22, v22
	v_mul_f32_e32 v18, v18, v19
	v_rcp_f32_e32 v18, v18
	v_mul_f32_e32 v19, v31, v39
; __device__ __forceinline__ u32x4 pack8(const float (&f)[8]) { u32x4 r; r[0] = cvt_pk_bf16(f[0], f[1]); r[1] = cvt_pk_bf16(f[2], f[3]); r[2] = cvt_pk_bf16(f[4], f[5]); r[3] = cvt_pk_bf16(f[6], f[7]); return r; }
; #define PG8_WAIT_V(n) asm volatile("s_waitcnt vmcnt(" #n ")" ::: "memory")
; #define PG8_BAR __builtin_amdgcn_s_barrier()
; template <class Sched, class Epi>
; __device__ __forceinline__ void gemm_phase(LAS unsigned char* lds, const Sched& S, const Epi& E, const int K, const int lda, const int ldb) {
;     ...
;         if (!has_next) break;
; #pragma unroll
;         for (int a = 0; a < 2; ++a)
; #pragma unroll
;             for (int b = 0; b < 2; ++b)
; #pragma unroll
;                 for (int m = 0; m < 4; ++m)
; #pragma unroll
;                     for (int n = 0; n < 2; ++n) acc[a][b][m][n] = (f32x4){0.f, 0.f, 0.f, 0.f};
;         cur = nxt; cA = nA; cB = nB; ++ui;
;     }
;     PG8_WAIT_V(0);
;     if (wr == 0) PG8_BAR;
;     PG8_BAR;
;     __device__ __forceinline__ void operator()(EPI_ARGS) const {
;     ...
;             for (int m = 0; m < 4; ++m) zz[m] = *(const u32x4*)(parts + E_PZB + (size_t)EPI_ROW * 1024 + col);
; #pragma unroll
;             for (int m = 0; m < 4; ++m) { float z[8]; unpack8(zz[m], z);
;                 const f32x4 a0 = acc[ai][0][m][0], a1 = acc[ai][0][m][1], b0 = acc[ai][1][m][0], b1 = acc[ai][1][m][1]; float o[8];
; #pragma unroll
;                 for (int j = 0; j < 4; ++j) { o[j] = a0[j] * z[j] * __builtin_amdgcn_rcpf((1.0f + __expf(-b0[j])) * (1.0f + __expf(-z[j]))); o[4 + j] = a1[j] * z[4 + j] * __builtin_amdgcn_rcpf((1.0f + __expf(-b1[j])) * (1.0f + __expf(-z[4 + j]))); }
;                 *(u32x4*)(O + (size_t)EPI_ROW * 1024 + col) = pack8(o); } }
	v_mul_f32_e32 v31, v19, v22
	v_mul_f32_e32 v19, v27, v43
	v_mul_f32_e32 v27, v19, v18
	v_mul_f32_e32 v18, 0xbfb8aa3b, v24
	v_mul_f32_e32 v19, 0xbfb8aa3b, v40
	v_exp_f32_e32 v18, v18
	v_exp_f32_e32 v19, v19
	v_exp_f32_e32 v22, v20
	v_mul_f32_e32 v20, 0xbfb8aa3b, v44
	v_exp_f32_e32 v23, v20
	v_pk_add_f32 v[18:19], v[18:19], 1.0 op_sel_hi:[1,0]
	v_and_b32_e32 v45, 0xffff0000, v73
	v_mul_f32_e32 v18, v18, v19
	v_rcp_f32_e32 v20, v18
	v_pk_add_f32 v[18:19], v[22:23], 1.0 op_sel_hi:[1,0]
	s_nop 0
	v_mul_f32_e32 v18, v18, v19
	v_rcp_f32_e32 v18, v18
	v_mul_f32_e32 v19, v32, v40
	v_mul_f32_e32 v22, v19, v20
	v_mul_f32_e32 v19, v28, v44
	v_mul_f32_e32 v23, v19, v18
	v_mul_f32_e32 v18, 0xbfb8aa3b, v25
	v_mul_f32_e32 v19, 0xbfb8aa3b, v41
	v_exp_f32_e32 v18, v18
	v_exp_f32_e32 v19, v19
	v_mul_f32_e32 v20, 0xbfb8aa3b, v21
	v_mul_f32_e32 v21, 0xbfb8aa3b, v45
	v_exp_f32_e32 v20, v20
	v_exp_f32_e32 v21, v21
	v_pk_add_f32 v[18:19], v[18:19], 1.0 op_sel_hi:[1,0]
	v_lshlrev_b32_e32 v28, 16, v69
	v_mul_f32_e32 v18, v18, v19
	v_rcp_f32_e32 v24, v18
	v_pk_add_f32 v[18:19], v[20:21], 1.0 op_sel_hi:[1,0]
	v_mul_f32_e32 v20, v29, v45
	v_mul_f32_e32 v18, v18, v19
	v_rcp_f32_e32 v18, v18
	v_mul_f32_e32 v19, v33, v41
	v_mul_f32_e32 v19, v19, v24
	v_lshlrev_b32_e32 v24, 16, v67
	v_mul_f32_e32 v21, v20, v18
	v_cvt_pk_bf16_f32 v18, v30, v31
	v_cvt_pk_bf16_f32 v19, v22, v19
	v_cvt_pk_bf16_f32 v20, v26, v27
	v_cvt_pk_bf16_f32 v21, v23, v21
	v_lshl_add_u64 v[22:23], s[6:7], 0, v[76:77]
	v_lshl_add_u64 v[22:23], v[22:23], 0, v[144:145]
	global_store_dwordx4 v[22:23], v[18:21], off
	v_lshlrev_b32_e32 v22, 16, v66
	v_lshlrev_b32_e32 v26, 16, v68
	v_exp_f32_e32 v18, v6
	v_mul_f32_e32 v6, 0xbfb8aa3b, v22
	v_exp_f32_e32 v19, v6
	v_exp_f32_e32 v20, v2
	v_mul_f32_e32 v2, 0xbfb8aa3b, v26
	v_exp_f32_e32 v21, v2
	v_pk_add_f32 v[18:19], v[18:19], 1.0 op_sel_hi:[1,0]
	v_mul_f32_e32 v14, v14, v22
	v_mul_f32_e32 v2, v18, v19
	v_pk_add_f32 v[18:19], v[20:21], 1.0 op_sel_hi:[1,0]
	v_rcp_f32_e32 v2, v2
	v_mul_f32_e32 v6, v18, v19
	v_rcp_f32_e32 v6, v6
	v_and_b32_e32 v23, 0xffff0000, v66
	v_mul_f32_e32 v14, v14, v2
	v_mul_f32_e32 v2, v10, v26
	v_mul_f32_e32 v10, v2, v6
	v_mul_f32_e32 v2, 0xbfb8aa3b, v7
	v_and_b32_e32 v27, 0xffff0000, v68
	v_exp_f32_e32 v6, v2
	v_mul_f32_e32 v2, 0xbfb8aa3b, v23
	v_exp_f32_e32 v7, v2
	v_mul_f32_e32 v2, 0xbfb8aa3b, v3
	v_mul_f32_e32 v3, 0xbfb8aa3b, v27
	v_exp_f32_e32 v2, v2
	v_exp_f32_e32 v3, v3
	v_pk_add_f32 v[6:7], v[6:7], 1.0 op_sel_hi:[1,0]
	v_and_b32_e32 v25, 0xffff0000, v67
	v_mul_f32_e32 v6, v6, v7
	v_pk_add_f32 v[2:3], v[2:3], 1.0 op_sel_hi:[1,0]
	v_rcp_f32_e32 v6, v6
	v_mul_f32_e32 v2, v2, v3
	v_rcp_f32_e32 v2, v2
	v_mul_f32_e32 v3, v15, v23
	v_mul_f32_e32 v15, v3, v6
	v_mul_f32_e32 v3, v11, v27
	v_mul_f32_e32 v11, v3, v2
	v_mul_f32_e32 v2, 0xbfb8aa3b, v8
	v_mul_f32_e32 v3, 0xbfb8aa3b, v24
	v_exp_f32_e32 v2, v2
	v_exp_f32_e32 v3, v3
	v_exp_f32_e32 v6, v4
	v_mul_f32_e32 v4, 0xbfb8aa3b, v28
	v_exp_f32_e32 v7, v4
	v_pk_add_f32 v[2:3], v[2:3], 1.0 op_sel_hi:[1,0]
	v_and_b32_e32 v29, 0xffff0000, v69
	v_mul_f32_e32 v2, v2, v3
	v_rcp_f32_e32 v4, v2
	v_pk_add_f32 v[2:3], v[6:7], 1.0 op_sel_hi:[1,0]
	s_nop 0
	v_mul_f32_e32 v2, v2, v3
	v_rcp_f32_e32 v2, v2
	v_mul_f32_e32 v3, v16, v24
	v_mul_f32_e32 v6, v3, v4
	v_mul_f32_e32 v3, v12, v28
	v_mul_f32_e32 v7, v3, v2
	v_mul_f32_e32 v2, 0xbfb8aa3b, v9
	v_mul_f32_e32 v3, 0xbfb8aa3b, v25
	v_exp_f32_e32 v2, v2
	v_exp_f32_e32 v3, v3
	v_mul_f32_e32 v4, 0xbfb8aa3b, v5
	v_mul_f32_e32 v5, 0xbfb8aa3b, v29
	v_exp_f32_e32 v4, v4
	v_exp_f32_e32 v5, v5
	v_pk_add_f32 v[2:3], v[2:3], 1.0 op_sel_hi:[1,0]
	s_nop 0
	v_mul_f32_e32 v2, v2, v3
	v_rcp_f32_e32 v8, v2
	v_pk_add_f32 v[2:3], v[4:5], 1.0 op_sel_hi:[1,0]
	v_mul_f32_e32 v4, v13, v29
	v_mul_f32_e32 v2, v2, v3
	v_rcp_f32_e32 v2, v2
	v_mul_f32_e32 v3, v17, v25
	v_mul_f32_e32 v3, v3, v8
	v_mul_f32_e32 v5, v4, v2
	v_cvt_pk_bf16_f32 v2, v14, v15
	v_cvt_pk_bf16_f32 v3, v6, v3
	v_cvt_pk_bf16_f32 v4, v10, v11
	v_cvt_pk_bf16_f32 v5, v7, v5
	v_lshl_add_u64 v[6:7], s[6:7], 0, v[74:75]
	v_lshl_add_u64 v[6:7], v[6:7], 0, v[144:145]
	global_store_dwordx4 v[6:7], v[2:5], off
	s_cbranch_vccz .LBB0_1408
	s_waitcnt vmcnt(0)
	s_cmpk_gt_u32 s2, 0xff
	s_cbranch_scc1 .LBB0_1419
	s_barrier

; #define PG8_STAGE(bufoff, gbase, voff) do { _Pragma("unroll") for (int _i = 0; _i < 2; ++_i) \
;         __builtin_amdgcn_global_load_lds((const unsigned*)((const char*)(gbase) + (voff)[_i]), (LAS unsigned*)(lds + (bufoff) + ldsw + _i * 8192), 16, 0, 0); } while (0)
; #define PG8_LDA(dst, b, h) do { _Pragma("unroll") for (int m = 0; m < 4; ++m) _Pragma("unroll") for (int k = 0; k < 2; ++k) dst[m][k] = *(const LAS bf16x8*)(lds + PG8_SA(b, h) + aoff + m * 2048 + k * 1024); } while (0)
; #define PG8_LDB(dst, b, h) do { _Pragma("unroll") for (int n = 0; n < 2; ++n) _Pragma("unroll") for (int k = 0; k < 2; ++k) dst[n][k] = *(const LAS bf16x8*)(lds + PG8_SB(b, h) + boff + n * 2048 + k * 1024); } while (0)
; #define PG8_MMA(ai, bj, At, Bt) do { __builtin_amdgcn_s_setprio(1); _Pragma("unroll") for (int m = 0; m < 4; ++m) _Pragma("unroll") for (int n = 0; n < 2; ++n) _Pragma("unroll") for (int k = 0; k < 2; ++k) \
;         acc[ai][bj][m][n] = __builtin_amdgcn_mfma_f32_16x16x32_bf16(Bt[n][k], At[m][k], acc[ai][bj][m][n], 0, 0, 0); __builtin_amdgcn_s_setprio(0); } while (0)
; #define PG8_WAIT_L(n) asm volatile("s_waitcnt lgkmcnt(" #n ")" ::: "memory")
; template <class Sched, class Epi>
; __device__ __forceinline__ void gemm_phase(LAS unsigned char* lds, const Sched& S, const Epi& E, const int K, const int lda, const int ldb) {
;     ...
;         for (int t = 0; t < nt; t += 2) {
;             const bool last = (t == nt - 2);
;             const char* a1 = cA + (size_t)(t + 1) * kstep;
;             const char* a2 = last ? nA : cA + (size_t)(t + 2) * kstep; const char* b2 = last ? nB : cB + (size_t)(t + 2) * kstep;
;             const char* a3 = a2 + kstep; const char* b3 = b2 + kstep;
;             PG8_LDB(B0, 0, 0); PG8_SCHED; PG8_LDA(At, 0, 0); PG8_STAGE(PG8_SA(1, 1), a1 + hstepA, voffA);
;             PG8_WAIT_L(8); PG8_BAR; PG8_WAIT_L(0); PG8_MMA(0, 0, At, B0); PG8_BAR; PG8_SCHED;
;             PG8_LDB(B1, 0, 1); PG8_STAGE(PG8_SB(0, 0), b2, voffB);
;             PG8_BAR; PG8_WAIT_L(0); PG8_MMA(0, 1, At, B1); PG8_BAR;
;     ...
; #pragma unroll
;         for (int a = 0; a < 2; ++a)
; #pragma unroll
;             for (int b = 0; b < 2; ++b)
; #pragma unroll
;                 for (int m = 0; m < 4; ++m)
; #pragma unroll
;                     for (int n = 0; n < 2; ++n) acc[a][b][m][n] = (f32x4){0.f, 0.f, 0.f, 0.f};
;         cur = nxt; cA = nA; cB = nB; ++ui;
.LBB0_1485:
	s_add_u32 s15, s26, 0x100
	s_addc_u32 s17, s27, 0
	s_add_u32 s6, s6, 0x40080
	v_mov_b32_e32 v2, 0
	s_addc_u32 s7, s7, 0
	s_mov_b32 s19, -2
	v_mov_b32_e32 v3, v2
	v_mov_b32_e32 v4, v2
	v_mov_b32_e32 v5, v2
	v_mov_b32_e32 v6, v2
	v_mov_b32_e32 v7, v2
	v_mov_b32_e32 v8, v2
	v_mov_b32_e32 v9, v2
	v_mov_b32_e32 v10, v2
	v_mov_b32_e32 v11, v2
	v_mov_b32_e32 v12, v2
	v_mov_b32_e32 v13, v2
	v_mov_b32_e32 v14, v2
	v_mov_b32_e32 v15, v2
	v_mov_b32_e32 v16, v2
	v_mov_b32_e32 v17, v2
	v_mov_b32_e32 v18, v2
	v_mov_b32_e32 v19, v2
	v_mov_b32_e32 v20, v2
	v_mov_b32_e32 v21, v2
	v_mov_b32_e32 v22, v2
	v_mov_b32_e32 v23, v2
	v_mov_b32_e32 v24, v2
	v_mov_b32_e32 v25, v2
	v_mov_b32_e32 v26, v2
	v_mov_b32_e32 v27, v2
	v_mov_b32_e32 v28, v2
	v_mov_b32_e32 v29, v2
	v_mov_b32_e32 v30, v2
	v_mov_b32_e32 v31, v2
	v_mov_b32_e32 v32, v2
	v_mov_b32_e32 v33, v2
	v_mov_b32_e32 v34, v2
	v_mov_b32_e32 v35, v2
	v_mov_b32_e32 v36, v2
	v_mov_b32_e32 v37, v2
	v_mov_b32_e32 v38, v2
	v_mov_b32_e32 v39, v2
	v_mov_b32_e32 v40, v2
	v_mov_b32_e32 v41, v2
	v_mov_b32_e32 v42, v2
	v_mov_b32_e32 v43, v2
	v_mov_b32_e32 v44, v2
	v_mov_b32_e32 v45, v2
	v_mov_b32_e32 v46, v2
	v_mov_b32_e32 v47, v2
	v_mov_b32_e32 v48, v2
	v_mov_b32_e32 v49, v2
	v_mov_b32_e32 v50, v2
	v_mov_b32_e32 v51, v2
	v_mov_b32_e32 v52, v2
	v_mov_b32_e32 v53, v2
	v_mov_b32_e32 v54, v2
	v_mov_b32_e32 v55, v2
	v_mov_b32_e32 v56, v2
	v_mov_b32_e32 v57, v2
	v_mov_b32_e32 v58, v2
	v_mov_b32_e32 v59, v2
	v_mov_b32_e32 v60, v2
	v_mov_b32_e32 v61, v2
	v_mov_b32_e32 v62, v2
	v_mov_b32_e32 v63, v2
	v_mov_b32_e32 v64, v2
	v_mov_b32_e32 v65, v2
	v_mov_b32_e32 v66, v2
	v_mov_b32_e32 v67, v2
	v_mov_b32_e32 v68, v2
	v_mov_b32_e32 v69, v2
	v_mov_b32_e32 v70, v2
	v_mov_b32_e32 v71, v2
	v_mov_b32_e32 v72, v2
	v_mov_b32_e32 v73, v2
	v_mov_b32_e32 v74, v2
	v_mov_b32_e32 v75, v2
	v_mov_b32_e32 v76, v2
	v_mov_b32_e32 v77, v2
	v_mov_b32_e32 v78, v2
	v_mov_b32_e32 v79, v2
	v_mov_b32_e32 v80, v2
	v_mov_b32_e32 v81, v2
	v_mov_b32_e32 v82, v2
	v_mov_b32_e32 v83, v2
	v_mov_b32_e32 v84, v2
	v_mov_b32_e32 v85, v2
	v_mov_b32_e32 v86, v2
	v_mov_b32_e32 v87, v2
	v_mov_b32_e32 v88, v2
	v_mov_b32_e32 v89, v2
	v_mov_b32_e32 v90, v2
	v_mov_b32_e32 v91, v2
	v_mov_b32_e32 v92, v2
	v_mov_b32_e32 v93, v2
	v_mov_b32_e32 v94, v2
	v_mov_b32_e32 v95, v2
	v_mov_b32_e32 v96, v2
	v_mov_b32_e32 v97, v2
	v_mov_b32_e32 v98, v2
	v_mov_b32_e32 v99, v2
	v_mov_b32_e32 v100, v2
	v_mov_b32_e32 v101, v2
	v_mov_b32_e32 v102, v2
	v_mov_b32_e32 v103, v2
	v_mov_b32_e32 v104, v2
	v_mov_b32_e32 v105, v2
	v_mov_b32_e32 v106, v2
	v_mov_b32_e32 v107, v2
	v_mov_b32_e32 v108, v2
	v_mov_b32_e32 v109, v2
	v_mov_b32_e32 v110, v2
	v_mov_b32_e32 v111, v2
	v_mov_b32_e32 v112, v2
	v_mov_b32_e32 v113, v2
	v_mov_b32_e32 v114, v2
	v_mov_b32_e32 v115, v2
	v_mov_b32_e32 v116, v2
	v_mov_b32_e32 v117, v2
	v_mov_b32_e32 v118, v2
	v_mov_b32_e32 v119, v2
	v_mov_b32_e32 v120, v2
	v_mov_b32_e32 v121, v2
	v_mov_b32_e32 v122, v2
	v_mov_b32_e32 v123, v2
	v_mov_b32_e32 v124, v2
	v_mov_b32_e32 v125, v2
	v_mov_b32_e32 v126, v2
	v_mov_b32_e32 v127, v2
	v_mov_b32_e32 v128, v2
	v_mov_b32_e32 v129, v2
	v_add_u32_e32 v239, 0x18010, v224
	v_add_u32_e32 v240, 0x1c010, v224
	s_branch .Lal_1486
	.p2align 11
.Lal_1486:
.LBB0_1486:
	ds_read_b128 v[130:133], v233
	ds_read_b128 v[134:137], v233 offset:1024
	ds_read_b128 v[138:141], v233 offset:2048
	ds_read_b128 v[142:145], v233 offset:3072
	s_add_u32 s26, s6, 0xfffc0080
	s_addc_u32 s27, s7, -1
	s_cmp_eq_u32 s19, 12
	s_cselect_b32 s29, s21, s27
	s_cselect_b32 s28, s20, s26
	s_cselect_b32 s27, s23, s17
	s_cselect_b32 s26, s22, s15
	s_add_i32 m0, s31, 0xc000
	ds_read_b128 v[146:149], v234
	ds_read_b128 v[150:153], v234 offset:1024
	ds_read_b128 v[154:157], v234 offset:2048
	ds_read_b128 v[158:161], v234 offset:3072
	ds_read_b128 v[162:165], v234 offset:4096
	ds_read_b128 v[166:169], v234 offset:5120
	ds_read_b128 v[170:173], v234 offset:6144
	ds_read_b128 v[174:177], v234 offset:7168
	global_load_lds_dwordx4 v208, s[6:7]
	s_add_i32 m0, s31, 0xe000
	s_nop 0
	global_load_lds_dwordx4 v206, s[6:7]
	s_waitcnt lgkmcnt(8)
	s_barrier
	s_waitcnt lgkmcnt(0)
	s_setprio 1
	s_waitcnt lgkmcnt(0)
	v_mfma_f32_16x16x32_bf16 v[126:129], v[130:133], v[146:149], v[126:129]
	v_mfma_f32_16x16x32_bf16 v[122:125], v[138:141], v[146:149], v[122:125]
	v_mfma_f32_16x16x32_bf16 v[118:121], v[130:133], v[154:157], v[118:121]
	v_mfma_f32_16x16x32_bf16 v[114:117], v[138:141], v[154:157], v[114:117]
	v_mfma_f32_16x16x32_bf16 v[110:113], v[130:133], v[162:165], v[110:113]
	v_mfma_f32_16x16x32_bf16 v[106:109], v[138:141], v[162:165], v[106:109]
	v_mfma_f32_16x16x32_bf16 v[102:105], v[130:133], v[170:173], v[102:105]
	v_mfma_f32_16x16x32_bf16 v[98:101], v[138:141], v[170:173], v[98:101]
	v_mfma_f32_16x16x32_bf16 v[126:129], v[134:137], v[150:153], v[126:129]
	v_mfma_f32_16x16x32_bf16 v[122:125], v[142:145], v[150:153], v[122:125]
	v_mfma_f32_16x16x32_bf16 v[118:121], v[134:137], v[158:161], v[118:121]
	v_mfma_f32_16x16x32_bf16 v[114:117], v[142:145], v[158:161], v[114:117]
	v_mfma_f32_16x16x32_bf16 v[110:113], v[134:137], v[166:169], v[110:113]
	v_mfma_f32_16x16x32_bf16 v[106:109], v[142:145], v[166:169], v[106:109]
	v_mfma_f32_16x16x32_bf16 v[102:105], v[134:137], v[174:177], v[102:105]
	v_mfma_f32_16x16x32_bf16 v[98:101], v[142:145], v[174:177], v[98:101]
	s_setprio 0
	s_barrier
	s_add_i32 s49, s43, s25
	s_add_u32 s52, s26, s12
	s_addc_u32 s53, s27, s13
	s_mov_b32 m0, s49
	ds_read_b128 v[178:181], v235
	ds_read_b128 v[182:185], v235 offset:1024
	ds_read_b128 v[186:189], v235 offset:2048
	ds_read_b128 v[190:193], v235 offset:3072
	global_load_lds_dwordx4 v200, s[26:27]
	s_add_u32 s54, s26, s12
	s_addc_u32 s55, s27, s13
	s_add_i32 m0, s49, 0x2000
	s_nop 0
	global_load_lds_dwordx4 v204, s[26:27]
	s_barrier
; #define PG8_STAGE(bufoff, gbase, voff) do { _Pragma("unroll") for (int _i = 0; _i < 2; ++_i) \
;         __builtin_amdgcn_global_load_lds((const unsigned*)((const char*)(gbase) + (voff)[_i]), (LAS unsigned*)(lds + (bufoff) + ldsw + _i * 8192), 16, 0, 0); } while (0)
; #define PG8_LDA(dst, b, h) do { _Pragma("unroll") for (int m = 0; m < 4; ++m) _Pragma("unroll") for (int k = 0; k < 2; ++k) dst[m][k] = *(const LAS bf16x8*)(lds + PG8_SA(b, h) + aoff + m * 2048 + k * 1024); } while (0)
; #define PG8_LDB(dst, b, h) do { _Pragma("unroll") for (int n = 0; n < 2; ++n) _Pragma("unroll") for (int k = 0; k < 2; ++k) dst[n][k] = *(const LAS bf16x8*)(lds + PG8_SB(b, h) + boff + n * 2048 + k * 1024); } while (0)
; #define PG8_MMA(ai, bj, At, Bt) do { __builtin_amdgcn_s_setprio(1); _Pragma("unroll") for (int m = 0; m < 4; ++m) _Pragma("unroll") for (int n = 0; n < 2; ++n) _Pragma("unroll") for (int k = 0; k < 2; ++k) \
;         acc[ai][bj][m][n] = __builtin_amdgcn_mfma_f32_16x16x32_bf16(Bt[n][k], At[m][k], acc[ai][bj][m][n], 0, 0, 0); __builtin_amdgcn_s_setprio(0); } while (0)
; #define PG8_WAIT_V(n) asm volatile("s_waitcnt vmcnt(" #n ")" ::: "memory")
; #define PG8_WAIT_L(n) asm volatile("s_waitcnt lgkmcnt(" #n ")" ::: "memory")
; #define PG8_BAR __builtin_amdgcn_s_barrier()
; #define PG8_SCHED __builtin_amdgcn_sched_barrier(0)
; template <class Sched, class Epi>
; __device__ __forceinline__ void gemm_phase(LAS unsigned char* lds, const Sched& S, const Epi& E, const int K, const int lda, const int ldb) {
;     ...
;             PG8_BAR; PG8_WAIT_L(0); PG8_MMA(0, 1, At, B1); PG8_BAR;
;             PG8_LDA(At, 0, 1); PG8_STAGE(PG8_SA(0, 0), a2, voffA);
;             PG8_BAR; PG8_WAIT_L(0); if (!chalf) PG8_MMA(1, 0, At, B0); PG8_BAR; PG8_SCHED;
;             PG8_STAGE(PG8_SB(0, 1), b2 + hstepB, voffB);
;             PG8_WAIT_V(6); PG8_BAR; if (!chalf) PG8_MMA(1, 1, At, B1); PG8_BAR;
;             PG8_LDB(B0, 1, 0); PG8_SCHED; PG8_LDA(At, 1, 0); PG8_STAGE(PG8_SA(0, 1), a2 + hstepA, voffA);
;             PG8_WAIT_L(8); PG8_BAR; PG8_WAIT_L(0); PG8_MMA(0, 0, At, B0); PG8_BAR; PG8_SCHED;
	s_waitcnt lgkmcnt(0)
	s_setprio 1
	s_waitcnt lgkmcnt(0)
	v_mfma_f32_16x16x32_bf16 v[94:97], v[178:181], v[146:149], v[94:97]
	v_mfma_f32_16x16x32_bf16 v[90:93], v[186:189], v[146:149], v[90:93]
	v_mfma_f32_16x16x32_bf16 v[86:89], v[178:181], v[154:157], v[86:89]
	v_mfma_f32_16x16x32_bf16 v[82:85], v[186:189], v[154:157], v[82:85]
	v_mfma_f32_16x16x32_bf16 v[78:81], v[178:181], v[162:165], v[78:81]
	v_mfma_f32_16x16x32_bf16 v[74:77], v[186:189], v[162:165], v[74:77]
	v_mfma_f32_16x16x32_bf16 v[70:73], v[178:181], v[170:173], v[70:73]
	v_mfma_f32_16x16x32_bf16 v[66:69], v[186:189], v[170:173], v[66:69]
	v_mfma_f32_16x16x32_bf16 v[94:97], v[182:185], v[150:153], v[94:97]
	v_mfma_f32_16x16x32_bf16 v[90:93], v[190:193], v[150:153], v[90:93]
	v_mfma_f32_16x16x32_bf16 v[86:89], v[182:185], v[158:161], v[86:89]
	v_mfma_f32_16x16x32_bf16 v[82:85], v[190:193], v[158:161], v[82:85]
	v_mfma_f32_16x16x32_bf16 v[78:81], v[182:185], v[166:169], v[78:81]
	v_mfma_f32_16x16x32_bf16 v[74:77], v[190:193], v[166:169], v[74:77]
	v_mfma_f32_16x16x32_bf16 v[70:73], v[182:185], v[174:177], v[70:73]
	v_mfma_f32_16x16x32_bf16 v[66:69], v[190:193], v[174:177], v[66:69]
	s_setprio 0
	s_mov_b32 m0, s31
	s_add_u32 s56, s28, s12
	s_addc_u32 s57, s29, s13
	s_barrier
	ds_read_b128 v[146:149], v234 offset:16384
	ds_read_b128 v[150:153], v234 offset:17408
	ds_read_b128 v[154:157], v234 offset:18432
	ds_read_b128 v[158:161], v234 offset:19456
	ds_read_b128 v[162:165], v234 offset:20480
	ds_read_b128 v[166:169], v234 offset:21504
	ds_read_b128 v[170:173], v234 offset:22528
	ds_read_b128 v[174:177], v234 offset:23552
	global_load_lds_dwordx4 v198, s[28:29]
	s_add_u32 s58, s28, s12
	s_addc_u32 s59, s29, s13
	s_mov_b32 m0, s33
	s_nop 0
	global_load_lds_dwordx4 v202, s[28:29]
	s_barrier
	s_waitcnt lgkmcnt(0)
	s_setprio 1
	s_waitcnt lgkmcnt(0)
	v_mfma_f32_16x16x32_bf16 v[62:65], v[130:133], v[146:149], v[62:65]
	v_mfma_f32_16x16x32_bf16 v[58:61], v[138:141], v[146:149], v[58:61]
	v_mfma_f32_16x16x32_bf16 v[54:57], v[130:133], v[154:157], v[54:57]
	v_mfma_f32_16x16x32_bf16 v[50:53], v[138:141], v[154:157], v[50:53]
	v_mfma_f32_16x16x32_bf16 v[46:49], v[130:133], v[162:165], v[46:49]
	v_mfma_f32_16x16x32_bf16 v[42:45], v[138:141], v[162:165], v[42:45]
	v_mfma_f32_16x16x32_bf16 v[38:41], v[130:133], v[170:173], v[38:41]
	v_mfma_f32_16x16x32_bf16 v[34:37], v[138:141], v[170:173], v[34:37]
	v_mfma_f32_16x16x32_bf16 v[62:65], v[134:137], v[150:153], v[62:65]
	v_mfma_f32_16x16x32_bf16 v[58:61], v[142:145], v[150:153], v[58:61]
	v_mfma_f32_16x16x32_bf16 v[54:57], v[134:137], v[158:161], v[54:57]
	v_mfma_f32_16x16x32_bf16 v[50:53], v[142:145], v[158:161], v[50:53]
	v_mfma_f32_16x16x32_bf16 v[46:49], v[134:137], v[166:169], v[46:49]
	v_mfma_f32_16x16x32_bf16 v[42:45], v[142:145], v[166:169], v[42:45]
	v_mfma_f32_16x16x32_bf16 v[38:41], v[134:137], v[174:177], v[38:41]
	v_mfma_f32_16x16x32_bf16 v[34:37], v[142:145], v[174:177], v[34:37]
	s_setprio 0
	s_barrier
	s_add_u32 s50, s26, 0x40000
	s_addc_u32 s51, s27, 0
	s_add_i32 s49, s44, s25
	s_mov_b32 m0, s49
	s_nop 0
	global_load_lds_dwordx4 v200, s[50:51]
	s_add_i32 m0, s49, 0x2000
	s_nop 0
	global_load_lds_dwordx4 v204, s[50:51]
	s_waitcnt vmcnt(6)
	s_barrier
	s_setprio 1
	v_mfma_f32_16x16x32_bf16 v[30:33], v[178:181], v[146:149], v[30:33]
	v_mfma_f32_16x16x32_bf16 v[26:29], v[186:189], v[146:149], v[26:29]
	v_mfma_f32_16x16x32_bf16 v[22:25], v[178:181], v[154:157], v[22:25]
	v_mfma_f32_16x16x32_bf16 v[18:21], v[186:189], v[154:157], v[18:21]
	v_mfma_f32_16x16x32_bf16 v[14:17], v[178:181], v[162:165], v[14:17]
	v_mfma_f32_16x16x32_bf16 v[10:13], v[186:189], v[162:165], v[10:13]
	v_mfma_f32_16x16x32_bf16 v[6:9], v[178:181], v[170:173], v[6:9]
	v_mfma_f32_16x16x32_bf16 v[2:5], v[186:189], v[170:173], v[2:5]
	v_mfma_f32_16x16x32_bf16 v[30:33], v[182:185], v[150:153], v[30:33]
	v_mfma_f32_16x16x32_bf16 v[26:29], v[190:193], v[150:153], v[26:29]
	v_mfma_f32_16x16x32_bf16 v[22:25], v[182:185], v[158:161], v[22:25]
	v_mfma_f32_16x16x32_bf16 v[18:21], v[190:193], v[158:161], v[18:21]
	v_mfma_f32_16x16x32_bf16 v[14:17], v[182:185], v[166:169], v[14:17]
	v_mfma_f32_16x16x32_bf16 v[10:13], v[190:193], v[166:169], v[10:13]
	v_mfma_f32_16x16x32_bf16 v[6:9], v[182:185], v[174:177], v[6:9]
	v_mfma_f32_16x16x32_bf16 v[2:5], v[190:193], v[174:177], v[2:5]
	s_setprio 0
	s_add_i32 s49, 16, 0x18000
	s_barrier
	ds_read_b128 v[130:133], v239
	ds_read_b128 v[134:137], v239 offset:1024
	ds_read_b128 v[138:141], v239 offset:2048
	ds_read_b128 v[142:145], v239 offset:3072
	s_add_u32 s28, s28, 0x40000
	s_addc_u32 s29, s29, 0
	s_mov_b32 m0, s34
	ds_read_b128 v[146:149], v234 offset:32768
	ds_read_b128 v[150:153], v234 offset:33792
	ds_read_b128 v[154:157], v234 offset:34816
	ds_read_b128 v[158:161], v234 offset:35840
	ds_read_b128 v[162:165], v234 offset:36864
	ds_read_b128 v[166:169], v234 offset:37888
	ds_read_b128 v[170:173], v234 offset:38912
	ds_read_b128 v[174:177], v234 offset:39936
	global_load_lds_dwordx4 v198, s[28:29]
	s_mov_b32 m0, s35
	s_nop 0
	global_load_lds_dwordx4 v202, s[28:29]
	s_waitcnt lgkmcnt(8)
	s_barrier
; #define PG8_STAGE(bufoff, gbase, voff) do { _Pragma("unroll") for (int _i = 0; _i < 2; ++_i) \
;         __builtin_amdgcn_global_load_lds((const unsigned*)((const char*)(gbase) + (voff)[_i]), (LAS unsigned*)(lds + (bufoff) + ldsw + _i * 8192), 16, 0, 0); } while (0)
; #define PG8_LDA(dst, b, h) do { _Pragma("unroll") for (int m = 0; m < 4; ++m) _Pragma("unroll") for (int k = 0; k < 2; ++k) dst[m][k] = *(const LAS bf16x8*)(lds + PG8_SA(b, h) + aoff + m * 2048 + k * 1024); } while (0)
; #define PG8_LDB(dst, b, h) do { _Pragma("unroll") for (int n = 0; n < 2; ++n) _Pragma("unroll") for (int k = 0; k < 2; ++k) dst[n][k] = *(const LAS bf16x8*)(lds + PG8_SB(b, h) + boff + n * 2048 + k * 1024); } while (0)
; #define PG8_MMA(ai, bj, At, Bt) do { __builtin_amdgcn_s_setprio(1); _Pragma("unroll") for (int m = 0; m < 4; ++m) _Pragma("unroll") for (int n = 0; n < 2; ++n) _Pragma("unroll") for (int k = 0; k < 2; ++k) \
;         acc[ai][bj][m][n] = __builtin_amdgcn_mfma_f32_16x16x32_bf16(Bt[n][k], At[m][k], acc[ai][bj][m][n], 0, 0, 0); __builtin_amdgcn_s_setprio(0); } while (0)
; #define PG8_WAIT_V(n) asm volatile("s_waitcnt vmcnt(" #n ")" ::: "memory")
; #define PG8_WAIT_L(n) asm volatile("s_waitcnt lgkmcnt(" #n ")" ::: "memory")
; #define PG8_BAR __builtin_amdgcn_s_barrier()
; #define PG8_SCHED __builtin_amdgcn_sched_barrier(0)
; template <class Sched, class Epi>
; __device__ __forceinline__ void gemm_phase(LAS unsigned char* lds, const Sched& S, const Epi& E, const int K, const int lda, const int ldb) {
;     ...
;             PG8_WAIT_L(8); PG8_BAR; PG8_WAIT_L(0); PG8_MMA(0, 0, At, B0); PG8_BAR; PG8_SCHED;
;             PG8_LDB(B1, 1, 1); PG8_STAGE(PG8_SB(1, 0), b3, voffB);
;             PG8_BAR; PG8_WAIT_L(0); PG8_MMA(0, 1, At, B1); PG8_BAR;
;             PG8_LDA(At, 1, 1); PG8_STAGE(PG8_SA(1, 0), a3, voffA);
;             PG8_BAR; PG8_WAIT_L(0); if (!chalf) PG8_MMA(1, 0, At, B0); PG8_BAR; PG8_SCHED;
;             PG8_STAGE(PG8_SB(1, 1), b3 + hstepB, voffB);
;             PG8_WAIT_V(6); PG8_BAR; if (!chalf) PG8_MMA(1, 1, At, B1); PG8_BAR;
	s_waitcnt lgkmcnt(0)
	s_setprio 1
	s_waitcnt lgkmcnt(0)
	v_mfma_f32_16x16x32_bf16 v[126:129], v[130:133], v[146:149], v[126:129]
	v_mfma_f32_16x16x32_bf16 v[122:125], v[138:141], v[146:149], v[122:125]
	v_mfma_f32_16x16x32_bf16 v[118:121], v[130:133], v[154:157], v[118:121]
	v_mfma_f32_16x16x32_bf16 v[114:117], v[138:141], v[154:157], v[114:117]
	v_mfma_f32_16x16x32_bf16 v[110:113], v[130:133], v[162:165], v[110:113]
	v_mfma_f32_16x16x32_bf16 v[106:109], v[138:141], v[162:165], v[106:109]
	v_mfma_f32_16x16x32_bf16 v[102:105], v[130:133], v[170:173], v[102:105]
	v_mfma_f32_16x16x32_bf16 v[98:101], v[138:141], v[170:173], v[98:101]
	v_mfma_f32_16x16x32_bf16 v[126:129], v[134:137], v[150:153], v[126:129]
	v_mfma_f32_16x16x32_bf16 v[122:125], v[142:145], v[150:153], v[122:125]
	v_mfma_f32_16x16x32_bf16 v[118:121], v[134:137], v[158:161], v[118:121]
	v_mfma_f32_16x16x32_bf16 v[114:117], v[142:145], v[158:161], v[114:117]
	v_mfma_f32_16x16x32_bf16 v[110:113], v[134:137], v[166:169], v[110:113]
	v_mfma_f32_16x16x32_bf16 v[106:109], v[142:145], v[166:169], v[106:109]
	v_mfma_f32_16x16x32_bf16 v[102:105], v[134:137], v[174:177], v[102:105]
	v_mfma_f32_16x16x32_bf16 v[98:101], v[142:145], v[174:177], v[98:101]
	s_setprio 0
	s_barrier
	s_add_i32 s28, 16, 0x1c000
	s_add_i32 s29, s49, s25
	s_mov_b32 m0, s29
	ds_read_b128 v[178:181], v240
	ds_read_b128 v[182:185], v240 offset:1024
	ds_read_b128 v[186:189], v240 offset:2048
	ds_read_b128 v[190:193], v240 offset:3072
	global_load_lds_dwordx4 v200, s[52:53]
	s_add_i32 m0, s29, 0x2000
	s_nop 0
	global_load_lds_dwordx4 v204, s[54:55]
	s_barrier
	s_waitcnt lgkmcnt(0)
	s_setprio 1
	s_waitcnt lgkmcnt(0)
	v_mfma_f32_16x16x32_bf16 v[94:97], v[178:181], v[146:149], v[94:97]
	v_mfma_f32_16x16x32_bf16 v[90:93], v[186:189], v[146:149], v[90:93]
	v_mfma_f32_16x16x32_bf16 v[86:89], v[178:181], v[154:157], v[86:89]
	v_mfma_f32_16x16x32_bf16 v[82:85], v[186:189], v[154:157], v[82:85]
	v_mfma_f32_16x16x32_bf16 v[78:81], v[178:181], v[162:165], v[78:81]
	v_mfma_f32_16x16x32_bf16 v[74:77], v[186:189], v[162:165], v[74:77]
	v_mfma_f32_16x16x32_bf16 v[70:73], v[178:181], v[170:173], v[70:73]
	v_mfma_f32_16x16x32_bf16 v[66:69], v[186:189], v[170:173], v[66:69]
	v_mfma_f32_16x16x32_bf16 v[94:97], v[182:185], v[150:153], v[94:97]
	v_mfma_f32_16x16x32_bf16 v[90:93], v[190:193], v[150:153], v[90:93]
	v_mfma_f32_16x16x32_bf16 v[86:89], v[182:185], v[158:161], v[86:89]
	v_mfma_f32_16x16x32_bf16 v[82:85], v[190:193], v[158:161], v[82:85]
	v_mfma_f32_16x16x32_bf16 v[78:81], v[182:185], v[166:169], v[78:81]
	v_mfma_f32_16x16x32_bf16 v[74:77], v[190:193], v[166:169], v[74:77]
	v_mfma_f32_16x16x32_bf16 v[70:73], v[182:185], v[174:177], v[70:73]
	v_mfma_f32_16x16x32_bf16 v[66:69], v[190:193], v[174:177], v[66:69]
	s_setprio 0
	s_mov_b32 m0, s39
	s_barrier
	ds_read_b128 v[146:149], v234 offset:49152
	ds_read_b128 v[150:153], v234 offset:50176
	ds_read_b128 v[154:157], v234 offset:51200
	ds_read_b128 v[158:161], v234 offset:52224
	ds_read_b128 v[162:165], v234 offset:53248
	ds_read_b128 v[166:169], v234 offset:54272
	ds_read_b128 v[170:173], v234 offset:55296
	ds_read_b128 v[174:177], v234 offset:56320
	global_load_lds_dwordx4 v198, s[56:57]
	s_mov_b32 m0, s40
	s_nop 0
	global_load_lds_dwordx4 v202, s[58:59]
	s_barrier
	s_waitcnt lgkmcnt(0)
	s_setprio 1
	s_waitcnt lgkmcnt(0)
	v_mfma_f32_16x16x32_bf16 v[62:65], v[130:133], v[146:149], v[62:65]
	v_mfma_f32_16x16x32_bf16 v[58:61], v[138:141], v[146:149], v[58:61]
	v_mfma_f32_16x16x32_bf16 v[54:57], v[130:133], v[154:157], v[54:57]
	v_mfma_f32_16x16x32_bf16 v[50:53], v[138:141], v[154:157], v[50:53]
	v_mfma_f32_16x16x32_bf16 v[46:49], v[130:133], v[162:165], v[46:49]
	v_mfma_f32_16x16x32_bf16 v[42:45], v[138:141], v[162:165], v[42:45]
	v_mfma_f32_16x16x32_bf16 v[38:41], v[130:133], v[170:173], v[38:41]
	v_mfma_f32_16x16x32_bf16 v[34:37], v[138:141], v[170:173], v[34:37]
	v_mfma_f32_16x16x32_bf16 v[62:65], v[134:137], v[150:153], v[62:65]
	v_mfma_f32_16x16x32_bf16 v[58:61], v[142:145], v[150:153], v[58:61]
	v_mfma_f32_16x16x32_bf16 v[54:57], v[134:137], v[158:161], v[54:57]
	v_mfma_f32_16x16x32_bf16 v[50:53], v[142:145], v[158:161], v[50:53]
	v_mfma_f32_16x16x32_bf16 v[46:49], v[134:137], v[166:169], v[46:49]
	v_mfma_f32_16x16x32_bf16 v[42:45], v[142:145], v[166:169], v[42:45]
	v_mfma_f32_16x16x32_bf16 v[38:41], v[134:137], v[174:177], v[38:41]
	v_mfma_f32_16x16x32_bf16 v[34:37], v[142:145], v[174:177], v[34:37]
	s_setprio 0
	s_barrier
	s_add_u32 s26, s26, 0x40080
	s_addc_u32 s27, s27, 0
	s_add_i32 s28, s28, s25
	s_mov_b32 m0, s28
	s_nop 0
	global_load_lds_dwordx4 v200, s[26:27]
	s_add_i32 m0, s28, 0x2000
	s_nop 0
	global_load_lds_dwordx4 v204, s[26:27]
	s_waitcnt vmcnt(6)
	s_barrier
	s_setprio 1
	v_mfma_f32_16x16x32_bf16 v[30:33], v[178:181], v[146:149], v[30:33]
	v_mfma_f32_16x16x32_bf16 v[26:29], v[186:189], v[146:149], v[26:29]
	v_mfma_f32_16x16x32_bf16 v[22:25], v[178:181], v[154:157], v[22:25]
	v_mfma_f32_16x16x32_bf16 v[18:21], v[186:189], v[154:157], v[18:21]
	v_mfma_f32_16x16x32_bf16 v[14:17], v[178:181], v[162:165], v[14:17]
	v_mfma_f32_16x16x32_bf16 v[10:13], v[186:189], v[162:165], v[10:13]
	v_mfma_f32_16x16x32_bf16 v[6:9], v[178:181], v[170:173], v[6:9]
	v_mfma_f32_16x16x32_bf16 v[2:5], v[186:189], v[170:173], v[2:5]
	v_mfma_f32_16x16x32_bf16 v[30:33], v[182:185], v[150:153], v[30:33]
	v_mfma_f32_16x16x32_bf16 v[26:29], v[190:193], v[150:153], v[26:29]
	v_mfma_f32_16x16x32_bf16 v[22:25], v[182:185], v[158:161], v[22:25]
	v_mfma_f32_16x16x32_bf16 v[18:21], v[190:193], v[158:161], v[18:21]
	v_mfma_f32_16x16x32_bf16 v[14:17], v[182:185], v[166:169], v[14:17]
	v_mfma_f32_16x16x32_bf16 v[10:13], v[190:193], v[166:169], v[10:13]
	v_mfma_f32_16x16x32_bf16 v[6:9], v[182:185], v[174:177], v[6:9]
	v_mfma_f32_16x16x32_bf16 v[2:5], v[190:193], v[174:177], v[2:5]
	s_setprio 0
	s_add_i32 s19, s19, 2
	s_add_u32 s15, s15, 0x100
	s_addc_u32 s17, s17, 0
	s_add_u32 s6, s6, 0x100
	s_addc_u32 s7, s7, 0
	s_cmp_gt_u32 s19, 13
	s_barrier
	s_cbranch_scc0 .LBB0_1486
	s_lshl_b32 s6, s48, 11
	s_ashr_i32 s7, s6, 31
	s_lshl_b64 s[26:27], s[6:7], 1
	v_lshl_or_b32 v134, s47, 8, v232
	s_add_u32 s6, s41, s26
	v_ashrrev_i32_e32 v135, 31, v134
	s_addc_u32 s7, s42, s27
	v_lshlrev_b64 v[212:213], 1, v[134:135]
	v_add_u32_e32 v130, s24, v1
	v_lshl_add_u64 v[216:217], s[6:7], 0, v[212:213]
	v_mad_i64_i32 v[132:133], s[6:7], v130, s45, v[216:217]
	global_load_dwordx4 v[194:197], v[132:133], off
	v_ashrrev_i32_e32 v131, 31, v130
	s_cmp_gt_i32 s48, 0
	v_lshl_add_u64 v[218:219], s[8:9], 0, v[212:213]
	v_lshlrev_b64 v[132:133], 12, v[130:131]
	s_cselect_b64 s[28:29], -1, 0
	s_cmp_lt_i32 s48, 1
	v_lshl_add_u64 v[136:137], v[218:219], 0, v[132:133]
	s_cbranch_scc1 .LBB0_1489
	global_load_dwordx4 v[190:193], v[136:137], off
	s_branch .LBB0_1490

; #define PG8_STAGE(bufoff, gbase, voff) do { _Pragma("unroll") for (int _i = 0; _i < 2; ++_i) \
;         __builtin_amdgcn_global_load_lds((const unsigned*)((const char*)(gbase) + (voff)[_i]), (LAS unsigned*)(lds + (bufoff) + ldsw + _i * 8192), 16, 0, 0); } while (0)
; #define PG8_LDA(dst, b, h) do { _Pragma("unroll") for (int m = 0; m < 4; ++m) _Pragma("unroll") for (int k = 0; k < 2; ++k) dst[m][k] = *(const LAS bf16x8*)(lds + PG8_SA(b, h) + aoff + m * 2048 + k * 1024); } while (0)
; #define PG8_LDB(dst, b, h) do { _Pragma("unroll") for (int n = 0; n < 2; ++n) _Pragma("unroll") for (int k = 0; k < 2; ++k) dst[n][k] = *(const LAS bf16x8*)(lds + PG8_SB(b, h) + boff + n * 2048 + k * 1024); } while (0)
; #define PG8_MMA(ai, bj, At, Bt) do { __builtin_amdgcn_s_setprio(1); _Pragma("unroll") for (int m = 0; m < 4; ++m) _Pragma("unroll") for (int n = 0; n < 2; ++n) _Pragma("unroll") for (int k = 0; k < 2; ++k) \
;         acc[ai][bj][m][n] = __builtin_amdgcn_mfma_f32_16x16x32_bf16(Bt[n][k], At[m][k], acc[ai][bj][m][n], 0, 0, 0); __builtin_amdgcn_s_setprio(0); } while (0)
; #define PG8_WAIT_L(n) asm volatile("s_waitcnt lgkmcnt(" #n ")" ::: "memory")
; template <class Sched, class Epi>
; __device__ __forceinline__ void gemm_phase(LAS unsigned char* lds, const Sched& S, const Epi& E, const int K, const int lda, const int ldb) {
;     ...
;         for (int t = 0; t < nt; t += 2) {
;             const bool last = (t == nt - 2);
;             const char* a1 = cA + (size_t)(t + 1) * kstep;
;             const char* a2 = last ? nA : cA + (size_t)(t + 2) * kstep; const char* b2 = last ? nB : cB + (size_t)(t + 2) * kstep;
;             const char* a3 = a2 + kstep; const char* b3 = b2 + kstep;
;             PG8_LDB(B0, 0, 0); PG8_SCHED; PG8_LDA(At, 0, 0); PG8_STAGE(PG8_SA(1, 1), a1 + hstepA, voffA);
;             PG8_WAIT_L(8); PG8_BAR; PG8_WAIT_L(0); PG8_MMA(0, 0, At, B0); PG8_BAR; PG8_SCHED;
;             PG8_LDB(B1, 0, 1); PG8_STAGE(PG8_SB(0, 0), b2, voffB);
;             PG8_BAR; PG8_WAIT_L(0); PG8_MMA(0, 1, At, B1); PG8_BAR;
;     ...
; #pragma unroll
;         for (int a = 0; a < 2; ++a)
; #pragma unroll
;             for (int b = 0; b < 2; ++b)
; #pragma unroll
;                 for (int m = 0; m < 4; ++m)
; #pragma unroll
;                     for (int n = 0; n < 2; ++n) acc[a][b][m][n] = (f32x4){0.f, 0.f, 0.f, 0.f};
;         cur = nxt; cA = nA; cB = nB; ++ui;
.LBB0_1592:
	s_add_u32 s15, s28, 0x100
	s_addc_u32 s17, s29, 0
	s_add_u32 s26, s26, 0x80080
	v_mov_b32_e32 v2, 0
	s_addc_u32 s27, s27, 0
	s_mov_b32 s46, -2
	v_mov_b32_e32 v3, v2
	v_mov_b32_e32 v4, v2
	v_mov_b32_e32 v5, v2
	v_mov_b32_e32 v6, v2
	v_mov_b32_e32 v7, v2
	v_mov_b32_e32 v8, v2
	v_mov_b32_e32 v9, v2
	v_mov_b32_e32 v10, v2
	v_mov_b32_e32 v11, v2
	v_mov_b32_e32 v12, v2
	v_mov_b32_e32 v13, v2
	v_mov_b32_e32 v18, v2
	v_mov_b32_e32 v19, v2
	v_mov_b32_e32 v20, v2
	v_mov_b32_e32 v21, v2
	v_mov_b32_e32 v26, v2
	v_mov_b32_e32 v27, v2
	v_mov_b32_e32 v28, v2
	v_mov_b32_e32 v29, v2
	v_mov_b32_e32 v34, v2
	v_mov_b32_e32 v35, v2
	v_mov_b32_e32 v36, v2
	v_mov_b32_e32 v37, v2
	v_mov_b32_e32 v42, v2
	v_mov_b32_e32 v43, v2
	v_mov_b32_e32 v44, v2
	v_mov_b32_e32 v45, v2
	v_mov_b32_e32 v50, v2
	v_mov_b32_e32 v51, v2
	v_mov_b32_e32 v52, v2
	v_mov_b32_e32 v53, v2
	v_mov_b32_e32 v14, v2
	v_mov_b32_e32 v15, v2
	v_mov_b32_e32 v16, v2
	v_mov_b32_e32 v17, v2
	v_mov_b32_e32 v22, v2
	v_mov_b32_e32 v23, v2
	v_mov_b32_e32 v24, v2
	v_mov_b32_e32 v25, v2
	v_mov_b32_e32 v30, v2
	v_mov_b32_e32 v31, v2
	v_mov_b32_e32 v32, v2
	v_mov_b32_e32 v33, v2
	v_mov_b32_e32 v38, v2
	v_mov_b32_e32 v39, v2
	v_mov_b32_e32 v40, v2
	v_mov_b32_e32 v41, v2
	v_mov_b32_e32 v46, v2
	v_mov_b32_e32 v47, v2
	v_mov_b32_e32 v48, v2
	v_mov_b32_e32 v49, v2
	v_mov_b32_e32 v54, v2
	v_mov_b32_e32 v55, v2
	v_mov_b32_e32 v56, v2
	v_mov_b32_e32 v57, v2
	v_mov_b32_e32 v58, v2
	v_mov_b32_e32 v59, v2
	v_mov_b32_e32 v60, v2
	v_mov_b32_e32 v61, v2
	v_mov_b32_e32 v62, v2
	v_mov_b32_e32 v63, v2
	v_mov_b32_e32 v64, v2
	v_mov_b32_e32 v65, v2
	v_mov_b32_e32 v66, v2
	v_mov_b32_e32 v67, v2
	v_mov_b32_e32 v68, v2
	v_mov_b32_e32 v69, v2
	v_mov_b32_e32 v70, v2
	v_mov_b32_e32 v71, v2
	v_mov_b32_e32 v72, v2
	v_mov_b32_e32 v73, v2
	v_mov_b32_e32 v78, v2
	v_mov_b32_e32 v79, v2
	v_mov_b32_e32 v80, v2
	v_mov_b32_e32 v81, v2
	v_mov_b32_e32 v86, v2
	v_mov_b32_e32 v87, v2
	v_mov_b32_e32 v88, v2
	v_mov_b32_e32 v89, v2
	v_mov_b32_e32 v94, v2
	v_mov_b32_e32 v95, v2
	v_mov_b32_e32 v96, v2
	v_mov_b32_e32 v97, v2
	v_mov_b32_e32 v102, v2
	v_mov_b32_e32 v103, v2
	v_mov_b32_e32 v104, v2
	v_mov_b32_e32 v105, v2
	v_mov_b32_e32 v110, v2
	v_mov_b32_e32 v111, v2
	v_mov_b32_e32 v112, v2
	v_mov_b32_e32 v113, v2
	v_mov_b32_e32 v118, v2
	v_mov_b32_e32 v119, v2
	v_mov_b32_e32 v120, v2
	v_mov_b32_e32 v121, v2
	v_mov_b32_e32 v74, v2
	v_mov_b32_e32 v75, v2
	v_mov_b32_e32 v76, v2
	v_mov_b32_e32 v77, v2
	v_mov_b32_e32 v82, v2
	v_mov_b32_e32 v83, v2
	v_mov_b32_e32 v84, v2
	v_mov_b32_e32 v85, v2
	v_mov_b32_e32 v90, v2
	v_mov_b32_e32 v91, v2
	v_mov_b32_e32 v92, v2
	v_mov_b32_e32 v93, v2
	v_mov_b32_e32 v98, v2
	v_mov_b32_e32 v99, v2
	v_mov_b32_e32 v100, v2
	v_mov_b32_e32 v101, v2
	v_mov_b32_e32 v106, v2
	v_mov_b32_e32 v107, v2
	v_mov_b32_e32 v108, v2
	v_mov_b32_e32 v109, v2
	v_mov_b32_e32 v114, v2
	v_mov_b32_e32 v115, v2
	v_mov_b32_e32 v116, v2
	v_mov_b32_e32 v117, v2
	v_mov_b32_e32 v122, v2
	v_mov_b32_e32 v123, v2
	v_mov_b32_e32 v124, v2
	v_mov_b32_e32 v125, v2
	v_mov_b32_e32 v126, v2
	v_mov_b32_e32 v127, v2
	v_mov_b32_e32 v128, v2
	v_mov_b32_e32 v129, v2
	v_add_u32_e32 v220, 0x18010, v144
	v_add_u32_e32 v221, 0x1c010, v144
	s_branch .Lal_1593
	.p2align 11
.Lal_1593:
.LBB0_1593:
	ds_read_b128 v[156:159], v153
	ds_read_b128 v[160:163], v153 offset:1024
	ds_read_b128 v[164:167], v153 offset:2048
	ds_read_b128 v[168:171], v153 offset:3072
	s_add_u32 s28, s26, 0xfff80080
	s_addc_u32 s29, s27, -1
	s_cmp_eq_u32 s46, 28
	s_cselect_b32 s35, s23, s29
	s_cselect_b32 s34, s22, s28
	s_cselect_b32 s29, s25, s17
	s_cselect_b32 s28, s24, s15
	s_add_i32 m0, s5, 0xc000
	ds_read_b128 v[172:175], v154
	ds_read_b128 v[176:179], v154 offset:1024
	ds_read_b128 v[180:183], v154 offset:2048
	ds_read_b128 v[184:187], v154 offset:3072
	ds_read_b128 v[188:191], v154 offset:4096
	ds_read_b128 v[192:195], v154 offset:5120
	ds_read_b128 v[196:199], v154 offset:6144
	ds_read_b128 v[200:203], v154 offset:7168
	global_load_lds_dwordx4 v140, s[26:27]
	s_add_i32 m0, s5, 0xe000
	s_nop 0
	global_load_lds_dwordx4 v138, s[26:27]
	s_waitcnt lgkmcnt(8)
	s_barrier
	s_waitcnt lgkmcnt(0)
	s_setprio 1
	s_waitcnt lgkmcnt(0)
	v_mfma_f32_16x16x32_bf16 v[126:129], v[156:159], v[172:175], v[126:129]
	v_mfma_f32_16x16x32_bf16 v[122:125], v[164:167], v[172:175], v[122:125]
	v_mfma_f32_16x16x32_bf16 v[114:117], v[156:159], v[180:183], v[114:117]
	v_mfma_f32_16x16x32_bf16 v[106:109], v[164:167], v[180:183], v[106:109]
	v_mfma_f32_16x16x32_bf16 v[98:101], v[156:159], v[188:191], v[98:101]
	v_mfma_f32_16x16x32_bf16 v[90:93], v[164:167], v[188:191], v[90:93]
	v_mfma_f32_16x16x32_bf16 v[82:85], v[156:159], v[196:199], v[82:85]
	v_mfma_f32_16x16x32_bf16 v[74:77], v[164:167], v[196:199], v[74:77]
	v_mfma_f32_16x16x32_bf16 v[126:129], v[160:163], v[176:179], v[126:129]
	v_mfma_f32_16x16x32_bf16 v[122:125], v[168:171], v[176:179], v[122:125]
	v_mfma_f32_16x16x32_bf16 v[114:117], v[160:163], v[184:187], v[114:117]
	v_mfma_f32_16x16x32_bf16 v[106:109], v[168:171], v[184:187], v[106:109]
	v_mfma_f32_16x16x32_bf16 v[98:101], v[160:163], v[192:195], v[98:101]
	v_mfma_f32_16x16x32_bf16 v[90:93], v[168:171], v[192:195], v[90:93]
	v_mfma_f32_16x16x32_bf16 v[82:85], v[160:163], v[200:203], v[82:85]
	v_mfma_f32_16x16x32_bf16 v[74:77], v[168:171], v[200:203], v[74:77]
	s_setprio 0
	s_barrier
	s_add_i32 s47, s43, s31
	s_add_u32 s52, s28, s8
	s_addc_u32 s53, s29, s9
	s_mov_b32 m0, s47
	ds_read_b128 v[204:207], v155
	ds_read_b128 v[208:211], v155 offset:1024
	ds_read_b128 v[212:215], v155 offset:2048
	ds_read_b128 v[216:219], v155 offset:3072
	global_load_lds_dwordx4 v132, s[28:29]
	s_add_u32 s54, s28, s8
	s_addc_u32 s55, s29, s9
	s_add_i32 m0, s47, 0x2000
	s_nop 0
	global_load_lds_dwordx4 v136, s[28:29]
	s_barrier
; #define PG8_STAGE(bufoff, gbase, voff) do { _Pragma("unroll") for (int _i = 0; _i < 2; ++_i) \
;         __builtin_amdgcn_global_load_lds((const unsigned*)((const char*)(gbase) + (voff)[_i]), (LAS unsigned*)(lds + (bufoff) + ldsw + _i * 8192), 16, 0, 0); } while (0)
; #define PG8_LDA(dst, b, h) do { _Pragma("unroll") for (int m = 0; m < 4; ++m) _Pragma("unroll") for (int k = 0; k < 2; ++k) dst[m][k] = *(const LAS bf16x8*)(lds + PG8_SA(b, h) + aoff + m * 2048 + k * 1024); } while (0)
; #define PG8_LDB(dst, b, h) do { _Pragma("unroll") for (int n = 0; n < 2; ++n) _Pragma("unroll") for (int k = 0; k < 2; ++k) dst[n][k] = *(const LAS bf16x8*)(lds + PG8_SB(b, h) + boff + n * 2048 + k * 1024); } while (0)
; #define PG8_MMA(ai, bj, At, Bt) do { __builtin_amdgcn_s_setprio(1); _Pragma("unroll") for (int m = 0; m < 4; ++m) _Pragma("unroll") for (int n = 0; n < 2; ++n) _Pragma("unroll") for (int k = 0; k < 2; ++k) \
;         acc[ai][bj][m][n] = __builtin_amdgcn_mfma_f32_16x16x32_bf16(Bt[n][k], At[m][k], acc[ai][bj][m][n], 0, 0, 0); __builtin_amdgcn_s_setprio(0); } while (0)
; #define PG8_WAIT_V(n) asm volatile("s_waitcnt vmcnt(" #n ")" ::: "memory")
; #define PG8_WAIT_L(n) asm volatile("s_waitcnt lgkmcnt(" #n ")" ::: "memory")
; #define PG8_BAR __builtin_amdgcn_s_barrier()
; #define PG8_SCHED __builtin_amdgcn_sched_barrier(0)
; template <class Sched, class Epi>
; __device__ __forceinline__ void gemm_phase(LAS unsigned char* lds, const Sched& S, const Epi& E, const int K, const int lda, const int ldb) {
;     ...
;             PG8_BAR; PG8_WAIT_L(0); PG8_MMA(0, 1, At, B1); PG8_BAR;
;             PG8_LDA(At, 0, 1); PG8_STAGE(PG8_SA(0, 0), a2, voffA);
;             PG8_BAR; PG8_WAIT_L(0); if (!chalf) PG8_MMA(1, 0, At, B0); PG8_BAR; PG8_SCHED;
;             PG8_STAGE(PG8_SB(0, 1), b2 + hstepB, voffB);
;             PG8_WAIT_V(6); PG8_BAR; if (!chalf) PG8_MMA(1, 1, At, B1); PG8_BAR;
;             PG8_LDB(B0, 1, 0); PG8_SCHED; PG8_LDA(At, 1, 0); PG8_STAGE(PG8_SA(0, 1), a2 + hstepA, voffA);
;             PG8_WAIT_L(8); PG8_BAR; PG8_WAIT_L(0); PG8_MMA(0, 0, At, B0); PG8_BAR; PG8_SCHED;
	s_waitcnt lgkmcnt(0)
	s_setprio 1
	s_waitcnt lgkmcnt(0)
	v_mfma_f32_16x16x32_bf16 v[118:121], v[204:207], v[172:175], v[118:121]
	v_mfma_f32_16x16x32_bf16 v[110:113], v[212:215], v[172:175], v[110:113]
	v_mfma_f32_16x16x32_bf16 v[102:105], v[204:207], v[180:183], v[102:105]
	v_mfma_f32_16x16x32_bf16 v[94:97], v[212:215], v[180:183], v[94:97]
	v_mfma_f32_16x16x32_bf16 v[86:89], v[204:207], v[188:191], v[86:89]
	v_mfma_f32_16x16x32_bf16 v[78:81], v[212:215], v[188:191], v[78:81]
	v_mfma_f32_16x16x32_bf16 v[70:73], v[204:207], v[196:199], v[70:73]
	v_mfma_f32_16x16x32_bf16 v[66:69], v[212:215], v[196:199], v[66:69]
	v_mfma_f32_16x16x32_bf16 v[118:121], v[208:211], v[176:179], v[118:121]
	v_mfma_f32_16x16x32_bf16 v[110:113], v[216:219], v[176:179], v[110:113]
	v_mfma_f32_16x16x32_bf16 v[102:105], v[208:211], v[184:187], v[102:105]
	v_mfma_f32_16x16x32_bf16 v[94:97], v[216:219], v[184:187], v[94:97]
	v_mfma_f32_16x16x32_bf16 v[86:89], v[208:211], v[192:195], v[86:89]
	v_mfma_f32_16x16x32_bf16 v[78:81], v[216:219], v[192:195], v[78:81]
	v_mfma_f32_16x16x32_bf16 v[70:73], v[208:211], v[200:203], v[70:73]
	v_mfma_f32_16x16x32_bf16 v[66:69], v[216:219], v[200:203], v[66:69]
	s_setprio 0
	s_mov_b32 m0, s5
	s_add_u32 s56, s34, s8
	s_addc_u32 s57, s35, s9
	s_barrier
	ds_read_b128 v[172:175], v154 offset:16384
	ds_read_b128 v[176:179], v154 offset:17408
	ds_read_b128 v[180:183], v154 offset:18432
	ds_read_b128 v[184:187], v154 offset:19456
	ds_read_b128 v[188:191], v154 offset:20480
	ds_read_b128 v[192:195], v154 offset:21504
	ds_read_b128 v[196:199], v154 offset:22528
	ds_read_b128 v[200:203], v154 offset:23552
	global_load_lds_dwordx4 v130, s[34:35]
	s_add_u32 s58, s34, s8
	s_addc_u32 s59, s35, s9
	s_mov_b32 m0, s33
	s_nop 0
	global_load_lds_dwordx4 v134, s[34:35]
	s_barrier
	s_waitcnt lgkmcnt(0)
	s_setprio 1
	s_waitcnt lgkmcnt(0)
	v_mfma_f32_16x16x32_bf16 v[62:65], v[156:159], v[172:175], v[62:65]
	v_mfma_f32_16x16x32_bf16 v[58:61], v[164:167], v[172:175], v[58:61]
	v_mfma_f32_16x16x32_bf16 v[54:57], v[156:159], v[180:183], v[54:57]
	v_mfma_f32_16x16x32_bf16 v[46:49], v[164:167], v[180:183], v[46:49]
	v_mfma_f32_16x16x32_bf16 v[38:41], v[156:159], v[188:191], v[38:41]
	v_mfma_f32_16x16x32_bf16 v[30:33], v[164:167], v[188:191], v[30:33]
	v_mfma_f32_16x16x32_bf16 v[22:25], v[156:159], v[196:199], v[22:25]
	v_mfma_f32_16x16x32_bf16 v[14:17], v[164:167], v[196:199], v[14:17]
	v_mfma_f32_16x16x32_bf16 v[62:65], v[160:163], v[176:179], v[62:65]
	v_mfma_f32_16x16x32_bf16 v[58:61], v[168:171], v[176:179], v[58:61]
	v_mfma_f32_16x16x32_bf16 v[54:57], v[160:163], v[184:187], v[54:57]
	v_mfma_f32_16x16x32_bf16 v[46:49], v[168:171], v[184:187], v[46:49]
	v_mfma_f32_16x16x32_bf16 v[38:41], v[160:163], v[192:195], v[38:41]
	v_mfma_f32_16x16x32_bf16 v[30:33], v[168:171], v[192:195], v[30:33]
	v_mfma_f32_16x16x32_bf16 v[22:25], v[160:163], v[200:203], v[22:25]
	v_mfma_f32_16x16x32_bf16 v[14:17], v[168:171], v[200:203], v[14:17]
	s_setprio 0
	s_barrier
	s_add_u32 s48, s28, 0x80000
	s_addc_u32 s49, s29, 0
	s_add_i32 s47, s44, s31
	s_mov_b32 m0, s47
	s_nop 0
	global_load_lds_dwordx4 v132, s[48:49]
	s_add_i32 m0, s47, 0x2000
	s_nop 0
	global_load_lds_dwordx4 v136, s[48:49]
	s_waitcnt vmcnt(6)
	s_barrier
	s_setprio 1
	v_mfma_f32_16x16x32_bf16 v[50:53], v[204:207], v[172:175], v[50:53]
	v_mfma_f32_16x16x32_bf16 v[42:45], v[212:215], v[172:175], v[42:45]
	v_mfma_f32_16x16x32_bf16 v[34:37], v[204:207], v[180:183], v[34:37]
	v_mfma_f32_16x16x32_bf16 v[26:29], v[212:215], v[180:183], v[26:29]
	v_mfma_f32_16x16x32_bf16 v[18:21], v[204:207], v[188:191], v[18:21]
	v_mfma_f32_16x16x32_bf16 v[10:13], v[212:215], v[188:191], v[10:13]
	v_mfma_f32_16x16x32_bf16 v[6:9], v[204:207], v[196:199], v[6:9]
	v_mfma_f32_16x16x32_bf16 v[2:5], v[212:215], v[196:199], v[2:5]
	v_mfma_f32_16x16x32_bf16 v[50:53], v[208:211], v[176:179], v[50:53]
	v_mfma_f32_16x16x32_bf16 v[42:45], v[216:219], v[176:179], v[42:45]
	v_mfma_f32_16x16x32_bf16 v[34:37], v[208:211], v[184:187], v[34:37]
	v_mfma_f32_16x16x32_bf16 v[26:29], v[216:219], v[184:187], v[26:29]
	v_mfma_f32_16x16x32_bf16 v[18:21], v[208:211], v[192:195], v[18:21]
	v_mfma_f32_16x16x32_bf16 v[10:13], v[216:219], v[192:195], v[10:13]
	v_mfma_f32_16x16x32_bf16 v[6:9], v[208:211], v[200:203], v[6:9]
	v_mfma_f32_16x16x32_bf16 v[2:5], v[216:219], v[200:203], v[2:5]
	s_setprio 0
	s_add_i32 s47, 16, 0x18000
	s_barrier
	ds_read_b128 v[156:159], v220
	ds_read_b128 v[160:163], v220 offset:1024
	ds_read_b128 v[164:167], v220 offset:2048
	ds_read_b128 v[168:171], v220 offset:3072
	s_add_u32 s34, s34, 0x80000
	s_addc_u32 s35, s35, 0
	s_mov_b32 m0, s36
	ds_read_b128 v[172:175], v154 offset:32768
	ds_read_b128 v[176:179], v154 offset:33792
	ds_read_b128 v[180:183], v154 offset:34816
	ds_read_b128 v[184:187], v154 offset:35840
	ds_read_b128 v[188:191], v154 offset:36864
	ds_read_b128 v[192:195], v154 offset:37888
	ds_read_b128 v[196:199], v154 offset:38912
	ds_read_b128 v[200:203], v154 offset:39936
	global_load_lds_dwordx4 v130, s[34:35]
	s_mov_b32 m0, s37
	s_nop 0
	global_load_lds_dwordx4 v134, s[34:35]
	s_waitcnt lgkmcnt(8)
	s_barrier
; #define PG8_STAGE(bufoff, gbase, voff) do { _Pragma("unroll") for (int _i = 0; _i < 2; ++_i) \
;         __builtin_amdgcn_global_load_lds((const unsigned*)((const char*)(gbase) + (voff)[_i]), (LAS unsigned*)(lds + (bufoff) + ldsw + _i * 8192), 16, 0, 0); } while (0)
; #define PG8_LDA(dst, b, h) do { _Pragma("unroll") for (int m = 0; m < 4; ++m) _Pragma("unroll") for (int k = 0; k < 2; ++k) dst[m][k] = *(const LAS bf16x8*)(lds + PG8_SA(b, h) + aoff + m * 2048 + k * 1024); } while (0)
; #define PG8_LDB(dst, b, h) do { _Pragma("unroll") for (int n = 0; n < 2; ++n) _Pragma("unroll") for (int k = 0; k < 2; ++k) dst[n][k] = *(const LAS bf16x8*)(lds + PG8_SB(b, h) + boff + n * 2048 + k * 1024); } while (0)
; #define PG8_MMA(ai, bj, At, Bt) do { __builtin_amdgcn_s_setprio(1); _Pragma("unroll") for (int m = 0; m < 4; ++m) _Pragma("unroll") for (int n = 0; n < 2; ++n) _Pragma("unroll") for (int k = 0; k < 2; ++k) \
;         acc[ai][bj][m][n] = __builtin_amdgcn_mfma_f32_16x16x32_bf16(Bt[n][k], At[m][k], acc[ai][bj][m][n], 0, 0, 0); __builtin_amdgcn_s_setprio(0); } while (0)
; #define PG8_WAIT_V(n) asm volatile("s_waitcnt vmcnt(" #n ")" ::: "memory")
; #define PG8_WAIT_L(n) asm volatile("s_waitcnt lgkmcnt(" #n ")" ::: "memory")
; #define PG8_BAR __builtin_amdgcn_s_barrier()
; #define PG8_SCHED __builtin_amdgcn_sched_barrier(0)
; template <class Sched, class Epi>
; __device__ __forceinline__ void gemm_phase(LAS unsigned char* lds, const Sched& S, const Epi& E, const int K, const int lda, const int ldb) {
;     ...
;             PG8_WAIT_L(8); PG8_BAR; PG8_WAIT_L(0); PG8_MMA(0, 0, At, B0); PG8_BAR; PG8_SCHED;
;             PG8_LDB(B1, 1, 1); PG8_STAGE(PG8_SB(1, 0), b3, voffB);
;             PG8_BAR; PG8_WAIT_L(0); PG8_MMA(0, 1, At, B1); PG8_BAR;
;             PG8_LDA(At, 1, 1); PG8_STAGE(PG8_SA(1, 0), a3, voffA);
;             PG8_BAR; PG8_WAIT_L(0); if (!chalf) PG8_MMA(1, 0, At, B0); PG8_BAR; PG8_SCHED;
;             PG8_STAGE(PG8_SB(1, 1), b3 + hstepB, voffB);
;             PG8_WAIT_V(6); PG8_BAR; if (!chalf) PG8_MMA(1, 1, At, B1); PG8_BAR;
	s_waitcnt lgkmcnt(0)
	s_setprio 1
	s_waitcnt lgkmcnt(0)
	v_mfma_f32_16x16x32_bf16 v[126:129], v[156:159], v[172:175], v[126:129]
	v_mfma_f32_16x16x32_bf16 v[122:125], v[164:167], v[172:175], v[122:125]
	v_mfma_f32_16x16x32_bf16 v[114:117], v[156:159], v[180:183], v[114:117]
	v_mfma_f32_16x16x32_bf16 v[106:109], v[164:167], v[180:183], v[106:109]
	v_mfma_f32_16x16x32_bf16 v[98:101], v[156:159], v[188:191], v[98:101]
	v_mfma_f32_16x16x32_bf16 v[90:93], v[164:167], v[188:191], v[90:93]
	v_mfma_f32_16x16x32_bf16 v[82:85], v[156:159], v[196:199], v[82:85]
	v_mfma_f32_16x16x32_bf16 v[74:77], v[164:167], v[196:199], v[74:77]
	v_mfma_f32_16x16x32_bf16 v[126:129], v[160:163], v[176:179], v[126:129]
	v_mfma_f32_16x16x32_bf16 v[122:125], v[168:171], v[176:179], v[122:125]
	v_mfma_f32_16x16x32_bf16 v[114:117], v[160:163], v[184:187], v[114:117]
	v_mfma_f32_16x16x32_bf16 v[106:109], v[168:171], v[184:187], v[106:109]
	v_mfma_f32_16x16x32_bf16 v[98:101], v[160:163], v[192:195], v[98:101]
	v_mfma_f32_16x16x32_bf16 v[90:93], v[168:171], v[192:195], v[90:93]
	v_mfma_f32_16x16x32_bf16 v[82:85], v[160:163], v[200:203], v[82:85]
	v_mfma_f32_16x16x32_bf16 v[74:77], v[168:171], v[200:203], v[74:77]
	s_setprio 0
	s_barrier
	s_add_i32 s34, 16, 0x1c000
	s_add_i32 s35, s47, s31
	s_mov_b32 m0, s35
	ds_read_b128 v[204:207], v221
	ds_read_b128 v[208:211], v221 offset:1024
	ds_read_b128 v[212:215], v221 offset:2048
	ds_read_b128 v[216:219], v221 offset:3072
	global_load_lds_dwordx4 v132, s[52:53]
	s_add_i32 m0, s35, 0x2000
	s_nop 0
	global_load_lds_dwordx4 v136, s[54:55]
	s_barrier
	s_waitcnt lgkmcnt(0)
	s_setprio 1
	s_waitcnt lgkmcnt(0)
	v_mfma_f32_16x16x32_bf16 v[118:121], v[204:207], v[172:175], v[118:121]
	v_mfma_f32_16x16x32_bf16 v[110:113], v[212:215], v[172:175], v[110:113]
	v_mfma_f32_16x16x32_bf16 v[102:105], v[204:207], v[180:183], v[102:105]
	v_mfma_f32_16x16x32_bf16 v[94:97], v[212:215], v[180:183], v[94:97]
	v_mfma_f32_16x16x32_bf16 v[86:89], v[204:207], v[188:191], v[86:89]
	v_mfma_f32_16x16x32_bf16 v[78:81], v[212:215], v[188:191], v[78:81]
	v_mfma_f32_16x16x32_bf16 v[70:73], v[204:207], v[196:199], v[70:73]
	v_mfma_f32_16x16x32_bf16 v[66:69], v[212:215], v[196:199], v[66:69]
	v_mfma_f32_16x16x32_bf16 v[118:121], v[208:211], v[176:179], v[118:121]
	v_mfma_f32_16x16x32_bf16 v[110:113], v[216:219], v[176:179], v[110:113]
	v_mfma_f32_16x16x32_bf16 v[102:105], v[208:211], v[184:187], v[102:105]
	v_mfma_f32_16x16x32_bf16 v[94:97], v[216:219], v[184:187], v[94:97]
	v_mfma_f32_16x16x32_bf16 v[86:89], v[208:211], v[192:195], v[86:89]
	v_mfma_f32_16x16x32_bf16 v[78:81], v[216:219], v[192:195], v[78:81]
	v_mfma_f32_16x16x32_bf16 v[70:73], v[208:211], v[200:203], v[70:73]
	v_mfma_f32_16x16x32_bf16 v[66:69], v[216:219], v[200:203], v[66:69]
	s_setprio 0
	s_mov_b32 m0, s39
	s_barrier
	ds_read_b128 v[172:175], v154 offset:49152
	ds_read_b128 v[176:179], v154 offset:50176
	ds_read_b128 v[180:183], v154 offset:51200
	ds_read_b128 v[184:187], v154 offset:52224
	ds_read_b128 v[188:191], v154 offset:53248
	ds_read_b128 v[192:195], v154 offset:54272
	ds_read_b128 v[196:199], v154 offset:55296
	ds_read_b128 v[200:203], v154 offset:56320
	global_load_lds_dwordx4 v130, s[56:57]
	s_mov_b32 m0, s40
	s_nop 0
	global_load_lds_dwordx4 v134, s[58:59]
	s_barrier
	s_waitcnt lgkmcnt(0)
	s_setprio 1
	s_waitcnt lgkmcnt(0)
	v_mfma_f32_16x16x32_bf16 v[62:65], v[156:159], v[172:175], v[62:65]
	v_mfma_f32_16x16x32_bf16 v[58:61], v[164:167], v[172:175], v[58:61]
	v_mfma_f32_16x16x32_bf16 v[54:57], v[156:159], v[180:183], v[54:57]
	v_mfma_f32_16x16x32_bf16 v[46:49], v[164:167], v[180:183], v[46:49]
	v_mfma_f32_16x16x32_bf16 v[38:41], v[156:159], v[188:191], v[38:41]
	v_mfma_f32_16x16x32_bf16 v[30:33], v[164:167], v[188:191], v[30:33]
	v_mfma_f32_16x16x32_bf16 v[22:25], v[156:159], v[196:199], v[22:25]
	v_mfma_f32_16x16x32_bf16 v[14:17], v[164:167], v[196:199], v[14:17]
	v_mfma_f32_16x16x32_bf16 v[62:65], v[160:163], v[176:179], v[62:65]
	v_mfma_f32_16x16x32_bf16 v[58:61], v[168:171], v[176:179], v[58:61]
	v_mfma_f32_16x16x32_bf16 v[54:57], v[160:163], v[184:187], v[54:57]
	v_mfma_f32_16x16x32_bf16 v[46:49], v[168:171], v[184:187], v[46:49]
	v_mfma_f32_16x16x32_bf16 v[38:41], v[160:163], v[192:195], v[38:41]
	v_mfma_f32_16x16x32_bf16 v[30:33], v[168:171], v[192:195], v[30:33]
	v_mfma_f32_16x16x32_bf16 v[22:25], v[160:163], v[200:203], v[22:25]
	v_mfma_f32_16x16x32_bf16 v[14:17], v[168:171], v[200:203], v[14:17]
	s_setprio 0
	s_barrier
	s_add_u32 s28, s28, 0x80080
	s_addc_u32 s29, s29, 0
	s_add_i32 s34, s34, s31
	s_mov_b32 m0, s34
	s_nop 0
	global_load_lds_dwordx4 v132, s[28:29]
	s_add_i32 m0, s34, 0x2000
	s_nop 0
	global_load_lds_dwordx4 v136, s[28:29]
	s_waitcnt vmcnt(6)
	s_barrier
	s_setprio 1
	v_mfma_f32_16x16x32_bf16 v[50:53], v[204:207], v[172:175], v[50:53]
	v_mfma_f32_16x16x32_bf16 v[42:45], v[212:215], v[172:175], v[42:45]
	v_mfma_f32_16x16x32_bf16 v[34:37], v[204:207], v[180:183], v[34:37]
	v_mfma_f32_16x16x32_bf16 v[26:29], v[212:215], v[180:183], v[26:29]
	v_mfma_f32_16x16x32_bf16 v[18:21], v[204:207], v[188:191], v[18:21]
	v_mfma_f32_16x16x32_bf16 v[10:13], v[212:215], v[188:191], v[10:13]
	v_mfma_f32_16x16x32_bf16 v[6:9], v[204:207], v[196:199], v[6:9]
	v_mfma_f32_16x16x32_bf16 v[2:5], v[212:215], v[196:199], v[2:5]
	v_mfma_f32_16x16x32_bf16 v[50:53], v[208:211], v[176:179], v[50:53]
	v_mfma_f32_16x16x32_bf16 v[42:45], v[216:219], v[176:179], v[42:45]
	v_mfma_f32_16x16x32_bf16 v[34:37], v[208:211], v[184:187], v[34:37]
	v_mfma_f32_16x16x32_bf16 v[26:29], v[216:219], v[184:187], v[26:29]
	v_mfma_f32_16x16x32_bf16 v[18:21], v[208:211], v[192:195], v[18:21]
	v_mfma_f32_16x16x32_bf16 v[10:13], v[216:219], v[192:195], v[10:13]
	v_mfma_f32_16x16x32_bf16 v[6:9], v[208:211], v[200:203], v[6:9]
	v_mfma_f32_16x16x32_bf16 v[2:5], v[216:219], v[200:203], v[2:5]
	s_setprio 0
	s_add_i32 s46, s46, 2
	s_add_u32 s15, s15, 0x100
	s_addc_u32 s17, s17, 0
	s_add_u32 s26, s26, 0x100
	s_addc_u32 s27, s27, 0
	s_cmp_gt_u32 s46, 29
	s_barrier
; __device__ __forceinline__ unsigned cvt_pk_bf16(float lo, float hi) { unsigned r; asm volatile("v_cvt_pk_bf16_f32 %0, %1, %2" : "=v"(r) : "v"(lo), "v"(hi)); return r; }
; #define PG8_WAIT_V(n) asm volatile("s_waitcnt vmcnt(" #n ")" ::: "memory")
; #define PG8_BAR __builtin_amdgcn_s_barrier()
; #define EPI_FOR_ROWS _Pragma("unroll") for (int ai = 0; ai < 2; ++ai) if (ai == 0 || !u.half) _Pragma("unroll") for (int m = 0; m < 4; ++m)
; template <class Sched, class Epi>
; __device__ __forceinline__ void gemm_phase(LAS unsigned char* lds, const Sched& S, const Epi& E, const int K, const int lda, const int ldb) {
;     ...
;         E(acc, cur, wr, wc, fr, fq);
;         if (!has_next) break;
; #pragma unroll
;         for (int a = 0; a < 2; ++a)
; #pragma unroll
;             for (int b = 0; b < 2; ++b)
; #pragma unroll
;                 for (int m = 0; m < 4; ++m)
; #pragma unroll
;                     for (int n = 0; n < 2; ++n) acc[a][b][m][n] = (f32x4){0.f, 0.f, 0.f, 0.f};
;         cur = nxt; cA = nA; cB = nB; ++ui;
;     }
;     PG8_WAIT_V(0);
;     if (wr == 0) PG8_BAR;
;     PG8_BAR;
;     __device__ __forceinline__ void operator()(EPI_ARGS) const {
;         EPI_FOR_ROWS { bf16_t* rp = O + (size_t)EPI_ROW * ldc;
; #pragma unroll
;             for (int bj = 0; bj < 2; ++bj) { const f32x4 v0 = acc[ai][bj][m][0], v1 = acc[ai][bj][m][1]; u32x4 o;
;                 o[0] = cvt_pk_bf16(v0[0], v0[1]); o[1] = cvt_pk_bf16(v0[2], v0[3]); o[2] = cvt_pk_bf16(v1[0], v1[1]); o[3] = cvt_pk_bf16(v1[2], v1[3]);
;                 *(u32x4*)(rp + EPI_COL(bj)) = o; } }
;     }
	s_cbranch_scc0 .LBB0_1593
	v_add_u32_e32 v156, s4, v1
	v_ashrrev_i32_e32 v157, 31, v156
	v_cvt_pk_bf16_f32 v126, v126, v127
	v_cvt_pk_bf16_f32 v127, v128, v129
	v_cvt_pk_bf16_f32 v128, v122, v123
	v_lshl_or_b32 v122, s45, 8, v152
	v_lshlrev_b64 v[156:157], 12, v[156:157]
	v_ashrrev_i32_e32 v123, 31, v122
	v_lshl_add_u64 v[156:157], s[6:7], 0, v[156:157]
	v_lshlrev_b64 v[122:123], 1, v[122:123]
	v_cvt_pk_bf16_f32 v129, v124, v125
	v_lshl_add_u64 v[124:125], v[156:157], 0, v[122:123]
	global_store_dwordx4 v[124:125], v[126:129], off
	v_cvt_pk_bf16_f32 v118, v118, v119
	v_cvt_pk_bf16_f32 v119, v120, v121
	v_cvt_pk_bf16_f32 v120, v110, v111
	v_add_u32_e32 v110, s4, v145
	v_ashrrev_i32_e32 v111, 31, v110
	v_lshlrev_b64 v[110:111], 12, v[110:111]
	v_cvt_pk_bf16_f32 v121, v112, v113
	global_store_dwordx4 v[124:125], v[118:121], off offset:256
	s_and_b64 vcc, exec, s[12:13]
	s_mov_b32 s45, s14
	v_lshl_add_u64 v[118:119], s[6:7], 0, v[110:111]
	v_cvt_pk_bf16_f32 v110, v114, v115
	v_cvt_pk_bf16_f32 v111, v116, v117
	v_cvt_pk_bf16_f32 v112, v106, v107
	v_lshl_add_u64 v[106:107], v[118:119], 0, v[122:123]
	v_cvt_pk_bf16_f32 v113, v108, v109
	global_store_dwordx4 v[106:107], v[110:113], off
	v_cvt_pk_bf16_f32 v102, v102, v103
	v_cvt_pk_bf16_f32 v103, v104, v105
	v_cvt_pk_bf16_f32 v104, v94, v95
	v_add_u32_e32 v94, s4, v146
	v_ashrrev_i32_e32 v95, 31, v94
	v_lshlrev_b64 v[94:95], 12, v[94:95]
	v_cvt_pk_bf16_f32 v105, v96, v97
	global_store_dwordx4 v[106:107], v[102:105], off offset:256
	s_mov_b64 s[28:29], s[20:21]
	s_mov_b64 s[26:27], s[18:19]
	v_lshl_add_u64 v[102:103], s[6:7], 0, v[94:95]
	v_cvt_pk_bf16_f32 v94, v98, v99
	v_cvt_pk_bf16_f32 v95, v100, v101
	v_cvt_pk_bf16_f32 v96, v90, v91
	v_lshl_add_u64 v[90:91], v[102:103], 0, v[122:123]
	v_cvt_pk_bf16_f32 v97, v92, v93
	global_store_dwordx4 v[90:91], v[94:97], off
	v_cvt_pk_bf16_f32 v86, v86, v87
	v_cvt_pk_bf16_f32 v87, v88, v89
	v_cvt_pk_bf16_f32 v88, v78, v79
	v_add_u32_e32 v78, s4, v147
	v_ashrrev_i32_e32 v79, 31, v78
	v_lshlrev_b64 v[78:79], 12, v[78:79]
	v_cvt_pk_bf16_f32 v89, v80, v81
	global_store_dwordx4 v[90:91], v[86:89], off offset:256
	s_nop 1
	v_lshl_add_u64 v[86:87], s[6:7], 0, v[78:79]
	v_cvt_pk_bf16_f32 v78, v82, v83
	v_cvt_pk_bf16_f32 v79, v84, v85
	v_cvt_pk_bf16_f32 v80, v74, v75
	v_lshl_add_u64 v[74:75], v[86:87], 0, v[122:123]
	v_cvt_pk_bf16_f32 v81, v76, v77
	global_store_dwordx4 v[74:75], v[78:81], off
	v_cvt_pk_bf16_f32 v70, v70, v71
	v_cvt_pk_bf16_f32 v71, v72, v73
	v_cvt_pk_bf16_f32 v72, v66, v67
	v_add_u32_e32 v66, s4, v148
	v_ashrrev_i32_e32 v67, 31, v66
	v_lshlrev_b64 v[66:67], 12, v[66:67]
	v_lshl_add_u64 v[66:67], s[6:7], 0, v[66:67]
	v_cvt_pk_bf16_f32 v73, v68, v69
	global_store_dwordx4 v[74:75], v[70:73], off offset:256
	v_cvt_pk_bf16_f32 v62, v62, v63
	v_cvt_pk_bf16_f32 v63, v64, v65
	v_cvt_pk_bf16_f32 v64, v58, v59
	v_lshl_add_u64 v[58:59], v[66:67], 0, v[122:123]
	v_cvt_pk_bf16_f32 v65, v60, v61
	global_store_dwordx4 v[58:59], v[62:65], off
	v_cvt_pk_bf16_f32 v50, v50, v51
	v_cvt_pk_bf16_f32 v51, v52, v53
	v_cvt_pk_bf16_f32 v52, v42, v43
	v_add_u32_e32 v42, s4, v149
	v_ashrrev_i32_e32 v43, 31, v42
	v_lshlrev_b64 v[42:43], 12, v[42:43]
	v_cvt_pk_bf16_f32 v53, v44, v45
	global_store_dwordx4 v[58:59], v[50:53], off offset:256
	s_nop 1
	v_lshl_add_u64 v[50:51], s[6:7], 0, v[42:43]
	v_cvt_pk_bf16_f32 v42, v54, v55
	v_cvt_pk_bf16_f32 v43, v56, v57
	v_cvt_pk_bf16_f32 v44, v46, v47
	v_lshl_add_u64 v[46:47], v[50:51], 0, v[122:123]
	v_cvt_pk_bf16_f32 v45, v48, v49
	global_store_dwordx4 v[46:47], v[42:45], off
	v_cvt_pk_bf16_f32 v34, v34, v35
	v_cvt_pk_bf16_f32 v35, v36, v37
	v_cvt_pk_bf16_f32 v36, v26, v27
	v_add_u32_e32 v26, s4, v150
	v_ashrrev_i32_e32 v27, 31, v26
	v_lshlrev_b64 v[26:27], 12, v[26:27]
	v_cvt_pk_bf16_f32 v37, v28, v29
	global_store_dwordx4 v[46:47], v[34:37], off offset:256
	s_nop 1
	v_lshl_add_u64 v[34:35], s[6:7], 0, v[26:27]
	v_cvt_pk_bf16_f32 v26, v38, v39
	v_cvt_pk_bf16_f32 v27, v40, v41
	v_cvt_pk_bf16_f32 v28, v30, v31
	v_lshl_add_u64 v[30:31], v[34:35], 0, v[122:123]
	v_cvt_pk_bf16_f32 v29, v32, v33
	global_store_dwordx4 v[30:31], v[26:29], off
	v_cvt_pk_bf16_f32 v18, v18, v19
	v_cvt_pk_bf16_f32 v19, v20, v21
	v_cvt_pk_bf16_f32 v20, v10, v11
	v_add_u32_e32 v10, s4, v151
	v_ashrrev_i32_e32 v11, 31, v10
	v_lshlrev_b64 v[10:11], 12, v[10:11]
	v_cvt_pk_bf16_f32 v21, v12, v13
	global_store_dwordx4 v[30:31], v[18:21], off offset:256
	s_mov_b32 s4, s16
	s_nop 0
	v_lshl_add_u64 v[18:19], s[6:7], 0, v[10:11]
	v_cvt_pk_bf16_f32 v10, v22, v23
	v_cvt_pk_bf16_f32 v11, v24, v25
	v_cvt_pk_bf16_f32 v12, v14, v15
	v_lshl_add_u64 v[14:15], v[18:19], 0, v[122:123]
	v_cvt_pk_bf16_f32 v13, v16, v17
	global_store_dwordx4 v[14:15], v[10:13], off
	v_cvt_pk_bf16_f32 v6, v6, v7
	v_cvt_pk_bf16_f32 v7, v8, v9
	v_cvt_pk_bf16_f32 v8, v2, v3
	v_cvt_pk_bf16_f32 v9, v4, v5
	global_store_dwordx4 v[14:15], v[6:9], off offset:256
	s_cbranch_vccz .LBB0_1586
	s_waitcnt vmcnt(0)
	s_cmpk_gt_u32 s1, 0xff
	s_cbranch_scc1 .LBB0_1597
	s_barrier

; #define PREF const __attribute__((address_space(4))) Params&
; __device__ __forceinline__ int tid_opaque() { int t = threadIdx.x; asm volatile("" : "+v"(t)); return t; }
; __device__ __forceinline__ int bid_opaque() { int b = blockIdx.x; asm volatile("" : "+s"(b)); return b; }
; __device__ __forceinline__ float lo_f(unsigned u) { return __uint_as_float(u << 16); }
; __device__ __forceinline__ float hi_f(unsigned u) { return __uint_as_float(u & 0xffff0000u); }
; __device__ __forceinline__ void phase_postnorm(PREF P, int l) {
;     const int tidx = tid_opaque(); const int lane = tidx & 63, gw = (tidx >> 6) * (int)gridDim.x + bid_opaque(), nw = gridDim.x * 8;
;     const float* MOD = (const float*)(P.ws + l * SZ_LAYER + LO_MOD); const float* MOD1 = (const float*)(P.ws + SZ_LAYER + LO_MOD);
;     bf16_t* HB = (bf16_t*)(P.ws + O_HB); const bf16_t* OB = (const bf16_t*)(P.ws + O_PARTS); float* X1 = (float*)(P.ws + O_X1);
;     const int rows = l == 0 ? MTOT : MX;
;     for (int row = gw; row < rows; row += nw) {
;         const int mr = row < MX ? (row >> 12) : 2; const float* md = MOD + mr * 6144;
;         const float* xo = l == 0 ? (row < MX ? P.x + (size_t)row * DM : P.ctx + (size_t)(row - MX) * DM) : X1 + (size_t)row * DM;
;         const bf16_t* op = OB + (size_t)row * DM;
;         f32x4 o[8], xv[8]; float ss = 0.f;
; #pragma unroll
;         for (int i = 0; i < 8; ++i) { const u32x2 ob = *(const u32x2*)(op + (i * 64 + lane) * 4); o[i] = (f32x4){lo_f(ob[0]), hi_f(ob[0]), lo_f(ob[1]), hi_f(ob[1])}; xv[i] = *(const f32x4*)(xo + (i * 64 + lane) * 4); ss += o[i][0] * o[i][0] + o[i][1] * o[i][1] + o[i][2] * o[i][2] + o[i][3] * o[i][3]; }
;         f32x4 gpq[8], gtq[8];
; #pragma unroll
;         for (int i = 0; i < 8; ++i) { const int c = (i * 64 + lane) * 4; gpq[i] = *(const f32x4*)(P.g_post + l * DM + c); gtq[i] = *(const f32x4*)(md + 4096 + c); }
.LBB0_1653:
	s_nop 0
	s_nop 0
	s_mov_b64 s[8:9], s[86:87]
	s_load_dword s0, s[86:87], 0xe0
	s_mov_b32 s1, s84
	s_movk_i32 s1, 0x2000
	v_ashrrev_i32_e32 v1, 6, v0
	s_waitcnt lgkmcnt(0)
	v_mul_lo_u32 v1, v1, s0
	v_add_u32_e32 v32, s84, v1
	v_cmp_gt_i32_e32 vcc, s1, v32
	s_and_saveexec_b64 s[2:3], vcc
	s_cbranch_execz .LBB0_1656
	s_load_dwordx2 s[10:11], s[8:9], 0x38
	s_load_dwordx4 s[4:7], s[8:9], 0xc8
	s_lshl_b32 s2, s0, 3
	v_lshlrev_b32_e32 v1, 2, v0
	s_waitcnt vmcnt(0)
	v_and_b32_e32 v2, 0xfc, v1
	s_waitcnt lgkmcnt(0)
	s_add_u32 s0, s10, 0x2000
	s_addc_u32 s1, s11, 0
	v_mov_b32_e32 v35, 0
	v_or_b32_e32 v4, 0x100, v2
	v_lshlrev_b32_e32 v34, 2, v2
	v_or_b32_e32 v6, 0x200, v2
	v_lshl_add_u64 v[36:37], s[0:1], 0, v[34:35]
	v_lshlrev_b32_e32 v34, 2, v4
	v_or_b32_e32 v8, 0x300, v2
	v_lshl_add_u64 v[38:39], s[0:1], 0, v[34:35]
	v_lshlrev_b32_e32 v34, 2, v6
	v_or_b32_e32 v10, 0x400, v2
	v_lshl_add_u64 v[40:41], s[0:1], 0, v[34:35]
	v_lshlrev_b32_e32 v34, 2, v8
	v_or_b32_e32 v12, 0x500, v2
	v_lshl_add_u64 v[42:43], s[0:1], 0, v[34:35]
	v_lshlrev_b32_e32 v34, 2, v10
	v_or_b32_e32 v14, 0x600, v2
	v_lshl_add_u64 v[44:45], s[0:1], 0, v[34:35]
	v_lshlrev_b32_e32 v34, 2, v12
	s_movk_i32 s3, 0x80
	v_bfrev_b32_e32 v3, 0.5
	v_or_b32_e32 v16, 0x700, v2
	v_lshl_add_u64 v[46:47], s[0:1], 0, v[34:35]
	v_lshlrev_b32_e32 v34, 2, v14
	v_ashrrev_i32_e32 v33, 31, v32
	v_bitop3_b32 v76, v1, s3, v3 bitop3:0x6c
	v_lshl_add_u64 v[48:49], s[0:1], 0, v[34:35]
	v_lshlrev_b32_e32 v34, 2, v16
	v_lshlrev_b64 v[52:53], 12, v[32:33]
	v_and_b32_e32 v0, 63, v0
	s_ashr_i32 s3, s2, 31
	v_lshlrev_b64 v[54:55], 13, v[32:33]
	v_bitop3_b32 v77, v1, 64, v3 bitop3:0x6c
	v_bitop3_b32 v78, v1, 32, v3 bitop3:0x6c
	v_bitop3_b32 v79, v1, 16, v3 bitop3:0x6c
	v_bitop3_b32 v80, v1, 8, v3 bitop3:0x6c
	v_bitop3_b32 v81, v1, 4, v3 bitop3:0x6c
	v_lshl_add_u64 v[50:51], s[0:1], 0, v[34:35]
	v_lshl_or_b32 v52, v0, 3, v52
	s_lshl_b64 s[8:9], s[2:3], 12
	v_lshl_or_b32 v54, v0, 4, v54
	s_lshl_b64 s[10:11], s[2:3], 13
	s_mov_b64 s[12:13], 0
	s_mov_b64 s[14:15], 0xdc36000
	v_lshlrev_b32_e32 v56, 2, v2
	v_lshlrev_b32_e32 v58, 2, v4
	v_lshlrev_b32_e32 v60, 2, v6
	v_lshlrev_b32_e32 v62, 2, v8
	v_lshlrev_b32_e32 v64, 2, v10
	v_lshlrev_b32_e32 v34, 2, v12
	v_lshlrev_b32_e32 v66, 2, v14
	v_lshlrev_b32_e32 v68, 2, v16
	v_mov_b32_e32 v33, 0x358637bd
	s_mov_b32 s3, 0x800000
	s_movk_i32 s16, 0x1000
	s_movk_i32 s17, 0x1fff
	v_mov_b32_e32 v57, v35
	v_mov_b32_e32 v59, v35
	v_mov_b32_e32 v61, v35
	v_mov_b32_e32 v63, v35
	v_mov_b32_e32 v65, v35
